# best with a 12-quad stream ring instead of 20 (P4 + prologue de-serialised + K-loop rotation)
# baseline (speedup 1.0000x reference)
; #define LAS __attribute__((address_space(3)))
; #define RS_LOAD(dst, it0) do { _Pragma("unroll") for (int u = 0; u < 8; ++u) dst[u] = __builtin_nontemporal_load((const f32x4*)(S0 + (size_t)(4 * ((it0) + u)) * DV)); } while (0)
; __device__ __forceinline__ void ret_sample_item(Frame& F, int item) {
;     ...
;     const float gam = 1.0f - exp2f(-5.0f - (float)h);
;     const float g7 = exp2f(7.0f * log2f(gam)), g8 = g7 * gam;
;     ...
;     f32x4 v4[8];
; #pragma unroll
;     for (int m = 0; m < 8; ++m) v4[m] = *(const LAS f32x4*)(vs + m * 512 + e4);
;     f32x4 oacc[4];
; #pragma unroll
;     for (int i = 0; i < 4; ++i) oacc[i] = (f32x4){0.f, 0.f, 0.f, 0.f};
;     ...
;     for (int it0 = 0; it0 < 64; it0 += 16) {
;         RS_LOAD(sb, it0 + 8);
;         RS_PROC(sa, it0);
;         { const int itn = it0 + 16 < 64 ? it0 + 16 : it0; RS_LOAD(sa, itn); }
;         RS_PROC(sb, it0 + 8);
;     }
.LBB0_584:
	s_or_b64 exec, exec, s[78:79]
	v_cvt_f32_ubyte0_e32 v2, s10
	v_sub_f32_e32 v2, 0xc0a00000, v2
	v_cmp_gt_f32_e32 vcc, s82, v2
	s_and_b64 s[68:69], vcc, exec
	s_cselect_b32 s10, 0xffffffc0, 0
	v_cndmask_b32_e32 v3, 0, v169, vcc
	v_add_f32_e32 v2, v2, v3
	v_exp_f32_e32 v2, v2
	s_waitcnt lgkmcnt(0)
	s_barrier
	v_ldexp_f32 v2, v2, s10
	v_sub_f32_e32 v138, 1.0, v2
	v_cmp_gt_f32_e32 vcc, s83, v138
	s_and_b64 s[68:69], vcc, exec
	s_cselect_b32 s10, 32, 0
	v_ldexp_f32 v3, v138, s10
	v_log_f32_e32 v3, v3
	v_cndmask_b32_e32 v2, 0, v170, vcc
	v_mov_b32_e32 v98, 0
	s_mov_b32 s10, 0
	v_sub_f32_e32 v2, v3, v2
	v_mul_f32_e32 v3, 0x40e00000, v2
	v_cmp_gt_f32_e32 vcc, s82, v3
	s_and_b64 s[68:69], vcc, exec
	s_cselect_b32 s22, 0xffffffc0, 0
	v_cndmask_b32_e32 v3, 0, v169, vcc
	v_fmac_f32_e32 v3, 0x40e00000, v2
	v_exp_f32_e32 v2, v3
	v_mov_b64_e32 v[148:149], v[130:131]
	v_mov_b64_e32 v[150:151], v[128:129]
	v_mov_b32_e32 v171, v161
	v_ldexp_f32 v140, v2, s22
	ds_read_b128 v[30:33], v139 offset:16512
	ds_read_b128 v[26:29], v139 offset:18560
	ds_read_b128 v[22:25], v139 offset:20608
	ds_read_b128 v[18:21], v139 offset:22656
	ds_read_b128 v[14:17], v139 offset:24704
	ds_read_b128 v[10:13], v139 offset:26752
	ds_read_b128 v[6:9], v139 offset:28800
	ds_read_b128 v[2:5], v139 offset:30848
	v_mul_f32_e32 v142, v138, v140
	v_mov_b32_e32 v144, v142
	v_mov_b32_e32 v145, v142
	v_mov_b32_e32 v146, v140
	v_mov_b32_e32 v147, v140
	v_mov_b32_e32 v172, v160
	v_mov_b32_e32 v99, v98
	v_mov_b32_e32 v100, v98
	v_mov_b32_e32 v101, v98
	v_mov_b32_e32 v102, v98
	v_mov_b32_e32 v103, v98
	v_mov_b32_e32 v104, v98
	v_mov_b32_e32 v105, v98
	v_mov_b32_e32 v106, v98
	v_mov_b32_e32 v107, v98
	v_mov_b32_e32 v108, v98
	v_mov_b32_e32 v109, v98
	v_mov_b32_e32 v110, v98
	v_mov_b32_e32 v111, v98
	v_mov_b32_e32 v112, v98
	v_mov_b32_e32 v113, v98
	v_lshl_add_u64 v[148:149], v[130:131], 0, v[122:123]
	v_lshl_add_u64 v[150:151], v[128:129], 0, v[122:123]
	s_mov_b32 s74, 0x10000
	s_mov_b32 s75, 0
	v_add_co_u32_e32 v150, vcc, 0x5878000, v150
	v_lshl_add_u64 v[148:149], v[148:149], 0, s[74:75]
	s_mov_b32 s74, 0x2000
	v_addc_co_u32_e32 v151, vcc, 0, v151, vcc
	ds_read_b32 v141, v160
	ds_read_b128 v[114:117], v161
	ds_read_b128 v[176:179], v161 offset:16
	global_load_dwordx4 v[58:61], v[148:149], off nt
	v_lshl_add_u64 v[148:149], v[148:149], 0, s[74:75]
	global_load_dwordx4 v[66:69], v[148:149], off nt
	v_lshl_add_u64 v[148:149], v[148:149], 0, s[74:75]
	global_load_dwordx4 v[74:77], v[148:149], off nt
	v_lshl_add_u64 v[148:149], v[148:149], 0, s[74:75]
	global_load_dwordx4 v[78:81], v[148:149], off nt
	v_lshl_add_u64 v[148:149], v[148:149], 0, s[74:75]
	ds_read_b32 v143, v160 offset:16
	ds_read_b128 v[172:175], v161 offset:128
	ds_read_b128 v[232:235], v161 offset:144
	s_waitcnt vmcnt(11)
	s_waitcnt lgkmcnt(3)
	v_cndmask_b32_e64 v141, 0, v141, s[8:9]
	v_pk_mul_f32 v[180:181], v[26:27], v[114:115] op_sel:[0,1]
	v_pk_mul_f32 v[192:193], v[28:29], v[114:115] op_sel:[0,1]
	v_mfma_f32_16x16x4_f32 v[110:113], v141, v70, v[110:113]
	v_pk_fma_f32 v[180:181], v[30:31], v[114:115], v[180:181] op_sel_hi:[1,0,1]
	v_pk_fma_f32 v[192:193], v[32:33], v[114:115], v[192:193] op_sel_hi:[1,0,1]
	v_pk_fma_f32 v[180:181], v[22:23], v[116:117], v[180:181] op_sel_hi:[1,0,1]
	v_pk_fma_f32 v[192:193], v[24:25], v[116:117], v[192:193] op_sel_hi:[1,0,1]
	v_mfma_f32_16x16x4_f32 v[106:109], v141, v71, v[106:109]
	v_pk_fma_f32 v[180:181], v[18:19], v[116:117], v[180:181] op_sel:[0,1,0]
	v_pk_fma_f32 v[192:193], v[20:21], v[116:117], v[192:193] op_sel:[0,1,0]
	v_pk_fma_f32 v[180:181], v[14:15], v[176:177], v[180:181] op_sel_hi:[1,0,1]
	v_pk_fma_f32 v[192:193], v[16:17], v[176:177], v[192:193] op_sel_hi:[1,0,1]
	v_mfma_f32_16x16x4_f32 v[102:105], v141, v72, v[102:105]
	v_pk_fma_f32 v[180:181], v[10:11], v[176:177], v[180:181] op_sel:[0,1,0]
	v_pk_fma_f32 v[192:193], v[12:13], v[176:177], v[192:193] op_sel:[0,1,0]
	v_pk_fma_f32 v[180:181], v[6:7], v[178:179], v[180:181] op_sel_hi:[1,0,1]
	v_pk_fma_f32 v[192:193], v[8:9], v[178:179], v[192:193] op_sel_hi:[1,0,1]
	v_mfma_f32_16x16x4_f32 v[98:101], v141, v73, v[98:101]
	v_pk_fma_f32 v[180:181], v[2:3], v[178:179], v[180:181] op_sel:[0,1,0]
	v_pk_fma_f32 v[192:193], v[4:5], v[178:179], v[192:193] op_sel:[0,1,0]
	v_pk_mul_f32 v[180:181], v[146:147], v[180:181]
	v_pk_mul_f32 v[192:193], v[146:147], v[192:193]
	v_pk_fma_f32 v[236:237], v[144:145], v[70:71], v[180:181]
	v_pk_fma_f32 v[238:239], v[144:145], v[72:73], v[192:193]
	global_store_dwordx4 v[150:151], v[236:239], off nt
	v_lshl_add_u64 v[150:151], v[150:151], 0, s[74:75]
	global_load_dwordx4 v[70:73], v[148:149], off nt
	v_lshl_add_u64 v[148:149], v[148:149], 0, s[74:75]
	ds_read_b32 v141, v160 offset:32
	ds_read_b128 v[114:117], v161 offset:256
	ds_read_b128 v[176:179], v161 offset:272
	s_waitcnt vmcnt(12)
	s_waitcnt lgkmcnt(3)
; #define RS_LOAD(dst, it0) do { _Pragma("unroll") for (int u = 0; u < 8; ++u) dst[u] = __builtin_nontemporal_load((const f32x4*)(S0 + (size_t)(4 * ((it0) + u)) * DV)); } while (0)
; __device__ __forceinline__ void ret_sample_item(Frame& F, int item) {
;     ...
;     for (int it0 = 0; it0 < 64; it0 += 16) {
;         RS_LOAD(sb, it0 + 8);
;         RS_PROC(sa, it0);
;         { const int itn = it0 + 16 < 64 ? it0 + 16 : it0; RS_LOAD(sa, itn); }
;         RS_PROC(sb, it0 + 8);
;     }
	v_cndmask_b32_e64 v143, 0, v143, s[8:9]
	v_pk_mul_f32 v[180:181], v[26:27], v[172:173] op_sel:[0,1]
	v_pk_mul_f32 v[192:193], v[28:29], v[172:173] op_sel:[0,1]
	v_mfma_f32_16x16x4_f32 v[110:113], v143, v62, v[110:113]
	v_pk_fma_f32 v[180:181], v[30:31], v[172:173], v[180:181] op_sel_hi:[1,0,1]
	v_pk_fma_f32 v[192:193], v[32:33], v[172:173], v[192:193] op_sel_hi:[1,0,1]
	v_pk_fma_f32 v[180:181], v[22:23], v[174:175], v[180:181] op_sel_hi:[1,0,1]
	v_pk_fma_f32 v[192:193], v[24:25], v[174:175], v[192:193] op_sel_hi:[1,0,1]
	v_mfma_f32_16x16x4_f32 v[106:109], v143, v63, v[106:109]
	v_pk_fma_f32 v[180:181], v[18:19], v[174:175], v[180:181] op_sel:[0,1,0]
	v_pk_fma_f32 v[192:193], v[20:21], v[174:175], v[192:193] op_sel:[0,1,0]
	v_pk_fma_f32 v[180:181], v[14:15], v[232:233], v[180:181] op_sel_hi:[1,0,1]
	v_pk_fma_f32 v[192:193], v[16:17], v[232:233], v[192:193] op_sel_hi:[1,0,1]
	v_mfma_f32_16x16x4_f32 v[102:105], v143, v64, v[102:105]
	v_pk_fma_f32 v[180:181], v[10:11], v[232:233], v[180:181] op_sel:[0,1,0]
	v_pk_fma_f32 v[192:193], v[12:13], v[232:233], v[192:193] op_sel:[0,1,0]
	v_pk_fma_f32 v[180:181], v[6:7], v[234:235], v[180:181] op_sel_hi:[1,0,1]
	v_pk_fma_f32 v[192:193], v[8:9], v[234:235], v[192:193] op_sel_hi:[1,0,1]
	v_mfma_f32_16x16x4_f32 v[98:101], v143, v65, v[98:101]
	v_pk_fma_f32 v[180:181], v[2:3], v[234:235], v[180:181] op_sel:[0,1,0]
	v_pk_fma_f32 v[192:193], v[4:5], v[234:235], v[192:193] op_sel:[0,1,0]
	v_pk_mul_f32 v[180:181], v[146:147], v[180:181]
	v_pk_mul_f32 v[192:193], v[146:147], v[192:193]
	v_pk_fma_f32 v[236:237], v[144:145], v[62:63], v[180:181]
	v_pk_fma_f32 v[238:239], v[144:145], v[64:65], v[192:193]
	global_store_dwordx4 v[150:151], v[236:239], off nt
	v_lshl_add_u64 v[150:151], v[150:151], 0, s[74:75]
	global_load_dwordx4 v[62:65], v[148:149], off nt
	v_lshl_add_u64 v[148:149], v[148:149], 0, s[74:75]
	ds_read_b32 v143, v160 offset:48
	ds_read_b128 v[172:175], v161 offset:384
	ds_read_b128 v[232:235], v161 offset:400
	s_waitcnt vmcnt(13)
	s_waitcnt lgkmcnt(3)
	v_cndmask_b32_e64 v141, 0, v141, s[8:9]
	v_pk_mul_f32 v[180:181], v[26:27], v[114:115] op_sel:[0,1]
	v_pk_mul_f32 v[192:193], v[28:29], v[114:115] op_sel:[0,1]
	v_mfma_f32_16x16x4_f32 v[110:113], v141, v54, v[110:113]
	v_pk_fma_f32 v[180:181], v[30:31], v[114:115], v[180:181] op_sel_hi:[1,0,1]
	v_pk_fma_f32 v[192:193], v[32:33], v[114:115], v[192:193] op_sel_hi:[1,0,1]
	v_pk_fma_f32 v[180:181], v[22:23], v[116:117], v[180:181] op_sel_hi:[1,0,1]
	v_pk_fma_f32 v[192:193], v[24:25], v[116:117], v[192:193] op_sel_hi:[1,0,1]
	v_mfma_f32_16x16x4_f32 v[106:109], v141, v55, v[106:109]
	v_pk_fma_f32 v[180:181], v[18:19], v[116:117], v[180:181] op_sel:[0,1,0]
	v_pk_fma_f32 v[192:193], v[20:21], v[116:117], v[192:193] op_sel:[0,1,0]
	v_pk_fma_f32 v[180:181], v[14:15], v[176:177], v[180:181] op_sel_hi:[1,0,1]
	v_pk_fma_f32 v[192:193], v[16:17], v[176:177], v[192:193] op_sel_hi:[1,0,1]
	v_mfma_f32_16x16x4_f32 v[102:105], v141, v56, v[102:105]
	v_pk_fma_f32 v[180:181], v[10:11], v[176:177], v[180:181] op_sel:[0,1,0]
	v_pk_fma_f32 v[192:193], v[12:13], v[176:177], v[192:193] op_sel:[0,1,0]
	v_pk_fma_f32 v[180:181], v[6:7], v[178:179], v[180:181] op_sel_hi:[1,0,1]
	v_pk_fma_f32 v[192:193], v[8:9], v[178:179], v[192:193] op_sel_hi:[1,0,1]
	v_mfma_f32_16x16x4_f32 v[98:101], v141, v57, v[98:101]
	v_pk_fma_f32 v[180:181], v[2:3], v[178:179], v[180:181] op_sel:[0,1,0]
	v_pk_fma_f32 v[192:193], v[4:5], v[178:179], v[192:193] op_sel:[0,1,0]
	v_pk_mul_f32 v[180:181], v[146:147], v[180:181]
	v_pk_mul_f32 v[192:193], v[146:147], v[192:193]
	v_pk_fma_f32 v[236:237], v[144:145], v[54:55], v[180:181]
	v_pk_fma_f32 v[238:239], v[144:145], v[56:57], v[192:193]
	global_store_dwordx4 v[150:151], v[236:239], off nt
	v_lshl_add_u64 v[150:151], v[150:151], 0, s[74:75]
	global_load_dwordx4 v[54:57], v[148:149], off nt
	v_lshl_add_u64 v[148:149], v[148:149], 0, s[74:75]
	ds_read_b32 v141, v160 offset:64
	ds_read_b128 v[114:117], v161 offset:512
	ds_read_b128 v[176:179], v161 offset:528
	s_waitcnt vmcnt(14)
	s_waitcnt lgkmcnt(3)
	v_cndmask_b32_e64 v143, 0, v143, s[8:9]
	v_pk_mul_f32 v[180:181], v[26:27], v[172:173] op_sel:[0,1]
	v_pk_mul_f32 v[192:193], v[28:29], v[172:173] op_sel:[0,1]
	v_mfma_f32_16x16x4_f32 v[110:113], v143, v50, v[110:113]
	v_pk_fma_f32 v[180:181], v[30:31], v[172:173], v[180:181] op_sel_hi:[1,0,1]
	v_pk_fma_f32 v[192:193], v[32:33], v[172:173], v[192:193] op_sel_hi:[1,0,1]
	v_pk_fma_f32 v[180:181], v[22:23], v[174:175], v[180:181] op_sel_hi:[1,0,1]
	v_pk_fma_f32 v[192:193], v[24:25], v[174:175], v[192:193] op_sel_hi:[1,0,1]
	v_mfma_f32_16x16x4_f32 v[106:109], v143, v51, v[106:109]
	v_pk_fma_f32 v[180:181], v[18:19], v[174:175], v[180:181] op_sel:[0,1,0]
	v_pk_fma_f32 v[192:193], v[20:21], v[174:175], v[192:193] op_sel:[0,1,0]
	v_pk_fma_f32 v[180:181], v[14:15], v[232:233], v[180:181] op_sel_hi:[1,0,1]
	v_pk_fma_f32 v[192:193], v[16:17], v[232:233], v[192:193] op_sel_hi:[1,0,1]
	v_mfma_f32_16x16x4_f32 v[102:105], v143, v52, v[102:105]
	v_pk_fma_f32 v[180:181], v[10:11], v[232:233], v[180:181] op_sel:[0,1,0]
	v_pk_fma_f32 v[192:193], v[12:13], v[232:233], v[192:193] op_sel:[0,1,0]
	v_pk_fma_f32 v[180:181], v[6:7], v[234:235], v[180:181] op_sel_hi:[1,0,1]
	v_pk_fma_f32 v[192:193], v[8:9], v[234:235], v[192:193] op_sel_hi:[1,0,1]
	v_mfma_f32_16x16x4_f32 v[98:101], v143, v53, v[98:101]
	v_pk_fma_f32 v[180:181], v[2:3], v[234:235], v[180:181] op_sel:[0,1,0]
	v_pk_fma_f32 v[192:193], v[4:5], v[234:235], v[192:193] op_sel:[0,1,0]
	v_pk_mul_f32 v[180:181], v[146:147], v[180:181]
	v_pk_mul_f32 v[192:193], v[146:147], v[192:193]
	v_pk_fma_f32 v[236:237], v[144:145], v[50:51], v[180:181]
	v_pk_fma_f32 v[238:239], v[144:145], v[52:53], v[192:193]
	global_store_dwordx4 v[150:151], v[236:239], off nt
	v_lshl_add_u64 v[150:151], v[150:151], 0, s[74:75]
	global_load_dwordx4 v[50:53], v[148:149], off nt
	v_lshl_add_u64 v[148:149], v[148:149], 0, s[74:75]
	ds_read_b32 v143, v160 offset:80
	ds_read_b128 v[172:175], v161 offset:640
	ds_read_b128 v[232:235], v161 offset:656
	s_waitcnt vmcnt(15)
; #define RS_LOAD(dst, it0) do { _Pragma("unroll") for (int u = 0; u < 8; ++u) dst[u] = __builtin_nontemporal_load((const f32x4*)(S0 + (size_t)(4 * ((it0) + u)) * DV)); } while (0)
; __device__ __forceinline__ void ret_sample_item(Frame& F, int item) {
;     ...
;     for (int it0 = 0; it0 < 64; it0 += 16) {
;         RS_LOAD(sb, it0 + 8);
;         RS_PROC(sa, it0);
;         { const int itn = it0 + 16 < 64 ? it0 + 16 : it0; RS_LOAD(sa, itn); }
;         RS_PROC(sb, it0 + 8);
;     }
	s_waitcnt lgkmcnt(3)
	v_cndmask_b32_e64 v141, 0, v141, s[8:9]
	v_pk_mul_f32 v[180:181], v[26:27], v[114:115] op_sel:[0,1]
	v_pk_mul_f32 v[192:193], v[28:29], v[114:115] op_sel:[0,1]
	v_mfma_f32_16x16x4_f32 v[110:113], v141, v46, v[110:113]
	v_pk_fma_f32 v[180:181], v[30:31], v[114:115], v[180:181] op_sel_hi:[1,0,1]
	v_pk_fma_f32 v[192:193], v[32:33], v[114:115], v[192:193] op_sel_hi:[1,0,1]
	v_pk_fma_f32 v[180:181], v[22:23], v[116:117], v[180:181] op_sel_hi:[1,0,1]
	v_pk_fma_f32 v[192:193], v[24:25], v[116:117], v[192:193] op_sel_hi:[1,0,1]
	v_mfma_f32_16x16x4_f32 v[106:109], v141, v47, v[106:109]
	v_pk_fma_f32 v[180:181], v[18:19], v[116:117], v[180:181] op_sel:[0,1,0]
	v_pk_fma_f32 v[192:193], v[20:21], v[116:117], v[192:193] op_sel:[0,1,0]
	v_pk_fma_f32 v[180:181], v[14:15], v[176:177], v[180:181] op_sel_hi:[1,0,1]
	v_pk_fma_f32 v[192:193], v[16:17], v[176:177], v[192:193] op_sel_hi:[1,0,1]
	v_mfma_f32_16x16x4_f32 v[102:105], v141, v48, v[102:105]
	v_pk_fma_f32 v[180:181], v[10:11], v[176:177], v[180:181] op_sel:[0,1,0]
	v_pk_fma_f32 v[192:193], v[12:13], v[176:177], v[192:193] op_sel:[0,1,0]
	v_pk_fma_f32 v[180:181], v[6:7], v[178:179], v[180:181] op_sel_hi:[1,0,1]
	v_pk_fma_f32 v[192:193], v[8:9], v[178:179], v[192:193] op_sel_hi:[1,0,1]
	v_mfma_f32_16x16x4_f32 v[98:101], v141, v49, v[98:101]
	v_pk_fma_f32 v[180:181], v[2:3], v[178:179], v[180:181] op_sel:[0,1,0]
	v_pk_fma_f32 v[192:193], v[4:5], v[178:179], v[192:193] op_sel:[0,1,0]
	v_pk_mul_f32 v[180:181], v[146:147], v[180:181]
	v_pk_mul_f32 v[192:193], v[146:147], v[192:193]
	v_pk_fma_f32 v[236:237], v[144:145], v[46:47], v[180:181]
	v_pk_fma_f32 v[238:239], v[144:145], v[48:49], v[192:193]
	global_store_dwordx4 v[150:151], v[236:239], off nt
	v_lshl_add_u64 v[150:151], v[150:151], 0, s[74:75]
	global_load_dwordx4 v[46:49], v[148:149], off nt
	v_lshl_add_u64 v[148:149], v[148:149], 0, s[74:75]
	ds_read_b32 v141, v160 offset:96
	ds_read_b128 v[114:117], v161 offset:768
	ds_read_b128 v[176:179], v161 offset:784
	s_waitcnt vmcnt(16)
	s_waitcnt lgkmcnt(3)
	v_cndmask_b32_e64 v143, 0, v143, s[8:9]
	v_pk_mul_f32 v[180:181], v[26:27], v[172:173] op_sel:[0,1]
	v_pk_mul_f32 v[192:193], v[28:29], v[172:173] op_sel:[0,1]
	v_mfma_f32_16x16x4_f32 v[110:113], v143, v42, v[110:113]
	v_pk_fma_f32 v[180:181], v[30:31], v[172:173], v[180:181] op_sel_hi:[1,0,1]
	v_pk_fma_f32 v[192:193], v[32:33], v[172:173], v[192:193] op_sel_hi:[1,0,1]
	v_pk_fma_f32 v[180:181], v[22:23], v[174:175], v[180:181] op_sel_hi:[1,0,1]
	v_pk_fma_f32 v[192:193], v[24:25], v[174:175], v[192:193] op_sel_hi:[1,0,1]
	v_mfma_f32_16x16x4_f32 v[106:109], v143, v43, v[106:109]
	v_pk_fma_f32 v[180:181], v[18:19], v[174:175], v[180:181] op_sel:[0,1,0]
	v_pk_fma_f32 v[192:193], v[20:21], v[174:175], v[192:193] op_sel:[0,1,0]
	v_pk_fma_f32 v[180:181], v[14:15], v[232:233], v[180:181] op_sel_hi:[1,0,1]
	v_pk_fma_f32 v[192:193], v[16:17], v[232:233], v[192:193] op_sel_hi:[1,0,1]
	v_mfma_f32_16x16x4_f32 v[102:105], v143, v44, v[102:105]
	v_pk_fma_f32 v[180:181], v[10:11], v[232:233], v[180:181] op_sel:[0,1,0]
	v_pk_fma_f32 v[192:193], v[12:13], v[232:233], v[192:193] op_sel:[0,1,0]
	v_pk_fma_f32 v[180:181], v[6:7], v[234:235], v[180:181] op_sel_hi:[1,0,1]
	v_pk_fma_f32 v[192:193], v[8:9], v[234:235], v[192:193] op_sel_hi:[1,0,1]
	v_mfma_f32_16x16x4_f32 v[98:101], v143, v45, v[98:101]
	v_pk_fma_f32 v[180:181], v[2:3], v[234:235], v[180:181] op_sel:[0,1,0]
	v_pk_fma_f32 v[192:193], v[4:5], v[234:235], v[192:193] op_sel:[0,1,0]
	v_pk_mul_f32 v[180:181], v[146:147], v[180:181]
	v_pk_mul_f32 v[192:193], v[146:147], v[192:193]
	v_pk_fma_f32 v[236:237], v[144:145], v[42:43], v[180:181]
	v_pk_fma_f32 v[238:239], v[144:145], v[44:45], v[192:193]
	global_store_dwordx4 v[150:151], v[236:239], off nt
	v_lshl_add_u64 v[150:151], v[150:151], 0, s[74:75]
	global_load_dwordx4 v[42:45], v[148:149], off nt
	v_lshl_add_u64 v[148:149], v[148:149], 0, s[74:75]
	ds_read_b32 v143, v160 offset:112
	ds_read_b128 v[172:175], v161 offset:896
	ds_read_b128 v[232:235], v161 offset:912
	s_waitcnt vmcnt(17)
	s_waitcnt lgkmcnt(3)
	v_cndmask_b32_e64 v141, 0, v141, s[8:9]
	v_pk_mul_f32 v[180:181], v[26:27], v[114:115] op_sel:[0,1]
	v_pk_mul_f32 v[192:193], v[28:29], v[114:115] op_sel:[0,1]
	v_mfma_f32_16x16x4_f32 v[110:113], v141, v38, v[110:113]
	v_pk_fma_f32 v[180:181], v[30:31], v[114:115], v[180:181] op_sel_hi:[1,0,1]
	v_pk_fma_f32 v[192:193], v[32:33], v[114:115], v[192:193] op_sel_hi:[1,0,1]
	v_pk_fma_f32 v[180:181], v[22:23], v[116:117], v[180:181] op_sel_hi:[1,0,1]
	v_pk_fma_f32 v[192:193], v[24:25], v[116:117], v[192:193] op_sel_hi:[1,0,1]
	v_mfma_f32_16x16x4_f32 v[106:109], v141, v39, v[106:109]
	v_pk_fma_f32 v[180:181], v[18:19], v[116:117], v[180:181] op_sel:[0,1,0]
	v_pk_fma_f32 v[192:193], v[20:21], v[116:117], v[192:193] op_sel:[0,1,0]
	v_pk_fma_f32 v[180:181], v[14:15], v[176:177], v[180:181] op_sel_hi:[1,0,1]
	v_pk_fma_f32 v[192:193], v[16:17], v[176:177], v[192:193] op_sel_hi:[1,0,1]
	v_mfma_f32_16x16x4_f32 v[102:105], v141, v40, v[102:105]
	v_pk_fma_f32 v[180:181], v[10:11], v[176:177], v[180:181] op_sel:[0,1,0]
	v_pk_fma_f32 v[192:193], v[12:13], v[176:177], v[192:193] op_sel:[0,1,0]
	v_pk_fma_f32 v[180:181], v[6:7], v[178:179], v[180:181] op_sel_hi:[1,0,1]
	v_pk_fma_f32 v[192:193], v[8:9], v[178:179], v[192:193] op_sel_hi:[1,0,1]
	v_mfma_f32_16x16x4_f32 v[98:101], v141, v41, v[98:101]
	v_pk_fma_f32 v[180:181], v[2:3], v[178:179], v[180:181] op_sel:[0,1,0]
	v_pk_fma_f32 v[192:193], v[4:5], v[178:179], v[192:193] op_sel:[0,1,0]
	v_pk_mul_f32 v[180:181], v[146:147], v[180:181]
	v_pk_mul_f32 v[192:193], v[146:147], v[192:193]
	v_pk_fma_f32 v[236:237], v[144:145], v[38:39], v[180:181]
	v_pk_fma_f32 v[238:239], v[144:145], v[40:41], v[192:193]
	global_store_dwordx4 v[150:151], v[236:239], off nt
	v_lshl_add_u64 v[150:151], v[150:151], 0, s[74:75]
	global_load_dwordx4 v[38:41], v[148:149], off nt
	v_lshl_add_u64 v[148:149], v[148:149], 0, s[74:75]
	ds_read_b32 v141, v160 offset:128
	ds_read_b128 v[114:117], v161 offset:1024
	ds_read_b128 v[176:179], v161 offset:1040
	s_waitcnt vmcnt(18)
; #define RS_LOAD(dst, it0) do { _Pragma("unroll") for (int u = 0; u < 8; ++u) dst[u] = __builtin_nontemporal_load((const f32x4*)(S0 + (size_t)(4 * ((it0) + u)) * DV)); } while (0)
; __device__ __forceinline__ void ret_sample_item(Frame& F, int item) {
;     ...
;     for (int it0 = 0; it0 < 64; it0 += 16) {
;         RS_LOAD(sb, it0 + 8);
;         RS_PROC(sa, it0);
;         { const int itn = it0 + 16 < 64 ? it0 + 16 : it0; RS_LOAD(sa, itn); }
;         RS_PROC(sb, it0 + 8);
;     }
	s_waitcnt lgkmcnt(3)
	v_cndmask_b32_e64 v143, 0, v143, s[8:9]
	v_pk_mul_f32 v[180:181], v[26:27], v[172:173] op_sel:[0,1]
	v_pk_mul_f32 v[192:193], v[28:29], v[172:173] op_sel:[0,1]
	v_mfma_f32_16x16x4_f32 v[110:113], v143, v34, v[110:113]
	v_pk_fma_f32 v[180:181], v[30:31], v[172:173], v[180:181] op_sel_hi:[1,0,1]
	v_pk_fma_f32 v[192:193], v[32:33], v[172:173], v[192:193] op_sel_hi:[1,0,1]
	v_pk_fma_f32 v[180:181], v[22:23], v[174:175], v[180:181] op_sel_hi:[1,0,1]
	v_pk_fma_f32 v[192:193], v[24:25], v[174:175], v[192:193] op_sel_hi:[1,0,1]
	v_mfma_f32_16x16x4_f32 v[106:109], v143, v35, v[106:109]
	v_pk_fma_f32 v[180:181], v[18:19], v[174:175], v[180:181] op_sel:[0,1,0]
	v_pk_fma_f32 v[192:193], v[20:21], v[174:175], v[192:193] op_sel:[0,1,0]
	v_pk_fma_f32 v[180:181], v[14:15], v[232:233], v[180:181] op_sel_hi:[1,0,1]
	v_pk_fma_f32 v[192:193], v[16:17], v[232:233], v[192:193] op_sel_hi:[1,0,1]
	v_mfma_f32_16x16x4_f32 v[102:105], v143, v36, v[102:105]
	v_pk_fma_f32 v[180:181], v[10:11], v[232:233], v[180:181] op_sel:[0,1,0]
	v_pk_fma_f32 v[192:193], v[12:13], v[232:233], v[192:193] op_sel:[0,1,0]
	v_pk_fma_f32 v[180:181], v[6:7], v[234:235], v[180:181] op_sel_hi:[1,0,1]
	v_pk_fma_f32 v[192:193], v[8:9], v[234:235], v[192:193] op_sel_hi:[1,0,1]
	v_mfma_f32_16x16x4_f32 v[98:101], v143, v37, v[98:101]
	v_pk_fma_f32 v[180:181], v[2:3], v[234:235], v[180:181] op_sel:[0,1,0]
	v_pk_fma_f32 v[192:193], v[4:5], v[234:235], v[192:193] op_sel:[0,1,0]
	v_pk_mul_f32 v[180:181], v[146:147], v[180:181]
	v_pk_mul_f32 v[192:193], v[146:147], v[192:193]
	v_pk_fma_f32 v[236:237], v[144:145], v[34:35], v[180:181]
	v_pk_fma_f32 v[238:239], v[144:145], v[36:37], v[192:193]
	global_store_dwordx4 v[150:151], v[236:239], off nt
	v_lshl_add_u64 v[150:151], v[150:151], 0, s[74:75]
	global_load_dwordx4 v[34:37], v[148:149], off nt
	v_lshl_add_u64 v[148:149], v[148:149], 0, s[74:75]
	ds_read_b32 v143, v160 offset:144
	ds_read_b128 v[172:175], v161 offset:1152
	ds_read_b128 v[232:235], v161 offset:1168
	s_waitcnt vmcnt(19)
	s_waitcnt lgkmcnt(3)
	v_cndmask_b32_e64 v141, 0, v141, s[8:9]
	v_pk_mul_f32 v[180:181], v[26:27], v[114:115] op_sel:[0,1]
	v_pk_mul_f32 v[192:193], v[28:29], v[114:115] op_sel:[0,1]
	v_mfma_f32_16x16x4_f32 v[110:113], v141, v58, v[110:113]
	v_pk_fma_f32 v[180:181], v[30:31], v[114:115], v[180:181] op_sel_hi:[1,0,1]
	v_pk_fma_f32 v[192:193], v[32:33], v[114:115], v[192:193] op_sel_hi:[1,0,1]
	v_pk_fma_f32 v[180:181], v[22:23], v[116:117], v[180:181] op_sel_hi:[1,0,1]
	v_pk_fma_f32 v[192:193], v[24:25], v[116:117], v[192:193] op_sel_hi:[1,0,1]
	v_mfma_f32_16x16x4_f32 v[106:109], v141, v59, v[106:109]
	v_pk_fma_f32 v[180:181], v[18:19], v[116:117], v[180:181] op_sel:[0,1,0]
	v_pk_fma_f32 v[192:193], v[20:21], v[116:117], v[192:193] op_sel:[0,1,0]
	v_pk_fma_f32 v[180:181], v[14:15], v[176:177], v[180:181] op_sel_hi:[1,0,1]
	v_pk_fma_f32 v[192:193], v[16:17], v[176:177], v[192:193] op_sel_hi:[1,0,1]
	v_mfma_f32_16x16x4_f32 v[102:105], v141, v60, v[102:105]
	v_pk_fma_f32 v[180:181], v[10:11], v[176:177], v[180:181] op_sel:[0,1,0]
	v_pk_fma_f32 v[192:193], v[12:13], v[176:177], v[192:193] op_sel:[0,1,0]
	v_pk_fma_f32 v[180:181], v[6:7], v[178:179], v[180:181] op_sel_hi:[1,0,1]
	v_pk_fma_f32 v[192:193], v[8:9], v[178:179], v[192:193] op_sel_hi:[1,0,1]
	v_mfma_f32_16x16x4_f32 v[98:101], v141, v61, v[98:101]
	v_pk_fma_f32 v[180:181], v[2:3], v[178:179], v[180:181] op_sel:[0,1,0]
	v_pk_fma_f32 v[192:193], v[4:5], v[178:179], v[192:193] op_sel:[0,1,0]
	v_pk_mul_f32 v[180:181], v[146:147], v[180:181]
	v_pk_mul_f32 v[192:193], v[146:147], v[192:193]
	v_pk_fma_f32 v[236:237], v[144:145], v[58:59], v[180:181]
	v_pk_fma_f32 v[238:239], v[144:145], v[60:61], v[192:193]
	global_store_dwordx4 v[150:151], v[236:239], off nt
	v_lshl_add_u64 v[150:151], v[150:151], 0, s[74:75]
	global_load_dwordx4 v[58:61], v[148:149], off nt
	v_lshl_add_u64 v[148:149], v[148:149], 0, s[74:75]
	ds_read_b32 v141, v160 offset:160
	ds_read_b128 v[114:117], v161 offset:1280
	ds_read_b128 v[176:179], v161 offset:1296
	s_waitcnt vmcnt(20)
	s_waitcnt lgkmcnt(3)
	v_cndmask_b32_e64 v143, 0, v143, s[8:9]
	v_pk_mul_f32 v[180:181], v[26:27], v[172:173] op_sel:[0,1]
	v_pk_mul_f32 v[192:193], v[28:29], v[172:173] op_sel:[0,1]
	v_mfma_f32_16x16x4_f32 v[110:113], v143, v66, v[110:113]
	v_pk_fma_f32 v[180:181], v[30:31], v[172:173], v[180:181] op_sel_hi:[1,0,1]
	v_pk_fma_f32 v[192:193], v[32:33], v[172:173], v[192:193] op_sel_hi:[1,0,1]
	v_pk_fma_f32 v[180:181], v[22:23], v[174:175], v[180:181] op_sel_hi:[1,0,1]
	v_pk_fma_f32 v[192:193], v[24:25], v[174:175], v[192:193] op_sel_hi:[1,0,1]
	v_mfma_f32_16x16x4_f32 v[106:109], v143, v67, v[106:109]
	v_pk_fma_f32 v[180:181], v[18:19], v[174:175], v[180:181] op_sel:[0,1,0]
	v_pk_fma_f32 v[192:193], v[20:21], v[174:175], v[192:193] op_sel:[0,1,0]
	v_pk_fma_f32 v[180:181], v[14:15], v[232:233], v[180:181] op_sel_hi:[1,0,1]
	v_pk_fma_f32 v[192:193], v[16:17], v[232:233], v[192:193] op_sel_hi:[1,0,1]
	v_mfma_f32_16x16x4_f32 v[102:105], v143, v68, v[102:105]
	v_pk_fma_f32 v[180:181], v[10:11], v[232:233], v[180:181] op_sel:[0,1,0]
	v_pk_fma_f32 v[192:193], v[12:13], v[232:233], v[192:193] op_sel:[0,1,0]
	v_pk_fma_f32 v[180:181], v[6:7], v[234:235], v[180:181] op_sel_hi:[1,0,1]
	v_pk_fma_f32 v[192:193], v[8:9], v[234:235], v[192:193] op_sel_hi:[1,0,1]
	v_mfma_f32_16x16x4_f32 v[98:101], v143, v69, v[98:101]
	v_pk_fma_f32 v[180:181], v[2:3], v[234:235], v[180:181] op_sel:[0,1,0]
	v_pk_fma_f32 v[192:193], v[4:5], v[234:235], v[192:193] op_sel:[0,1,0]
	v_pk_mul_f32 v[180:181], v[146:147], v[180:181]
	v_pk_mul_f32 v[192:193], v[146:147], v[192:193]
	v_pk_fma_f32 v[236:237], v[144:145], v[66:67], v[180:181]
	v_pk_fma_f32 v[238:239], v[144:145], v[68:69], v[192:193]
	global_store_dwordx4 v[150:151], v[236:239], off nt
	v_lshl_add_u64 v[150:151], v[150:151], 0, s[74:75]
	global_load_dwordx4 v[66:69], v[148:149], off nt
	v_lshl_add_u64 v[148:149], v[148:149], 0, s[74:75]
	ds_read_b32 v143, v160 offset:176
	ds_read_b128 v[172:175], v161 offset:1408
	ds_read_b128 v[232:235], v161 offset:1424
	s_waitcnt vmcnt(21)
; #define RS_LOAD(dst, it0) do { _Pragma("unroll") for (int u = 0; u < 8; ++u) dst[u] = __builtin_nontemporal_load((const f32x4*)(S0 + (size_t)(4 * ((it0) + u)) * DV)); } while (0)
; __device__ __forceinline__ void ret_sample_item(Frame& F, int item) {
;     ...
;     for (int it0 = 0; it0 < 64; it0 += 16) {
;         RS_LOAD(sb, it0 + 8);
;         RS_PROC(sa, it0);
;         { const int itn = it0 + 16 < 64 ? it0 + 16 : it0; RS_LOAD(sa, itn); }
;         RS_PROC(sb, it0 + 8);
;     }
	s_waitcnt lgkmcnt(3)
	v_cndmask_b32_e64 v141, 0, v141, s[8:9]
	v_pk_mul_f32 v[180:181], v[26:27], v[114:115] op_sel:[0,1]
	v_pk_mul_f32 v[192:193], v[28:29], v[114:115] op_sel:[0,1]
	v_mfma_f32_16x16x4_f32 v[110:113], v141, v74, v[110:113]
	v_pk_fma_f32 v[180:181], v[30:31], v[114:115], v[180:181] op_sel_hi:[1,0,1]
	v_pk_fma_f32 v[192:193], v[32:33], v[114:115], v[192:193] op_sel_hi:[1,0,1]
	v_pk_fma_f32 v[180:181], v[22:23], v[116:117], v[180:181] op_sel_hi:[1,0,1]
	v_pk_fma_f32 v[192:193], v[24:25], v[116:117], v[192:193] op_sel_hi:[1,0,1]
	v_mfma_f32_16x16x4_f32 v[106:109], v141, v75, v[106:109]
	v_pk_fma_f32 v[180:181], v[18:19], v[116:117], v[180:181] op_sel:[0,1,0]
	v_pk_fma_f32 v[192:193], v[20:21], v[116:117], v[192:193] op_sel:[0,1,0]
	v_pk_fma_f32 v[180:181], v[14:15], v[176:177], v[180:181] op_sel_hi:[1,0,1]
	v_pk_fma_f32 v[192:193], v[16:17], v[176:177], v[192:193] op_sel_hi:[1,0,1]
	v_mfma_f32_16x16x4_f32 v[102:105], v141, v76, v[102:105]
	v_pk_fma_f32 v[180:181], v[10:11], v[176:177], v[180:181] op_sel:[0,1,0]
	v_pk_fma_f32 v[192:193], v[12:13], v[176:177], v[192:193] op_sel:[0,1,0]
	v_pk_fma_f32 v[180:181], v[6:7], v[178:179], v[180:181] op_sel_hi:[1,0,1]
	v_pk_fma_f32 v[192:193], v[8:9], v[178:179], v[192:193] op_sel_hi:[1,0,1]
	v_mfma_f32_16x16x4_f32 v[98:101], v141, v77, v[98:101]
	v_pk_fma_f32 v[180:181], v[2:3], v[178:179], v[180:181] op_sel:[0,1,0]
	v_pk_fma_f32 v[192:193], v[4:5], v[178:179], v[192:193] op_sel:[0,1,0]
	v_pk_mul_f32 v[180:181], v[146:147], v[180:181]
	v_pk_mul_f32 v[192:193], v[146:147], v[192:193]
	v_pk_fma_f32 v[236:237], v[144:145], v[74:75], v[180:181]
	v_pk_fma_f32 v[238:239], v[144:145], v[76:77], v[192:193]
	global_store_dwordx4 v[150:151], v[236:239], off nt
	v_lshl_add_u64 v[150:151], v[150:151], 0, s[74:75]
	global_load_dwordx4 v[74:77], v[148:149], off nt
	v_lshl_add_u64 v[148:149], v[148:149], 0, s[74:75]
	ds_read_b32 v141, v160 offset:192
	ds_read_b128 v[114:117], v161 offset:1536
	ds_read_b128 v[176:179], v161 offset:1552
	s_waitcnt vmcnt(22)
	s_waitcnt lgkmcnt(3)
	v_cndmask_b32_e64 v143, 0, v143, s[8:9]
	v_pk_mul_f32 v[180:181], v[26:27], v[172:173] op_sel:[0,1]
	v_pk_mul_f32 v[192:193], v[28:29], v[172:173] op_sel:[0,1]
	v_mfma_f32_16x16x4_f32 v[110:113], v143, v78, v[110:113]
	v_pk_fma_f32 v[180:181], v[30:31], v[172:173], v[180:181] op_sel_hi:[1,0,1]
	v_pk_fma_f32 v[192:193], v[32:33], v[172:173], v[192:193] op_sel_hi:[1,0,1]
	v_pk_fma_f32 v[180:181], v[22:23], v[174:175], v[180:181] op_sel_hi:[1,0,1]
	v_pk_fma_f32 v[192:193], v[24:25], v[174:175], v[192:193] op_sel_hi:[1,0,1]
	v_mfma_f32_16x16x4_f32 v[106:109], v143, v79, v[106:109]
	v_pk_fma_f32 v[180:181], v[18:19], v[174:175], v[180:181] op_sel:[0,1,0]
	v_pk_fma_f32 v[192:193], v[20:21], v[174:175], v[192:193] op_sel:[0,1,0]
	v_pk_fma_f32 v[180:181], v[14:15], v[232:233], v[180:181] op_sel_hi:[1,0,1]
	v_pk_fma_f32 v[192:193], v[16:17], v[232:233], v[192:193] op_sel_hi:[1,0,1]
	v_mfma_f32_16x16x4_f32 v[102:105], v143, v80, v[102:105]
	v_pk_fma_f32 v[180:181], v[10:11], v[232:233], v[180:181] op_sel:[0,1,0]
	v_pk_fma_f32 v[192:193], v[12:13], v[232:233], v[192:193] op_sel:[0,1,0]
	v_pk_fma_f32 v[180:181], v[6:7], v[234:235], v[180:181] op_sel_hi:[1,0,1]
	v_pk_fma_f32 v[192:193], v[8:9], v[234:235], v[192:193] op_sel_hi:[1,0,1]
	v_mfma_f32_16x16x4_f32 v[98:101], v143, v81, v[98:101]
	v_pk_fma_f32 v[180:181], v[2:3], v[234:235], v[180:181] op_sel:[0,1,0]
	v_pk_fma_f32 v[192:193], v[4:5], v[234:235], v[192:193] op_sel:[0,1,0]
	v_pk_mul_f32 v[180:181], v[146:147], v[180:181]
	v_pk_mul_f32 v[192:193], v[146:147], v[192:193]
	v_pk_fma_f32 v[236:237], v[144:145], v[78:79], v[180:181]
	v_pk_fma_f32 v[238:239], v[144:145], v[80:81], v[192:193]
	global_store_dwordx4 v[150:151], v[236:239], off nt
	v_lshl_add_u64 v[150:151], v[150:151], 0, s[74:75]
	global_load_dwordx4 v[78:81], v[148:149], off nt
	v_lshl_add_u64 v[148:149], v[148:149], 0, s[74:75]
	ds_read_b32 v143, v160 offset:208
	ds_read_b128 v[172:175], v161 offset:1664
	ds_read_b128 v[232:235], v161 offset:1680
	s_waitcnt vmcnt(22)
	s_waitcnt lgkmcnt(3)
	v_cndmask_b32_e64 v141, 0, v141, s[8:9]
	v_pk_mul_f32 v[180:181], v[26:27], v[114:115] op_sel:[0,1]
	v_pk_mul_f32 v[192:193], v[28:29], v[114:115] op_sel:[0,1]
	v_mfma_f32_16x16x4_f32 v[110:113], v141, v70, v[110:113]
	v_pk_fma_f32 v[180:181], v[30:31], v[114:115], v[180:181] op_sel_hi:[1,0,1]
	v_pk_fma_f32 v[192:193], v[32:33], v[114:115], v[192:193] op_sel_hi:[1,0,1]
	v_pk_fma_f32 v[180:181], v[22:23], v[116:117], v[180:181] op_sel_hi:[1,0,1]
	v_pk_fma_f32 v[192:193], v[24:25], v[116:117], v[192:193] op_sel_hi:[1,0,1]
	v_mfma_f32_16x16x4_f32 v[106:109], v141, v71, v[106:109]
	v_pk_fma_f32 v[180:181], v[18:19], v[116:117], v[180:181] op_sel:[0,1,0]
	v_pk_fma_f32 v[192:193], v[20:21], v[116:117], v[192:193] op_sel:[0,1,0]
	v_pk_fma_f32 v[180:181], v[14:15], v[176:177], v[180:181] op_sel_hi:[1,0,1]
	v_pk_fma_f32 v[192:193], v[16:17], v[176:177], v[192:193] op_sel_hi:[1,0,1]
	v_mfma_f32_16x16x4_f32 v[102:105], v141, v72, v[102:105]
	v_pk_fma_f32 v[180:181], v[10:11], v[176:177], v[180:181] op_sel:[0,1,0]
	v_pk_fma_f32 v[192:193], v[12:13], v[176:177], v[192:193] op_sel:[0,1,0]
	v_pk_fma_f32 v[180:181], v[6:7], v[178:179], v[180:181] op_sel_hi:[1,0,1]
	v_pk_fma_f32 v[192:193], v[8:9], v[178:179], v[192:193] op_sel_hi:[1,0,1]
	v_mfma_f32_16x16x4_f32 v[98:101], v141, v73, v[98:101]
	v_pk_fma_f32 v[180:181], v[2:3], v[178:179], v[180:181] op_sel:[0,1,0]
	v_pk_fma_f32 v[192:193], v[4:5], v[178:179], v[192:193] op_sel:[0,1,0]
	v_pk_mul_f32 v[180:181], v[146:147], v[180:181]
	v_pk_mul_f32 v[192:193], v[146:147], v[192:193]
	v_pk_fma_f32 v[236:237], v[144:145], v[70:71], v[180:181]
	v_pk_fma_f32 v[238:239], v[144:145], v[72:73], v[192:193]
	global_store_dwordx4 v[150:151], v[236:239], off nt
	v_lshl_add_u64 v[150:151], v[150:151], 0, s[74:75]
	global_load_dwordx4 v[70:73], v[148:149], off nt
	v_lshl_add_u64 v[148:149], v[148:149], 0, s[74:75]
	ds_read_b32 v141, v160 offset:224
	ds_read_b128 v[114:117], v161 offset:1792
	ds_read_b128 v[176:179], v161 offset:1808
	s_waitcnt vmcnt(22)
; #define RS_LOAD(dst, it0) do { _Pragma("unroll") for (int u = 0; u < 8; ++u) dst[u] = __builtin_nontemporal_load((const f32x4*)(S0 + (size_t)(4 * ((it0) + u)) * DV)); } while (0)
; __device__ __forceinline__ void ret_sample_item(Frame& F, int item) {
;     ...
;     for (int it0 = 0; it0 < 64; it0 += 16) {
;         RS_LOAD(sb, it0 + 8);
;         RS_PROC(sa, it0);
;         { const int itn = it0 + 16 < 64 ? it0 + 16 : it0; RS_LOAD(sa, itn); }
;         RS_PROC(sb, it0 + 8);
;     }
	s_waitcnt lgkmcnt(3)
	v_cndmask_b32_e64 v143, 0, v143, s[8:9]
	v_pk_mul_f32 v[180:181], v[26:27], v[172:173] op_sel:[0,1]
	v_pk_mul_f32 v[192:193], v[28:29], v[172:173] op_sel:[0,1]
	v_mfma_f32_16x16x4_f32 v[110:113], v143, v62, v[110:113]
	v_pk_fma_f32 v[180:181], v[30:31], v[172:173], v[180:181] op_sel_hi:[1,0,1]
	v_pk_fma_f32 v[192:193], v[32:33], v[172:173], v[192:193] op_sel_hi:[1,0,1]
	v_pk_fma_f32 v[180:181], v[22:23], v[174:175], v[180:181] op_sel_hi:[1,0,1]
	v_pk_fma_f32 v[192:193], v[24:25], v[174:175], v[192:193] op_sel_hi:[1,0,1]
	v_mfma_f32_16x16x4_f32 v[106:109], v143, v63, v[106:109]
	v_pk_fma_f32 v[180:181], v[18:19], v[174:175], v[180:181] op_sel:[0,1,0]
	v_pk_fma_f32 v[192:193], v[20:21], v[174:175], v[192:193] op_sel:[0,1,0]
	v_pk_fma_f32 v[180:181], v[14:15], v[232:233], v[180:181] op_sel_hi:[1,0,1]
	v_pk_fma_f32 v[192:193], v[16:17], v[232:233], v[192:193] op_sel_hi:[1,0,1]
	v_mfma_f32_16x16x4_f32 v[102:105], v143, v64, v[102:105]
	v_pk_fma_f32 v[180:181], v[10:11], v[232:233], v[180:181] op_sel:[0,1,0]
	v_pk_fma_f32 v[192:193], v[12:13], v[232:233], v[192:193] op_sel:[0,1,0]
	v_pk_fma_f32 v[180:181], v[6:7], v[234:235], v[180:181] op_sel_hi:[1,0,1]
	v_pk_fma_f32 v[192:193], v[8:9], v[234:235], v[192:193] op_sel_hi:[1,0,1]
	v_mfma_f32_16x16x4_f32 v[98:101], v143, v65, v[98:101]
	v_pk_fma_f32 v[180:181], v[2:3], v[234:235], v[180:181] op_sel:[0,1,0]
	v_pk_fma_f32 v[192:193], v[4:5], v[234:235], v[192:193] op_sel:[0,1,0]
	v_pk_mul_f32 v[180:181], v[146:147], v[180:181]
	v_pk_mul_f32 v[192:193], v[146:147], v[192:193]
	v_pk_fma_f32 v[236:237], v[144:145], v[62:63], v[180:181]
	v_pk_fma_f32 v[238:239], v[144:145], v[64:65], v[192:193]
	global_store_dwordx4 v[150:151], v[236:239], off nt
	v_lshl_add_u64 v[150:151], v[150:151], 0, s[74:75]
	global_load_dwordx4 v[62:65], v[148:149], off nt
	v_lshl_add_u64 v[148:149], v[148:149], 0, s[74:75]
	ds_read_b32 v143, v160 offset:240
	ds_read_b128 v[172:175], v161 offset:1920
	ds_read_b128 v[232:235], v161 offset:1936
	s_waitcnt vmcnt(22)
	s_waitcnt lgkmcnt(3)
	v_cndmask_b32_e64 v141, 0, v141, s[8:9]
	v_pk_mul_f32 v[180:181], v[26:27], v[114:115] op_sel:[0,1]
	v_pk_mul_f32 v[192:193], v[28:29], v[114:115] op_sel:[0,1]
	v_mfma_f32_16x16x4_f32 v[110:113], v141, v54, v[110:113]
	v_pk_fma_f32 v[180:181], v[30:31], v[114:115], v[180:181] op_sel_hi:[1,0,1]
	v_pk_fma_f32 v[192:193], v[32:33], v[114:115], v[192:193] op_sel_hi:[1,0,1]
	v_pk_fma_f32 v[180:181], v[22:23], v[116:117], v[180:181] op_sel_hi:[1,0,1]
	v_pk_fma_f32 v[192:193], v[24:25], v[116:117], v[192:193] op_sel_hi:[1,0,1]
	v_mfma_f32_16x16x4_f32 v[106:109], v141, v55, v[106:109]
	v_pk_fma_f32 v[180:181], v[18:19], v[116:117], v[180:181] op_sel:[0,1,0]
	v_pk_fma_f32 v[192:193], v[20:21], v[116:117], v[192:193] op_sel:[0,1,0]
	v_pk_fma_f32 v[180:181], v[14:15], v[176:177], v[180:181] op_sel_hi:[1,0,1]
	v_pk_fma_f32 v[192:193], v[16:17], v[176:177], v[192:193] op_sel_hi:[1,0,1]
	v_mfma_f32_16x16x4_f32 v[102:105], v141, v56, v[102:105]
	v_pk_fma_f32 v[180:181], v[10:11], v[176:177], v[180:181] op_sel:[0,1,0]
	v_pk_fma_f32 v[192:193], v[12:13], v[176:177], v[192:193] op_sel:[0,1,0]
	v_pk_fma_f32 v[180:181], v[6:7], v[178:179], v[180:181] op_sel_hi:[1,0,1]
	v_pk_fma_f32 v[192:193], v[8:9], v[178:179], v[192:193] op_sel_hi:[1,0,1]
	v_mfma_f32_16x16x4_f32 v[98:101], v141, v57, v[98:101]
	v_pk_fma_f32 v[180:181], v[2:3], v[178:179], v[180:181] op_sel:[0,1,0]
	v_pk_fma_f32 v[192:193], v[4:5], v[178:179], v[192:193] op_sel:[0,1,0]
	v_pk_mul_f32 v[180:181], v[146:147], v[180:181]
	v_pk_mul_f32 v[192:193], v[146:147], v[192:193]
	v_pk_fma_f32 v[236:237], v[144:145], v[54:55], v[180:181]
	v_pk_fma_f32 v[238:239], v[144:145], v[56:57], v[192:193]
	global_store_dwordx4 v[150:151], v[236:239], off nt
	v_lshl_add_u64 v[150:151], v[150:151], 0, s[74:75]
	global_load_dwordx4 v[54:57], v[148:149], off nt
	v_lshl_add_u64 v[148:149], v[148:149], 0, s[74:75]
	ds_read_b32 v141, v160 offset:256
	ds_read_b128 v[114:117], v161 offset:2048
	ds_read_b128 v[176:179], v161 offset:2064
	s_waitcnt vmcnt(22)
	s_waitcnt lgkmcnt(3)
	v_cndmask_b32_e64 v143, 0, v143, s[8:9]
	v_pk_mul_f32 v[180:181], v[26:27], v[172:173] op_sel:[0,1]
	v_pk_mul_f32 v[192:193], v[28:29], v[172:173] op_sel:[0,1]
	v_mfma_f32_16x16x4_f32 v[110:113], v143, v50, v[110:113]
	v_pk_fma_f32 v[180:181], v[30:31], v[172:173], v[180:181] op_sel_hi:[1,0,1]
	v_pk_fma_f32 v[192:193], v[32:33], v[172:173], v[192:193] op_sel_hi:[1,0,1]
	v_pk_fma_f32 v[180:181], v[22:23], v[174:175], v[180:181] op_sel_hi:[1,0,1]
	v_pk_fma_f32 v[192:193], v[24:25], v[174:175], v[192:193] op_sel_hi:[1,0,1]
	v_mfma_f32_16x16x4_f32 v[106:109], v143, v51, v[106:109]
	v_pk_fma_f32 v[180:181], v[18:19], v[174:175], v[180:181] op_sel:[0,1,0]
	v_pk_fma_f32 v[192:193], v[20:21], v[174:175], v[192:193] op_sel:[0,1,0]
	v_pk_fma_f32 v[180:181], v[14:15], v[232:233], v[180:181] op_sel_hi:[1,0,1]
	v_pk_fma_f32 v[192:193], v[16:17], v[232:233], v[192:193] op_sel_hi:[1,0,1]
	v_mfma_f32_16x16x4_f32 v[102:105], v143, v52, v[102:105]
	v_pk_fma_f32 v[180:181], v[10:11], v[232:233], v[180:181] op_sel:[0,1,0]
	v_pk_fma_f32 v[192:193], v[12:13], v[232:233], v[192:193] op_sel:[0,1,0]
	v_pk_fma_f32 v[180:181], v[6:7], v[234:235], v[180:181] op_sel_hi:[1,0,1]
	v_pk_fma_f32 v[192:193], v[8:9], v[234:235], v[192:193] op_sel_hi:[1,0,1]
	v_mfma_f32_16x16x4_f32 v[98:101], v143, v53, v[98:101]
	v_pk_fma_f32 v[180:181], v[2:3], v[234:235], v[180:181] op_sel:[0,1,0]
	v_pk_fma_f32 v[192:193], v[4:5], v[234:235], v[192:193] op_sel:[0,1,0]
	v_pk_mul_f32 v[180:181], v[146:147], v[180:181]
	v_pk_mul_f32 v[192:193], v[146:147], v[192:193]
	v_pk_fma_f32 v[236:237], v[144:145], v[50:51], v[180:181]
	v_pk_fma_f32 v[238:239], v[144:145], v[52:53], v[192:193]
	global_store_dwordx4 v[150:151], v[236:239], off nt
	v_lshl_add_u64 v[150:151], v[150:151], 0, s[74:75]
	global_load_dwordx4 v[50:53], v[148:149], off nt
	v_lshl_add_u64 v[148:149], v[148:149], 0, s[74:75]
	ds_read_b32 v143, v160 offset:272
	ds_read_b128 v[172:175], v161 offset:2176
	ds_read_b128 v[232:235], v161 offset:2192
	s_waitcnt vmcnt(22)
; #define RS_LOAD(dst, it0) do { _Pragma("unroll") for (int u = 0; u < 8; ++u) dst[u] = __builtin_nontemporal_load((const f32x4*)(S0 + (size_t)(4 * ((it0) + u)) * DV)); } while (0)
; __device__ __forceinline__ void ret_sample_item(Frame& F, int item) {
;     ...
;     for (int it0 = 0; it0 < 64; it0 += 16) {
;         RS_LOAD(sb, it0 + 8);
;         RS_PROC(sa, it0);
;         { const int itn = it0 + 16 < 64 ? it0 + 16 : it0; RS_LOAD(sa, itn); }
;         RS_PROC(sb, it0 + 8);
;     }
	s_waitcnt lgkmcnt(3)
	v_cndmask_b32_e64 v141, 0, v141, s[8:9]
	v_pk_mul_f32 v[180:181], v[26:27], v[114:115] op_sel:[0,1]
	v_pk_mul_f32 v[192:193], v[28:29], v[114:115] op_sel:[0,1]
	v_mfma_f32_16x16x4_f32 v[110:113], v141, v46, v[110:113]
	v_pk_fma_f32 v[180:181], v[30:31], v[114:115], v[180:181] op_sel_hi:[1,0,1]
	v_pk_fma_f32 v[192:193], v[32:33], v[114:115], v[192:193] op_sel_hi:[1,0,1]
	v_pk_fma_f32 v[180:181], v[22:23], v[116:117], v[180:181] op_sel_hi:[1,0,1]
	v_pk_fma_f32 v[192:193], v[24:25], v[116:117], v[192:193] op_sel_hi:[1,0,1]
	v_mfma_f32_16x16x4_f32 v[106:109], v141, v47, v[106:109]
	v_pk_fma_f32 v[180:181], v[18:19], v[116:117], v[180:181] op_sel:[0,1,0]
	v_pk_fma_f32 v[192:193], v[20:21], v[116:117], v[192:193] op_sel:[0,1,0]
	v_pk_fma_f32 v[180:181], v[14:15], v[176:177], v[180:181] op_sel_hi:[1,0,1]
	v_pk_fma_f32 v[192:193], v[16:17], v[176:177], v[192:193] op_sel_hi:[1,0,1]
	v_mfma_f32_16x16x4_f32 v[102:105], v141, v48, v[102:105]
	v_pk_fma_f32 v[180:181], v[10:11], v[176:177], v[180:181] op_sel:[0,1,0]
	v_pk_fma_f32 v[192:193], v[12:13], v[176:177], v[192:193] op_sel:[0,1,0]
	v_pk_fma_f32 v[180:181], v[6:7], v[178:179], v[180:181] op_sel_hi:[1,0,1]
	v_pk_fma_f32 v[192:193], v[8:9], v[178:179], v[192:193] op_sel_hi:[1,0,1]
	v_mfma_f32_16x16x4_f32 v[98:101], v141, v49, v[98:101]
	v_pk_fma_f32 v[180:181], v[2:3], v[178:179], v[180:181] op_sel:[0,1,0]
	v_pk_fma_f32 v[192:193], v[4:5], v[178:179], v[192:193] op_sel:[0,1,0]
	v_pk_mul_f32 v[180:181], v[146:147], v[180:181]
	v_pk_mul_f32 v[192:193], v[146:147], v[192:193]
	v_pk_fma_f32 v[236:237], v[144:145], v[46:47], v[180:181]
	v_pk_fma_f32 v[238:239], v[144:145], v[48:49], v[192:193]
	global_store_dwordx4 v[150:151], v[236:239], off nt
	v_lshl_add_u64 v[150:151], v[150:151], 0, s[74:75]
	global_load_dwordx4 v[46:49], v[148:149], off nt
	v_lshl_add_u64 v[148:149], v[148:149], 0, s[74:75]
	ds_read_b32 v141, v160 offset:288
	ds_read_b128 v[114:117], v161 offset:2304
	ds_read_b128 v[176:179], v161 offset:2320
	s_waitcnt vmcnt(22)
	s_waitcnt lgkmcnt(3)
	v_cndmask_b32_e64 v143, 0, v143, s[8:9]
	v_pk_mul_f32 v[180:181], v[26:27], v[172:173] op_sel:[0,1]
	v_pk_mul_f32 v[192:193], v[28:29], v[172:173] op_sel:[0,1]
	v_mfma_f32_16x16x4_f32 v[110:113], v143, v42, v[110:113]
	v_pk_fma_f32 v[180:181], v[30:31], v[172:173], v[180:181] op_sel_hi:[1,0,1]
	v_pk_fma_f32 v[192:193], v[32:33], v[172:173], v[192:193] op_sel_hi:[1,0,1]
	v_pk_fma_f32 v[180:181], v[22:23], v[174:175], v[180:181] op_sel_hi:[1,0,1]
	v_pk_fma_f32 v[192:193], v[24:25], v[174:175], v[192:193] op_sel_hi:[1,0,1]
	v_mfma_f32_16x16x4_f32 v[106:109], v143, v43, v[106:109]
	v_pk_fma_f32 v[180:181], v[18:19], v[174:175], v[180:181] op_sel:[0,1,0]
	v_pk_fma_f32 v[192:193], v[20:21], v[174:175], v[192:193] op_sel:[0,1,0]
	v_pk_fma_f32 v[180:181], v[14:15], v[232:233], v[180:181] op_sel_hi:[1,0,1]
	v_pk_fma_f32 v[192:193], v[16:17], v[232:233], v[192:193] op_sel_hi:[1,0,1]
	v_mfma_f32_16x16x4_f32 v[102:105], v143, v44, v[102:105]
	v_pk_fma_f32 v[180:181], v[10:11], v[232:233], v[180:181] op_sel:[0,1,0]
	v_pk_fma_f32 v[192:193], v[12:13], v[232:233], v[192:193] op_sel:[0,1,0]
	v_pk_fma_f32 v[180:181], v[6:7], v[234:235], v[180:181] op_sel_hi:[1,0,1]
	v_pk_fma_f32 v[192:193], v[8:9], v[234:235], v[192:193] op_sel_hi:[1,0,1]
	v_mfma_f32_16x16x4_f32 v[98:101], v143, v45, v[98:101]
	v_pk_fma_f32 v[180:181], v[2:3], v[234:235], v[180:181] op_sel:[0,1,0]
	v_pk_fma_f32 v[192:193], v[4:5], v[234:235], v[192:193] op_sel:[0,1,0]
	v_pk_mul_f32 v[180:181], v[146:147], v[180:181]
	v_pk_mul_f32 v[192:193], v[146:147], v[192:193]
	v_pk_fma_f32 v[236:237], v[144:145], v[42:43], v[180:181]
	v_pk_fma_f32 v[238:239], v[144:145], v[44:45], v[192:193]
	global_store_dwordx4 v[150:151], v[236:239], off nt
	v_lshl_add_u64 v[150:151], v[150:151], 0, s[74:75]
	global_load_dwordx4 v[42:45], v[148:149], off nt
	v_lshl_add_u64 v[148:149], v[148:149], 0, s[74:75]
	ds_read_b32 v143, v160 offset:304
	ds_read_b128 v[172:175], v161 offset:2432
	ds_read_b128 v[232:235], v161 offset:2448
	s_waitcnt vmcnt(22)
	s_waitcnt lgkmcnt(3)
	v_cndmask_b32_e64 v141, 0, v141, s[8:9]
	v_pk_mul_f32 v[180:181], v[26:27], v[114:115] op_sel:[0,1]
	v_pk_mul_f32 v[192:193], v[28:29], v[114:115] op_sel:[0,1]
	v_mfma_f32_16x16x4_f32 v[110:113], v141, v38, v[110:113]
	v_pk_fma_f32 v[180:181], v[30:31], v[114:115], v[180:181] op_sel_hi:[1,0,1]
	v_pk_fma_f32 v[192:193], v[32:33], v[114:115], v[192:193] op_sel_hi:[1,0,1]
	v_pk_fma_f32 v[180:181], v[22:23], v[116:117], v[180:181] op_sel_hi:[1,0,1]
	v_pk_fma_f32 v[192:193], v[24:25], v[116:117], v[192:193] op_sel_hi:[1,0,1]
	v_mfma_f32_16x16x4_f32 v[106:109], v141, v39, v[106:109]
	v_pk_fma_f32 v[180:181], v[18:19], v[116:117], v[180:181] op_sel:[0,1,0]
	v_pk_fma_f32 v[192:193], v[20:21], v[116:117], v[192:193] op_sel:[0,1,0]
	v_pk_fma_f32 v[180:181], v[14:15], v[176:177], v[180:181] op_sel_hi:[1,0,1]
	v_pk_fma_f32 v[192:193], v[16:17], v[176:177], v[192:193] op_sel_hi:[1,0,1]
	v_mfma_f32_16x16x4_f32 v[102:105], v141, v40, v[102:105]
	v_pk_fma_f32 v[180:181], v[10:11], v[176:177], v[180:181] op_sel:[0,1,0]
	v_pk_fma_f32 v[192:193], v[12:13], v[176:177], v[192:193] op_sel:[0,1,0]
	v_pk_fma_f32 v[180:181], v[6:7], v[178:179], v[180:181] op_sel_hi:[1,0,1]
	v_pk_fma_f32 v[192:193], v[8:9], v[178:179], v[192:193] op_sel_hi:[1,0,1]
	v_mfma_f32_16x16x4_f32 v[98:101], v141, v41, v[98:101]
	v_pk_fma_f32 v[180:181], v[2:3], v[178:179], v[180:181] op_sel:[0,1,0]
	v_pk_fma_f32 v[192:193], v[4:5], v[178:179], v[192:193] op_sel:[0,1,0]
	v_pk_mul_f32 v[180:181], v[146:147], v[180:181]
	v_pk_mul_f32 v[192:193], v[146:147], v[192:193]
	v_pk_fma_f32 v[236:237], v[144:145], v[38:39], v[180:181]
	v_pk_fma_f32 v[238:239], v[144:145], v[40:41], v[192:193]
	global_store_dwordx4 v[150:151], v[236:239], off nt
	v_lshl_add_u64 v[150:151], v[150:151], 0, s[74:75]
	global_load_dwordx4 v[38:41], v[148:149], off nt
	v_lshl_add_u64 v[148:149], v[148:149], 0, s[74:75]
	ds_read_b32 v141, v160 offset:320
	ds_read_b128 v[114:117], v161 offset:2560
	ds_read_b128 v[176:179], v161 offset:2576
	s_waitcnt vmcnt(22)
; #define RS_LOAD(dst, it0) do { _Pragma("unroll") for (int u = 0; u < 8; ++u) dst[u] = __builtin_nontemporal_load((const f32x4*)(S0 + (size_t)(4 * ((it0) + u)) * DV)); } while (0)
; __device__ __forceinline__ void ret_sample_item(Frame& F, int item) {
;     ...
;     for (int it0 = 0; it0 < 64; it0 += 16) {
;         RS_LOAD(sb, it0 + 8);
;         RS_PROC(sa, it0);
;         { const int itn = it0 + 16 < 64 ? it0 + 16 : it0; RS_LOAD(sa, itn); }
;         RS_PROC(sb, it0 + 8);
;     }
	s_waitcnt lgkmcnt(3)
	v_cndmask_b32_e64 v143, 0, v143, s[8:9]
	v_pk_mul_f32 v[180:181], v[26:27], v[172:173] op_sel:[0,1]
	v_pk_mul_f32 v[192:193], v[28:29], v[172:173] op_sel:[0,1]
	v_mfma_f32_16x16x4_f32 v[110:113], v143, v34, v[110:113]
	v_pk_fma_f32 v[180:181], v[30:31], v[172:173], v[180:181] op_sel_hi:[1,0,1]
	v_pk_fma_f32 v[192:193], v[32:33], v[172:173], v[192:193] op_sel_hi:[1,0,1]
	v_pk_fma_f32 v[180:181], v[22:23], v[174:175], v[180:181] op_sel_hi:[1,0,1]
	v_pk_fma_f32 v[192:193], v[24:25], v[174:175], v[192:193] op_sel_hi:[1,0,1]
	v_mfma_f32_16x16x4_f32 v[106:109], v143, v35, v[106:109]
	v_pk_fma_f32 v[180:181], v[18:19], v[174:175], v[180:181] op_sel:[0,1,0]
	v_pk_fma_f32 v[192:193], v[20:21], v[174:175], v[192:193] op_sel:[0,1,0]
	v_pk_fma_f32 v[180:181], v[14:15], v[232:233], v[180:181] op_sel_hi:[1,0,1]
	v_pk_fma_f32 v[192:193], v[16:17], v[232:233], v[192:193] op_sel_hi:[1,0,1]
	v_mfma_f32_16x16x4_f32 v[102:105], v143, v36, v[102:105]
	v_pk_fma_f32 v[180:181], v[10:11], v[232:233], v[180:181] op_sel:[0,1,0]
	v_pk_fma_f32 v[192:193], v[12:13], v[232:233], v[192:193] op_sel:[0,1,0]
	v_pk_fma_f32 v[180:181], v[6:7], v[234:235], v[180:181] op_sel_hi:[1,0,1]
	v_pk_fma_f32 v[192:193], v[8:9], v[234:235], v[192:193] op_sel_hi:[1,0,1]
	v_mfma_f32_16x16x4_f32 v[98:101], v143, v37, v[98:101]
	v_pk_fma_f32 v[180:181], v[2:3], v[234:235], v[180:181] op_sel:[0,1,0]
	v_pk_fma_f32 v[192:193], v[4:5], v[234:235], v[192:193] op_sel:[0,1,0]
	v_pk_mul_f32 v[180:181], v[146:147], v[180:181]
	v_pk_mul_f32 v[192:193], v[146:147], v[192:193]
	v_pk_fma_f32 v[236:237], v[144:145], v[34:35], v[180:181]
	v_pk_fma_f32 v[238:239], v[144:145], v[36:37], v[192:193]
	global_store_dwordx4 v[150:151], v[236:239], off nt
	v_lshl_add_u64 v[150:151], v[150:151], 0, s[74:75]
	global_load_dwordx4 v[34:37], v[148:149], off nt
	v_lshl_add_u64 v[148:149], v[148:149], 0, s[74:75]
	ds_read_b32 v143, v160 offset:336
	ds_read_b128 v[172:175], v161 offset:2688
	ds_read_b128 v[232:235], v161 offset:2704
	s_waitcnt vmcnt(22)
	s_waitcnt lgkmcnt(3)
	v_cndmask_b32_e64 v141, 0, v141, s[8:9]
	v_pk_mul_f32 v[180:181], v[26:27], v[114:115] op_sel:[0,1]
	v_pk_mul_f32 v[192:193], v[28:29], v[114:115] op_sel:[0,1]
	v_mfma_f32_16x16x4_f32 v[110:113], v141, v58, v[110:113]
	v_pk_fma_f32 v[180:181], v[30:31], v[114:115], v[180:181] op_sel_hi:[1,0,1]
	v_pk_fma_f32 v[192:193], v[32:33], v[114:115], v[192:193] op_sel_hi:[1,0,1]
	v_pk_fma_f32 v[180:181], v[22:23], v[116:117], v[180:181] op_sel_hi:[1,0,1]
	v_pk_fma_f32 v[192:193], v[24:25], v[116:117], v[192:193] op_sel_hi:[1,0,1]
	v_mfma_f32_16x16x4_f32 v[106:109], v141, v59, v[106:109]
	v_pk_fma_f32 v[180:181], v[18:19], v[116:117], v[180:181] op_sel:[0,1,0]
	v_pk_fma_f32 v[192:193], v[20:21], v[116:117], v[192:193] op_sel:[0,1,0]
	v_pk_fma_f32 v[180:181], v[14:15], v[176:177], v[180:181] op_sel_hi:[1,0,1]
	v_pk_fma_f32 v[192:193], v[16:17], v[176:177], v[192:193] op_sel_hi:[1,0,1]
	v_mfma_f32_16x16x4_f32 v[102:105], v141, v60, v[102:105]
	v_pk_fma_f32 v[180:181], v[10:11], v[176:177], v[180:181] op_sel:[0,1,0]
	v_pk_fma_f32 v[192:193], v[12:13], v[176:177], v[192:193] op_sel:[0,1,0]
	v_pk_fma_f32 v[180:181], v[6:7], v[178:179], v[180:181] op_sel_hi:[1,0,1]
	v_pk_fma_f32 v[192:193], v[8:9], v[178:179], v[192:193] op_sel_hi:[1,0,1]
	v_mfma_f32_16x16x4_f32 v[98:101], v141, v61, v[98:101]
	v_pk_fma_f32 v[180:181], v[2:3], v[178:179], v[180:181] op_sel:[0,1,0]
	v_pk_fma_f32 v[192:193], v[4:5], v[178:179], v[192:193] op_sel:[0,1,0]
	v_pk_mul_f32 v[180:181], v[146:147], v[180:181]
	v_pk_mul_f32 v[192:193], v[146:147], v[192:193]
	v_pk_fma_f32 v[236:237], v[144:145], v[58:59], v[180:181]
	v_pk_fma_f32 v[238:239], v[144:145], v[60:61], v[192:193]
	global_store_dwordx4 v[150:151], v[236:239], off nt
	v_lshl_add_u64 v[150:151], v[150:151], 0, s[74:75]
	global_load_dwordx4 v[58:61], v[148:149], off nt
	v_lshl_add_u64 v[148:149], v[148:149], 0, s[74:75]
	ds_read_b32 v141, v160 offset:352
	ds_read_b128 v[114:117], v161 offset:2816
	ds_read_b128 v[176:179], v161 offset:2832
	s_waitcnt vmcnt(22)
	s_waitcnt lgkmcnt(3)
	v_cndmask_b32_e64 v143, 0, v143, s[8:9]
	v_pk_mul_f32 v[180:181], v[26:27], v[172:173] op_sel:[0,1]
	v_pk_mul_f32 v[192:193], v[28:29], v[172:173] op_sel:[0,1]
	v_mfma_f32_16x16x4_f32 v[110:113], v143, v66, v[110:113]
	v_pk_fma_f32 v[180:181], v[30:31], v[172:173], v[180:181] op_sel_hi:[1,0,1]
	v_pk_fma_f32 v[192:193], v[32:33], v[172:173], v[192:193] op_sel_hi:[1,0,1]
	v_pk_fma_f32 v[180:181], v[22:23], v[174:175], v[180:181] op_sel_hi:[1,0,1]
	v_pk_fma_f32 v[192:193], v[24:25], v[174:175], v[192:193] op_sel_hi:[1,0,1]
	v_mfma_f32_16x16x4_f32 v[106:109], v143, v67, v[106:109]
	v_pk_fma_f32 v[180:181], v[18:19], v[174:175], v[180:181] op_sel:[0,1,0]
	v_pk_fma_f32 v[192:193], v[20:21], v[174:175], v[192:193] op_sel:[0,1,0]
	v_pk_fma_f32 v[180:181], v[14:15], v[232:233], v[180:181] op_sel_hi:[1,0,1]
	v_pk_fma_f32 v[192:193], v[16:17], v[232:233], v[192:193] op_sel_hi:[1,0,1]
	v_mfma_f32_16x16x4_f32 v[102:105], v143, v68, v[102:105]
	v_pk_fma_f32 v[180:181], v[10:11], v[232:233], v[180:181] op_sel:[0,1,0]
	v_pk_fma_f32 v[192:193], v[12:13], v[232:233], v[192:193] op_sel:[0,1,0]
	v_pk_fma_f32 v[180:181], v[6:7], v[234:235], v[180:181] op_sel_hi:[1,0,1]
	v_pk_fma_f32 v[192:193], v[8:9], v[234:235], v[192:193] op_sel_hi:[1,0,1]
	v_mfma_f32_16x16x4_f32 v[98:101], v143, v69, v[98:101]
	v_pk_fma_f32 v[180:181], v[2:3], v[234:235], v[180:181] op_sel:[0,1,0]
	v_pk_fma_f32 v[192:193], v[4:5], v[234:235], v[192:193] op_sel:[0,1,0]
	v_pk_mul_f32 v[180:181], v[146:147], v[180:181]
	v_pk_mul_f32 v[192:193], v[146:147], v[192:193]
	v_pk_fma_f32 v[236:237], v[144:145], v[66:67], v[180:181]
	v_pk_fma_f32 v[238:239], v[144:145], v[68:69], v[192:193]
	global_store_dwordx4 v[150:151], v[236:239], off nt
	v_lshl_add_u64 v[150:151], v[150:151], 0, s[74:75]
	global_load_dwordx4 v[66:69], v[148:149], off nt
	v_lshl_add_u64 v[148:149], v[148:149], 0, s[74:75]
	ds_read_b32 v143, v160 offset:368
	ds_read_b128 v[172:175], v161 offset:2944
	ds_read_b128 v[232:235], v161 offset:2960
	s_waitcnt vmcnt(22)
; #define RS_LOAD(dst, it0) do { _Pragma("unroll") for (int u = 0; u < 8; ++u) dst[u] = __builtin_nontemporal_load((const f32x4*)(S0 + (size_t)(4 * ((it0) + u)) * DV)); } while (0)
; __device__ __forceinline__ void ret_sample_item(Frame& F, int item) {
;     ...
;     for (int it0 = 0; it0 < 64; it0 += 16) {
;         RS_LOAD(sb, it0 + 8);
;         RS_PROC(sa, it0);
;         { const int itn = it0 + 16 < 64 ? it0 + 16 : it0; RS_LOAD(sa, itn); }
;         RS_PROC(sb, it0 + 8);
;     }
	s_waitcnt lgkmcnt(3)
	v_cndmask_b32_e64 v141, 0, v141, s[8:9]
	v_pk_mul_f32 v[180:181], v[26:27], v[114:115] op_sel:[0,1]
	v_pk_mul_f32 v[192:193], v[28:29], v[114:115] op_sel:[0,1]
	v_mfma_f32_16x16x4_f32 v[110:113], v141, v74, v[110:113]
	v_pk_fma_f32 v[180:181], v[30:31], v[114:115], v[180:181] op_sel_hi:[1,0,1]
	v_pk_fma_f32 v[192:193], v[32:33], v[114:115], v[192:193] op_sel_hi:[1,0,1]
	v_pk_fma_f32 v[180:181], v[22:23], v[116:117], v[180:181] op_sel_hi:[1,0,1]
	v_pk_fma_f32 v[192:193], v[24:25], v[116:117], v[192:193] op_sel_hi:[1,0,1]
	v_mfma_f32_16x16x4_f32 v[106:109], v141, v75, v[106:109]
	v_pk_fma_f32 v[180:181], v[18:19], v[116:117], v[180:181] op_sel:[0,1,0]
	v_pk_fma_f32 v[192:193], v[20:21], v[116:117], v[192:193] op_sel:[0,1,0]
	v_pk_fma_f32 v[180:181], v[14:15], v[176:177], v[180:181] op_sel_hi:[1,0,1]
	v_pk_fma_f32 v[192:193], v[16:17], v[176:177], v[192:193] op_sel_hi:[1,0,1]
	v_mfma_f32_16x16x4_f32 v[102:105], v141, v76, v[102:105]
	v_pk_fma_f32 v[180:181], v[10:11], v[176:177], v[180:181] op_sel:[0,1,0]
	v_pk_fma_f32 v[192:193], v[12:13], v[176:177], v[192:193] op_sel:[0,1,0]
	v_pk_fma_f32 v[180:181], v[6:7], v[178:179], v[180:181] op_sel_hi:[1,0,1]
	v_pk_fma_f32 v[192:193], v[8:9], v[178:179], v[192:193] op_sel_hi:[1,0,1]
	v_mfma_f32_16x16x4_f32 v[98:101], v141, v77, v[98:101]
	v_pk_fma_f32 v[180:181], v[2:3], v[178:179], v[180:181] op_sel:[0,1,0]
	v_pk_fma_f32 v[192:193], v[4:5], v[178:179], v[192:193] op_sel:[0,1,0]
	v_pk_mul_f32 v[180:181], v[146:147], v[180:181]
	v_pk_mul_f32 v[192:193], v[146:147], v[192:193]
	v_pk_fma_f32 v[236:237], v[144:145], v[74:75], v[180:181]
	v_pk_fma_f32 v[238:239], v[144:145], v[76:77], v[192:193]
	global_store_dwordx4 v[150:151], v[236:239], off nt
	v_lshl_add_u64 v[150:151], v[150:151], 0, s[74:75]
	global_load_dwordx4 v[74:77], v[148:149], off nt
	v_lshl_add_u64 v[148:149], v[148:149], 0, s[74:75]
	ds_read_b32 v141, v160 offset:384
	ds_read_b128 v[114:117], v161 offset:3072
	ds_read_b128 v[176:179], v161 offset:3088
	s_waitcnt vmcnt(22)
	s_waitcnt lgkmcnt(3)
	v_cndmask_b32_e64 v143, 0, v143, s[8:9]
	v_pk_mul_f32 v[180:181], v[26:27], v[172:173] op_sel:[0,1]
	v_pk_mul_f32 v[192:193], v[28:29], v[172:173] op_sel:[0,1]
	v_mfma_f32_16x16x4_f32 v[110:113], v143, v78, v[110:113]
	v_pk_fma_f32 v[180:181], v[30:31], v[172:173], v[180:181] op_sel_hi:[1,0,1]
	v_pk_fma_f32 v[192:193], v[32:33], v[172:173], v[192:193] op_sel_hi:[1,0,1]
	v_pk_fma_f32 v[180:181], v[22:23], v[174:175], v[180:181] op_sel_hi:[1,0,1]
	v_pk_fma_f32 v[192:193], v[24:25], v[174:175], v[192:193] op_sel_hi:[1,0,1]
	v_mfma_f32_16x16x4_f32 v[106:109], v143, v79, v[106:109]
	v_pk_fma_f32 v[180:181], v[18:19], v[174:175], v[180:181] op_sel:[0,1,0]
	v_pk_fma_f32 v[192:193], v[20:21], v[174:175], v[192:193] op_sel:[0,1,0]
	v_pk_fma_f32 v[180:181], v[14:15], v[232:233], v[180:181] op_sel_hi:[1,0,1]
	v_pk_fma_f32 v[192:193], v[16:17], v[232:233], v[192:193] op_sel_hi:[1,0,1]
	v_mfma_f32_16x16x4_f32 v[102:105], v143, v80, v[102:105]
	v_pk_fma_f32 v[180:181], v[10:11], v[232:233], v[180:181] op_sel:[0,1,0]
	v_pk_fma_f32 v[192:193], v[12:13], v[232:233], v[192:193] op_sel:[0,1,0]
	v_pk_fma_f32 v[180:181], v[6:7], v[234:235], v[180:181] op_sel_hi:[1,0,1]
	v_pk_fma_f32 v[192:193], v[8:9], v[234:235], v[192:193] op_sel_hi:[1,0,1]
	v_mfma_f32_16x16x4_f32 v[98:101], v143, v81, v[98:101]
	v_pk_fma_f32 v[180:181], v[2:3], v[234:235], v[180:181] op_sel:[0,1,0]
	v_pk_fma_f32 v[192:193], v[4:5], v[234:235], v[192:193] op_sel:[0,1,0]
	v_pk_mul_f32 v[180:181], v[146:147], v[180:181]
	v_pk_mul_f32 v[192:193], v[146:147], v[192:193]
	v_pk_fma_f32 v[236:237], v[144:145], v[78:79], v[180:181]
	v_pk_fma_f32 v[238:239], v[144:145], v[80:81], v[192:193]
	global_store_dwordx4 v[150:151], v[236:239], off nt
	v_lshl_add_u64 v[150:151], v[150:151], 0, s[74:75]
	global_load_dwordx4 v[78:81], v[148:149], off nt
	v_lshl_add_u64 v[148:149], v[148:149], 0, s[74:75]
	ds_read_b32 v143, v160 offset:400
	ds_read_b128 v[172:175], v161 offset:3200
	ds_read_b128 v[232:235], v161 offset:3216
	s_waitcnt vmcnt(22)
	s_waitcnt lgkmcnt(3)
	v_cndmask_b32_e64 v141, 0, v141, s[8:9]
	v_pk_mul_f32 v[180:181], v[26:27], v[114:115] op_sel:[0,1]
	v_pk_mul_f32 v[192:193], v[28:29], v[114:115] op_sel:[0,1]
	v_mfma_f32_16x16x4_f32 v[110:113], v141, v70, v[110:113]
	v_pk_fma_f32 v[180:181], v[30:31], v[114:115], v[180:181] op_sel_hi:[1,0,1]
	v_pk_fma_f32 v[192:193], v[32:33], v[114:115], v[192:193] op_sel_hi:[1,0,1]
	v_pk_fma_f32 v[180:181], v[22:23], v[116:117], v[180:181] op_sel_hi:[1,0,1]
	v_pk_fma_f32 v[192:193], v[24:25], v[116:117], v[192:193] op_sel_hi:[1,0,1]
	v_mfma_f32_16x16x4_f32 v[106:109], v141, v71, v[106:109]
	v_pk_fma_f32 v[180:181], v[18:19], v[116:117], v[180:181] op_sel:[0,1,0]
	v_pk_fma_f32 v[192:193], v[20:21], v[116:117], v[192:193] op_sel:[0,1,0]
	v_pk_fma_f32 v[180:181], v[14:15], v[176:177], v[180:181] op_sel_hi:[1,0,1]
	v_pk_fma_f32 v[192:193], v[16:17], v[176:177], v[192:193] op_sel_hi:[1,0,1]
	v_mfma_f32_16x16x4_f32 v[102:105], v141, v72, v[102:105]
	v_pk_fma_f32 v[180:181], v[10:11], v[176:177], v[180:181] op_sel:[0,1,0]
	v_pk_fma_f32 v[192:193], v[12:13], v[176:177], v[192:193] op_sel:[0,1,0]
	v_pk_fma_f32 v[180:181], v[6:7], v[178:179], v[180:181] op_sel_hi:[1,0,1]
	v_pk_fma_f32 v[192:193], v[8:9], v[178:179], v[192:193] op_sel_hi:[1,0,1]
	v_mfma_f32_16x16x4_f32 v[98:101], v141, v73, v[98:101]
	v_pk_fma_f32 v[180:181], v[2:3], v[178:179], v[180:181] op_sel:[0,1,0]
	v_pk_fma_f32 v[192:193], v[4:5], v[178:179], v[192:193] op_sel:[0,1,0]
	v_pk_mul_f32 v[180:181], v[146:147], v[180:181]
	v_pk_mul_f32 v[192:193], v[146:147], v[192:193]
	v_pk_fma_f32 v[236:237], v[144:145], v[70:71], v[180:181]
	v_pk_fma_f32 v[238:239], v[144:145], v[72:73], v[192:193]
	global_store_dwordx4 v[150:151], v[236:239], off nt
	v_lshl_add_u64 v[150:151], v[150:151], 0, s[74:75]
	global_load_dwordx4 v[70:73], v[148:149], off nt
	v_lshl_add_u64 v[148:149], v[148:149], 0, s[74:75]
	ds_read_b32 v141, v160 offset:416
	ds_read_b128 v[114:117], v161 offset:3328
	ds_read_b128 v[176:179], v161 offset:3344
	s_waitcnt vmcnt(22)
; #define RS_LOAD(dst, it0) do { _Pragma("unroll") for (int u = 0; u < 8; ++u) dst[u] = __builtin_nontemporal_load((const f32x4*)(S0 + (size_t)(4 * ((it0) + u)) * DV)); } while (0)
; __device__ __forceinline__ void ret_sample_item(Frame& F, int item) {
;     ...
;     for (int it0 = 0; it0 < 64; it0 += 16) {
;         RS_LOAD(sb, it0 + 8);
;         RS_PROC(sa, it0);
;         { const int itn = it0 + 16 < 64 ? it0 + 16 : it0; RS_LOAD(sa, itn); }
;         RS_PROC(sb, it0 + 8);
;     }
	s_waitcnt lgkmcnt(3)
	v_cndmask_b32_e64 v143, 0, v143, s[8:9]
	v_pk_mul_f32 v[180:181], v[26:27], v[172:173] op_sel:[0,1]
	v_pk_mul_f32 v[192:193], v[28:29], v[172:173] op_sel:[0,1]
	v_mfma_f32_16x16x4_f32 v[110:113], v143, v62, v[110:113]
	v_pk_fma_f32 v[180:181], v[30:31], v[172:173], v[180:181] op_sel_hi:[1,0,1]
	v_pk_fma_f32 v[192:193], v[32:33], v[172:173], v[192:193] op_sel_hi:[1,0,1]
	v_pk_fma_f32 v[180:181], v[22:23], v[174:175], v[180:181] op_sel_hi:[1,0,1]
	v_pk_fma_f32 v[192:193], v[24:25], v[174:175], v[192:193] op_sel_hi:[1,0,1]
	v_mfma_f32_16x16x4_f32 v[106:109], v143, v63, v[106:109]
	v_pk_fma_f32 v[180:181], v[18:19], v[174:175], v[180:181] op_sel:[0,1,0]
	v_pk_fma_f32 v[192:193], v[20:21], v[174:175], v[192:193] op_sel:[0,1,0]
	v_pk_fma_f32 v[180:181], v[14:15], v[232:233], v[180:181] op_sel_hi:[1,0,1]
	v_pk_fma_f32 v[192:193], v[16:17], v[232:233], v[192:193] op_sel_hi:[1,0,1]
	v_mfma_f32_16x16x4_f32 v[102:105], v143, v64, v[102:105]
	v_pk_fma_f32 v[180:181], v[10:11], v[232:233], v[180:181] op_sel:[0,1,0]
	v_pk_fma_f32 v[192:193], v[12:13], v[232:233], v[192:193] op_sel:[0,1,0]
	v_pk_fma_f32 v[180:181], v[6:7], v[234:235], v[180:181] op_sel_hi:[1,0,1]
	v_pk_fma_f32 v[192:193], v[8:9], v[234:235], v[192:193] op_sel_hi:[1,0,1]
	v_mfma_f32_16x16x4_f32 v[98:101], v143, v65, v[98:101]
	v_pk_fma_f32 v[180:181], v[2:3], v[234:235], v[180:181] op_sel:[0,1,0]
	v_pk_fma_f32 v[192:193], v[4:5], v[234:235], v[192:193] op_sel:[0,1,0]
	v_pk_mul_f32 v[180:181], v[146:147], v[180:181]
	v_pk_mul_f32 v[192:193], v[146:147], v[192:193]
	v_pk_fma_f32 v[236:237], v[144:145], v[62:63], v[180:181]
	v_pk_fma_f32 v[238:239], v[144:145], v[64:65], v[192:193]
	global_store_dwordx4 v[150:151], v[236:239], off nt
	v_lshl_add_u64 v[150:151], v[150:151], 0, s[74:75]
	global_load_dwordx4 v[62:65], v[148:149], off nt
	v_lshl_add_u64 v[148:149], v[148:149], 0, s[74:75]
	ds_read_b32 v143, v160 offset:432
	ds_read_b128 v[172:175], v161 offset:3456
	ds_read_b128 v[232:235], v161 offset:3472
	s_waitcnt vmcnt(22)
	s_waitcnt lgkmcnt(3)
	v_cndmask_b32_e64 v141, 0, v141, s[8:9]
	v_pk_mul_f32 v[180:181], v[26:27], v[114:115] op_sel:[0,1]
	v_pk_mul_f32 v[192:193], v[28:29], v[114:115] op_sel:[0,1]
	v_mfma_f32_16x16x4_f32 v[110:113], v141, v54, v[110:113]
	v_pk_fma_f32 v[180:181], v[30:31], v[114:115], v[180:181] op_sel_hi:[1,0,1]
	v_pk_fma_f32 v[192:193], v[32:33], v[114:115], v[192:193] op_sel_hi:[1,0,1]
	v_pk_fma_f32 v[180:181], v[22:23], v[116:117], v[180:181] op_sel_hi:[1,0,1]
	v_pk_fma_f32 v[192:193], v[24:25], v[116:117], v[192:193] op_sel_hi:[1,0,1]
	v_mfma_f32_16x16x4_f32 v[106:109], v141, v55, v[106:109]
	v_pk_fma_f32 v[180:181], v[18:19], v[116:117], v[180:181] op_sel:[0,1,0]
	v_pk_fma_f32 v[192:193], v[20:21], v[116:117], v[192:193] op_sel:[0,1,0]
	v_pk_fma_f32 v[180:181], v[14:15], v[176:177], v[180:181] op_sel_hi:[1,0,1]
	v_pk_fma_f32 v[192:193], v[16:17], v[176:177], v[192:193] op_sel_hi:[1,0,1]
	v_mfma_f32_16x16x4_f32 v[102:105], v141, v56, v[102:105]
	v_pk_fma_f32 v[180:181], v[10:11], v[176:177], v[180:181] op_sel:[0,1,0]
	v_pk_fma_f32 v[192:193], v[12:13], v[176:177], v[192:193] op_sel:[0,1,0]
	v_pk_fma_f32 v[180:181], v[6:7], v[178:179], v[180:181] op_sel_hi:[1,0,1]
	v_pk_fma_f32 v[192:193], v[8:9], v[178:179], v[192:193] op_sel_hi:[1,0,1]
	v_mfma_f32_16x16x4_f32 v[98:101], v141, v57, v[98:101]
	v_pk_fma_f32 v[180:181], v[2:3], v[178:179], v[180:181] op_sel:[0,1,0]
	v_pk_fma_f32 v[192:193], v[4:5], v[178:179], v[192:193] op_sel:[0,1,0]
	v_pk_mul_f32 v[180:181], v[146:147], v[180:181]
	v_pk_mul_f32 v[192:193], v[146:147], v[192:193]
	v_pk_fma_f32 v[236:237], v[144:145], v[54:55], v[180:181]
	v_pk_fma_f32 v[238:239], v[144:145], v[56:57], v[192:193]
	global_store_dwordx4 v[150:151], v[236:239], off nt
	v_lshl_add_u64 v[150:151], v[150:151], 0, s[74:75]
	global_load_dwordx4 v[54:57], v[148:149], off nt
	v_lshl_add_u64 v[148:149], v[148:149], 0, s[74:75]
	ds_read_b32 v141, v160 offset:448
	ds_read_b128 v[114:117], v161 offset:3584
	ds_read_b128 v[176:179], v161 offset:3600
	s_waitcnt vmcnt(22)
	s_waitcnt lgkmcnt(3)
	v_cndmask_b32_e64 v143, 0, v143, s[8:9]
	v_pk_mul_f32 v[180:181], v[26:27], v[172:173] op_sel:[0,1]
	v_pk_mul_f32 v[192:193], v[28:29], v[172:173] op_sel:[0,1]
	v_mfma_f32_16x16x4_f32 v[110:113], v143, v50, v[110:113]
	v_pk_fma_f32 v[180:181], v[30:31], v[172:173], v[180:181] op_sel_hi:[1,0,1]
	v_pk_fma_f32 v[192:193], v[32:33], v[172:173], v[192:193] op_sel_hi:[1,0,1]
	v_pk_fma_f32 v[180:181], v[22:23], v[174:175], v[180:181] op_sel_hi:[1,0,1]
	v_pk_fma_f32 v[192:193], v[24:25], v[174:175], v[192:193] op_sel_hi:[1,0,1]
	v_mfma_f32_16x16x4_f32 v[106:109], v143, v51, v[106:109]
	v_pk_fma_f32 v[180:181], v[18:19], v[174:175], v[180:181] op_sel:[0,1,0]
	v_pk_fma_f32 v[192:193], v[20:21], v[174:175], v[192:193] op_sel:[0,1,0]
	v_pk_fma_f32 v[180:181], v[14:15], v[232:233], v[180:181] op_sel_hi:[1,0,1]
	v_pk_fma_f32 v[192:193], v[16:17], v[232:233], v[192:193] op_sel_hi:[1,0,1]
	v_mfma_f32_16x16x4_f32 v[102:105], v143, v52, v[102:105]
	v_pk_fma_f32 v[180:181], v[10:11], v[232:233], v[180:181] op_sel:[0,1,0]
	v_pk_fma_f32 v[192:193], v[12:13], v[232:233], v[192:193] op_sel:[0,1,0]
	v_pk_fma_f32 v[180:181], v[6:7], v[234:235], v[180:181] op_sel_hi:[1,0,1]
	v_pk_fma_f32 v[192:193], v[8:9], v[234:235], v[192:193] op_sel_hi:[1,0,1]
	v_mfma_f32_16x16x4_f32 v[98:101], v143, v53, v[98:101]
	v_pk_fma_f32 v[180:181], v[2:3], v[234:235], v[180:181] op_sel:[0,1,0]
	v_pk_fma_f32 v[192:193], v[4:5], v[234:235], v[192:193] op_sel:[0,1,0]
	v_pk_mul_f32 v[180:181], v[146:147], v[180:181]
	v_pk_mul_f32 v[192:193], v[146:147], v[192:193]
	v_pk_fma_f32 v[236:237], v[144:145], v[50:51], v[180:181]
	v_pk_fma_f32 v[238:239], v[144:145], v[52:53], v[192:193]
	global_store_dwordx4 v[150:151], v[236:239], off nt
	v_lshl_add_u64 v[150:151], v[150:151], 0, s[74:75]
	global_load_dwordx4 v[50:53], v[148:149], off nt
	v_lshl_add_u64 v[148:149], v[148:149], 0, s[74:75]
	ds_read_b32 v143, v160 offset:464
	ds_read_b128 v[172:175], v161 offset:3712
	ds_read_b128 v[232:235], v161 offset:3728
	s_waitcnt vmcnt(22)
; #define RS_LOAD(dst, it0) do { _Pragma("unroll") for (int u = 0; u < 8; ++u) dst[u] = __builtin_nontemporal_load((const f32x4*)(S0 + (size_t)(4 * ((it0) + u)) * DV)); } while (0)
; __device__ __forceinline__ void ret_sample_item(Frame& F, int item) {
;     ...
;     for (int it0 = 0; it0 < 64; it0 += 16) {
;         RS_LOAD(sb, it0 + 8);
;         RS_PROC(sa, it0);
;         { const int itn = it0 + 16 < 64 ? it0 + 16 : it0; RS_LOAD(sa, itn); }
;         RS_PROC(sb, it0 + 8);
;     }
	s_waitcnt lgkmcnt(3)
	v_cndmask_b32_e64 v141, 0, v141, s[8:9]
	v_pk_mul_f32 v[180:181], v[26:27], v[114:115] op_sel:[0,1]
	v_pk_mul_f32 v[192:193], v[28:29], v[114:115] op_sel:[0,1]
	v_mfma_f32_16x16x4_f32 v[110:113], v141, v46, v[110:113]
	v_pk_fma_f32 v[180:181], v[30:31], v[114:115], v[180:181] op_sel_hi:[1,0,1]
	v_pk_fma_f32 v[192:193], v[32:33], v[114:115], v[192:193] op_sel_hi:[1,0,1]
	v_pk_fma_f32 v[180:181], v[22:23], v[116:117], v[180:181] op_sel_hi:[1,0,1]
	v_pk_fma_f32 v[192:193], v[24:25], v[116:117], v[192:193] op_sel_hi:[1,0,1]
	v_mfma_f32_16x16x4_f32 v[106:109], v141, v47, v[106:109]
	v_pk_fma_f32 v[180:181], v[18:19], v[116:117], v[180:181] op_sel:[0,1,0]
	v_pk_fma_f32 v[192:193], v[20:21], v[116:117], v[192:193] op_sel:[0,1,0]
	v_pk_fma_f32 v[180:181], v[14:15], v[176:177], v[180:181] op_sel_hi:[1,0,1]
	v_pk_fma_f32 v[192:193], v[16:17], v[176:177], v[192:193] op_sel_hi:[1,0,1]
	v_mfma_f32_16x16x4_f32 v[102:105], v141, v48, v[102:105]
	v_pk_fma_f32 v[180:181], v[10:11], v[176:177], v[180:181] op_sel:[0,1,0]
	v_pk_fma_f32 v[192:193], v[12:13], v[176:177], v[192:193] op_sel:[0,1,0]
	v_pk_fma_f32 v[180:181], v[6:7], v[178:179], v[180:181] op_sel_hi:[1,0,1]
	v_pk_fma_f32 v[192:193], v[8:9], v[178:179], v[192:193] op_sel_hi:[1,0,1]
	v_mfma_f32_16x16x4_f32 v[98:101], v141, v49, v[98:101]
	v_pk_fma_f32 v[180:181], v[2:3], v[178:179], v[180:181] op_sel:[0,1,0]
	v_pk_fma_f32 v[192:193], v[4:5], v[178:179], v[192:193] op_sel:[0,1,0]
	v_pk_mul_f32 v[180:181], v[146:147], v[180:181]
	v_pk_mul_f32 v[192:193], v[146:147], v[192:193]
	v_pk_fma_f32 v[236:237], v[144:145], v[46:47], v[180:181]
	v_pk_fma_f32 v[238:239], v[144:145], v[48:49], v[192:193]
	global_store_dwordx4 v[150:151], v[236:239], off nt
	v_lshl_add_u64 v[150:151], v[150:151], 0, s[74:75]
	global_load_dwordx4 v[46:49], v[148:149], off nt
	v_lshl_add_u64 v[148:149], v[148:149], 0, s[74:75]
	ds_read_b32 v141, v160 offset:480
	ds_read_b128 v[114:117], v161 offset:3840
	ds_read_b128 v[176:179], v161 offset:3856
	s_waitcnt vmcnt(22)
	s_waitcnt lgkmcnt(3)
	v_cndmask_b32_e64 v143, 0, v143, s[8:9]
	v_pk_mul_f32 v[180:181], v[26:27], v[172:173] op_sel:[0,1]
	v_pk_mul_f32 v[192:193], v[28:29], v[172:173] op_sel:[0,1]
	v_mfma_f32_16x16x4_f32 v[110:113], v143, v42, v[110:113]
	v_pk_fma_f32 v[180:181], v[30:31], v[172:173], v[180:181] op_sel_hi:[1,0,1]
	v_pk_fma_f32 v[192:193], v[32:33], v[172:173], v[192:193] op_sel_hi:[1,0,1]
	v_pk_fma_f32 v[180:181], v[22:23], v[174:175], v[180:181] op_sel_hi:[1,0,1]
	v_pk_fma_f32 v[192:193], v[24:25], v[174:175], v[192:193] op_sel_hi:[1,0,1]
	v_mfma_f32_16x16x4_f32 v[106:109], v143, v43, v[106:109]
	v_pk_fma_f32 v[180:181], v[18:19], v[174:175], v[180:181] op_sel:[0,1,0]
	v_pk_fma_f32 v[192:193], v[20:21], v[174:175], v[192:193] op_sel:[0,1,0]
	v_pk_fma_f32 v[180:181], v[14:15], v[232:233], v[180:181] op_sel_hi:[1,0,1]
	v_pk_fma_f32 v[192:193], v[16:17], v[232:233], v[192:193] op_sel_hi:[1,0,1]
	v_mfma_f32_16x16x4_f32 v[102:105], v143, v44, v[102:105]
	v_pk_fma_f32 v[180:181], v[10:11], v[232:233], v[180:181] op_sel:[0,1,0]
	v_pk_fma_f32 v[192:193], v[12:13], v[232:233], v[192:193] op_sel:[0,1,0]
	v_pk_fma_f32 v[180:181], v[6:7], v[234:235], v[180:181] op_sel_hi:[1,0,1]
	v_pk_fma_f32 v[192:193], v[8:9], v[234:235], v[192:193] op_sel_hi:[1,0,1]
	v_mfma_f32_16x16x4_f32 v[98:101], v143, v45, v[98:101]
	v_pk_fma_f32 v[180:181], v[2:3], v[234:235], v[180:181] op_sel:[0,1,0]
	v_pk_fma_f32 v[192:193], v[4:5], v[234:235], v[192:193] op_sel:[0,1,0]
	v_pk_mul_f32 v[180:181], v[146:147], v[180:181]
	v_pk_mul_f32 v[192:193], v[146:147], v[192:193]
	v_pk_fma_f32 v[236:237], v[144:145], v[42:43], v[180:181]
	v_pk_fma_f32 v[238:239], v[144:145], v[44:45], v[192:193]
	global_store_dwordx4 v[150:151], v[236:239], off nt
	v_lshl_add_u64 v[150:151], v[150:151], 0, s[74:75]
	global_load_dwordx4 v[42:45], v[148:149], off nt
	v_lshl_add_u64 v[148:149], v[148:149], 0, s[74:75]
	ds_read_b32 v143, v160 offset:496
	ds_read_b128 v[172:175], v161 offset:3968
	ds_read_b128 v[232:235], v161 offset:3984
	s_waitcnt vmcnt(22)
	s_waitcnt lgkmcnt(3)
	v_cndmask_b32_e64 v141, 0, v141, s[8:9]
	v_pk_mul_f32 v[180:181], v[26:27], v[114:115] op_sel:[0,1]
	v_pk_mul_f32 v[192:193], v[28:29], v[114:115] op_sel:[0,1]
	v_mfma_f32_16x16x4_f32 v[110:113], v141, v38, v[110:113]
	v_pk_fma_f32 v[180:181], v[30:31], v[114:115], v[180:181] op_sel_hi:[1,0,1]
	v_pk_fma_f32 v[192:193], v[32:33], v[114:115], v[192:193] op_sel_hi:[1,0,1]
	v_pk_fma_f32 v[180:181], v[22:23], v[116:117], v[180:181] op_sel_hi:[1,0,1]
	v_pk_fma_f32 v[192:193], v[24:25], v[116:117], v[192:193] op_sel_hi:[1,0,1]
	v_mfma_f32_16x16x4_f32 v[106:109], v141, v39, v[106:109]
	v_pk_fma_f32 v[180:181], v[18:19], v[116:117], v[180:181] op_sel:[0,1,0]
	v_pk_fma_f32 v[192:193], v[20:21], v[116:117], v[192:193] op_sel:[0,1,0]
	v_pk_fma_f32 v[180:181], v[14:15], v[176:177], v[180:181] op_sel_hi:[1,0,1]
	v_pk_fma_f32 v[192:193], v[16:17], v[176:177], v[192:193] op_sel_hi:[1,0,1]
	v_mfma_f32_16x16x4_f32 v[102:105], v141, v40, v[102:105]
	v_pk_fma_f32 v[180:181], v[10:11], v[176:177], v[180:181] op_sel:[0,1,0]
	v_pk_fma_f32 v[192:193], v[12:13], v[176:177], v[192:193] op_sel:[0,1,0]
	v_pk_fma_f32 v[180:181], v[6:7], v[178:179], v[180:181] op_sel_hi:[1,0,1]
	v_pk_fma_f32 v[192:193], v[8:9], v[178:179], v[192:193] op_sel_hi:[1,0,1]
	v_mfma_f32_16x16x4_f32 v[98:101], v141, v41, v[98:101]
	v_pk_fma_f32 v[180:181], v[2:3], v[178:179], v[180:181] op_sel:[0,1,0]
	v_pk_fma_f32 v[192:193], v[4:5], v[178:179], v[192:193] op_sel:[0,1,0]
	v_pk_mul_f32 v[180:181], v[146:147], v[180:181]
	v_pk_mul_f32 v[192:193], v[146:147], v[192:193]
	v_pk_fma_f32 v[236:237], v[144:145], v[38:39], v[180:181]
	v_pk_fma_f32 v[238:239], v[144:145], v[40:41], v[192:193]
	global_store_dwordx4 v[150:151], v[236:239], off nt
	v_lshl_add_u64 v[150:151], v[150:151], 0, s[74:75]
	global_load_dwordx4 v[38:41], v[148:149], off nt
	v_lshl_add_u64 v[148:149], v[148:149], 0, s[74:75]
	ds_read_b32 v141, v160 offset:512
	ds_read_b128 v[114:117], v161 offset:4096
	ds_read_b128 v[176:179], v161 offset:4112
	s_waitcnt vmcnt(22)
; #define RS_LOAD(dst, it0) do { _Pragma("unroll") for (int u = 0; u < 8; ++u) dst[u] = __builtin_nontemporal_load((const f32x4*)(S0 + (size_t)(4 * ((it0) + u)) * DV)); } while (0)
; __device__ __forceinline__ void ret_sample_item(Frame& F, int item) {
;     ...
;     for (int it0 = 0; it0 < 64; it0 += 16) {
;         RS_LOAD(sb, it0 + 8);
;         RS_PROC(sa, it0);
;         { const int itn = it0 + 16 < 64 ? it0 + 16 : it0; RS_LOAD(sa, itn); }
;         RS_PROC(sb, it0 + 8);
;     }
	s_waitcnt lgkmcnt(3)
	v_cndmask_b32_e64 v143, 0, v143, s[8:9]
	v_pk_mul_f32 v[180:181], v[26:27], v[172:173] op_sel:[0,1]
	v_pk_mul_f32 v[192:193], v[28:29], v[172:173] op_sel:[0,1]
	v_mfma_f32_16x16x4_f32 v[110:113], v143, v34, v[110:113]
	v_pk_fma_f32 v[180:181], v[30:31], v[172:173], v[180:181] op_sel_hi:[1,0,1]
	v_pk_fma_f32 v[192:193], v[32:33], v[172:173], v[192:193] op_sel_hi:[1,0,1]
	v_pk_fma_f32 v[180:181], v[22:23], v[174:175], v[180:181] op_sel_hi:[1,0,1]
	v_pk_fma_f32 v[192:193], v[24:25], v[174:175], v[192:193] op_sel_hi:[1,0,1]
	v_mfma_f32_16x16x4_f32 v[106:109], v143, v35, v[106:109]
	v_pk_fma_f32 v[180:181], v[18:19], v[174:175], v[180:181] op_sel:[0,1,0]
	v_pk_fma_f32 v[192:193], v[20:21], v[174:175], v[192:193] op_sel:[0,1,0]
	v_pk_fma_f32 v[180:181], v[14:15], v[232:233], v[180:181] op_sel_hi:[1,0,1]
	v_pk_fma_f32 v[192:193], v[16:17], v[232:233], v[192:193] op_sel_hi:[1,0,1]
	v_mfma_f32_16x16x4_f32 v[102:105], v143, v36, v[102:105]
	v_pk_fma_f32 v[180:181], v[10:11], v[232:233], v[180:181] op_sel:[0,1,0]
	v_pk_fma_f32 v[192:193], v[12:13], v[232:233], v[192:193] op_sel:[0,1,0]
	v_pk_fma_f32 v[180:181], v[6:7], v[234:235], v[180:181] op_sel_hi:[1,0,1]
	v_pk_fma_f32 v[192:193], v[8:9], v[234:235], v[192:193] op_sel_hi:[1,0,1]
	v_mfma_f32_16x16x4_f32 v[98:101], v143, v37, v[98:101]
	v_pk_fma_f32 v[180:181], v[2:3], v[234:235], v[180:181] op_sel:[0,1,0]
	v_pk_fma_f32 v[192:193], v[4:5], v[234:235], v[192:193] op_sel:[0,1,0]
	v_pk_mul_f32 v[180:181], v[146:147], v[180:181]
	v_pk_mul_f32 v[192:193], v[146:147], v[192:193]
	v_pk_fma_f32 v[236:237], v[144:145], v[34:35], v[180:181]
	v_pk_fma_f32 v[238:239], v[144:145], v[36:37], v[192:193]
	global_store_dwordx4 v[150:151], v[236:239], off nt
	v_lshl_add_u64 v[150:151], v[150:151], 0, s[74:75]
	global_load_dwordx4 v[34:37], v[148:149], off nt
	v_lshl_add_u64 v[148:149], v[148:149], 0, s[74:75]
	ds_read_b32 v143, v160 offset:528
	ds_read_b128 v[172:175], v161 offset:4224
	ds_read_b128 v[232:235], v161 offset:4240
	s_waitcnt vmcnt(22)
	s_waitcnt lgkmcnt(3)
	v_cndmask_b32_e64 v141, 0, v141, s[8:9]
	v_pk_mul_f32 v[180:181], v[26:27], v[114:115] op_sel:[0,1]
	v_pk_mul_f32 v[192:193], v[28:29], v[114:115] op_sel:[0,1]
	v_mfma_f32_16x16x4_f32 v[110:113], v141, v58, v[110:113]
	v_pk_fma_f32 v[180:181], v[30:31], v[114:115], v[180:181] op_sel_hi:[1,0,1]
	v_pk_fma_f32 v[192:193], v[32:33], v[114:115], v[192:193] op_sel_hi:[1,0,1]
	v_pk_fma_f32 v[180:181], v[22:23], v[116:117], v[180:181] op_sel_hi:[1,0,1]
	v_pk_fma_f32 v[192:193], v[24:25], v[116:117], v[192:193] op_sel_hi:[1,0,1]
	v_mfma_f32_16x16x4_f32 v[106:109], v141, v59, v[106:109]
	v_pk_fma_f32 v[180:181], v[18:19], v[116:117], v[180:181] op_sel:[0,1,0]
	v_pk_fma_f32 v[192:193], v[20:21], v[116:117], v[192:193] op_sel:[0,1,0]
	v_pk_fma_f32 v[180:181], v[14:15], v[176:177], v[180:181] op_sel_hi:[1,0,1]
	v_pk_fma_f32 v[192:193], v[16:17], v[176:177], v[192:193] op_sel_hi:[1,0,1]
	v_mfma_f32_16x16x4_f32 v[102:105], v141, v60, v[102:105]
	v_pk_fma_f32 v[180:181], v[10:11], v[176:177], v[180:181] op_sel:[0,1,0]
	v_pk_fma_f32 v[192:193], v[12:13], v[176:177], v[192:193] op_sel:[0,1,0]
	v_pk_fma_f32 v[180:181], v[6:7], v[178:179], v[180:181] op_sel_hi:[1,0,1]
	v_pk_fma_f32 v[192:193], v[8:9], v[178:179], v[192:193] op_sel_hi:[1,0,1]
	v_mfma_f32_16x16x4_f32 v[98:101], v141, v61, v[98:101]
	v_pk_fma_f32 v[180:181], v[2:3], v[178:179], v[180:181] op_sel:[0,1,0]
	v_pk_fma_f32 v[192:193], v[4:5], v[178:179], v[192:193] op_sel:[0,1,0]
	v_pk_mul_f32 v[180:181], v[146:147], v[180:181]
	v_pk_mul_f32 v[192:193], v[146:147], v[192:193]
	v_pk_fma_f32 v[236:237], v[144:145], v[58:59], v[180:181]
	v_pk_fma_f32 v[238:239], v[144:145], v[60:61], v[192:193]
	global_store_dwordx4 v[150:151], v[236:239], off nt
	v_lshl_add_u64 v[150:151], v[150:151], 0, s[74:75]
	global_load_dwordx4 v[58:61], v[148:149], off nt
	v_lshl_add_u64 v[148:149], v[148:149], 0, s[74:75]
	ds_read_b32 v141, v160 offset:544
	ds_read_b128 v[114:117], v161 offset:4352
	ds_read_b128 v[176:179], v161 offset:4368
	s_waitcnt vmcnt(22)
	s_waitcnt lgkmcnt(3)
	v_cndmask_b32_e64 v143, 0, v143, s[8:9]
	v_pk_mul_f32 v[180:181], v[26:27], v[172:173] op_sel:[0,1]
	v_pk_mul_f32 v[192:193], v[28:29], v[172:173] op_sel:[0,1]
	v_mfma_f32_16x16x4_f32 v[110:113], v143, v66, v[110:113]
	v_pk_fma_f32 v[180:181], v[30:31], v[172:173], v[180:181] op_sel_hi:[1,0,1]
	v_pk_fma_f32 v[192:193], v[32:33], v[172:173], v[192:193] op_sel_hi:[1,0,1]
	v_pk_fma_f32 v[180:181], v[22:23], v[174:175], v[180:181] op_sel_hi:[1,0,1]
	v_pk_fma_f32 v[192:193], v[24:25], v[174:175], v[192:193] op_sel_hi:[1,0,1]
	v_mfma_f32_16x16x4_f32 v[106:109], v143, v67, v[106:109]
	v_pk_fma_f32 v[180:181], v[18:19], v[174:175], v[180:181] op_sel:[0,1,0]
	v_pk_fma_f32 v[192:193], v[20:21], v[174:175], v[192:193] op_sel:[0,1,0]
	v_pk_fma_f32 v[180:181], v[14:15], v[232:233], v[180:181] op_sel_hi:[1,0,1]
	v_pk_fma_f32 v[192:193], v[16:17], v[232:233], v[192:193] op_sel_hi:[1,0,1]
	v_mfma_f32_16x16x4_f32 v[102:105], v143, v68, v[102:105]
	v_pk_fma_f32 v[180:181], v[10:11], v[232:233], v[180:181] op_sel:[0,1,0]
	v_pk_fma_f32 v[192:193], v[12:13], v[232:233], v[192:193] op_sel:[0,1,0]
	v_pk_fma_f32 v[180:181], v[6:7], v[234:235], v[180:181] op_sel_hi:[1,0,1]
	v_pk_fma_f32 v[192:193], v[8:9], v[234:235], v[192:193] op_sel_hi:[1,0,1]
	v_mfma_f32_16x16x4_f32 v[98:101], v143, v69, v[98:101]
	v_pk_fma_f32 v[180:181], v[2:3], v[234:235], v[180:181] op_sel:[0,1,0]
	v_pk_fma_f32 v[192:193], v[4:5], v[234:235], v[192:193] op_sel:[0,1,0]
	v_pk_mul_f32 v[180:181], v[146:147], v[180:181]
	v_pk_mul_f32 v[192:193], v[146:147], v[192:193]
	v_pk_fma_f32 v[236:237], v[144:145], v[66:67], v[180:181]
	v_pk_fma_f32 v[238:239], v[144:145], v[68:69], v[192:193]
	global_store_dwordx4 v[150:151], v[236:239], off nt
	v_lshl_add_u64 v[150:151], v[150:151], 0, s[74:75]
	global_load_dwordx4 v[66:69], v[148:149], off nt
	v_lshl_add_u64 v[148:149], v[148:149], 0, s[74:75]
	ds_read_b32 v143, v160 offset:560
	ds_read_b128 v[172:175], v161 offset:4480
	ds_read_b128 v[232:235], v161 offset:4496
	s_waitcnt vmcnt(22)
; #define RS_LOAD(dst, it0) do { _Pragma("unroll") for (int u = 0; u < 8; ++u) dst[u] = __builtin_nontemporal_load((const f32x4*)(S0 + (size_t)(4 * ((it0) + u)) * DV)); } while (0)
; __device__ __forceinline__ void ret_sample_item(Frame& F, int item) {
;     ...
;     for (int it0 = 0; it0 < 64; it0 += 16) {
;         RS_LOAD(sb, it0 + 8);
;         RS_PROC(sa, it0);
;         { const int itn = it0 + 16 < 64 ? it0 + 16 : it0; RS_LOAD(sa, itn); }
;         RS_PROC(sb, it0 + 8);
;     }
	s_waitcnt lgkmcnt(3)
	v_cndmask_b32_e64 v141, 0, v141, s[8:9]
	v_pk_mul_f32 v[180:181], v[26:27], v[114:115] op_sel:[0,1]
	v_pk_mul_f32 v[192:193], v[28:29], v[114:115] op_sel:[0,1]
	v_mfma_f32_16x16x4_f32 v[110:113], v141, v74, v[110:113]
	v_pk_fma_f32 v[180:181], v[30:31], v[114:115], v[180:181] op_sel_hi:[1,0,1]
	v_pk_fma_f32 v[192:193], v[32:33], v[114:115], v[192:193] op_sel_hi:[1,0,1]
	v_pk_fma_f32 v[180:181], v[22:23], v[116:117], v[180:181] op_sel_hi:[1,0,1]
	v_pk_fma_f32 v[192:193], v[24:25], v[116:117], v[192:193] op_sel_hi:[1,0,1]
	v_mfma_f32_16x16x4_f32 v[106:109], v141, v75, v[106:109]
	v_pk_fma_f32 v[180:181], v[18:19], v[116:117], v[180:181] op_sel:[0,1,0]
	v_pk_fma_f32 v[192:193], v[20:21], v[116:117], v[192:193] op_sel:[0,1,0]
	v_pk_fma_f32 v[180:181], v[14:15], v[176:177], v[180:181] op_sel_hi:[1,0,1]
	v_pk_fma_f32 v[192:193], v[16:17], v[176:177], v[192:193] op_sel_hi:[1,0,1]
	v_mfma_f32_16x16x4_f32 v[102:105], v141, v76, v[102:105]
	v_pk_fma_f32 v[180:181], v[10:11], v[176:177], v[180:181] op_sel:[0,1,0]
	v_pk_fma_f32 v[192:193], v[12:13], v[176:177], v[192:193] op_sel:[0,1,0]
	v_pk_fma_f32 v[180:181], v[6:7], v[178:179], v[180:181] op_sel_hi:[1,0,1]
	v_pk_fma_f32 v[192:193], v[8:9], v[178:179], v[192:193] op_sel_hi:[1,0,1]
	v_mfma_f32_16x16x4_f32 v[98:101], v141, v77, v[98:101]
	v_pk_fma_f32 v[180:181], v[2:3], v[178:179], v[180:181] op_sel:[0,1,0]
	v_pk_fma_f32 v[192:193], v[4:5], v[178:179], v[192:193] op_sel:[0,1,0]
	v_pk_mul_f32 v[180:181], v[146:147], v[180:181]
	v_pk_mul_f32 v[192:193], v[146:147], v[192:193]
	v_pk_fma_f32 v[236:237], v[144:145], v[74:75], v[180:181]
	v_pk_fma_f32 v[238:239], v[144:145], v[76:77], v[192:193]
	global_store_dwordx4 v[150:151], v[236:239], off nt
	v_lshl_add_u64 v[150:151], v[150:151], 0, s[74:75]
	global_load_dwordx4 v[74:77], v[148:149], off nt
	v_lshl_add_u64 v[148:149], v[148:149], 0, s[74:75]
	ds_read_b32 v141, v160 offset:576
	ds_read_b128 v[114:117], v161 offset:4608
	ds_read_b128 v[176:179], v161 offset:4624
	s_waitcnt vmcnt(22)
	s_waitcnt lgkmcnt(3)
	v_cndmask_b32_e64 v143, 0, v143, s[8:9]
	v_pk_mul_f32 v[180:181], v[26:27], v[172:173] op_sel:[0,1]
	v_pk_mul_f32 v[192:193], v[28:29], v[172:173] op_sel:[0,1]
	v_mfma_f32_16x16x4_f32 v[110:113], v143, v78, v[110:113]
	v_pk_fma_f32 v[180:181], v[30:31], v[172:173], v[180:181] op_sel_hi:[1,0,1]
	v_pk_fma_f32 v[192:193], v[32:33], v[172:173], v[192:193] op_sel_hi:[1,0,1]
	v_pk_fma_f32 v[180:181], v[22:23], v[174:175], v[180:181] op_sel_hi:[1,0,1]
	v_pk_fma_f32 v[192:193], v[24:25], v[174:175], v[192:193] op_sel_hi:[1,0,1]
	v_mfma_f32_16x16x4_f32 v[106:109], v143, v79, v[106:109]
	v_pk_fma_f32 v[180:181], v[18:19], v[174:175], v[180:181] op_sel:[0,1,0]
	v_pk_fma_f32 v[192:193], v[20:21], v[174:175], v[192:193] op_sel:[0,1,0]
	v_pk_fma_f32 v[180:181], v[14:15], v[232:233], v[180:181] op_sel_hi:[1,0,1]
	v_pk_fma_f32 v[192:193], v[16:17], v[232:233], v[192:193] op_sel_hi:[1,0,1]
	v_mfma_f32_16x16x4_f32 v[102:105], v143, v80, v[102:105]
	v_pk_fma_f32 v[180:181], v[10:11], v[232:233], v[180:181] op_sel:[0,1,0]
	v_pk_fma_f32 v[192:193], v[12:13], v[232:233], v[192:193] op_sel:[0,1,0]
	v_pk_fma_f32 v[180:181], v[6:7], v[234:235], v[180:181] op_sel_hi:[1,0,1]
	v_pk_fma_f32 v[192:193], v[8:9], v[234:235], v[192:193] op_sel_hi:[1,0,1]
	v_mfma_f32_16x16x4_f32 v[98:101], v143, v81, v[98:101]
	v_pk_fma_f32 v[180:181], v[2:3], v[234:235], v[180:181] op_sel:[0,1,0]
	v_pk_fma_f32 v[192:193], v[4:5], v[234:235], v[192:193] op_sel:[0,1,0]
	v_pk_mul_f32 v[180:181], v[146:147], v[180:181]
	v_pk_mul_f32 v[192:193], v[146:147], v[192:193]
	v_pk_fma_f32 v[236:237], v[144:145], v[78:79], v[180:181]
	v_pk_fma_f32 v[238:239], v[144:145], v[80:81], v[192:193]
	global_store_dwordx4 v[150:151], v[236:239], off nt
	v_lshl_add_u64 v[150:151], v[150:151], 0, s[74:75]
	global_load_dwordx4 v[78:81], v[148:149], off nt
	v_lshl_add_u64 v[148:149], v[148:149], 0, s[74:75]
	ds_read_b32 v143, v160 offset:592
	ds_read_b128 v[172:175], v161 offset:4736
	ds_read_b128 v[232:235], v161 offset:4752
	s_waitcnt vmcnt(22)
	s_waitcnt lgkmcnt(3)
	v_cndmask_b32_e64 v141, 0, v141, s[8:9]
	v_pk_mul_f32 v[180:181], v[26:27], v[114:115] op_sel:[0,1]
	v_pk_mul_f32 v[192:193], v[28:29], v[114:115] op_sel:[0,1]
	v_mfma_f32_16x16x4_f32 v[110:113], v141, v70, v[110:113]
	v_pk_fma_f32 v[180:181], v[30:31], v[114:115], v[180:181] op_sel_hi:[1,0,1]
	v_pk_fma_f32 v[192:193], v[32:33], v[114:115], v[192:193] op_sel_hi:[1,0,1]
	v_pk_fma_f32 v[180:181], v[22:23], v[116:117], v[180:181] op_sel_hi:[1,0,1]
	v_pk_fma_f32 v[192:193], v[24:25], v[116:117], v[192:193] op_sel_hi:[1,0,1]
	v_mfma_f32_16x16x4_f32 v[106:109], v141, v71, v[106:109]
	v_pk_fma_f32 v[180:181], v[18:19], v[116:117], v[180:181] op_sel:[0,1,0]
	v_pk_fma_f32 v[192:193], v[20:21], v[116:117], v[192:193] op_sel:[0,1,0]
	v_pk_fma_f32 v[180:181], v[14:15], v[176:177], v[180:181] op_sel_hi:[1,0,1]
	v_pk_fma_f32 v[192:193], v[16:17], v[176:177], v[192:193] op_sel_hi:[1,0,1]
	v_mfma_f32_16x16x4_f32 v[102:105], v141, v72, v[102:105]
	v_pk_fma_f32 v[180:181], v[10:11], v[176:177], v[180:181] op_sel:[0,1,0]
	v_pk_fma_f32 v[192:193], v[12:13], v[176:177], v[192:193] op_sel:[0,1,0]
	v_pk_fma_f32 v[180:181], v[6:7], v[178:179], v[180:181] op_sel_hi:[1,0,1]
	v_pk_fma_f32 v[192:193], v[8:9], v[178:179], v[192:193] op_sel_hi:[1,0,1]
	v_mfma_f32_16x16x4_f32 v[98:101], v141, v73, v[98:101]
	v_pk_fma_f32 v[180:181], v[2:3], v[178:179], v[180:181] op_sel:[0,1,0]
	v_pk_fma_f32 v[192:193], v[4:5], v[178:179], v[192:193] op_sel:[0,1,0]
	v_pk_mul_f32 v[180:181], v[146:147], v[180:181]
	v_pk_mul_f32 v[192:193], v[146:147], v[192:193]
	v_pk_fma_f32 v[236:237], v[144:145], v[70:71], v[180:181]
	v_pk_fma_f32 v[238:239], v[144:145], v[72:73], v[192:193]
	global_store_dwordx4 v[150:151], v[236:239], off nt
	v_lshl_add_u64 v[150:151], v[150:151], 0, s[74:75]
	global_load_dwordx4 v[70:73], v[148:149], off nt
	v_lshl_add_u64 v[148:149], v[148:149], 0, s[74:75]
	ds_read_b32 v141, v160 offset:608
	ds_read_b128 v[114:117], v161 offset:4864
	ds_read_b128 v[176:179], v161 offset:4880
	s_waitcnt vmcnt(22)
; #define RS_LOAD(dst, it0) do { _Pragma("unroll") for (int u = 0; u < 8; ++u) dst[u] = __builtin_nontemporal_load((const f32x4*)(S0 + (size_t)(4 * ((it0) + u)) * DV)); } while (0)
; __device__ __forceinline__ void ret_sample_item(Frame& F, int item) {
;     ...
;     for (int it0 = 0; it0 < 64; it0 += 16) {
;         RS_LOAD(sb, it0 + 8);
;         RS_PROC(sa, it0);
;         { const int itn = it0 + 16 < 64 ? it0 + 16 : it0; RS_LOAD(sa, itn); }
;         RS_PROC(sb, it0 + 8);
;     }
	s_waitcnt lgkmcnt(3)
	v_cndmask_b32_e64 v143, 0, v143, s[8:9]
	v_pk_mul_f32 v[180:181], v[26:27], v[172:173] op_sel:[0,1]
	v_pk_mul_f32 v[192:193], v[28:29], v[172:173] op_sel:[0,1]
	v_mfma_f32_16x16x4_f32 v[110:113], v143, v62, v[110:113]
	v_pk_fma_f32 v[180:181], v[30:31], v[172:173], v[180:181] op_sel_hi:[1,0,1]
	v_pk_fma_f32 v[192:193], v[32:33], v[172:173], v[192:193] op_sel_hi:[1,0,1]
	v_pk_fma_f32 v[180:181], v[22:23], v[174:175], v[180:181] op_sel_hi:[1,0,1]
	v_pk_fma_f32 v[192:193], v[24:25], v[174:175], v[192:193] op_sel_hi:[1,0,1]
	v_mfma_f32_16x16x4_f32 v[106:109], v143, v63, v[106:109]
	v_pk_fma_f32 v[180:181], v[18:19], v[174:175], v[180:181] op_sel:[0,1,0]
	v_pk_fma_f32 v[192:193], v[20:21], v[174:175], v[192:193] op_sel:[0,1,0]
	v_pk_fma_f32 v[180:181], v[14:15], v[232:233], v[180:181] op_sel_hi:[1,0,1]
	v_pk_fma_f32 v[192:193], v[16:17], v[232:233], v[192:193] op_sel_hi:[1,0,1]
	v_mfma_f32_16x16x4_f32 v[102:105], v143, v64, v[102:105]
	v_pk_fma_f32 v[180:181], v[10:11], v[232:233], v[180:181] op_sel:[0,1,0]
	v_pk_fma_f32 v[192:193], v[12:13], v[232:233], v[192:193] op_sel:[0,1,0]
	v_pk_fma_f32 v[180:181], v[6:7], v[234:235], v[180:181] op_sel_hi:[1,0,1]
	v_pk_fma_f32 v[192:193], v[8:9], v[234:235], v[192:193] op_sel_hi:[1,0,1]
	v_mfma_f32_16x16x4_f32 v[98:101], v143, v65, v[98:101]
	v_pk_fma_f32 v[180:181], v[2:3], v[234:235], v[180:181] op_sel:[0,1,0]
	v_pk_fma_f32 v[192:193], v[4:5], v[234:235], v[192:193] op_sel:[0,1,0]
	v_pk_mul_f32 v[180:181], v[146:147], v[180:181]
	v_pk_mul_f32 v[192:193], v[146:147], v[192:193]
	v_pk_fma_f32 v[236:237], v[144:145], v[62:63], v[180:181]
	v_pk_fma_f32 v[238:239], v[144:145], v[64:65], v[192:193]
	global_store_dwordx4 v[150:151], v[236:239], off nt
	v_lshl_add_u64 v[150:151], v[150:151], 0, s[74:75]
	global_load_dwordx4 v[62:65], v[148:149], off nt
	v_lshl_add_u64 v[148:149], v[148:149], 0, s[74:75]
	ds_read_b32 v143, v160 offset:624
	ds_read_b128 v[172:175], v161 offset:4992
	ds_read_b128 v[232:235], v161 offset:5008
	s_waitcnt vmcnt(22)
	s_waitcnt lgkmcnt(3)
	v_cndmask_b32_e64 v141, 0, v141, s[8:9]
	v_pk_mul_f32 v[180:181], v[26:27], v[114:115] op_sel:[0,1]
	v_pk_mul_f32 v[192:193], v[28:29], v[114:115] op_sel:[0,1]
	v_mfma_f32_16x16x4_f32 v[110:113], v141, v54, v[110:113]
	v_pk_fma_f32 v[180:181], v[30:31], v[114:115], v[180:181] op_sel_hi:[1,0,1]
	v_pk_fma_f32 v[192:193], v[32:33], v[114:115], v[192:193] op_sel_hi:[1,0,1]
	v_pk_fma_f32 v[180:181], v[22:23], v[116:117], v[180:181] op_sel_hi:[1,0,1]
	v_pk_fma_f32 v[192:193], v[24:25], v[116:117], v[192:193] op_sel_hi:[1,0,1]
	v_mfma_f32_16x16x4_f32 v[106:109], v141, v55, v[106:109]
	v_pk_fma_f32 v[180:181], v[18:19], v[116:117], v[180:181] op_sel:[0,1,0]
	v_pk_fma_f32 v[192:193], v[20:21], v[116:117], v[192:193] op_sel:[0,1,0]
	v_pk_fma_f32 v[180:181], v[14:15], v[176:177], v[180:181] op_sel_hi:[1,0,1]
	v_pk_fma_f32 v[192:193], v[16:17], v[176:177], v[192:193] op_sel_hi:[1,0,1]
	v_mfma_f32_16x16x4_f32 v[102:105], v141, v56, v[102:105]
	v_pk_fma_f32 v[180:181], v[10:11], v[176:177], v[180:181] op_sel:[0,1,0]
	v_pk_fma_f32 v[192:193], v[12:13], v[176:177], v[192:193] op_sel:[0,1,0]
	v_pk_fma_f32 v[180:181], v[6:7], v[178:179], v[180:181] op_sel_hi:[1,0,1]
	v_pk_fma_f32 v[192:193], v[8:9], v[178:179], v[192:193] op_sel_hi:[1,0,1]
	v_mfma_f32_16x16x4_f32 v[98:101], v141, v57, v[98:101]
	v_pk_fma_f32 v[180:181], v[2:3], v[178:179], v[180:181] op_sel:[0,1,0]
	v_pk_fma_f32 v[192:193], v[4:5], v[178:179], v[192:193] op_sel:[0,1,0]
	v_pk_mul_f32 v[180:181], v[146:147], v[180:181]
	v_pk_mul_f32 v[192:193], v[146:147], v[192:193]
	v_pk_fma_f32 v[236:237], v[144:145], v[54:55], v[180:181]
	v_pk_fma_f32 v[238:239], v[144:145], v[56:57], v[192:193]
	global_store_dwordx4 v[150:151], v[236:239], off nt
	v_lshl_add_u64 v[150:151], v[150:151], 0, s[74:75]
	global_load_dwordx4 v[54:57], v[148:149], off nt
	v_lshl_add_u64 v[148:149], v[148:149], 0, s[74:75]
	ds_read_b32 v141, v160 offset:640
	ds_read_b128 v[114:117], v161 offset:5120
	ds_read_b128 v[176:179], v161 offset:5136
	s_waitcnt vmcnt(22)
	s_waitcnt lgkmcnt(3)
	v_cndmask_b32_e64 v143, 0, v143, s[8:9]
	v_pk_mul_f32 v[180:181], v[26:27], v[172:173] op_sel:[0,1]
	v_pk_mul_f32 v[192:193], v[28:29], v[172:173] op_sel:[0,1]
	v_mfma_f32_16x16x4_f32 v[110:113], v143, v50, v[110:113]
	v_pk_fma_f32 v[180:181], v[30:31], v[172:173], v[180:181] op_sel_hi:[1,0,1]
	v_pk_fma_f32 v[192:193], v[32:33], v[172:173], v[192:193] op_sel_hi:[1,0,1]
	v_pk_fma_f32 v[180:181], v[22:23], v[174:175], v[180:181] op_sel_hi:[1,0,1]
	v_pk_fma_f32 v[192:193], v[24:25], v[174:175], v[192:193] op_sel_hi:[1,0,1]
	v_mfma_f32_16x16x4_f32 v[106:109], v143, v51, v[106:109]
	v_pk_fma_f32 v[180:181], v[18:19], v[174:175], v[180:181] op_sel:[0,1,0]
	v_pk_fma_f32 v[192:193], v[20:21], v[174:175], v[192:193] op_sel:[0,1,0]
	v_pk_fma_f32 v[180:181], v[14:15], v[232:233], v[180:181] op_sel_hi:[1,0,1]
	v_pk_fma_f32 v[192:193], v[16:17], v[232:233], v[192:193] op_sel_hi:[1,0,1]
	v_mfma_f32_16x16x4_f32 v[102:105], v143, v52, v[102:105]
	v_pk_fma_f32 v[180:181], v[10:11], v[232:233], v[180:181] op_sel:[0,1,0]
	v_pk_fma_f32 v[192:193], v[12:13], v[232:233], v[192:193] op_sel:[0,1,0]
	v_pk_fma_f32 v[180:181], v[6:7], v[234:235], v[180:181] op_sel_hi:[1,0,1]
	v_pk_fma_f32 v[192:193], v[8:9], v[234:235], v[192:193] op_sel_hi:[1,0,1]
	v_mfma_f32_16x16x4_f32 v[98:101], v143, v53, v[98:101]
	v_pk_fma_f32 v[180:181], v[2:3], v[234:235], v[180:181] op_sel:[0,1,0]
	v_pk_fma_f32 v[192:193], v[4:5], v[234:235], v[192:193] op_sel:[0,1,0]
	v_pk_mul_f32 v[180:181], v[146:147], v[180:181]
	v_pk_mul_f32 v[192:193], v[146:147], v[192:193]
	v_pk_fma_f32 v[236:237], v[144:145], v[50:51], v[180:181]
	v_pk_fma_f32 v[238:239], v[144:145], v[52:53], v[192:193]
	global_store_dwordx4 v[150:151], v[236:239], off nt
	v_lshl_add_u64 v[150:151], v[150:151], 0, s[74:75]
	global_load_dwordx4 v[50:53], v[148:149], off nt
	v_lshl_add_u64 v[148:149], v[148:149], 0, s[74:75]
	ds_read_b32 v143, v160 offset:656
	ds_read_b128 v[172:175], v161 offset:5248
	ds_read_b128 v[232:235], v161 offset:5264
	s_waitcnt vmcnt(22)
; #define RS_LOAD(dst, it0) do { _Pragma("unroll") for (int u = 0; u < 8; ++u) dst[u] = __builtin_nontemporal_load((const f32x4*)(S0 + (size_t)(4 * ((it0) + u)) * DV)); } while (0)
; __device__ __forceinline__ void ret_sample_item(Frame& F, int item) {
;     ...
;     for (int it0 = 0; it0 < 64; it0 += 16) {
;         RS_LOAD(sb, it0 + 8);
;         RS_PROC(sa, it0);
;         { const int itn = it0 + 16 < 64 ? it0 + 16 : it0; RS_LOAD(sa, itn); }
;         RS_PROC(sb, it0 + 8);
;     }
	s_waitcnt lgkmcnt(3)
	v_cndmask_b32_e64 v141, 0, v141, s[8:9]
	v_pk_mul_f32 v[180:181], v[26:27], v[114:115] op_sel:[0,1]
	v_pk_mul_f32 v[192:193], v[28:29], v[114:115] op_sel:[0,1]
	v_mfma_f32_16x16x4_f32 v[110:113], v141, v46, v[110:113]
	v_pk_fma_f32 v[180:181], v[30:31], v[114:115], v[180:181] op_sel_hi:[1,0,1]
	v_pk_fma_f32 v[192:193], v[32:33], v[114:115], v[192:193] op_sel_hi:[1,0,1]
	v_pk_fma_f32 v[180:181], v[22:23], v[116:117], v[180:181] op_sel_hi:[1,0,1]
	v_pk_fma_f32 v[192:193], v[24:25], v[116:117], v[192:193] op_sel_hi:[1,0,1]
	v_mfma_f32_16x16x4_f32 v[106:109], v141, v47, v[106:109]
	v_pk_fma_f32 v[180:181], v[18:19], v[116:117], v[180:181] op_sel:[0,1,0]
	v_pk_fma_f32 v[192:193], v[20:21], v[116:117], v[192:193] op_sel:[0,1,0]
	v_pk_fma_f32 v[180:181], v[14:15], v[176:177], v[180:181] op_sel_hi:[1,0,1]
	v_pk_fma_f32 v[192:193], v[16:17], v[176:177], v[192:193] op_sel_hi:[1,0,1]
	v_mfma_f32_16x16x4_f32 v[102:105], v141, v48, v[102:105]
	v_pk_fma_f32 v[180:181], v[10:11], v[176:177], v[180:181] op_sel:[0,1,0]
	v_pk_fma_f32 v[192:193], v[12:13], v[176:177], v[192:193] op_sel:[0,1,0]
	v_pk_fma_f32 v[180:181], v[6:7], v[178:179], v[180:181] op_sel_hi:[1,0,1]
	v_pk_fma_f32 v[192:193], v[8:9], v[178:179], v[192:193] op_sel_hi:[1,0,1]
	v_mfma_f32_16x16x4_f32 v[98:101], v141, v49, v[98:101]
	v_pk_fma_f32 v[180:181], v[2:3], v[178:179], v[180:181] op_sel:[0,1,0]
	v_pk_fma_f32 v[192:193], v[4:5], v[178:179], v[192:193] op_sel:[0,1,0]
	v_pk_mul_f32 v[180:181], v[146:147], v[180:181]
	v_pk_mul_f32 v[192:193], v[146:147], v[192:193]
	v_pk_fma_f32 v[236:237], v[144:145], v[46:47], v[180:181]
	v_pk_fma_f32 v[238:239], v[144:145], v[48:49], v[192:193]
	global_store_dwordx4 v[150:151], v[236:239], off nt
	v_lshl_add_u64 v[150:151], v[150:151], 0, s[74:75]
	global_load_dwordx4 v[46:49], v[148:149], off nt
	v_lshl_add_u64 v[148:149], v[148:149], 0, s[74:75]
	ds_read_b32 v141, v160 offset:672
	ds_read_b128 v[114:117], v161 offset:5376
	ds_read_b128 v[176:179], v161 offset:5392
	s_waitcnt vmcnt(22)
	s_waitcnt lgkmcnt(3)
	v_cndmask_b32_e64 v143, 0, v143, s[8:9]
	v_pk_mul_f32 v[180:181], v[26:27], v[172:173] op_sel:[0,1]
	v_pk_mul_f32 v[192:193], v[28:29], v[172:173] op_sel:[0,1]
	v_mfma_f32_16x16x4_f32 v[110:113], v143, v42, v[110:113]
	v_pk_fma_f32 v[180:181], v[30:31], v[172:173], v[180:181] op_sel_hi:[1,0,1]
	v_pk_fma_f32 v[192:193], v[32:33], v[172:173], v[192:193] op_sel_hi:[1,0,1]
	v_pk_fma_f32 v[180:181], v[22:23], v[174:175], v[180:181] op_sel_hi:[1,0,1]
	v_pk_fma_f32 v[192:193], v[24:25], v[174:175], v[192:193] op_sel_hi:[1,0,1]
	v_mfma_f32_16x16x4_f32 v[106:109], v143, v43, v[106:109]
	v_pk_fma_f32 v[180:181], v[18:19], v[174:175], v[180:181] op_sel:[0,1,0]
	v_pk_fma_f32 v[192:193], v[20:21], v[174:175], v[192:193] op_sel:[0,1,0]
	v_pk_fma_f32 v[180:181], v[14:15], v[232:233], v[180:181] op_sel_hi:[1,0,1]
	v_pk_fma_f32 v[192:193], v[16:17], v[232:233], v[192:193] op_sel_hi:[1,0,1]
	v_mfma_f32_16x16x4_f32 v[102:105], v143, v44, v[102:105]
	v_pk_fma_f32 v[180:181], v[10:11], v[232:233], v[180:181] op_sel:[0,1,0]
	v_pk_fma_f32 v[192:193], v[12:13], v[232:233], v[192:193] op_sel:[0,1,0]
	v_pk_fma_f32 v[180:181], v[6:7], v[234:235], v[180:181] op_sel_hi:[1,0,1]
	v_pk_fma_f32 v[192:193], v[8:9], v[234:235], v[192:193] op_sel_hi:[1,0,1]
	v_mfma_f32_16x16x4_f32 v[98:101], v143, v45, v[98:101]
	v_pk_fma_f32 v[180:181], v[2:3], v[234:235], v[180:181] op_sel:[0,1,0]
	v_pk_fma_f32 v[192:193], v[4:5], v[234:235], v[192:193] op_sel:[0,1,0]
	v_pk_mul_f32 v[180:181], v[146:147], v[180:181]
	v_pk_mul_f32 v[192:193], v[146:147], v[192:193]
	v_pk_fma_f32 v[236:237], v[144:145], v[42:43], v[180:181]
	v_pk_fma_f32 v[238:239], v[144:145], v[44:45], v[192:193]
	global_store_dwordx4 v[150:151], v[236:239], off nt
	v_lshl_add_u64 v[150:151], v[150:151], 0, s[74:75]
	global_load_dwordx4 v[42:45], v[148:149], off nt
	v_lshl_add_u64 v[148:149], v[148:149], 0, s[74:75]
	ds_read_b32 v143, v160 offset:688
	ds_read_b128 v[172:175], v161 offset:5504
	ds_read_b128 v[232:235], v161 offset:5520
	s_waitcnt vmcnt(22)
	s_waitcnt lgkmcnt(3)
	v_cndmask_b32_e64 v141, 0, v141, s[8:9]
	v_pk_mul_f32 v[180:181], v[26:27], v[114:115] op_sel:[0,1]
	v_pk_mul_f32 v[192:193], v[28:29], v[114:115] op_sel:[0,1]
	v_mfma_f32_16x16x4_f32 v[110:113], v141, v38, v[110:113]
	v_pk_fma_f32 v[180:181], v[30:31], v[114:115], v[180:181] op_sel_hi:[1,0,1]
	v_pk_fma_f32 v[192:193], v[32:33], v[114:115], v[192:193] op_sel_hi:[1,0,1]
	v_pk_fma_f32 v[180:181], v[22:23], v[116:117], v[180:181] op_sel_hi:[1,0,1]
	v_pk_fma_f32 v[192:193], v[24:25], v[116:117], v[192:193] op_sel_hi:[1,0,1]
	v_mfma_f32_16x16x4_f32 v[106:109], v141, v39, v[106:109]
	v_pk_fma_f32 v[180:181], v[18:19], v[116:117], v[180:181] op_sel:[0,1,0]
	v_pk_fma_f32 v[192:193], v[20:21], v[116:117], v[192:193] op_sel:[0,1,0]
	v_pk_fma_f32 v[180:181], v[14:15], v[176:177], v[180:181] op_sel_hi:[1,0,1]
	v_pk_fma_f32 v[192:193], v[16:17], v[176:177], v[192:193] op_sel_hi:[1,0,1]
	v_mfma_f32_16x16x4_f32 v[102:105], v141, v40, v[102:105]
	v_pk_fma_f32 v[180:181], v[10:11], v[176:177], v[180:181] op_sel:[0,1,0]
	v_pk_fma_f32 v[192:193], v[12:13], v[176:177], v[192:193] op_sel:[0,1,0]
	v_pk_fma_f32 v[180:181], v[6:7], v[178:179], v[180:181] op_sel_hi:[1,0,1]
	v_pk_fma_f32 v[192:193], v[8:9], v[178:179], v[192:193] op_sel_hi:[1,0,1]
	v_mfma_f32_16x16x4_f32 v[98:101], v141, v41, v[98:101]
	v_pk_fma_f32 v[180:181], v[2:3], v[178:179], v[180:181] op_sel:[0,1,0]
	v_pk_fma_f32 v[192:193], v[4:5], v[178:179], v[192:193] op_sel:[0,1,0]
	v_pk_mul_f32 v[180:181], v[146:147], v[180:181]
	v_pk_mul_f32 v[192:193], v[146:147], v[192:193]
	v_pk_fma_f32 v[236:237], v[144:145], v[38:39], v[180:181]
	v_pk_fma_f32 v[238:239], v[144:145], v[40:41], v[192:193]
	global_store_dwordx4 v[150:151], v[236:239], off nt
	v_lshl_add_u64 v[150:151], v[150:151], 0, s[74:75]
	global_load_dwordx4 v[38:41], v[148:149], off nt
	v_lshl_add_u64 v[148:149], v[148:149], 0, s[74:75]
	ds_read_b32 v141, v160 offset:704
	ds_read_b128 v[114:117], v161 offset:5632
	ds_read_b128 v[176:179], v161 offset:5648
	s_waitcnt vmcnt(22)
; #define RS_LOAD(dst, it0) do { _Pragma("unroll") for (int u = 0; u < 8; ++u) dst[u] = __builtin_nontemporal_load((const f32x4*)(S0 + (size_t)(4 * ((it0) + u)) * DV)); } while (0)
; __device__ __forceinline__ void ret_sample_item(Frame& F, int item) {
;     ...
;     for (int it0 = 0; it0 < 64; it0 += 16) {
;         RS_LOAD(sb, it0 + 8);
;         RS_PROC(sa, it0);
;         { const int itn = it0 + 16 < 64 ? it0 + 16 : it0; RS_LOAD(sa, itn); }
;         RS_PROC(sb, it0 + 8);
;     }
	s_waitcnt lgkmcnt(3)
	v_cndmask_b32_e64 v143, 0, v143, s[8:9]
	v_pk_mul_f32 v[180:181], v[26:27], v[172:173] op_sel:[0,1]
	v_pk_mul_f32 v[192:193], v[28:29], v[172:173] op_sel:[0,1]
	v_mfma_f32_16x16x4_f32 v[110:113], v143, v34, v[110:113]
	v_pk_fma_f32 v[180:181], v[30:31], v[172:173], v[180:181] op_sel_hi:[1,0,1]
	v_pk_fma_f32 v[192:193], v[32:33], v[172:173], v[192:193] op_sel_hi:[1,0,1]
	v_pk_fma_f32 v[180:181], v[22:23], v[174:175], v[180:181] op_sel_hi:[1,0,1]
	v_pk_fma_f32 v[192:193], v[24:25], v[174:175], v[192:193] op_sel_hi:[1,0,1]
	v_mfma_f32_16x16x4_f32 v[106:109], v143, v35, v[106:109]
	v_pk_fma_f32 v[180:181], v[18:19], v[174:175], v[180:181] op_sel:[0,1,0]
	v_pk_fma_f32 v[192:193], v[20:21], v[174:175], v[192:193] op_sel:[0,1,0]
	v_pk_fma_f32 v[180:181], v[14:15], v[232:233], v[180:181] op_sel_hi:[1,0,1]
	v_pk_fma_f32 v[192:193], v[16:17], v[232:233], v[192:193] op_sel_hi:[1,0,1]
	v_mfma_f32_16x16x4_f32 v[102:105], v143, v36, v[102:105]
	v_pk_fma_f32 v[180:181], v[10:11], v[232:233], v[180:181] op_sel:[0,1,0]
	v_pk_fma_f32 v[192:193], v[12:13], v[232:233], v[192:193] op_sel:[0,1,0]
	v_pk_fma_f32 v[180:181], v[6:7], v[234:235], v[180:181] op_sel_hi:[1,0,1]
	v_pk_fma_f32 v[192:193], v[8:9], v[234:235], v[192:193] op_sel_hi:[1,0,1]
	v_mfma_f32_16x16x4_f32 v[98:101], v143, v37, v[98:101]
	v_pk_fma_f32 v[180:181], v[2:3], v[234:235], v[180:181] op_sel:[0,1,0]
	v_pk_fma_f32 v[192:193], v[4:5], v[234:235], v[192:193] op_sel:[0,1,0]
	v_pk_mul_f32 v[180:181], v[146:147], v[180:181]
	v_pk_mul_f32 v[192:193], v[146:147], v[192:193]
	v_pk_fma_f32 v[236:237], v[144:145], v[34:35], v[180:181]
	v_pk_fma_f32 v[238:239], v[144:145], v[36:37], v[192:193]
	global_store_dwordx4 v[150:151], v[236:239], off nt
	v_lshl_add_u64 v[150:151], v[150:151], 0, s[74:75]
	global_load_dwordx4 v[34:37], v[148:149], off nt
	v_lshl_add_u64 v[148:149], v[148:149], 0, s[74:75]
	ds_read_b32 v143, v160 offset:720
	ds_read_b128 v[172:175], v161 offset:5760
	ds_read_b128 v[232:235], v161 offset:5776
	s_waitcnt vmcnt(22)
	s_waitcnt lgkmcnt(3)
	v_cndmask_b32_e64 v141, 0, v141, s[8:9]
	v_pk_mul_f32 v[180:181], v[26:27], v[114:115] op_sel:[0,1]
	v_pk_mul_f32 v[192:193], v[28:29], v[114:115] op_sel:[0,1]
	v_mfma_f32_16x16x4_f32 v[110:113], v141, v58, v[110:113]
	v_pk_fma_f32 v[180:181], v[30:31], v[114:115], v[180:181] op_sel_hi:[1,0,1]
	v_pk_fma_f32 v[192:193], v[32:33], v[114:115], v[192:193] op_sel_hi:[1,0,1]
	v_pk_fma_f32 v[180:181], v[22:23], v[116:117], v[180:181] op_sel_hi:[1,0,1]
	v_pk_fma_f32 v[192:193], v[24:25], v[116:117], v[192:193] op_sel_hi:[1,0,1]
	v_mfma_f32_16x16x4_f32 v[106:109], v141, v59, v[106:109]
	v_pk_fma_f32 v[180:181], v[18:19], v[116:117], v[180:181] op_sel:[0,1,0]
	v_pk_fma_f32 v[192:193], v[20:21], v[116:117], v[192:193] op_sel:[0,1,0]
	v_pk_fma_f32 v[180:181], v[14:15], v[176:177], v[180:181] op_sel_hi:[1,0,1]
	v_pk_fma_f32 v[192:193], v[16:17], v[176:177], v[192:193] op_sel_hi:[1,0,1]
	v_mfma_f32_16x16x4_f32 v[102:105], v141, v60, v[102:105]
	v_pk_fma_f32 v[180:181], v[10:11], v[176:177], v[180:181] op_sel:[0,1,0]
	v_pk_fma_f32 v[192:193], v[12:13], v[176:177], v[192:193] op_sel:[0,1,0]
	v_pk_fma_f32 v[180:181], v[6:7], v[178:179], v[180:181] op_sel_hi:[1,0,1]
	v_pk_fma_f32 v[192:193], v[8:9], v[178:179], v[192:193] op_sel_hi:[1,0,1]
	v_mfma_f32_16x16x4_f32 v[98:101], v141, v61, v[98:101]
	v_pk_fma_f32 v[180:181], v[2:3], v[178:179], v[180:181] op_sel:[0,1,0]
	v_pk_fma_f32 v[192:193], v[4:5], v[178:179], v[192:193] op_sel:[0,1,0]
	v_pk_mul_f32 v[180:181], v[146:147], v[180:181]
	v_pk_mul_f32 v[192:193], v[146:147], v[192:193]
	v_pk_fma_f32 v[236:237], v[144:145], v[58:59], v[180:181]
	v_pk_fma_f32 v[238:239], v[144:145], v[60:61], v[192:193]
	global_store_dwordx4 v[150:151], v[236:239], off nt
	v_lshl_add_u64 v[150:151], v[150:151], 0, s[74:75]
	global_load_dwordx4 v[58:61], v[148:149], off nt
	v_lshl_add_u64 v[148:149], v[148:149], 0, s[74:75]
	ds_read_b32 v141, v160 offset:736
	ds_read_b128 v[114:117], v161 offset:5888
	ds_read_b128 v[176:179], v161 offset:5904
	s_waitcnt vmcnt(22)
	s_waitcnt lgkmcnt(3)
	v_cndmask_b32_e64 v143, 0, v143, s[8:9]
	v_pk_mul_f32 v[180:181], v[26:27], v[172:173] op_sel:[0,1]
	v_pk_mul_f32 v[192:193], v[28:29], v[172:173] op_sel:[0,1]
	v_mfma_f32_16x16x4_f32 v[110:113], v143, v66, v[110:113]
	v_pk_fma_f32 v[180:181], v[30:31], v[172:173], v[180:181] op_sel_hi:[1,0,1]
	v_pk_fma_f32 v[192:193], v[32:33], v[172:173], v[192:193] op_sel_hi:[1,0,1]
	v_pk_fma_f32 v[180:181], v[22:23], v[174:175], v[180:181] op_sel_hi:[1,0,1]
	v_pk_fma_f32 v[192:193], v[24:25], v[174:175], v[192:193] op_sel_hi:[1,0,1]
	v_mfma_f32_16x16x4_f32 v[106:109], v143, v67, v[106:109]
	v_pk_fma_f32 v[180:181], v[18:19], v[174:175], v[180:181] op_sel:[0,1,0]
	v_pk_fma_f32 v[192:193], v[20:21], v[174:175], v[192:193] op_sel:[0,1,0]
	v_pk_fma_f32 v[180:181], v[14:15], v[232:233], v[180:181] op_sel_hi:[1,0,1]
	v_pk_fma_f32 v[192:193], v[16:17], v[232:233], v[192:193] op_sel_hi:[1,0,1]
	v_mfma_f32_16x16x4_f32 v[102:105], v143, v68, v[102:105]
	v_pk_fma_f32 v[180:181], v[10:11], v[232:233], v[180:181] op_sel:[0,1,0]
	v_pk_fma_f32 v[192:193], v[12:13], v[232:233], v[192:193] op_sel:[0,1,0]
	v_pk_fma_f32 v[180:181], v[6:7], v[234:235], v[180:181] op_sel_hi:[1,0,1]
	v_pk_fma_f32 v[192:193], v[8:9], v[234:235], v[192:193] op_sel_hi:[1,0,1]
	v_mfma_f32_16x16x4_f32 v[98:101], v143, v69, v[98:101]
	v_pk_fma_f32 v[180:181], v[2:3], v[234:235], v[180:181] op_sel:[0,1,0]
	v_pk_fma_f32 v[192:193], v[4:5], v[234:235], v[192:193] op_sel:[0,1,0]
	v_pk_mul_f32 v[180:181], v[146:147], v[180:181]
	v_pk_mul_f32 v[192:193], v[146:147], v[192:193]
	v_pk_fma_f32 v[236:237], v[144:145], v[66:67], v[180:181]
	v_pk_fma_f32 v[238:239], v[144:145], v[68:69], v[192:193]
	global_store_dwordx4 v[150:151], v[236:239], off nt
	v_lshl_add_u64 v[150:151], v[150:151], 0, s[74:75]
	global_load_dwordx4 v[66:69], v[148:149], off nt
	v_lshl_add_u64 v[148:149], v[148:149], 0, s[74:75]
	ds_read_b32 v143, v160 offset:752
	ds_read_b128 v[172:175], v161 offset:6016
	ds_read_b128 v[232:235], v161 offset:6032
	s_waitcnt vmcnt(22)
; #define RS_LOAD(dst, it0) do { _Pragma("unroll") for (int u = 0; u < 8; ++u) dst[u] = __builtin_nontemporal_load((const f32x4*)(S0 + (size_t)(4 * ((it0) + u)) * DV)); } while (0)
; __device__ __forceinline__ void ret_sample_item(Frame& F, int item) {
;     ...
;     for (int it0 = 0; it0 < 64; it0 += 16) {
;         RS_LOAD(sb, it0 + 8);
;         RS_PROC(sa, it0);
;         { const int itn = it0 + 16 < 64 ? it0 + 16 : it0; RS_LOAD(sa, itn); }
;         RS_PROC(sb, it0 + 8);
;     }
	s_waitcnt lgkmcnt(3)
	v_cndmask_b32_e64 v141, 0, v141, s[8:9]
	v_pk_mul_f32 v[180:181], v[26:27], v[114:115] op_sel:[0,1]
	v_pk_mul_f32 v[192:193], v[28:29], v[114:115] op_sel:[0,1]
	v_mfma_f32_16x16x4_f32 v[110:113], v141, v74, v[110:113]
	v_pk_fma_f32 v[180:181], v[30:31], v[114:115], v[180:181] op_sel_hi:[1,0,1]
	v_pk_fma_f32 v[192:193], v[32:33], v[114:115], v[192:193] op_sel_hi:[1,0,1]
	v_pk_fma_f32 v[180:181], v[22:23], v[116:117], v[180:181] op_sel_hi:[1,0,1]
	v_pk_fma_f32 v[192:193], v[24:25], v[116:117], v[192:193] op_sel_hi:[1,0,1]
	v_mfma_f32_16x16x4_f32 v[106:109], v141, v75, v[106:109]
	v_pk_fma_f32 v[180:181], v[18:19], v[116:117], v[180:181] op_sel:[0,1,0]
	v_pk_fma_f32 v[192:193], v[20:21], v[116:117], v[192:193] op_sel:[0,1,0]
	v_pk_fma_f32 v[180:181], v[14:15], v[176:177], v[180:181] op_sel_hi:[1,0,1]
	v_pk_fma_f32 v[192:193], v[16:17], v[176:177], v[192:193] op_sel_hi:[1,0,1]
	v_mfma_f32_16x16x4_f32 v[102:105], v141, v76, v[102:105]
	v_pk_fma_f32 v[180:181], v[10:11], v[176:177], v[180:181] op_sel:[0,1,0]
	v_pk_fma_f32 v[192:193], v[12:13], v[176:177], v[192:193] op_sel:[0,1,0]
	v_pk_fma_f32 v[180:181], v[6:7], v[178:179], v[180:181] op_sel_hi:[1,0,1]
	v_pk_fma_f32 v[192:193], v[8:9], v[178:179], v[192:193] op_sel_hi:[1,0,1]
	v_mfma_f32_16x16x4_f32 v[98:101], v141, v77, v[98:101]
	v_pk_fma_f32 v[180:181], v[2:3], v[178:179], v[180:181] op_sel:[0,1,0]
	v_pk_fma_f32 v[192:193], v[4:5], v[178:179], v[192:193] op_sel:[0,1,0]
	v_pk_mul_f32 v[180:181], v[146:147], v[180:181]
	v_pk_mul_f32 v[192:193], v[146:147], v[192:193]
	v_pk_fma_f32 v[236:237], v[144:145], v[74:75], v[180:181]
	v_pk_fma_f32 v[238:239], v[144:145], v[76:77], v[192:193]
	global_store_dwordx4 v[150:151], v[236:239], off nt
	v_lshl_add_u64 v[150:151], v[150:151], 0, s[74:75]
	global_load_dwordx4 v[74:77], v[148:149], off nt
	v_lshl_add_u64 v[148:149], v[148:149], 0, s[74:75]
	ds_read_b32 v141, v160 offset:768
	ds_read_b128 v[114:117], v161 offset:6144
	ds_read_b128 v[176:179], v161 offset:6160
	s_waitcnt vmcnt(22)
	s_waitcnt lgkmcnt(3)
	v_cndmask_b32_e64 v143, 0, v143, s[8:9]
	v_pk_mul_f32 v[180:181], v[26:27], v[172:173] op_sel:[0,1]
	v_pk_mul_f32 v[192:193], v[28:29], v[172:173] op_sel:[0,1]
	v_mfma_f32_16x16x4_f32 v[110:113], v143, v78, v[110:113]
	v_pk_fma_f32 v[180:181], v[30:31], v[172:173], v[180:181] op_sel_hi:[1,0,1]
	v_pk_fma_f32 v[192:193], v[32:33], v[172:173], v[192:193] op_sel_hi:[1,0,1]
	v_pk_fma_f32 v[180:181], v[22:23], v[174:175], v[180:181] op_sel_hi:[1,0,1]
	v_pk_fma_f32 v[192:193], v[24:25], v[174:175], v[192:193] op_sel_hi:[1,0,1]
	v_mfma_f32_16x16x4_f32 v[106:109], v143, v79, v[106:109]
	v_pk_fma_f32 v[180:181], v[18:19], v[174:175], v[180:181] op_sel:[0,1,0]
	v_pk_fma_f32 v[192:193], v[20:21], v[174:175], v[192:193] op_sel:[0,1,0]
	v_pk_fma_f32 v[180:181], v[14:15], v[232:233], v[180:181] op_sel_hi:[1,0,1]
	v_pk_fma_f32 v[192:193], v[16:17], v[232:233], v[192:193] op_sel_hi:[1,0,1]
	v_mfma_f32_16x16x4_f32 v[102:105], v143, v80, v[102:105]
	v_pk_fma_f32 v[180:181], v[10:11], v[232:233], v[180:181] op_sel:[0,1,0]
	v_pk_fma_f32 v[192:193], v[12:13], v[232:233], v[192:193] op_sel:[0,1,0]
	v_pk_fma_f32 v[180:181], v[6:7], v[234:235], v[180:181] op_sel_hi:[1,0,1]
	v_pk_fma_f32 v[192:193], v[8:9], v[234:235], v[192:193] op_sel_hi:[1,0,1]
	v_mfma_f32_16x16x4_f32 v[98:101], v143, v81, v[98:101]
	v_pk_fma_f32 v[180:181], v[2:3], v[234:235], v[180:181] op_sel:[0,1,0]
	v_pk_fma_f32 v[192:193], v[4:5], v[234:235], v[192:193] op_sel:[0,1,0]
	v_pk_mul_f32 v[180:181], v[146:147], v[180:181]
	v_pk_mul_f32 v[192:193], v[146:147], v[192:193]
	v_pk_fma_f32 v[236:237], v[144:145], v[78:79], v[180:181]
	v_pk_fma_f32 v[238:239], v[144:145], v[80:81], v[192:193]
	global_store_dwordx4 v[150:151], v[236:239], off nt
	v_lshl_add_u64 v[150:151], v[150:151], 0, s[74:75]
	global_load_dwordx4 v[78:81], v[148:149], off nt
	v_lshl_add_u64 v[148:149], v[148:149], 0, s[74:75]
	ds_read_b32 v143, v160 offset:784
	ds_read_b128 v[172:175], v161 offset:6272
	ds_read_b128 v[232:235], v161 offset:6288
	s_waitcnt vmcnt(22)
	s_waitcnt lgkmcnt(3)
	v_cndmask_b32_e64 v141, 0, v141, s[8:9]
	v_pk_mul_f32 v[180:181], v[26:27], v[114:115] op_sel:[0,1]
	v_pk_mul_f32 v[192:193], v[28:29], v[114:115] op_sel:[0,1]
	v_mfma_f32_16x16x4_f32 v[110:113], v141, v70, v[110:113]
	v_pk_fma_f32 v[180:181], v[30:31], v[114:115], v[180:181] op_sel_hi:[1,0,1]
	v_pk_fma_f32 v[192:193], v[32:33], v[114:115], v[192:193] op_sel_hi:[1,0,1]
	v_pk_fma_f32 v[180:181], v[22:23], v[116:117], v[180:181] op_sel_hi:[1,0,1]
	v_pk_fma_f32 v[192:193], v[24:25], v[116:117], v[192:193] op_sel_hi:[1,0,1]
	v_mfma_f32_16x16x4_f32 v[106:109], v141, v71, v[106:109]
	v_pk_fma_f32 v[180:181], v[18:19], v[116:117], v[180:181] op_sel:[0,1,0]
	v_pk_fma_f32 v[192:193], v[20:21], v[116:117], v[192:193] op_sel:[0,1,0]
	v_pk_fma_f32 v[180:181], v[14:15], v[176:177], v[180:181] op_sel_hi:[1,0,1]
	v_pk_fma_f32 v[192:193], v[16:17], v[176:177], v[192:193] op_sel_hi:[1,0,1]
	v_mfma_f32_16x16x4_f32 v[102:105], v141, v72, v[102:105]
	v_pk_fma_f32 v[180:181], v[10:11], v[176:177], v[180:181] op_sel:[0,1,0]
	v_pk_fma_f32 v[192:193], v[12:13], v[176:177], v[192:193] op_sel:[0,1,0]
	v_pk_fma_f32 v[180:181], v[6:7], v[178:179], v[180:181] op_sel_hi:[1,0,1]
	v_pk_fma_f32 v[192:193], v[8:9], v[178:179], v[192:193] op_sel_hi:[1,0,1]
	v_mfma_f32_16x16x4_f32 v[98:101], v141, v73, v[98:101]
	v_pk_fma_f32 v[180:181], v[2:3], v[178:179], v[180:181] op_sel:[0,1,0]
	v_pk_fma_f32 v[192:193], v[4:5], v[178:179], v[192:193] op_sel:[0,1,0]
	v_pk_mul_f32 v[180:181], v[146:147], v[180:181]
	v_pk_mul_f32 v[192:193], v[146:147], v[192:193]
	v_pk_fma_f32 v[236:237], v[144:145], v[70:71], v[180:181]
	v_pk_fma_f32 v[238:239], v[144:145], v[72:73], v[192:193]
	global_store_dwordx4 v[150:151], v[236:239], off nt
	v_lshl_add_u64 v[150:151], v[150:151], 0, s[74:75]
	global_load_dwordx4 v[70:73], v[148:149], off nt
	v_lshl_add_u64 v[148:149], v[148:149], 0, s[74:75]
	ds_read_b32 v141, v160 offset:800
	ds_read_b128 v[114:117], v161 offset:6400
	ds_read_b128 v[176:179], v161 offset:6416
	s_waitcnt vmcnt(22)
; #define RS_LOAD(dst, it0) do { _Pragma("unroll") for (int u = 0; u < 8; ++u) dst[u] = __builtin_nontemporal_load((const f32x4*)(S0 + (size_t)(4 * ((it0) + u)) * DV)); } while (0)
; __device__ __forceinline__ void ret_sample_item(Frame& F, int item) {
;     ...
;     for (int it0 = 0; it0 < 64; it0 += 16) {
;         RS_LOAD(sb, it0 + 8);
;         RS_PROC(sa, it0);
;         { const int itn = it0 + 16 < 64 ? it0 + 16 : it0; RS_LOAD(sa, itn); }
;         RS_PROC(sb, it0 + 8);
;     }
	s_waitcnt lgkmcnt(3)
	v_cndmask_b32_e64 v143, 0, v143, s[8:9]
	v_pk_mul_f32 v[180:181], v[26:27], v[172:173] op_sel:[0,1]
	v_pk_mul_f32 v[192:193], v[28:29], v[172:173] op_sel:[0,1]
	v_mfma_f32_16x16x4_f32 v[110:113], v143, v62, v[110:113]
	v_pk_fma_f32 v[180:181], v[30:31], v[172:173], v[180:181] op_sel_hi:[1,0,1]
	v_pk_fma_f32 v[192:193], v[32:33], v[172:173], v[192:193] op_sel_hi:[1,0,1]
	v_pk_fma_f32 v[180:181], v[22:23], v[174:175], v[180:181] op_sel_hi:[1,0,1]
	v_pk_fma_f32 v[192:193], v[24:25], v[174:175], v[192:193] op_sel_hi:[1,0,1]
	v_mfma_f32_16x16x4_f32 v[106:109], v143, v63, v[106:109]
	v_pk_fma_f32 v[180:181], v[18:19], v[174:175], v[180:181] op_sel:[0,1,0]
	v_pk_fma_f32 v[192:193], v[20:21], v[174:175], v[192:193] op_sel:[0,1,0]
	v_pk_fma_f32 v[180:181], v[14:15], v[232:233], v[180:181] op_sel_hi:[1,0,1]
	v_pk_fma_f32 v[192:193], v[16:17], v[232:233], v[192:193] op_sel_hi:[1,0,1]
	v_mfma_f32_16x16x4_f32 v[102:105], v143, v64, v[102:105]
	v_pk_fma_f32 v[180:181], v[10:11], v[232:233], v[180:181] op_sel:[0,1,0]
	v_pk_fma_f32 v[192:193], v[12:13], v[232:233], v[192:193] op_sel:[0,1,0]
	v_pk_fma_f32 v[180:181], v[6:7], v[234:235], v[180:181] op_sel_hi:[1,0,1]
	v_pk_fma_f32 v[192:193], v[8:9], v[234:235], v[192:193] op_sel_hi:[1,0,1]
	v_mfma_f32_16x16x4_f32 v[98:101], v143, v65, v[98:101]
	v_pk_fma_f32 v[180:181], v[2:3], v[234:235], v[180:181] op_sel:[0,1,0]
	v_pk_fma_f32 v[192:193], v[4:5], v[234:235], v[192:193] op_sel:[0,1,0]
	v_pk_mul_f32 v[180:181], v[146:147], v[180:181]
	v_pk_mul_f32 v[192:193], v[146:147], v[192:193]
	v_pk_fma_f32 v[236:237], v[144:145], v[62:63], v[180:181]
	v_pk_fma_f32 v[238:239], v[144:145], v[64:65], v[192:193]
	global_store_dwordx4 v[150:151], v[236:239], off nt
	v_lshl_add_u64 v[150:151], v[150:151], 0, s[74:75]
	global_load_dwordx4 v[62:65], v[148:149], off nt
	v_lshl_add_u64 v[148:149], v[148:149], 0, s[74:75]
	ds_read_b32 v143, v160 offset:816
	ds_read_b128 v[172:175], v161 offset:6528
	ds_read_b128 v[232:235], v161 offset:6544
	s_waitcnt vmcnt(22)
	s_waitcnt lgkmcnt(3)
	v_cndmask_b32_e64 v141, 0, v141, s[8:9]
	v_pk_mul_f32 v[180:181], v[26:27], v[114:115] op_sel:[0,1]
	v_pk_mul_f32 v[192:193], v[28:29], v[114:115] op_sel:[0,1]
	v_mfma_f32_16x16x4_f32 v[110:113], v141, v54, v[110:113]
	v_pk_fma_f32 v[180:181], v[30:31], v[114:115], v[180:181] op_sel_hi:[1,0,1]
	v_pk_fma_f32 v[192:193], v[32:33], v[114:115], v[192:193] op_sel_hi:[1,0,1]
	v_pk_fma_f32 v[180:181], v[22:23], v[116:117], v[180:181] op_sel_hi:[1,0,1]
	v_pk_fma_f32 v[192:193], v[24:25], v[116:117], v[192:193] op_sel_hi:[1,0,1]
	v_mfma_f32_16x16x4_f32 v[106:109], v141, v55, v[106:109]
	v_pk_fma_f32 v[180:181], v[18:19], v[116:117], v[180:181] op_sel:[0,1,0]
	v_pk_fma_f32 v[192:193], v[20:21], v[116:117], v[192:193] op_sel:[0,1,0]
	v_pk_fma_f32 v[180:181], v[14:15], v[176:177], v[180:181] op_sel_hi:[1,0,1]
	v_pk_fma_f32 v[192:193], v[16:17], v[176:177], v[192:193] op_sel_hi:[1,0,1]
	v_mfma_f32_16x16x4_f32 v[102:105], v141, v56, v[102:105]
	v_pk_fma_f32 v[180:181], v[10:11], v[176:177], v[180:181] op_sel:[0,1,0]
	v_pk_fma_f32 v[192:193], v[12:13], v[176:177], v[192:193] op_sel:[0,1,0]
	v_pk_fma_f32 v[180:181], v[6:7], v[178:179], v[180:181] op_sel_hi:[1,0,1]
	v_pk_fma_f32 v[192:193], v[8:9], v[178:179], v[192:193] op_sel_hi:[1,0,1]
	v_mfma_f32_16x16x4_f32 v[98:101], v141, v57, v[98:101]
	v_pk_fma_f32 v[180:181], v[2:3], v[178:179], v[180:181] op_sel:[0,1,0]
	v_pk_fma_f32 v[192:193], v[4:5], v[178:179], v[192:193] op_sel:[0,1,0]
	v_pk_mul_f32 v[180:181], v[146:147], v[180:181]
	v_pk_mul_f32 v[192:193], v[146:147], v[192:193]
	v_pk_fma_f32 v[236:237], v[144:145], v[54:55], v[180:181]
	v_pk_fma_f32 v[238:239], v[144:145], v[56:57], v[192:193]
	global_store_dwordx4 v[150:151], v[236:239], off nt
	v_lshl_add_u64 v[150:151], v[150:151], 0, s[74:75]
	global_load_dwordx4 v[54:57], v[148:149], off nt
	v_lshl_add_u64 v[148:149], v[148:149], 0, s[74:75]
	ds_read_b32 v141, v160 offset:832
	ds_read_b128 v[114:117], v161 offset:6656
	ds_read_b128 v[176:179], v161 offset:6672
	s_waitcnt vmcnt(22)
	s_waitcnt lgkmcnt(3)
	v_cndmask_b32_e64 v143, 0, v143, s[8:9]
	v_pk_mul_f32 v[180:181], v[26:27], v[172:173] op_sel:[0,1]
	v_pk_mul_f32 v[192:193], v[28:29], v[172:173] op_sel:[0,1]
	v_mfma_f32_16x16x4_f32 v[110:113], v143, v50, v[110:113]
	v_pk_fma_f32 v[180:181], v[30:31], v[172:173], v[180:181] op_sel_hi:[1,0,1]
	v_pk_fma_f32 v[192:193], v[32:33], v[172:173], v[192:193] op_sel_hi:[1,0,1]
	v_pk_fma_f32 v[180:181], v[22:23], v[174:175], v[180:181] op_sel_hi:[1,0,1]
	v_pk_fma_f32 v[192:193], v[24:25], v[174:175], v[192:193] op_sel_hi:[1,0,1]
	v_mfma_f32_16x16x4_f32 v[106:109], v143, v51, v[106:109]
	v_pk_fma_f32 v[180:181], v[18:19], v[174:175], v[180:181] op_sel:[0,1,0]
	v_pk_fma_f32 v[192:193], v[20:21], v[174:175], v[192:193] op_sel:[0,1,0]
	v_pk_fma_f32 v[180:181], v[14:15], v[232:233], v[180:181] op_sel_hi:[1,0,1]
	v_pk_fma_f32 v[192:193], v[16:17], v[232:233], v[192:193] op_sel_hi:[1,0,1]
	v_mfma_f32_16x16x4_f32 v[102:105], v143, v52, v[102:105]
	v_pk_fma_f32 v[180:181], v[10:11], v[232:233], v[180:181] op_sel:[0,1,0]
	v_pk_fma_f32 v[192:193], v[12:13], v[232:233], v[192:193] op_sel:[0,1,0]
	v_pk_fma_f32 v[180:181], v[6:7], v[234:235], v[180:181] op_sel_hi:[1,0,1]
	v_pk_fma_f32 v[192:193], v[8:9], v[234:235], v[192:193] op_sel_hi:[1,0,1]
	v_mfma_f32_16x16x4_f32 v[98:101], v143, v53, v[98:101]
	v_pk_fma_f32 v[180:181], v[2:3], v[234:235], v[180:181] op_sel:[0,1,0]
	v_pk_fma_f32 v[192:193], v[4:5], v[234:235], v[192:193] op_sel:[0,1,0]
	v_pk_mul_f32 v[180:181], v[146:147], v[180:181]
	v_pk_mul_f32 v[192:193], v[146:147], v[192:193]
	v_pk_fma_f32 v[236:237], v[144:145], v[50:51], v[180:181]
	v_pk_fma_f32 v[238:239], v[144:145], v[52:53], v[192:193]
	global_store_dwordx4 v[150:151], v[236:239], off nt
	v_lshl_add_u64 v[150:151], v[150:151], 0, s[74:75]
	global_load_dwordx4 v[50:53], v[148:149], off nt
	v_lshl_add_u64 v[148:149], v[148:149], 0, s[74:75]
	ds_read_b32 v143, v160 offset:848
	ds_read_b128 v[172:175], v161 offset:6784
	ds_read_b128 v[232:235], v161 offset:6800
	s_waitcnt vmcnt(22)
; #define RS_LOAD(dst, it0) do { _Pragma("unroll") for (int u = 0; u < 8; ++u) dst[u] = __builtin_nontemporal_load((const f32x4*)(S0 + (size_t)(4 * ((it0) + u)) * DV)); } while (0)
; __device__ __forceinline__ void ret_sample_item(Frame& F, int item) {
;     ...
;     for (int it0 = 0; it0 < 64; it0 += 16) {
;         RS_LOAD(sb, it0 + 8);
;         RS_PROC(sa, it0);
;         { const int itn = it0 + 16 < 64 ? it0 + 16 : it0; RS_LOAD(sa, itn); }
;         RS_PROC(sb, it0 + 8);
;     }
	s_waitcnt lgkmcnt(3)
	v_cndmask_b32_e64 v141, 0, v141, s[8:9]
	v_pk_mul_f32 v[180:181], v[26:27], v[114:115] op_sel:[0,1]
	v_pk_mul_f32 v[192:193], v[28:29], v[114:115] op_sel:[0,1]
	v_mfma_f32_16x16x4_f32 v[110:113], v141, v46, v[110:113]
	v_pk_fma_f32 v[180:181], v[30:31], v[114:115], v[180:181] op_sel_hi:[1,0,1]
	v_pk_fma_f32 v[192:193], v[32:33], v[114:115], v[192:193] op_sel_hi:[1,0,1]
	v_pk_fma_f32 v[180:181], v[22:23], v[116:117], v[180:181] op_sel_hi:[1,0,1]
	v_pk_fma_f32 v[192:193], v[24:25], v[116:117], v[192:193] op_sel_hi:[1,0,1]
	v_mfma_f32_16x16x4_f32 v[106:109], v141, v47, v[106:109]
	v_pk_fma_f32 v[180:181], v[18:19], v[116:117], v[180:181] op_sel:[0,1,0]
	v_pk_fma_f32 v[192:193], v[20:21], v[116:117], v[192:193] op_sel:[0,1,0]
	v_pk_fma_f32 v[180:181], v[14:15], v[176:177], v[180:181] op_sel_hi:[1,0,1]
	v_pk_fma_f32 v[192:193], v[16:17], v[176:177], v[192:193] op_sel_hi:[1,0,1]
	v_mfma_f32_16x16x4_f32 v[102:105], v141, v48, v[102:105]
	v_pk_fma_f32 v[180:181], v[10:11], v[176:177], v[180:181] op_sel:[0,1,0]
	v_pk_fma_f32 v[192:193], v[12:13], v[176:177], v[192:193] op_sel:[0,1,0]
	v_pk_fma_f32 v[180:181], v[6:7], v[178:179], v[180:181] op_sel_hi:[1,0,1]
	v_pk_fma_f32 v[192:193], v[8:9], v[178:179], v[192:193] op_sel_hi:[1,0,1]
	v_mfma_f32_16x16x4_f32 v[98:101], v141, v49, v[98:101]
	v_pk_fma_f32 v[180:181], v[2:3], v[178:179], v[180:181] op_sel:[0,1,0]
	v_pk_fma_f32 v[192:193], v[4:5], v[178:179], v[192:193] op_sel:[0,1,0]
	v_pk_mul_f32 v[180:181], v[146:147], v[180:181]
	v_pk_mul_f32 v[192:193], v[146:147], v[192:193]
	v_pk_fma_f32 v[236:237], v[144:145], v[46:47], v[180:181]
	v_pk_fma_f32 v[238:239], v[144:145], v[48:49], v[192:193]
	global_store_dwordx4 v[150:151], v[236:239], off nt
	v_lshl_add_u64 v[150:151], v[150:151], 0, s[74:75]
	ds_read_b32 v141, v160 offset:864
	ds_read_b128 v[114:117], v161 offset:6912
	ds_read_b128 v[176:179], v161 offset:6928
	s_waitcnt vmcnt(21)
	s_waitcnt lgkmcnt(3)
	v_cndmask_b32_e64 v143, 0, v143, s[8:9]
	v_pk_mul_f32 v[180:181], v[26:27], v[172:173] op_sel:[0,1]
	v_pk_mul_f32 v[192:193], v[28:29], v[172:173] op_sel:[0,1]
	v_mfma_f32_16x16x4_f32 v[110:113], v143, v42, v[110:113]
	v_pk_fma_f32 v[180:181], v[30:31], v[172:173], v[180:181] op_sel_hi:[1,0,1]
	v_pk_fma_f32 v[192:193], v[32:33], v[172:173], v[192:193] op_sel_hi:[1,0,1]
	v_pk_fma_f32 v[180:181], v[22:23], v[174:175], v[180:181] op_sel_hi:[1,0,1]
	v_pk_fma_f32 v[192:193], v[24:25], v[174:175], v[192:193] op_sel_hi:[1,0,1]
	v_mfma_f32_16x16x4_f32 v[106:109], v143, v43, v[106:109]
	v_pk_fma_f32 v[180:181], v[18:19], v[174:175], v[180:181] op_sel:[0,1,0]
	v_pk_fma_f32 v[192:193], v[20:21], v[174:175], v[192:193] op_sel:[0,1,0]
	v_pk_fma_f32 v[180:181], v[14:15], v[232:233], v[180:181] op_sel_hi:[1,0,1]
	v_pk_fma_f32 v[192:193], v[16:17], v[232:233], v[192:193] op_sel_hi:[1,0,1]
	v_mfma_f32_16x16x4_f32 v[102:105], v143, v44, v[102:105]
	v_pk_fma_f32 v[180:181], v[10:11], v[232:233], v[180:181] op_sel:[0,1,0]
	v_pk_fma_f32 v[192:193], v[12:13], v[232:233], v[192:193] op_sel:[0,1,0]
	v_pk_fma_f32 v[180:181], v[6:7], v[234:235], v[180:181] op_sel_hi:[1,0,1]
	v_pk_fma_f32 v[192:193], v[8:9], v[234:235], v[192:193] op_sel_hi:[1,0,1]
	v_mfma_f32_16x16x4_f32 v[98:101], v143, v45, v[98:101]
	v_pk_fma_f32 v[180:181], v[2:3], v[234:235], v[180:181] op_sel:[0,1,0]
	v_pk_fma_f32 v[192:193], v[4:5], v[234:235], v[192:193] op_sel:[0,1,0]
	v_pk_mul_f32 v[180:181], v[146:147], v[180:181]
	v_pk_mul_f32 v[192:193], v[146:147], v[192:193]
	v_pk_fma_f32 v[236:237], v[144:145], v[42:43], v[180:181]
	v_pk_fma_f32 v[238:239], v[144:145], v[44:45], v[192:193]
	global_store_dwordx4 v[150:151], v[236:239], off nt
	v_lshl_add_u64 v[150:151], v[150:151], 0, s[74:75]
	ds_read_b32 v143, v160 offset:880
	ds_read_b128 v[172:175], v161 offset:7040
	ds_read_b128 v[232:235], v161 offset:7056
	s_waitcnt vmcnt(20)
	s_waitcnt lgkmcnt(3)
	v_cndmask_b32_e64 v141, 0, v141, s[8:9]
	v_pk_mul_f32 v[180:181], v[26:27], v[114:115] op_sel:[0,1]
	v_pk_mul_f32 v[192:193], v[28:29], v[114:115] op_sel:[0,1]
	v_mfma_f32_16x16x4_f32 v[110:113], v141, v38, v[110:113]
	v_pk_fma_f32 v[180:181], v[30:31], v[114:115], v[180:181] op_sel_hi:[1,0,1]
	v_pk_fma_f32 v[192:193], v[32:33], v[114:115], v[192:193] op_sel_hi:[1,0,1]
	v_pk_fma_f32 v[180:181], v[22:23], v[116:117], v[180:181] op_sel_hi:[1,0,1]
	v_pk_fma_f32 v[192:193], v[24:25], v[116:117], v[192:193] op_sel_hi:[1,0,1]
	v_mfma_f32_16x16x4_f32 v[106:109], v141, v39, v[106:109]
	v_pk_fma_f32 v[180:181], v[18:19], v[116:117], v[180:181] op_sel:[0,1,0]
	v_pk_fma_f32 v[192:193], v[20:21], v[116:117], v[192:193] op_sel:[0,1,0]
	v_pk_fma_f32 v[180:181], v[14:15], v[176:177], v[180:181] op_sel_hi:[1,0,1]
	v_pk_fma_f32 v[192:193], v[16:17], v[176:177], v[192:193] op_sel_hi:[1,0,1]
	v_mfma_f32_16x16x4_f32 v[102:105], v141, v40, v[102:105]
	v_pk_fma_f32 v[180:181], v[10:11], v[176:177], v[180:181] op_sel:[0,1,0]
	v_pk_fma_f32 v[192:193], v[12:13], v[176:177], v[192:193] op_sel:[0,1,0]
	v_pk_fma_f32 v[180:181], v[6:7], v[178:179], v[180:181] op_sel_hi:[1,0,1]
	v_pk_fma_f32 v[192:193], v[8:9], v[178:179], v[192:193] op_sel_hi:[1,0,1]
	v_mfma_f32_16x16x4_f32 v[98:101], v141, v41, v[98:101]
	v_pk_fma_f32 v[180:181], v[2:3], v[178:179], v[180:181] op_sel:[0,1,0]
	v_pk_fma_f32 v[192:193], v[4:5], v[178:179], v[192:193] op_sel:[0,1,0]
	v_pk_mul_f32 v[180:181], v[146:147], v[180:181]
	v_pk_mul_f32 v[192:193], v[146:147], v[192:193]
	v_pk_fma_f32 v[236:237], v[144:145], v[38:39], v[180:181]
	v_pk_fma_f32 v[238:239], v[144:145], v[40:41], v[192:193]
	global_store_dwordx4 v[150:151], v[236:239], off nt
	v_lshl_add_u64 v[150:151], v[150:151], 0, s[74:75]
	ds_read_b32 v141, v160 offset:896
	ds_read_b128 v[114:117], v161 offset:7168
	ds_read_b128 v[176:179], v161 offset:7184
	s_waitcnt vmcnt(19)
; #define RS_LOAD(dst, it0) do { _Pragma("unroll") for (int u = 0; u < 8; ++u) dst[u] = __builtin_nontemporal_load((const f32x4*)(S0 + (size_t)(4 * ((it0) + u)) * DV)); } while (0)
; __device__ __forceinline__ void ret_sample_item(Frame& F, int item) {
;     ...
;     for (int it0 = 0; it0 < 64; it0 += 16) {
;         RS_LOAD(sb, it0 + 8);
;         RS_PROC(sa, it0);
;         { const int itn = it0 + 16 < 64 ? it0 + 16 : it0; RS_LOAD(sa, itn); }
;         RS_PROC(sb, it0 + 8);
;     }
	s_waitcnt lgkmcnt(3)
	v_cndmask_b32_e64 v143, 0, v143, s[8:9]
	v_pk_mul_f32 v[180:181], v[26:27], v[172:173] op_sel:[0,1]
	v_pk_mul_f32 v[192:193], v[28:29], v[172:173] op_sel:[0,1]
	v_mfma_f32_16x16x4_f32 v[110:113], v143, v34, v[110:113]
	v_pk_fma_f32 v[180:181], v[30:31], v[172:173], v[180:181] op_sel_hi:[1,0,1]
	v_pk_fma_f32 v[192:193], v[32:33], v[172:173], v[192:193] op_sel_hi:[1,0,1]
	v_pk_fma_f32 v[180:181], v[22:23], v[174:175], v[180:181] op_sel_hi:[1,0,1]
	v_pk_fma_f32 v[192:193], v[24:25], v[174:175], v[192:193] op_sel_hi:[1,0,1]
	v_mfma_f32_16x16x4_f32 v[106:109], v143, v35, v[106:109]
	v_pk_fma_f32 v[180:181], v[18:19], v[174:175], v[180:181] op_sel:[0,1,0]
	v_pk_fma_f32 v[192:193], v[20:21], v[174:175], v[192:193] op_sel:[0,1,0]
	v_pk_fma_f32 v[180:181], v[14:15], v[232:233], v[180:181] op_sel_hi:[1,0,1]
	v_pk_fma_f32 v[192:193], v[16:17], v[232:233], v[192:193] op_sel_hi:[1,0,1]
	v_mfma_f32_16x16x4_f32 v[102:105], v143, v36, v[102:105]
	v_pk_fma_f32 v[180:181], v[10:11], v[232:233], v[180:181] op_sel:[0,1,0]
	v_pk_fma_f32 v[192:193], v[12:13], v[232:233], v[192:193] op_sel:[0,1,0]
	v_pk_fma_f32 v[180:181], v[6:7], v[234:235], v[180:181] op_sel_hi:[1,0,1]
	v_pk_fma_f32 v[192:193], v[8:9], v[234:235], v[192:193] op_sel_hi:[1,0,1]
	v_mfma_f32_16x16x4_f32 v[98:101], v143, v37, v[98:101]
	v_pk_fma_f32 v[180:181], v[2:3], v[234:235], v[180:181] op_sel:[0,1,0]
	v_pk_fma_f32 v[192:193], v[4:5], v[234:235], v[192:193] op_sel:[0,1,0]
	v_pk_mul_f32 v[180:181], v[146:147], v[180:181]
	v_pk_mul_f32 v[192:193], v[146:147], v[192:193]
	v_pk_fma_f32 v[236:237], v[144:145], v[34:35], v[180:181]
	v_pk_fma_f32 v[238:239], v[144:145], v[36:37], v[192:193]
	global_store_dwordx4 v[150:151], v[236:239], off nt
	v_lshl_add_u64 v[150:151], v[150:151], 0, s[74:75]
	ds_read_b32 v143, v160 offset:912
	ds_read_b128 v[172:175], v161 offset:7296
	ds_read_b128 v[232:235], v161 offset:7312
	s_waitcnt vmcnt(18)
	s_waitcnt lgkmcnt(3)
	v_cndmask_b32_e64 v141, 0, v141, s[8:9]
	v_pk_mul_f32 v[180:181], v[26:27], v[114:115] op_sel:[0,1]
	v_pk_mul_f32 v[192:193], v[28:29], v[114:115] op_sel:[0,1]
	v_mfma_f32_16x16x4_f32 v[110:113], v141, v58, v[110:113]
	v_pk_fma_f32 v[180:181], v[30:31], v[114:115], v[180:181] op_sel_hi:[1,0,1]
	v_pk_fma_f32 v[192:193], v[32:33], v[114:115], v[192:193] op_sel_hi:[1,0,1]
	v_pk_fma_f32 v[180:181], v[22:23], v[116:117], v[180:181] op_sel_hi:[1,0,1]
	v_pk_fma_f32 v[192:193], v[24:25], v[116:117], v[192:193] op_sel_hi:[1,0,1]
	v_mfma_f32_16x16x4_f32 v[106:109], v141, v59, v[106:109]
	v_pk_fma_f32 v[180:181], v[18:19], v[116:117], v[180:181] op_sel:[0,1,0]
	v_pk_fma_f32 v[192:193], v[20:21], v[116:117], v[192:193] op_sel:[0,1,0]
	v_pk_fma_f32 v[180:181], v[14:15], v[176:177], v[180:181] op_sel_hi:[1,0,1]
	v_pk_fma_f32 v[192:193], v[16:17], v[176:177], v[192:193] op_sel_hi:[1,0,1]
	v_mfma_f32_16x16x4_f32 v[102:105], v141, v60, v[102:105]
	v_pk_fma_f32 v[180:181], v[10:11], v[176:177], v[180:181] op_sel:[0,1,0]
	v_pk_fma_f32 v[192:193], v[12:13], v[176:177], v[192:193] op_sel:[0,1,0]
	v_pk_fma_f32 v[180:181], v[6:7], v[178:179], v[180:181] op_sel_hi:[1,0,1]
	v_pk_fma_f32 v[192:193], v[8:9], v[178:179], v[192:193] op_sel_hi:[1,0,1]
	v_mfma_f32_16x16x4_f32 v[98:101], v141, v61, v[98:101]
	v_pk_fma_f32 v[180:181], v[2:3], v[178:179], v[180:181] op_sel:[0,1,0]
	v_pk_fma_f32 v[192:193], v[4:5], v[178:179], v[192:193] op_sel:[0,1,0]
	v_pk_mul_f32 v[180:181], v[146:147], v[180:181]
	v_pk_mul_f32 v[192:193], v[146:147], v[192:193]
	v_pk_fma_f32 v[236:237], v[144:145], v[58:59], v[180:181]
	v_pk_fma_f32 v[238:239], v[144:145], v[60:61], v[192:193]
	global_store_dwordx4 v[150:151], v[236:239], off nt
	v_lshl_add_u64 v[150:151], v[150:151], 0, s[74:75]
	ds_read_b32 v141, v160 offset:928
	ds_read_b128 v[114:117], v161 offset:7424
	ds_read_b128 v[176:179], v161 offset:7440
	s_waitcnt vmcnt(17)
	s_waitcnt lgkmcnt(3)
	v_cndmask_b32_e64 v143, 0, v143, s[8:9]
	v_pk_mul_f32 v[180:181], v[26:27], v[172:173] op_sel:[0,1]
	v_pk_mul_f32 v[192:193], v[28:29], v[172:173] op_sel:[0,1]
	v_mfma_f32_16x16x4_f32 v[110:113], v143, v66, v[110:113]
	v_pk_fma_f32 v[180:181], v[30:31], v[172:173], v[180:181] op_sel_hi:[1,0,1]
	v_pk_fma_f32 v[192:193], v[32:33], v[172:173], v[192:193] op_sel_hi:[1,0,1]
	v_pk_fma_f32 v[180:181], v[22:23], v[174:175], v[180:181] op_sel_hi:[1,0,1]
	v_pk_fma_f32 v[192:193], v[24:25], v[174:175], v[192:193] op_sel_hi:[1,0,1]
	v_mfma_f32_16x16x4_f32 v[106:109], v143, v67, v[106:109]
	v_pk_fma_f32 v[180:181], v[18:19], v[174:175], v[180:181] op_sel:[0,1,0]
	v_pk_fma_f32 v[192:193], v[20:21], v[174:175], v[192:193] op_sel:[0,1,0]
	v_pk_fma_f32 v[180:181], v[14:15], v[232:233], v[180:181] op_sel_hi:[1,0,1]
	v_pk_fma_f32 v[192:193], v[16:17], v[232:233], v[192:193] op_sel_hi:[1,0,1]
	v_mfma_f32_16x16x4_f32 v[102:105], v143, v68, v[102:105]
	v_pk_fma_f32 v[180:181], v[10:11], v[232:233], v[180:181] op_sel:[0,1,0]
	v_pk_fma_f32 v[192:193], v[12:13], v[232:233], v[192:193] op_sel:[0,1,0]
	v_pk_fma_f32 v[180:181], v[6:7], v[234:235], v[180:181] op_sel_hi:[1,0,1]
	v_pk_fma_f32 v[192:193], v[8:9], v[234:235], v[192:193] op_sel_hi:[1,0,1]
	v_mfma_f32_16x16x4_f32 v[98:101], v143, v69, v[98:101]
	v_pk_fma_f32 v[180:181], v[2:3], v[234:235], v[180:181] op_sel:[0,1,0]
	v_pk_fma_f32 v[192:193], v[4:5], v[234:235], v[192:193] op_sel:[0,1,0]
	v_pk_mul_f32 v[180:181], v[146:147], v[180:181]
	v_pk_mul_f32 v[192:193], v[146:147], v[192:193]
	v_pk_fma_f32 v[236:237], v[144:145], v[66:67], v[180:181]
	v_pk_fma_f32 v[238:239], v[144:145], v[68:69], v[192:193]
	global_store_dwordx4 v[150:151], v[236:239], off nt
	v_lshl_add_u64 v[150:151], v[150:151], 0, s[74:75]
	ds_read_b32 v143, v160 offset:944
	ds_read_b128 v[172:175], v161 offset:7552
	ds_read_b128 v[232:235], v161 offset:7568
	s_waitcnt vmcnt(16)
; #define RS_LOAD(dst, it0) do { _Pragma("unroll") for (int u = 0; u < 8; ++u) dst[u] = __builtin_nontemporal_load((const f32x4*)(S0 + (size_t)(4 * ((it0) + u)) * DV)); } while (0)
; __device__ __forceinline__ void ret_sample_item(Frame& F, int item) {
;     ...
;     for (int it0 = 0; it0 < 64; it0 += 16) {
;         RS_LOAD(sb, it0 + 8);
;         RS_PROC(sa, it0);
;         { const int itn = it0 + 16 < 64 ? it0 + 16 : it0; RS_LOAD(sa, itn); }
;         RS_PROC(sb, it0 + 8);
;     }
	s_waitcnt lgkmcnt(3)
	v_cndmask_b32_e64 v141, 0, v141, s[8:9]
	v_pk_mul_f32 v[180:181], v[26:27], v[114:115] op_sel:[0,1]
	v_pk_mul_f32 v[192:193], v[28:29], v[114:115] op_sel:[0,1]
	v_mfma_f32_16x16x4_f32 v[110:113], v141, v74, v[110:113]
	v_pk_fma_f32 v[180:181], v[30:31], v[114:115], v[180:181] op_sel_hi:[1,0,1]
	v_pk_fma_f32 v[192:193], v[32:33], v[114:115], v[192:193] op_sel_hi:[1,0,1]
	v_pk_fma_f32 v[180:181], v[22:23], v[116:117], v[180:181] op_sel_hi:[1,0,1]
	v_pk_fma_f32 v[192:193], v[24:25], v[116:117], v[192:193] op_sel_hi:[1,0,1]
	v_mfma_f32_16x16x4_f32 v[106:109], v141, v75, v[106:109]
	v_pk_fma_f32 v[180:181], v[18:19], v[116:117], v[180:181] op_sel:[0,1,0]
	v_pk_fma_f32 v[192:193], v[20:21], v[116:117], v[192:193] op_sel:[0,1,0]
	v_pk_fma_f32 v[180:181], v[14:15], v[176:177], v[180:181] op_sel_hi:[1,0,1]
	v_pk_fma_f32 v[192:193], v[16:17], v[176:177], v[192:193] op_sel_hi:[1,0,1]
	v_mfma_f32_16x16x4_f32 v[102:105], v141, v76, v[102:105]
	v_pk_fma_f32 v[180:181], v[10:11], v[176:177], v[180:181] op_sel:[0,1,0]
	v_pk_fma_f32 v[192:193], v[12:13], v[176:177], v[192:193] op_sel:[0,1,0]
	v_pk_fma_f32 v[180:181], v[6:7], v[178:179], v[180:181] op_sel_hi:[1,0,1]
	v_pk_fma_f32 v[192:193], v[8:9], v[178:179], v[192:193] op_sel_hi:[1,0,1]
	v_mfma_f32_16x16x4_f32 v[98:101], v141, v77, v[98:101]
	v_pk_fma_f32 v[180:181], v[2:3], v[178:179], v[180:181] op_sel:[0,1,0]
	v_pk_fma_f32 v[192:193], v[4:5], v[178:179], v[192:193] op_sel:[0,1,0]
	v_pk_mul_f32 v[180:181], v[146:147], v[180:181]
	v_pk_mul_f32 v[192:193], v[146:147], v[192:193]
	v_pk_fma_f32 v[236:237], v[144:145], v[74:75], v[180:181]
	v_pk_fma_f32 v[238:239], v[144:145], v[76:77], v[192:193]
	global_store_dwordx4 v[150:151], v[236:239], off nt
	v_lshl_add_u64 v[150:151], v[150:151], 0, s[74:75]
	ds_read_b32 v141, v160 offset:960
	ds_read_b128 v[114:117], v161 offset:7680
	ds_read_b128 v[176:179], v161 offset:7696
	s_waitcnt vmcnt(15)
	s_waitcnt lgkmcnt(3)
	v_cndmask_b32_e64 v143, 0, v143, s[8:9]
	v_pk_mul_f32 v[180:181], v[26:27], v[172:173] op_sel:[0,1]
	v_pk_mul_f32 v[192:193], v[28:29], v[172:173] op_sel:[0,1]
	v_mfma_f32_16x16x4_f32 v[110:113], v143, v78, v[110:113]
	v_pk_fma_f32 v[180:181], v[30:31], v[172:173], v[180:181] op_sel_hi:[1,0,1]
	v_pk_fma_f32 v[192:193], v[32:33], v[172:173], v[192:193] op_sel_hi:[1,0,1]
	v_pk_fma_f32 v[180:181], v[22:23], v[174:175], v[180:181] op_sel_hi:[1,0,1]
	v_pk_fma_f32 v[192:193], v[24:25], v[174:175], v[192:193] op_sel_hi:[1,0,1]
	v_mfma_f32_16x16x4_f32 v[106:109], v143, v79, v[106:109]
	v_pk_fma_f32 v[180:181], v[18:19], v[174:175], v[180:181] op_sel:[0,1,0]
	v_pk_fma_f32 v[192:193], v[20:21], v[174:175], v[192:193] op_sel:[0,1,0]
	v_pk_fma_f32 v[180:181], v[14:15], v[232:233], v[180:181] op_sel_hi:[1,0,1]
	v_pk_fma_f32 v[192:193], v[16:17], v[232:233], v[192:193] op_sel_hi:[1,0,1]
	v_mfma_f32_16x16x4_f32 v[102:105], v143, v80, v[102:105]
	v_pk_fma_f32 v[180:181], v[10:11], v[232:233], v[180:181] op_sel:[0,1,0]
	v_pk_fma_f32 v[192:193], v[12:13], v[232:233], v[192:193] op_sel:[0,1,0]
	v_pk_fma_f32 v[180:181], v[6:7], v[234:235], v[180:181] op_sel_hi:[1,0,1]
	v_pk_fma_f32 v[192:193], v[8:9], v[234:235], v[192:193] op_sel_hi:[1,0,1]
	v_mfma_f32_16x16x4_f32 v[98:101], v143, v81, v[98:101]
	v_pk_fma_f32 v[180:181], v[2:3], v[234:235], v[180:181] op_sel:[0,1,0]
	v_pk_fma_f32 v[192:193], v[4:5], v[234:235], v[192:193] op_sel:[0,1,0]
	v_pk_mul_f32 v[180:181], v[146:147], v[180:181]
	v_pk_mul_f32 v[192:193], v[146:147], v[192:193]
	v_pk_fma_f32 v[236:237], v[144:145], v[78:79], v[180:181]
	v_pk_fma_f32 v[238:239], v[144:145], v[80:81], v[192:193]
	global_store_dwordx4 v[150:151], v[236:239], off nt
	v_lshl_add_u64 v[150:151], v[150:151], 0, s[74:75]
	ds_read_b32 v143, v160 offset:976
	ds_read_b128 v[172:175], v161 offset:7808
	ds_read_b128 v[232:235], v161 offset:7824
	s_waitcnt vmcnt(14)
	s_waitcnt lgkmcnt(3)
	v_cndmask_b32_e64 v141, 0, v141, s[8:9]
	v_pk_mul_f32 v[180:181], v[26:27], v[114:115] op_sel:[0,1]
	v_pk_mul_f32 v[192:193], v[28:29], v[114:115] op_sel:[0,1]
	v_mfma_f32_16x16x4_f32 v[110:113], v141, v70, v[110:113]
	v_pk_fma_f32 v[180:181], v[30:31], v[114:115], v[180:181] op_sel_hi:[1,0,1]
	v_pk_fma_f32 v[192:193], v[32:33], v[114:115], v[192:193] op_sel_hi:[1,0,1]
	v_pk_fma_f32 v[180:181], v[22:23], v[116:117], v[180:181] op_sel_hi:[1,0,1]
	v_pk_fma_f32 v[192:193], v[24:25], v[116:117], v[192:193] op_sel_hi:[1,0,1]
	v_mfma_f32_16x16x4_f32 v[106:109], v141, v71, v[106:109]
	v_pk_fma_f32 v[180:181], v[18:19], v[116:117], v[180:181] op_sel:[0,1,0]
	v_pk_fma_f32 v[192:193], v[20:21], v[116:117], v[192:193] op_sel:[0,1,0]
	v_pk_fma_f32 v[180:181], v[14:15], v[176:177], v[180:181] op_sel_hi:[1,0,1]
	v_pk_fma_f32 v[192:193], v[16:17], v[176:177], v[192:193] op_sel_hi:[1,0,1]
	v_mfma_f32_16x16x4_f32 v[102:105], v141, v72, v[102:105]
	v_pk_fma_f32 v[180:181], v[10:11], v[176:177], v[180:181] op_sel:[0,1,0]
	v_pk_fma_f32 v[192:193], v[12:13], v[176:177], v[192:193] op_sel:[0,1,0]
	v_pk_fma_f32 v[180:181], v[6:7], v[178:179], v[180:181] op_sel_hi:[1,0,1]
	v_pk_fma_f32 v[192:193], v[8:9], v[178:179], v[192:193] op_sel_hi:[1,0,1]
	v_mfma_f32_16x16x4_f32 v[98:101], v141, v73, v[98:101]
	v_pk_fma_f32 v[180:181], v[2:3], v[178:179], v[180:181] op_sel:[0,1,0]
	v_pk_fma_f32 v[192:193], v[4:5], v[178:179], v[192:193] op_sel:[0,1,0]
	v_pk_mul_f32 v[180:181], v[146:147], v[180:181]
	v_pk_mul_f32 v[192:193], v[146:147], v[192:193]
	v_pk_fma_f32 v[236:237], v[144:145], v[70:71], v[180:181]
	v_pk_fma_f32 v[238:239], v[144:145], v[72:73], v[192:193]
	global_store_dwordx4 v[150:151], v[236:239], off nt
	v_lshl_add_u64 v[150:151], v[150:151], 0, s[74:75]
	ds_read_b32 v141, v160 offset:992
	ds_read_b128 v[114:117], v161 offset:7936
	ds_read_b128 v[176:179], v161 offset:7952
	s_waitcnt vmcnt(13)
; #define RS_LOAD(dst, it0) do { _Pragma("unroll") for (int u = 0; u < 8; ++u) dst[u] = __builtin_nontemporal_load((const f32x4*)(S0 + (size_t)(4 * ((it0) + u)) * DV)); } while (0)
; __device__ __forceinline__ void ret_sample_item(Frame& F, int item) {
;     ...
;     for (int it0 = 0; it0 < 64; it0 += 16) {
;         RS_LOAD(sb, it0 + 8);
;         RS_PROC(sa, it0);
;         { const int itn = it0 + 16 < 64 ? it0 + 16 : it0; RS_LOAD(sa, itn); }
;         RS_PROC(sb, it0 + 8);
;     }
	s_waitcnt lgkmcnt(3)
	v_cndmask_b32_e64 v143, 0, v143, s[8:9]
	v_pk_mul_f32 v[180:181], v[26:27], v[172:173] op_sel:[0,1]
	v_pk_mul_f32 v[192:193], v[28:29], v[172:173] op_sel:[0,1]
	v_mfma_f32_16x16x4_f32 v[110:113], v143, v62, v[110:113]
	v_pk_fma_f32 v[180:181], v[30:31], v[172:173], v[180:181] op_sel_hi:[1,0,1]
	v_pk_fma_f32 v[192:193], v[32:33], v[172:173], v[192:193] op_sel_hi:[1,0,1]
	v_pk_fma_f32 v[180:181], v[22:23], v[174:175], v[180:181] op_sel_hi:[1,0,1]
	v_pk_fma_f32 v[192:193], v[24:25], v[174:175], v[192:193] op_sel_hi:[1,0,1]
	v_mfma_f32_16x16x4_f32 v[106:109], v143, v63, v[106:109]
	v_pk_fma_f32 v[180:181], v[18:19], v[174:175], v[180:181] op_sel:[0,1,0]
	v_pk_fma_f32 v[192:193], v[20:21], v[174:175], v[192:193] op_sel:[0,1,0]
	v_pk_fma_f32 v[180:181], v[14:15], v[232:233], v[180:181] op_sel_hi:[1,0,1]
	v_pk_fma_f32 v[192:193], v[16:17], v[232:233], v[192:193] op_sel_hi:[1,0,1]
	v_mfma_f32_16x16x4_f32 v[102:105], v143, v64, v[102:105]
	v_pk_fma_f32 v[180:181], v[10:11], v[232:233], v[180:181] op_sel:[0,1,0]
	v_pk_fma_f32 v[192:193], v[12:13], v[232:233], v[192:193] op_sel:[0,1,0]
	v_pk_fma_f32 v[180:181], v[6:7], v[234:235], v[180:181] op_sel_hi:[1,0,1]
	v_pk_fma_f32 v[192:193], v[8:9], v[234:235], v[192:193] op_sel_hi:[1,0,1]
	v_mfma_f32_16x16x4_f32 v[98:101], v143, v65, v[98:101]
	v_pk_fma_f32 v[180:181], v[2:3], v[234:235], v[180:181] op_sel:[0,1,0]
	v_pk_fma_f32 v[192:193], v[4:5], v[234:235], v[192:193] op_sel:[0,1,0]
	v_pk_mul_f32 v[180:181], v[146:147], v[180:181]
	v_pk_mul_f32 v[192:193], v[146:147], v[192:193]
	v_pk_fma_f32 v[236:237], v[144:145], v[62:63], v[180:181]
	v_pk_fma_f32 v[238:239], v[144:145], v[64:65], v[192:193]
	global_store_dwordx4 v[150:151], v[236:239], off nt
	v_lshl_add_u64 v[150:151], v[150:151], 0, s[74:75]
	ds_read_b32 v143, v160 offset:1008
	ds_read_b128 v[172:175], v161 offset:8064
	ds_read_b128 v[232:235], v161 offset:8080
	s_waitcnt vmcnt(12)
	s_waitcnt lgkmcnt(3)
	v_cndmask_b32_e64 v141, 0, v141, s[8:9]
	v_pk_mul_f32 v[180:181], v[26:27], v[114:115] op_sel:[0,1]
	v_pk_mul_f32 v[192:193], v[28:29], v[114:115] op_sel:[0,1]
	v_mfma_f32_16x16x4_f32 v[110:113], v141, v54, v[110:113]
	v_pk_fma_f32 v[180:181], v[30:31], v[114:115], v[180:181] op_sel_hi:[1,0,1]
	v_pk_fma_f32 v[192:193], v[32:33], v[114:115], v[192:193] op_sel_hi:[1,0,1]
	v_pk_fma_f32 v[180:181], v[22:23], v[116:117], v[180:181] op_sel_hi:[1,0,1]
	v_pk_fma_f32 v[192:193], v[24:25], v[116:117], v[192:193] op_sel_hi:[1,0,1]
	v_mfma_f32_16x16x4_f32 v[106:109], v141, v55, v[106:109]
	v_pk_fma_f32 v[180:181], v[18:19], v[116:117], v[180:181] op_sel:[0,1,0]
	v_pk_fma_f32 v[192:193], v[20:21], v[116:117], v[192:193] op_sel:[0,1,0]
	v_pk_fma_f32 v[180:181], v[14:15], v[176:177], v[180:181] op_sel_hi:[1,0,1]
	v_pk_fma_f32 v[192:193], v[16:17], v[176:177], v[192:193] op_sel_hi:[1,0,1]
	v_mfma_f32_16x16x4_f32 v[102:105], v141, v56, v[102:105]
	v_pk_fma_f32 v[180:181], v[10:11], v[176:177], v[180:181] op_sel:[0,1,0]
	v_pk_fma_f32 v[192:193], v[12:13], v[176:177], v[192:193] op_sel:[0,1,0]
	v_pk_fma_f32 v[180:181], v[6:7], v[178:179], v[180:181] op_sel_hi:[1,0,1]
	v_pk_fma_f32 v[192:193], v[8:9], v[178:179], v[192:193] op_sel_hi:[1,0,1]
	v_mfma_f32_16x16x4_f32 v[98:101], v141, v57, v[98:101]
	v_pk_fma_f32 v[180:181], v[2:3], v[178:179], v[180:181] op_sel:[0,1,0]
	v_pk_fma_f32 v[192:193], v[4:5], v[178:179], v[192:193] op_sel:[0,1,0]
	v_pk_mul_f32 v[180:181], v[146:147], v[180:181]
	v_pk_mul_f32 v[192:193], v[146:147], v[192:193]
	v_pk_fma_f32 v[236:237], v[144:145], v[54:55], v[180:181]
	v_pk_fma_f32 v[238:239], v[144:145], v[56:57], v[192:193]
	global_store_dwordx4 v[150:151], v[236:239], off nt
	v_lshl_add_u64 v[150:151], v[150:151], 0, s[74:75]
	s_waitcnt vmcnt(11)
	s_waitcnt lgkmcnt(0)
	v_cndmask_b32_e64 v143, 0, v143, s[8:9]
	v_pk_mul_f32 v[180:181], v[26:27], v[172:173] op_sel:[0,1]
	v_pk_mul_f32 v[192:193], v[28:29], v[172:173] op_sel:[0,1]
	v_mfma_f32_16x16x4_f32 v[110:113], v143, v50, v[110:113]
	v_pk_fma_f32 v[180:181], v[30:31], v[172:173], v[180:181] op_sel_hi:[1,0,1]
	v_pk_fma_f32 v[192:193], v[32:33], v[172:173], v[192:193] op_sel_hi:[1,0,1]
	v_pk_fma_f32 v[180:181], v[22:23], v[174:175], v[180:181] op_sel_hi:[1,0,1]
	v_pk_fma_f32 v[192:193], v[24:25], v[174:175], v[192:193] op_sel_hi:[1,0,1]
	v_mfma_f32_16x16x4_f32 v[106:109], v143, v51, v[106:109]
	v_pk_fma_f32 v[180:181], v[18:19], v[174:175], v[180:181] op_sel:[0,1,0]
	v_pk_fma_f32 v[192:193], v[20:21], v[174:175], v[192:193] op_sel:[0,1,0]
	v_pk_fma_f32 v[180:181], v[14:15], v[232:233], v[180:181] op_sel_hi:[1,0,1]
	v_pk_fma_f32 v[192:193], v[16:17], v[232:233], v[192:193] op_sel_hi:[1,0,1]
	v_mfma_f32_16x16x4_f32 v[102:105], v143, v52, v[102:105]
	v_pk_fma_f32 v[180:181], v[10:11], v[232:233], v[180:181] op_sel:[0,1,0]
	v_pk_fma_f32 v[192:193], v[12:13], v[232:233], v[192:193] op_sel:[0,1,0]
	v_pk_fma_f32 v[180:181], v[6:7], v[234:235], v[180:181] op_sel_hi:[1,0,1]
	v_pk_fma_f32 v[192:193], v[8:9], v[234:235], v[192:193] op_sel_hi:[1,0,1]
	v_mfma_f32_16x16x4_f32 v[98:101], v143, v53, v[98:101]
	v_pk_fma_f32 v[180:181], v[2:3], v[234:235], v[180:181] op_sel:[0,1,0]
	v_pk_fma_f32 v[192:193], v[4:5], v[234:235], v[192:193] op_sel:[0,1,0]
	v_pk_mul_f32 v[180:181], v[146:147], v[180:181]
	v_pk_mul_f32 v[192:193], v[146:147], v[192:193]
	v_pk_fma_f32 v[236:237], v[144:145], v[50:51], v[180:181]
	v_pk_fma_f32 v[238:239], v[144:145], v[52:53], v[192:193]
	global_store_dwordx4 v[150:151], v[236:239], off nt
	v_lshl_add_u64 v[150:151], v[150:151], 0, s[74:75]
	s_nop 7
	s_nop 3
	s_branch .LBB0_618
	s_nop 0
	s_nop 0
	s_nop 0
	s_nop 0
	s_nop 0
	s_nop 0
	s_nop 0
	s_nop 0
	s_nop 0
	s_nop 0
	s_nop 0
	s_nop 0
	s_nop 0
	s_nop 0
	s_nop 0
	s_nop 0
	s_nop 0
	s_nop 0
	s_nop 0
	s_nop 0
	s_nop 0
	s_nop 0
	s_nop 0
	s_nop 0
	s_nop 0
	s_nop 0
	s_nop 0
	s_nop 0
	s_nop 0
	s_nop 0
	s_nop 0
	s_nop 0
	s_nop 0
	s_nop 0
	s_nop 0
	s_nop 0
	s_nop 0
	s_nop 0
	s_nop 0
	s_nop 0
	s_nop 0
	s_nop 0
	s_nop 0
	s_nop 0
	s_nop 0
	s_nop 0
	s_nop 0
	s_nop 0
	s_nop 0
	s_nop 0
	s_nop 0
	s_nop 0
	s_nop 0
	s_nop 0
	s_nop 0
	s_nop 0
	s_nop 0
	s_nop 0
	s_nop 0
	s_nop 0
	s_nop 0

; #define LAS __attribute__((address_space(3)))
; #define RS_LOAD(dst, it0) do { _Pragma("unroll") for (int u = 0; u < 8; ++u) dst[u] = __builtin_nontemporal_load((const f32x4*)(S0 + (size_t)(4 * ((it0) + u)) * DV)); } while (0)
; __device__ __forceinline__ void ret_sample_item(Frame& F, int item) {
;     const int b = item >> 3, h = item & 7, w = F.wave, lane = F.lane, fr = lane & 15, fq = lane >> 4, tid = F.tid;
;     const float gam = 1.0f - exp2f(-5.0f - (float)h);
;     const float g7 = exp2f(7.0f * log2f(gam)), g8 = g7 * gam;
;     ...
;     f32x4 v4[8];
; #pragma unroll
;     for (int m = 0; m < 8; ++m) v4[m] = *(const LAS f32x4*)(vs + m * 512 + e4);
;     f32x4 oacc[4];
; #pragma unroll
;     for (int i = 0; i < 4; ++i) oacc[i] = (f32x4){0.f, 0.f, 0.f, 0.f};
;     ...
;     for (int it0 = 0; it0 < 64; it0 += 16) {
;         RS_LOAD(sb, it0 + 8);
;         RS_PROC(sa, it0);
;         { const int itn = it0 + 16 < 64 ? it0 + 16 : it0; RS_LOAD(sa, itn); }
;         RS_PROC(sb, it0 + 8);
;     }
.LBB0_643:
	s_or_b64 exec, exec, s[58:59]
	v_cvt_f32_ubyte0_e32 v2, s10
	v_sub_f32_e32 v2, 0xc0a00000, v2
	v_cmp_gt_f32_e32 vcc, s75, v2
	s_and_b64 s[58:59], vcc, exec
	s_cselect_b32 s10, 0xffffffc0, 0
	v_cndmask_b32_e32 v3, 0, v169, vcc
	v_add_f32_e32 v2, v2, v3
	v_exp_f32_e32 v2, v2
	s_waitcnt lgkmcnt(0)
	s_barrier
	v_ldexp_f32 v2, v2, s10
	v_sub_f32_e32 v138, 1.0, v2
	v_cmp_gt_f32_e32 vcc, s76, v138
	s_and_b64 s[58:59], vcc, exec
	s_cselect_b32 s10, 32, 0
	v_ldexp_f32 v3, v138, s10
	v_log_f32_e32 v3, v3
	v_cndmask_b32_e32 v2, 0, v170, vcc
	v_mov_b32_e32 v98, 0
	s_mov_b32 s10, 0
	v_sub_f32_e32 v2, v3, v2
	v_mul_f32_e32 v3, 0x40e00000, v2
	v_cmp_gt_f32_e32 vcc, s75, v3
	s_and_b64 s[58:59], vcc, exec
	s_cselect_b32 s18, 0xffffffc0, 0
	v_cndmask_b32_e32 v3, 0, v169, vcc
	v_fmac_f32_e32 v3, 0x40e00000, v2
	v_exp_f32_e32 v2, v3
	v_mov_b64_e32 v[148:149], v[130:131]
	v_mov_b64_e32 v[150:151], v[128:129]
	v_mov_b32_e32 v171, v161
	v_ldexp_f32 v140, v2, s18
	ds_read_b128 v[30:33], v139 offset:16512
	ds_read_b128 v[26:29], v139 offset:18560
	ds_read_b128 v[22:25], v139 offset:20608
	ds_read_b128 v[18:21], v139 offset:22656
	ds_read_b128 v[14:17], v139 offset:24704
	ds_read_b128 v[10:13], v139 offset:26752
	ds_read_b128 v[6:9], v139 offset:28800
	ds_read_b128 v[2:5], v139 offset:30848
	v_mul_f32_e32 v142, v138, v140
	v_mov_b32_e32 v144, v142
	v_mov_b32_e32 v145, v142
	v_mov_b32_e32 v146, v140
	v_mov_b32_e32 v147, v140
	v_mov_b32_e32 v172, v160
	v_mov_b32_e32 v99, v98
	v_mov_b32_e32 v100, v98
	v_mov_b32_e32 v101, v98
	v_mov_b32_e32 v102, v98
	v_mov_b32_e32 v103, v98
	v_mov_b32_e32 v104, v98
	v_mov_b32_e32 v105, v98
	v_mov_b32_e32 v106, v98
	v_mov_b32_e32 v107, v98
	v_mov_b32_e32 v108, v98
	v_mov_b32_e32 v109, v98
	v_mov_b32_e32 v110, v98
	v_mov_b32_e32 v111, v98
	v_mov_b32_e32 v112, v98
	v_mov_b32_e32 v113, v98
	v_lshl_add_u64 v[148:149], v[130:131], 0, v[122:123]
	v_lshl_add_u64 v[150:151], v[128:129], 0, v[122:123]
	s_mov_b32 s58, 0x10000
	s_mov_b32 s59, 0
	v_add_co_u32_e32 v150, vcc, 0x5878000, v150
	v_lshl_add_u64 v[148:149], v[148:149], 0, s[58:59]
	s_mov_b32 s58, 0x2000
	v_addc_co_u32_e32 v151, vcc, 0, v151, vcc
	ds_read_b32 v141, v160
	ds_read_b128 v[114:117], v161
	ds_read_b128 v[176:179], v161 offset:16
	global_load_dwordx4 v[58:61], v[148:149], off nt
	v_lshl_add_u64 v[148:149], v[148:149], 0, s[58:59]
	global_load_dwordx4 v[66:69], v[148:149], off nt
	v_lshl_add_u64 v[148:149], v[148:149], 0, s[58:59]
	global_load_dwordx4 v[74:77], v[148:149], off nt
	v_lshl_add_u64 v[148:149], v[148:149], 0, s[58:59]
	global_load_dwordx4 v[78:81], v[148:149], off nt
	v_lshl_add_u64 v[148:149], v[148:149], 0, s[58:59]
	ds_read_b32 v143, v160 offset:16
	ds_read_b128 v[172:175], v161 offset:128
	ds_read_b128 v[232:235], v161 offset:144
	s_waitcnt vmcnt(11)
	s_waitcnt lgkmcnt(3)
	v_cndmask_b32_e64 v141, 0, v141, s[6:7]
	v_pk_mul_f32 v[180:181], v[26:27], v[114:115] op_sel:[0,1]
	v_pk_mul_f32 v[192:193], v[28:29], v[114:115] op_sel:[0,1]
	v_mfma_f32_16x16x4_f32 v[110:113], v141, v70, v[110:113]
	v_pk_fma_f32 v[180:181], v[30:31], v[114:115], v[180:181] op_sel_hi:[1,0,1]
	v_pk_fma_f32 v[192:193], v[32:33], v[114:115], v[192:193] op_sel_hi:[1,0,1]
	v_pk_fma_f32 v[180:181], v[22:23], v[116:117], v[180:181] op_sel_hi:[1,0,1]
	v_pk_fma_f32 v[192:193], v[24:25], v[116:117], v[192:193] op_sel_hi:[1,0,1]
	v_mfma_f32_16x16x4_f32 v[106:109], v141, v71, v[106:109]
	v_pk_fma_f32 v[180:181], v[18:19], v[116:117], v[180:181] op_sel:[0,1,0]
	v_pk_fma_f32 v[192:193], v[20:21], v[116:117], v[192:193] op_sel:[0,1,0]
	v_pk_fma_f32 v[180:181], v[14:15], v[176:177], v[180:181] op_sel_hi:[1,0,1]
	v_pk_fma_f32 v[192:193], v[16:17], v[176:177], v[192:193] op_sel_hi:[1,0,1]
	v_mfma_f32_16x16x4_f32 v[102:105], v141, v72, v[102:105]
	v_pk_fma_f32 v[180:181], v[10:11], v[176:177], v[180:181] op_sel:[0,1,0]
	v_pk_fma_f32 v[192:193], v[12:13], v[176:177], v[192:193] op_sel:[0,1,0]
	v_pk_fma_f32 v[180:181], v[6:7], v[178:179], v[180:181] op_sel_hi:[1,0,1]
	v_pk_fma_f32 v[192:193], v[8:9], v[178:179], v[192:193] op_sel_hi:[1,0,1]
	v_mfma_f32_16x16x4_f32 v[98:101], v141, v73, v[98:101]
	v_pk_fma_f32 v[180:181], v[2:3], v[178:179], v[180:181] op_sel:[0,1,0]
	v_pk_fma_f32 v[192:193], v[4:5], v[178:179], v[192:193] op_sel:[0,1,0]
	v_pk_mul_f32 v[180:181], v[146:147], v[180:181]
	v_pk_mul_f32 v[192:193], v[146:147], v[192:193]
	v_pk_fma_f32 v[236:237], v[144:145], v[70:71], v[180:181]
	v_pk_fma_f32 v[238:239], v[144:145], v[72:73], v[192:193]
	global_store_dwordx4 v[150:151], v[236:239], off nt
	v_lshl_add_u64 v[150:151], v[150:151], 0, s[58:59]
	global_load_dwordx4 v[70:73], v[148:149], off nt
	v_lshl_add_u64 v[148:149], v[148:149], 0, s[58:59]
	ds_read_b32 v141, v160 offset:32
	ds_read_b128 v[114:117], v161 offset:256
	ds_read_b128 v[176:179], v161 offset:272
	s_waitcnt vmcnt(12)
	s_waitcnt lgkmcnt(3)
; #define RS_LOAD(dst, it0) do { _Pragma("unroll") for (int u = 0; u < 8; ++u) dst[u] = __builtin_nontemporal_load((const f32x4*)(S0 + (size_t)(4 * ((it0) + u)) * DV)); } while (0)
; __device__ __forceinline__ void ret_sample_item(Frame& F, int item) {
;     ...
;     for (int it0 = 0; it0 < 64; it0 += 16) {
;         RS_LOAD(sb, it0 + 8);
;         RS_PROC(sa, it0);
;         { const int itn = it0 + 16 < 64 ? it0 + 16 : it0; RS_LOAD(sa, itn); }
;         RS_PROC(sb, it0 + 8);
;     }
	v_cndmask_b32_e64 v143, 0, v143, s[6:7]
	v_pk_mul_f32 v[180:181], v[26:27], v[172:173] op_sel:[0,1]
	v_pk_mul_f32 v[192:193], v[28:29], v[172:173] op_sel:[0,1]
	v_mfma_f32_16x16x4_f32 v[110:113], v143, v62, v[110:113]
	v_pk_fma_f32 v[180:181], v[30:31], v[172:173], v[180:181] op_sel_hi:[1,0,1]
	v_pk_fma_f32 v[192:193], v[32:33], v[172:173], v[192:193] op_sel_hi:[1,0,1]
	v_pk_fma_f32 v[180:181], v[22:23], v[174:175], v[180:181] op_sel_hi:[1,0,1]
	v_pk_fma_f32 v[192:193], v[24:25], v[174:175], v[192:193] op_sel_hi:[1,0,1]
	v_mfma_f32_16x16x4_f32 v[106:109], v143, v63, v[106:109]
	v_pk_fma_f32 v[180:181], v[18:19], v[174:175], v[180:181] op_sel:[0,1,0]
	v_pk_fma_f32 v[192:193], v[20:21], v[174:175], v[192:193] op_sel:[0,1,0]
	v_pk_fma_f32 v[180:181], v[14:15], v[232:233], v[180:181] op_sel_hi:[1,0,1]
	v_pk_fma_f32 v[192:193], v[16:17], v[232:233], v[192:193] op_sel_hi:[1,0,1]
	v_mfma_f32_16x16x4_f32 v[102:105], v143, v64, v[102:105]
	v_pk_fma_f32 v[180:181], v[10:11], v[232:233], v[180:181] op_sel:[0,1,0]
	v_pk_fma_f32 v[192:193], v[12:13], v[232:233], v[192:193] op_sel:[0,1,0]
	v_pk_fma_f32 v[180:181], v[6:7], v[234:235], v[180:181] op_sel_hi:[1,0,1]
	v_pk_fma_f32 v[192:193], v[8:9], v[234:235], v[192:193] op_sel_hi:[1,0,1]
	v_mfma_f32_16x16x4_f32 v[98:101], v143, v65, v[98:101]
	v_pk_fma_f32 v[180:181], v[2:3], v[234:235], v[180:181] op_sel:[0,1,0]
	v_pk_fma_f32 v[192:193], v[4:5], v[234:235], v[192:193] op_sel:[0,1,0]
	v_pk_mul_f32 v[180:181], v[146:147], v[180:181]
	v_pk_mul_f32 v[192:193], v[146:147], v[192:193]
	v_pk_fma_f32 v[236:237], v[144:145], v[62:63], v[180:181]
	v_pk_fma_f32 v[238:239], v[144:145], v[64:65], v[192:193]
	global_store_dwordx4 v[150:151], v[236:239], off nt
	v_lshl_add_u64 v[150:151], v[150:151], 0, s[58:59]
	global_load_dwordx4 v[62:65], v[148:149], off nt
	v_lshl_add_u64 v[148:149], v[148:149], 0, s[58:59]
	ds_read_b32 v143, v160 offset:48
	ds_read_b128 v[172:175], v161 offset:384
	ds_read_b128 v[232:235], v161 offset:400
	s_waitcnt vmcnt(13)
	s_waitcnt lgkmcnt(3)
	v_cndmask_b32_e64 v141, 0, v141, s[6:7]
	v_pk_mul_f32 v[180:181], v[26:27], v[114:115] op_sel:[0,1]
	v_pk_mul_f32 v[192:193], v[28:29], v[114:115] op_sel:[0,1]
	v_mfma_f32_16x16x4_f32 v[110:113], v141, v54, v[110:113]
	v_pk_fma_f32 v[180:181], v[30:31], v[114:115], v[180:181] op_sel_hi:[1,0,1]
	v_pk_fma_f32 v[192:193], v[32:33], v[114:115], v[192:193] op_sel_hi:[1,0,1]
	v_pk_fma_f32 v[180:181], v[22:23], v[116:117], v[180:181] op_sel_hi:[1,0,1]
	v_pk_fma_f32 v[192:193], v[24:25], v[116:117], v[192:193] op_sel_hi:[1,0,1]
	v_mfma_f32_16x16x4_f32 v[106:109], v141, v55, v[106:109]
	v_pk_fma_f32 v[180:181], v[18:19], v[116:117], v[180:181] op_sel:[0,1,0]
	v_pk_fma_f32 v[192:193], v[20:21], v[116:117], v[192:193] op_sel:[0,1,0]
	v_pk_fma_f32 v[180:181], v[14:15], v[176:177], v[180:181] op_sel_hi:[1,0,1]
	v_pk_fma_f32 v[192:193], v[16:17], v[176:177], v[192:193] op_sel_hi:[1,0,1]
	v_mfma_f32_16x16x4_f32 v[102:105], v141, v56, v[102:105]
	v_pk_fma_f32 v[180:181], v[10:11], v[176:177], v[180:181] op_sel:[0,1,0]
	v_pk_fma_f32 v[192:193], v[12:13], v[176:177], v[192:193] op_sel:[0,1,0]
	v_pk_fma_f32 v[180:181], v[6:7], v[178:179], v[180:181] op_sel_hi:[1,0,1]
	v_pk_fma_f32 v[192:193], v[8:9], v[178:179], v[192:193] op_sel_hi:[1,0,1]
	v_mfma_f32_16x16x4_f32 v[98:101], v141, v57, v[98:101]
	v_pk_fma_f32 v[180:181], v[2:3], v[178:179], v[180:181] op_sel:[0,1,0]
	v_pk_fma_f32 v[192:193], v[4:5], v[178:179], v[192:193] op_sel:[0,1,0]
	v_pk_mul_f32 v[180:181], v[146:147], v[180:181]
	v_pk_mul_f32 v[192:193], v[146:147], v[192:193]
	v_pk_fma_f32 v[236:237], v[144:145], v[54:55], v[180:181]
	v_pk_fma_f32 v[238:239], v[144:145], v[56:57], v[192:193]
	global_store_dwordx4 v[150:151], v[236:239], off nt
	v_lshl_add_u64 v[150:151], v[150:151], 0, s[58:59]
	global_load_dwordx4 v[54:57], v[148:149], off nt
	v_lshl_add_u64 v[148:149], v[148:149], 0, s[58:59]
	ds_read_b32 v141, v160 offset:64
	ds_read_b128 v[114:117], v161 offset:512
	ds_read_b128 v[176:179], v161 offset:528
	s_waitcnt vmcnt(14)
	s_waitcnt lgkmcnt(3)
	v_cndmask_b32_e64 v143, 0, v143, s[6:7]
	v_pk_mul_f32 v[180:181], v[26:27], v[172:173] op_sel:[0,1]
	v_pk_mul_f32 v[192:193], v[28:29], v[172:173] op_sel:[0,1]
	v_mfma_f32_16x16x4_f32 v[110:113], v143, v50, v[110:113]
	v_pk_fma_f32 v[180:181], v[30:31], v[172:173], v[180:181] op_sel_hi:[1,0,1]
	v_pk_fma_f32 v[192:193], v[32:33], v[172:173], v[192:193] op_sel_hi:[1,0,1]
	v_pk_fma_f32 v[180:181], v[22:23], v[174:175], v[180:181] op_sel_hi:[1,0,1]
	v_pk_fma_f32 v[192:193], v[24:25], v[174:175], v[192:193] op_sel_hi:[1,0,1]
	v_mfma_f32_16x16x4_f32 v[106:109], v143, v51, v[106:109]
	v_pk_fma_f32 v[180:181], v[18:19], v[174:175], v[180:181] op_sel:[0,1,0]
	v_pk_fma_f32 v[192:193], v[20:21], v[174:175], v[192:193] op_sel:[0,1,0]
	v_pk_fma_f32 v[180:181], v[14:15], v[232:233], v[180:181] op_sel_hi:[1,0,1]
	v_pk_fma_f32 v[192:193], v[16:17], v[232:233], v[192:193] op_sel_hi:[1,0,1]
	v_mfma_f32_16x16x4_f32 v[102:105], v143, v52, v[102:105]
	v_pk_fma_f32 v[180:181], v[10:11], v[232:233], v[180:181] op_sel:[0,1,0]
	v_pk_fma_f32 v[192:193], v[12:13], v[232:233], v[192:193] op_sel:[0,1,0]
	v_pk_fma_f32 v[180:181], v[6:7], v[234:235], v[180:181] op_sel_hi:[1,0,1]
	v_pk_fma_f32 v[192:193], v[8:9], v[234:235], v[192:193] op_sel_hi:[1,0,1]
	v_mfma_f32_16x16x4_f32 v[98:101], v143, v53, v[98:101]
	v_pk_fma_f32 v[180:181], v[2:3], v[234:235], v[180:181] op_sel:[0,1,0]
	v_pk_fma_f32 v[192:193], v[4:5], v[234:235], v[192:193] op_sel:[0,1,0]
	v_pk_mul_f32 v[180:181], v[146:147], v[180:181]
	v_pk_mul_f32 v[192:193], v[146:147], v[192:193]
	v_pk_fma_f32 v[236:237], v[144:145], v[50:51], v[180:181]
	v_pk_fma_f32 v[238:239], v[144:145], v[52:53], v[192:193]
	global_store_dwordx4 v[150:151], v[236:239], off nt
	v_lshl_add_u64 v[150:151], v[150:151], 0, s[58:59]
	global_load_dwordx4 v[50:53], v[148:149], off nt
	v_lshl_add_u64 v[148:149], v[148:149], 0, s[58:59]
	ds_read_b32 v143, v160 offset:80
	ds_read_b128 v[172:175], v161 offset:640
	ds_read_b128 v[232:235], v161 offset:656
	s_waitcnt vmcnt(15)
; #define RS_LOAD(dst, it0) do { _Pragma("unroll") for (int u = 0; u < 8; ++u) dst[u] = __builtin_nontemporal_load((const f32x4*)(S0 + (size_t)(4 * ((it0) + u)) * DV)); } while (0)
; __device__ __forceinline__ void ret_sample_item(Frame& F, int item) {
;     ...
;     for (int it0 = 0; it0 < 64; it0 += 16) {
;         RS_LOAD(sb, it0 + 8);
;         RS_PROC(sa, it0);
;         { const int itn = it0 + 16 < 64 ? it0 + 16 : it0; RS_LOAD(sa, itn); }
;         RS_PROC(sb, it0 + 8);
;     }
	s_waitcnt lgkmcnt(3)
	v_cndmask_b32_e64 v141, 0, v141, s[6:7]
	v_pk_mul_f32 v[180:181], v[26:27], v[114:115] op_sel:[0,1]
	v_pk_mul_f32 v[192:193], v[28:29], v[114:115] op_sel:[0,1]
	v_mfma_f32_16x16x4_f32 v[110:113], v141, v46, v[110:113]
	v_pk_fma_f32 v[180:181], v[30:31], v[114:115], v[180:181] op_sel_hi:[1,0,1]
	v_pk_fma_f32 v[192:193], v[32:33], v[114:115], v[192:193] op_sel_hi:[1,0,1]
	v_pk_fma_f32 v[180:181], v[22:23], v[116:117], v[180:181] op_sel_hi:[1,0,1]
	v_pk_fma_f32 v[192:193], v[24:25], v[116:117], v[192:193] op_sel_hi:[1,0,1]
	v_mfma_f32_16x16x4_f32 v[106:109], v141, v47, v[106:109]
	v_pk_fma_f32 v[180:181], v[18:19], v[116:117], v[180:181] op_sel:[0,1,0]
	v_pk_fma_f32 v[192:193], v[20:21], v[116:117], v[192:193] op_sel:[0,1,0]
	v_pk_fma_f32 v[180:181], v[14:15], v[176:177], v[180:181] op_sel_hi:[1,0,1]
	v_pk_fma_f32 v[192:193], v[16:17], v[176:177], v[192:193] op_sel_hi:[1,0,1]
	v_mfma_f32_16x16x4_f32 v[102:105], v141, v48, v[102:105]
	v_pk_fma_f32 v[180:181], v[10:11], v[176:177], v[180:181] op_sel:[0,1,0]
	v_pk_fma_f32 v[192:193], v[12:13], v[176:177], v[192:193] op_sel:[0,1,0]
	v_pk_fma_f32 v[180:181], v[6:7], v[178:179], v[180:181] op_sel_hi:[1,0,1]
	v_pk_fma_f32 v[192:193], v[8:9], v[178:179], v[192:193] op_sel_hi:[1,0,1]
	v_mfma_f32_16x16x4_f32 v[98:101], v141, v49, v[98:101]
	v_pk_fma_f32 v[180:181], v[2:3], v[178:179], v[180:181] op_sel:[0,1,0]
	v_pk_fma_f32 v[192:193], v[4:5], v[178:179], v[192:193] op_sel:[0,1,0]
	v_pk_mul_f32 v[180:181], v[146:147], v[180:181]
	v_pk_mul_f32 v[192:193], v[146:147], v[192:193]
	v_pk_fma_f32 v[236:237], v[144:145], v[46:47], v[180:181]
	v_pk_fma_f32 v[238:239], v[144:145], v[48:49], v[192:193]
	global_store_dwordx4 v[150:151], v[236:239], off nt
	v_lshl_add_u64 v[150:151], v[150:151], 0, s[58:59]
	global_load_dwordx4 v[46:49], v[148:149], off nt
	v_lshl_add_u64 v[148:149], v[148:149], 0, s[58:59]
	ds_read_b32 v141, v160 offset:96
	ds_read_b128 v[114:117], v161 offset:768
	ds_read_b128 v[176:179], v161 offset:784
	s_waitcnt vmcnt(16)
	s_waitcnt lgkmcnt(3)
	v_cndmask_b32_e64 v143, 0, v143, s[6:7]
	v_pk_mul_f32 v[180:181], v[26:27], v[172:173] op_sel:[0,1]
	v_pk_mul_f32 v[192:193], v[28:29], v[172:173] op_sel:[0,1]
	v_mfma_f32_16x16x4_f32 v[110:113], v143, v42, v[110:113]
	v_pk_fma_f32 v[180:181], v[30:31], v[172:173], v[180:181] op_sel_hi:[1,0,1]
	v_pk_fma_f32 v[192:193], v[32:33], v[172:173], v[192:193] op_sel_hi:[1,0,1]
	v_pk_fma_f32 v[180:181], v[22:23], v[174:175], v[180:181] op_sel_hi:[1,0,1]
	v_pk_fma_f32 v[192:193], v[24:25], v[174:175], v[192:193] op_sel_hi:[1,0,1]
	v_mfma_f32_16x16x4_f32 v[106:109], v143, v43, v[106:109]
	v_pk_fma_f32 v[180:181], v[18:19], v[174:175], v[180:181] op_sel:[0,1,0]
	v_pk_fma_f32 v[192:193], v[20:21], v[174:175], v[192:193] op_sel:[0,1,0]
	v_pk_fma_f32 v[180:181], v[14:15], v[232:233], v[180:181] op_sel_hi:[1,0,1]
	v_pk_fma_f32 v[192:193], v[16:17], v[232:233], v[192:193] op_sel_hi:[1,0,1]
	v_mfma_f32_16x16x4_f32 v[102:105], v143, v44, v[102:105]
	v_pk_fma_f32 v[180:181], v[10:11], v[232:233], v[180:181] op_sel:[0,1,0]
	v_pk_fma_f32 v[192:193], v[12:13], v[232:233], v[192:193] op_sel:[0,1,0]
	v_pk_fma_f32 v[180:181], v[6:7], v[234:235], v[180:181] op_sel_hi:[1,0,1]
	v_pk_fma_f32 v[192:193], v[8:9], v[234:235], v[192:193] op_sel_hi:[1,0,1]
	v_mfma_f32_16x16x4_f32 v[98:101], v143, v45, v[98:101]
	v_pk_fma_f32 v[180:181], v[2:3], v[234:235], v[180:181] op_sel:[0,1,0]
	v_pk_fma_f32 v[192:193], v[4:5], v[234:235], v[192:193] op_sel:[0,1,0]
	v_pk_mul_f32 v[180:181], v[146:147], v[180:181]
	v_pk_mul_f32 v[192:193], v[146:147], v[192:193]
	v_pk_fma_f32 v[236:237], v[144:145], v[42:43], v[180:181]
	v_pk_fma_f32 v[238:239], v[144:145], v[44:45], v[192:193]
	global_store_dwordx4 v[150:151], v[236:239], off nt
	v_lshl_add_u64 v[150:151], v[150:151], 0, s[58:59]
	global_load_dwordx4 v[42:45], v[148:149], off nt
	v_lshl_add_u64 v[148:149], v[148:149], 0, s[58:59]
	ds_read_b32 v143, v160 offset:112
	ds_read_b128 v[172:175], v161 offset:896
	ds_read_b128 v[232:235], v161 offset:912
	s_waitcnt vmcnt(17)
	s_waitcnt lgkmcnt(3)
	v_cndmask_b32_e64 v141, 0, v141, s[6:7]
	v_pk_mul_f32 v[180:181], v[26:27], v[114:115] op_sel:[0,1]
	v_pk_mul_f32 v[192:193], v[28:29], v[114:115] op_sel:[0,1]
	v_mfma_f32_16x16x4_f32 v[110:113], v141, v38, v[110:113]
	v_pk_fma_f32 v[180:181], v[30:31], v[114:115], v[180:181] op_sel_hi:[1,0,1]
	v_pk_fma_f32 v[192:193], v[32:33], v[114:115], v[192:193] op_sel_hi:[1,0,1]
	v_pk_fma_f32 v[180:181], v[22:23], v[116:117], v[180:181] op_sel_hi:[1,0,1]
	v_pk_fma_f32 v[192:193], v[24:25], v[116:117], v[192:193] op_sel_hi:[1,0,1]
	v_mfma_f32_16x16x4_f32 v[106:109], v141, v39, v[106:109]
	v_pk_fma_f32 v[180:181], v[18:19], v[116:117], v[180:181] op_sel:[0,1,0]
	v_pk_fma_f32 v[192:193], v[20:21], v[116:117], v[192:193] op_sel:[0,1,0]
	v_pk_fma_f32 v[180:181], v[14:15], v[176:177], v[180:181] op_sel_hi:[1,0,1]
	v_pk_fma_f32 v[192:193], v[16:17], v[176:177], v[192:193] op_sel_hi:[1,0,1]
	v_mfma_f32_16x16x4_f32 v[102:105], v141, v40, v[102:105]
	v_pk_fma_f32 v[180:181], v[10:11], v[176:177], v[180:181] op_sel:[0,1,0]
	v_pk_fma_f32 v[192:193], v[12:13], v[176:177], v[192:193] op_sel:[0,1,0]
	v_pk_fma_f32 v[180:181], v[6:7], v[178:179], v[180:181] op_sel_hi:[1,0,1]
	v_pk_fma_f32 v[192:193], v[8:9], v[178:179], v[192:193] op_sel_hi:[1,0,1]
	v_mfma_f32_16x16x4_f32 v[98:101], v141, v41, v[98:101]
	v_pk_fma_f32 v[180:181], v[2:3], v[178:179], v[180:181] op_sel:[0,1,0]
	v_pk_fma_f32 v[192:193], v[4:5], v[178:179], v[192:193] op_sel:[0,1,0]
	v_pk_mul_f32 v[180:181], v[146:147], v[180:181]
	v_pk_mul_f32 v[192:193], v[146:147], v[192:193]
	v_pk_fma_f32 v[236:237], v[144:145], v[38:39], v[180:181]
	v_pk_fma_f32 v[238:239], v[144:145], v[40:41], v[192:193]
	global_store_dwordx4 v[150:151], v[236:239], off nt
	v_lshl_add_u64 v[150:151], v[150:151], 0, s[58:59]
	global_load_dwordx4 v[38:41], v[148:149], off nt
	v_lshl_add_u64 v[148:149], v[148:149], 0, s[58:59]
	ds_read_b32 v141, v160 offset:128
	ds_read_b128 v[114:117], v161 offset:1024
	ds_read_b128 v[176:179], v161 offset:1040
	s_waitcnt vmcnt(18)
; #define RS_LOAD(dst, it0) do { _Pragma("unroll") for (int u = 0; u < 8; ++u) dst[u] = __builtin_nontemporal_load((const f32x4*)(S0 + (size_t)(4 * ((it0) + u)) * DV)); } while (0)
; __device__ __forceinline__ void ret_sample_item(Frame& F, int item) {
;     ...
;     for (int it0 = 0; it0 < 64; it0 += 16) {
;         RS_LOAD(sb, it0 + 8);
;         RS_PROC(sa, it0);
;         { const int itn = it0 + 16 < 64 ? it0 + 16 : it0; RS_LOAD(sa, itn); }
;         RS_PROC(sb, it0 + 8);
;     }
	s_waitcnt lgkmcnt(3)
	v_cndmask_b32_e64 v143, 0, v143, s[6:7]
	v_pk_mul_f32 v[180:181], v[26:27], v[172:173] op_sel:[0,1]
	v_pk_mul_f32 v[192:193], v[28:29], v[172:173] op_sel:[0,1]
	v_mfma_f32_16x16x4_f32 v[110:113], v143, v34, v[110:113]
	v_pk_fma_f32 v[180:181], v[30:31], v[172:173], v[180:181] op_sel_hi:[1,0,1]
	v_pk_fma_f32 v[192:193], v[32:33], v[172:173], v[192:193] op_sel_hi:[1,0,1]
	v_pk_fma_f32 v[180:181], v[22:23], v[174:175], v[180:181] op_sel_hi:[1,0,1]
	v_pk_fma_f32 v[192:193], v[24:25], v[174:175], v[192:193] op_sel_hi:[1,0,1]
	v_mfma_f32_16x16x4_f32 v[106:109], v143, v35, v[106:109]
	v_pk_fma_f32 v[180:181], v[18:19], v[174:175], v[180:181] op_sel:[0,1,0]
	v_pk_fma_f32 v[192:193], v[20:21], v[174:175], v[192:193] op_sel:[0,1,0]
	v_pk_fma_f32 v[180:181], v[14:15], v[232:233], v[180:181] op_sel_hi:[1,0,1]
	v_pk_fma_f32 v[192:193], v[16:17], v[232:233], v[192:193] op_sel_hi:[1,0,1]
	v_mfma_f32_16x16x4_f32 v[102:105], v143, v36, v[102:105]
	v_pk_fma_f32 v[180:181], v[10:11], v[232:233], v[180:181] op_sel:[0,1,0]
	v_pk_fma_f32 v[192:193], v[12:13], v[232:233], v[192:193] op_sel:[0,1,0]
	v_pk_fma_f32 v[180:181], v[6:7], v[234:235], v[180:181] op_sel_hi:[1,0,1]
	v_pk_fma_f32 v[192:193], v[8:9], v[234:235], v[192:193] op_sel_hi:[1,0,1]
	v_mfma_f32_16x16x4_f32 v[98:101], v143, v37, v[98:101]
	v_pk_fma_f32 v[180:181], v[2:3], v[234:235], v[180:181] op_sel:[0,1,0]
	v_pk_fma_f32 v[192:193], v[4:5], v[234:235], v[192:193] op_sel:[0,1,0]
	v_pk_mul_f32 v[180:181], v[146:147], v[180:181]
	v_pk_mul_f32 v[192:193], v[146:147], v[192:193]
	v_pk_fma_f32 v[236:237], v[144:145], v[34:35], v[180:181]
	v_pk_fma_f32 v[238:239], v[144:145], v[36:37], v[192:193]
	global_store_dwordx4 v[150:151], v[236:239], off nt
	v_lshl_add_u64 v[150:151], v[150:151], 0, s[58:59]
	global_load_dwordx4 v[34:37], v[148:149], off nt
	v_lshl_add_u64 v[148:149], v[148:149], 0, s[58:59]
	ds_read_b32 v143, v160 offset:144
	ds_read_b128 v[172:175], v161 offset:1152
	ds_read_b128 v[232:235], v161 offset:1168
	s_waitcnt vmcnt(19)
	s_waitcnt lgkmcnt(3)
	v_cndmask_b32_e64 v141, 0, v141, s[6:7]
	v_pk_mul_f32 v[180:181], v[26:27], v[114:115] op_sel:[0,1]
	v_pk_mul_f32 v[192:193], v[28:29], v[114:115] op_sel:[0,1]
	v_mfma_f32_16x16x4_f32 v[110:113], v141, v58, v[110:113]
	v_pk_fma_f32 v[180:181], v[30:31], v[114:115], v[180:181] op_sel_hi:[1,0,1]
	v_pk_fma_f32 v[192:193], v[32:33], v[114:115], v[192:193] op_sel_hi:[1,0,1]
	v_pk_fma_f32 v[180:181], v[22:23], v[116:117], v[180:181] op_sel_hi:[1,0,1]
	v_pk_fma_f32 v[192:193], v[24:25], v[116:117], v[192:193] op_sel_hi:[1,0,1]
	v_mfma_f32_16x16x4_f32 v[106:109], v141, v59, v[106:109]
	v_pk_fma_f32 v[180:181], v[18:19], v[116:117], v[180:181] op_sel:[0,1,0]
	v_pk_fma_f32 v[192:193], v[20:21], v[116:117], v[192:193] op_sel:[0,1,0]
	v_pk_fma_f32 v[180:181], v[14:15], v[176:177], v[180:181] op_sel_hi:[1,0,1]
	v_pk_fma_f32 v[192:193], v[16:17], v[176:177], v[192:193] op_sel_hi:[1,0,1]
	v_mfma_f32_16x16x4_f32 v[102:105], v141, v60, v[102:105]
	v_pk_fma_f32 v[180:181], v[10:11], v[176:177], v[180:181] op_sel:[0,1,0]
	v_pk_fma_f32 v[192:193], v[12:13], v[176:177], v[192:193] op_sel:[0,1,0]
	v_pk_fma_f32 v[180:181], v[6:7], v[178:179], v[180:181] op_sel_hi:[1,0,1]
	v_pk_fma_f32 v[192:193], v[8:9], v[178:179], v[192:193] op_sel_hi:[1,0,1]
	v_mfma_f32_16x16x4_f32 v[98:101], v141, v61, v[98:101]
	v_pk_fma_f32 v[180:181], v[2:3], v[178:179], v[180:181] op_sel:[0,1,0]
	v_pk_fma_f32 v[192:193], v[4:5], v[178:179], v[192:193] op_sel:[0,1,0]
	v_pk_mul_f32 v[180:181], v[146:147], v[180:181]
	v_pk_mul_f32 v[192:193], v[146:147], v[192:193]
	v_pk_fma_f32 v[236:237], v[144:145], v[58:59], v[180:181]
	v_pk_fma_f32 v[238:239], v[144:145], v[60:61], v[192:193]
	global_store_dwordx4 v[150:151], v[236:239], off nt
	v_lshl_add_u64 v[150:151], v[150:151], 0, s[58:59]
	global_load_dwordx4 v[58:61], v[148:149], off nt
	v_lshl_add_u64 v[148:149], v[148:149], 0, s[58:59]
	ds_read_b32 v141, v160 offset:160
	ds_read_b128 v[114:117], v161 offset:1280
	ds_read_b128 v[176:179], v161 offset:1296
	s_waitcnt vmcnt(20)
	s_waitcnt lgkmcnt(3)
	v_cndmask_b32_e64 v143, 0, v143, s[6:7]
	v_pk_mul_f32 v[180:181], v[26:27], v[172:173] op_sel:[0,1]
	v_pk_mul_f32 v[192:193], v[28:29], v[172:173] op_sel:[0,1]
	v_mfma_f32_16x16x4_f32 v[110:113], v143, v66, v[110:113]
	v_pk_fma_f32 v[180:181], v[30:31], v[172:173], v[180:181] op_sel_hi:[1,0,1]
	v_pk_fma_f32 v[192:193], v[32:33], v[172:173], v[192:193] op_sel_hi:[1,0,1]
	v_pk_fma_f32 v[180:181], v[22:23], v[174:175], v[180:181] op_sel_hi:[1,0,1]
	v_pk_fma_f32 v[192:193], v[24:25], v[174:175], v[192:193] op_sel_hi:[1,0,1]
	v_mfma_f32_16x16x4_f32 v[106:109], v143, v67, v[106:109]
	v_pk_fma_f32 v[180:181], v[18:19], v[174:175], v[180:181] op_sel:[0,1,0]
	v_pk_fma_f32 v[192:193], v[20:21], v[174:175], v[192:193] op_sel:[0,1,0]
	v_pk_fma_f32 v[180:181], v[14:15], v[232:233], v[180:181] op_sel_hi:[1,0,1]
	v_pk_fma_f32 v[192:193], v[16:17], v[232:233], v[192:193] op_sel_hi:[1,0,1]
	v_mfma_f32_16x16x4_f32 v[102:105], v143, v68, v[102:105]
	v_pk_fma_f32 v[180:181], v[10:11], v[232:233], v[180:181] op_sel:[0,1,0]
	v_pk_fma_f32 v[192:193], v[12:13], v[232:233], v[192:193] op_sel:[0,1,0]
	v_pk_fma_f32 v[180:181], v[6:7], v[234:235], v[180:181] op_sel_hi:[1,0,1]
	v_pk_fma_f32 v[192:193], v[8:9], v[234:235], v[192:193] op_sel_hi:[1,0,1]
	v_mfma_f32_16x16x4_f32 v[98:101], v143, v69, v[98:101]
	v_pk_fma_f32 v[180:181], v[2:3], v[234:235], v[180:181] op_sel:[0,1,0]
	v_pk_fma_f32 v[192:193], v[4:5], v[234:235], v[192:193] op_sel:[0,1,0]
	v_pk_mul_f32 v[180:181], v[146:147], v[180:181]
	v_pk_mul_f32 v[192:193], v[146:147], v[192:193]
	v_pk_fma_f32 v[236:237], v[144:145], v[66:67], v[180:181]
	v_pk_fma_f32 v[238:239], v[144:145], v[68:69], v[192:193]
	global_store_dwordx4 v[150:151], v[236:239], off nt
	v_lshl_add_u64 v[150:151], v[150:151], 0, s[58:59]
	global_load_dwordx4 v[66:69], v[148:149], off nt
	v_lshl_add_u64 v[148:149], v[148:149], 0, s[58:59]
	ds_read_b32 v143, v160 offset:176
	ds_read_b128 v[172:175], v161 offset:1408
	ds_read_b128 v[232:235], v161 offset:1424
	s_waitcnt vmcnt(21)
; #define RS_LOAD(dst, it0) do { _Pragma("unroll") for (int u = 0; u < 8; ++u) dst[u] = __builtin_nontemporal_load((const f32x4*)(S0 + (size_t)(4 * ((it0) + u)) * DV)); } while (0)
; __device__ __forceinline__ void ret_sample_item(Frame& F, int item) {
;     ...
;     for (int it0 = 0; it0 < 64; it0 += 16) {
;         RS_LOAD(sb, it0 + 8);
;         RS_PROC(sa, it0);
;         { const int itn = it0 + 16 < 64 ? it0 + 16 : it0; RS_LOAD(sa, itn); }
;         RS_PROC(sb, it0 + 8);
;     }
	s_waitcnt lgkmcnt(3)
	v_cndmask_b32_e64 v141, 0, v141, s[6:7]
	v_pk_mul_f32 v[180:181], v[26:27], v[114:115] op_sel:[0,1]
	v_pk_mul_f32 v[192:193], v[28:29], v[114:115] op_sel:[0,1]
	v_mfma_f32_16x16x4_f32 v[110:113], v141, v74, v[110:113]
	v_pk_fma_f32 v[180:181], v[30:31], v[114:115], v[180:181] op_sel_hi:[1,0,1]
	v_pk_fma_f32 v[192:193], v[32:33], v[114:115], v[192:193] op_sel_hi:[1,0,1]
	v_pk_fma_f32 v[180:181], v[22:23], v[116:117], v[180:181] op_sel_hi:[1,0,1]
	v_pk_fma_f32 v[192:193], v[24:25], v[116:117], v[192:193] op_sel_hi:[1,0,1]
	v_mfma_f32_16x16x4_f32 v[106:109], v141, v75, v[106:109]
	v_pk_fma_f32 v[180:181], v[18:19], v[116:117], v[180:181] op_sel:[0,1,0]
	v_pk_fma_f32 v[192:193], v[20:21], v[116:117], v[192:193] op_sel:[0,1,0]
	v_pk_fma_f32 v[180:181], v[14:15], v[176:177], v[180:181] op_sel_hi:[1,0,1]
	v_pk_fma_f32 v[192:193], v[16:17], v[176:177], v[192:193] op_sel_hi:[1,0,1]
	v_mfma_f32_16x16x4_f32 v[102:105], v141, v76, v[102:105]
	v_pk_fma_f32 v[180:181], v[10:11], v[176:177], v[180:181] op_sel:[0,1,0]
	v_pk_fma_f32 v[192:193], v[12:13], v[176:177], v[192:193] op_sel:[0,1,0]
	v_pk_fma_f32 v[180:181], v[6:7], v[178:179], v[180:181] op_sel_hi:[1,0,1]
	v_pk_fma_f32 v[192:193], v[8:9], v[178:179], v[192:193] op_sel_hi:[1,0,1]
	v_mfma_f32_16x16x4_f32 v[98:101], v141, v77, v[98:101]
	v_pk_fma_f32 v[180:181], v[2:3], v[178:179], v[180:181] op_sel:[0,1,0]
	v_pk_fma_f32 v[192:193], v[4:5], v[178:179], v[192:193] op_sel:[0,1,0]
	v_pk_mul_f32 v[180:181], v[146:147], v[180:181]
	v_pk_mul_f32 v[192:193], v[146:147], v[192:193]
	v_pk_fma_f32 v[236:237], v[144:145], v[74:75], v[180:181]
	v_pk_fma_f32 v[238:239], v[144:145], v[76:77], v[192:193]
	global_store_dwordx4 v[150:151], v[236:239], off nt
	v_lshl_add_u64 v[150:151], v[150:151], 0, s[58:59]
	global_load_dwordx4 v[74:77], v[148:149], off nt
	v_lshl_add_u64 v[148:149], v[148:149], 0, s[58:59]
	ds_read_b32 v141, v160 offset:192
	ds_read_b128 v[114:117], v161 offset:1536
	ds_read_b128 v[176:179], v161 offset:1552
	s_waitcnt vmcnt(22)
	s_waitcnt lgkmcnt(3)
	v_cndmask_b32_e64 v143, 0, v143, s[6:7]
	v_pk_mul_f32 v[180:181], v[26:27], v[172:173] op_sel:[0,1]
	v_pk_mul_f32 v[192:193], v[28:29], v[172:173] op_sel:[0,1]
	v_mfma_f32_16x16x4_f32 v[110:113], v143, v78, v[110:113]
	v_pk_fma_f32 v[180:181], v[30:31], v[172:173], v[180:181] op_sel_hi:[1,0,1]
	v_pk_fma_f32 v[192:193], v[32:33], v[172:173], v[192:193] op_sel_hi:[1,0,1]
	v_pk_fma_f32 v[180:181], v[22:23], v[174:175], v[180:181] op_sel_hi:[1,0,1]
	v_pk_fma_f32 v[192:193], v[24:25], v[174:175], v[192:193] op_sel_hi:[1,0,1]
	v_mfma_f32_16x16x4_f32 v[106:109], v143, v79, v[106:109]
	v_pk_fma_f32 v[180:181], v[18:19], v[174:175], v[180:181] op_sel:[0,1,0]
	v_pk_fma_f32 v[192:193], v[20:21], v[174:175], v[192:193] op_sel:[0,1,0]
	v_pk_fma_f32 v[180:181], v[14:15], v[232:233], v[180:181] op_sel_hi:[1,0,1]
	v_pk_fma_f32 v[192:193], v[16:17], v[232:233], v[192:193] op_sel_hi:[1,0,1]
	v_mfma_f32_16x16x4_f32 v[102:105], v143, v80, v[102:105]
	v_pk_fma_f32 v[180:181], v[10:11], v[232:233], v[180:181] op_sel:[0,1,0]
	v_pk_fma_f32 v[192:193], v[12:13], v[232:233], v[192:193] op_sel:[0,1,0]
	v_pk_fma_f32 v[180:181], v[6:7], v[234:235], v[180:181] op_sel_hi:[1,0,1]
	v_pk_fma_f32 v[192:193], v[8:9], v[234:235], v[192:193] op_sel_hi:[1,0,1]
	v_mfma_f32_16x16x4_f32 v[98:101], v143, v81, v[98:101]
	v_pk_fma_f32 v[180:181], v[2:3], v[234:235], v[180:181] op_sel:[0,1,0]
	v_pk_fma_f32 v[192:193], v[4:5], v[234:235], v[192:193] op_sel:[0,1,0]
	v_pk_mul_f32 v[180:181], v[146:147], v[180:181]
	v_pk_mul_f32 v[192:193], v[146:147], v[192:193]
	v_pk_fma_f32 v[236:237], v[144:145], v[78:79], v[180:181]
	v_pk_fma_f32 v[238:239], v[144:145], v[80:81], v[192:193]
	global_store_dwordx4 v[150:151], v[236:239], off nt
	v_lshl_add_u64 v[150:151], v[150:151], 0, s[58:59]
	global_load_dwordx4 v[78:81], v[148:149], off nt
	v_lshl_add_u64 v[148:149], v[148:149], 0, s[58:59]
	ds_read_b32 v143, v160 offset:208
	ds_read_b128 v[172:175], v161 offset:1664
	ds_read_b128 v[232:235], v161 offset:1680
	s_waitcnt vmcnt(22)
	s_waitcnt lgkmcnt(3)
	v_cndmask_b32_e64 v141, 0, v141, s[6:7]
	v_pk_mul_f32 v[180:181], v[26:27], v[114:115] op_sel:[0,1]
	v_pk_mul_f32 v[192:193], v[28:29], v[114:115] op_sel:[0,1]
	v_mfma_f32_16x16x4_f32 v[110:113], v141, v70, v[110:113]
	v_pk_fma_f32 v[180:181], v[30:31], v[114:115], v[180:181] op_sel_hi:[1,0,1]
	v_pk_fma_f32 v[192:193], v[32:33], v[114:115], v[192:193] op_sel_hi:[1,0,1]
	v_pk_fma_f32 v[180:181], v[22:23], v[116:117], v[180:181] op_sel_hi:[1,0,1]
	v_pk_fma_f32 v[192:193], v[24:25], v[116:117], v[192:193] op_sel_hi:[1,0,1]
	v_mfma_f32_16x16x4_f32 v[106:109], v141, v71, v[106:109]
	v_pk_fma_f32 v[180:181], v[18:19], v[116:117], v[180:181] op_sel:[0,1,0]
	v_pk_fma_f32 v[192:193], v[20:21], v[116:117], v[192:193] op_sel:[0,1,0]
	v_pk_fma_f32 v[180:181], v[14:15], v[176:177], v[180:181] op_sel_hi:[1,0,1]
	v_pk_fma_f32 v[192:193], v[16:17], v[176:177], v[192:193] op_sel_hi:[1,0,1]
	v_mfma_f32_16x16x4_f32 v[102:105], v141, v72, v[102:105]
	v_pk_fma_f32 v[180:181], v[10:11], v[176:177], v[180:181] op_sel:[0,1,0]
	v_pk_fma_f32 v[192:193], v[12:13], v[176:177], v[192:193] op_sel:[0,1,0]
	v_pk_fma_f32 v[180:181], v[6:7], v[178:179], v[180:181] op_sel_hi:[1,0,1]
	v_pk_fma_f32 v[192:193], v[8:9], v[178:179], v[192:193] op_sel_hi:[1,0,1]
	v_mfma_f32_16x16x4_f32 v[98:101], v141, v73, v[98:101]
	v_pk_fma_f32 v[180:181], v[2:3], v[178:179], v[180:181] op_sel:[0,1,0]
	v_pk_fma_f32 v[192:193], v[4:5], v[178:179], v[192:193] op_sel:[0,1,0]
	v_pk_mul_f32 v[180:181], v[146:147], v[180:181]
	v_pk_mul_f32 v[192:193], v[146:147], v[192:193]
	v_pk_fma_f32 v[236:237], v[144:145], v[70:71], v[180:181]
	v_pk_fma_f32 v[238:239], v[144:145], v[72:73], v[192:193]
	global_store_dwordx4 v[150:151], v[236:239], off nt
	v_lshl_add_u64 v[150:151], v[150:151], 0, s[58:59]
	global_load_dwordx4 v[70:73], v[148:149], off nt
	v_lshl_add_u64 v[148:149], v[148:149], 0, s[58:59]
	ds_read_b32 v141, v160 offset:224
	ds_read_b128 v[114:117], v161 offset:1792
	ds_read_b128 v[176:179], v161 offset:1808
	s_waitcnt vmcnt(22)
; #define RS_LOAD(dst, it0) do { _Pragma("unroll") for (int u = 0; u < 8; ++u) dst[u] = __builtin_nontemporal_load((const f32x4*)(S0 + (size_t)(4 * ((it0) + u)) * DV)); } while (0)
; __device__ __forceinline__ void ret_sample_item(Frame& F, int item) {
;     ...
;     for (int it0 = 0; it0 < 64; it0 += 16) {
;         RS_LOAD(sb, it0 + 8);
;         RS_PROC(sa, it0);
;         { const int itn = it0 + 16 < 64 ? it0 + 16 : it0; RS_LOAD(sa, itn); }
;         RS_PROC(sb, it0 + 8);
;     }
	s_waitcnt lgkmcnt(3)
	v_cndmask_b32_e64 v143, 0, v143, s[6:7]
	v_pk_mul_f32 v[180:181], v[26:27], v[172:173] op_sel:[0,1]
	v_pk_mul_f32 v[192:193], v[28:29], v[172:173] op_sel:[0,1]
	v_mfma_f32_16x16x4_f32 v[110:113], v143, v62, v[110:113]
	v_pk_fma_f32 v[180:181], v[30:31], v[172:173], v[180:181] op_sel_hi:[1,0,1]
	v_pk_fma_f32 v[192:193], v[32:33], v[172:173], v[192:193] op_sel_hi:[1,0,1]
	v_pk_fma_f32 v[180:181], v[22:23], v[174:175], v[180:181] op_sel_hi:[1,0,1]
	v_pk_fma_f32 v[192:193], v[24:25], v[174:175], v[192:193] op_sel_hi:[1,0,1]
	v_mfma_f32_16x16x4_f32 v[106:109], v143, v63, v[106:109]
	v_pk_fma_f32 v[180:181], v[18:19], v[174:175], v[180:181] op_sel:[0,1,0]
	v_pk_fma_f32 v[192:193], v[20:21], v[174:175], v[192:193] op_sel:[0,1,0]
	v_pk_fma_f32 v[180:181], v[14:15], v[232:233], v[180:181] op_sel_hi:[1,0,1]
	v_pk_fma_f32 v[192:193], v[16:17], v[232:233], v[192:193] op_sel_hi:[1,0,1]
	v_mfma_f32_16x16x4_f32 v[102:105], v143, v64, v[102:105]
	v_pk_fma_f32 v[180:181], v[10:11], v[232:233], v[180:181] op_sel:[0,1,0]
	v_pk_fma_f32 v[192:193], v[12:13], v[232:233], v[192:193] op_sel:[0,1,0]
	v_pk_fma_f32 v[180:181], v[6:7], v[234:235], v[180:181] op_sel_hi:[1,0,1]
	v_pk_fma_f32 v[192:193], v[8:9], v[234:235], v[192:193] op_sel_hi:[1,0,1]
	v_mfma_f32_16x16x4_f32 v[98:101], v143, v65, v[98:101]
	v_pk_fma_f32 v[180:181], v[2:3], v[234:235], v[180:181] op_sel:[0,1,0]
	v_pk_fma_f32 v[192:193], v[4:5], v[234:235], v[192:193] op_sel:[0,1,0]
	v_pk_mul_f32 v[180:181], v[146:147], v[180:181]
	v_pk_mul_f32 v[192:193], v[146:147], v[192:193]
	v_pk_fma_f32 v[236:237], v[144:145], v[62:63], v[180:181]
	v_pk_fma_f32 v[238:239], v[144:145], v[64:65], v[192:193]
	global_store_dwordx4 v[150:151], v[236:239], off nt
	v_lshl_add_u64 v[150:151], v[150:151], 0, s[58:59]
	global_load_dwordx4 v[62:65], v[148:149], off nt
	v_lshl_add_u64 v[148:149], v[148:149], 0, s[58:59]
	ds_read_b32 v143, v160 offset:240
	ds_read_b128 v[172:175], v161 offset:1920
	ds_read_b128 v[232:235], v161 offset:1936
	s_waitcnt vmcnt(22)
	s_waitcnt lgkmcnt(3)
	v_cndmask_b32_e64 v141, 0, v141, s[6:7]
	v_pk_mul_f32 v[180:181], v[26:27], v[114:115] op_sel:[0,1]
	v_pk_mul_f32 v[192:193], v[28:29], v[114:115] op_sel:[0,1]
	v_mfma_f32_16x16x4_f32 v[110:113], v141, v54, v[110:113]
	v_pk_fma_f32 v[180:181], v[30:31], v[114:115], v[180:181] op_sel_hi:[1,0,1]
	v_pk_fma_f32 v[192:193], v[32:33], v[114:115], v[192:193] op_sel_hi:[1,0,1]
	v_pk_fma_f32 v[180:181], v[22:23], v[116:117], v[180:181] op_sel_hi:[1,0,1]
	v_pk_fma_f32 v[192:193], v[24:25], v[116:117], v[192:193] op_sel_hi:[1,0,1]
	v_mfma_f32_16x16x4_f32 v[106:109], v141, v55, v[106:109]
	v_pk_fma_f32 v[180:181], v[18:19], v[116:117], v[180:181] op_sel:[0,1,0]
	v_pk_fma_f32 v[192:193], v[20:21], v[116:117], v[192:193] op_sel:[0,1,0]
	v_pk_fma_f32 v[180:181], v[14:15], v[176:177], v[180:181] op_sel_hi:[1,0,1]
	v_pk_fma_f32 v[192:193], v[16:17], v[176:177], v[192:193] op_sel_hi:[1,0,1]
	v_mfma_f32_16x16x4_f32 v[102:105], v141, v56, v[102:105]
	v_pk_fma_f32 v[180:181], v[10:11], v[176:177], v[180:181] op_sel:[0,1,0]
	v_pk_fma_f32 v[192:193], v[12:13], v[176:177], v[192:193] op_sel:[0,1,0]
	v_pk_fma_f32 v[180:181], v[6:7], v[178:179], v[180:181] op_sel_hi:[1,0,1]
	v_pk_fma_f32 v[192:193], v[8:9], v[178:179], v[192:193] op_sel_hi:[1,0,1]
	v_mfma_f32_16x16x4_f32 v[98:101], v141, v57, v[98:101]
	v_pk_fma_f32 v[180:181], v[2:3], v[178:179], v[180:181] op_sel:[0,1,0]
	v_pk_fma_f32 v[192:193], v[4:5], v[178:179], v[192:193] op_sel:[0,1,0]
	v_pk_mul_f32 v[180:181], v[146:147], v[180:181]
	v_pk_mul_f32 v[192:193], v[146:147], v[192:193]
	v_pk_fma_f32 v[236:237], v[144:145], v[54:55], v[180:181]
	v_pk_fma_f32 v[238:239], v[144:145], v[56:57], v[192:193]
	global_store_dwordx4 v[150:151], v[236:239], off nt
	v_lshl_add_u64 v[150:151], v[150:151], 0, s[58:59]
	global_load_dwordx4 v[54:57], v[148:149], off nt
	v_lshl_add_u64 v[148:149], v[148:149], 0, s[58:59]
	ds_read_b32 v141, v160 offset:256
	ds_read_b128 v[114:117], v161 offset:2048
	ds_read_b128 v[176:179], v161 offset:2064
	s_waitcnt vmcnt(22)
	s_waitcnt lgkmcnt(3)
	v_cndmask_b32_e64 v143, 0, v143, s[6:7]
	v_pk_mul_f32 v[180:181], v[26:27], v[172:173] op_sel:[0,1]
	v_pk_mul_f32 v[192:193], v[28:29], v[172:173] op_sel:[0,1]
	v_mfma_f32_16x16x4_f32 v[110:113], v143, v50, v[110:113]
	v_pk_fma_f32 v[180:181], v[30:31], v[172:173], v[180:181] op_sel_hi:[1,0,1]
	v_pk_fma_f32 v[192:193], v[32:33], v[172:173], v[192:193] op_sel_hi:[1,0,1]
	v_pk_fma_f32 v[180:181], v[22:23], v[174:175], v[180:181] op_sel_hi:[1,0,1]
	v_pk_fma_f32 v[192:193], v[24:25], v[174:175], v[192:193] op_sel_hi:[1,0,1]
	v_mfma_f32_16x16x4_f32 v[106:109], v143, v51, v[106:109]
	v_pk_fma_f32 v[180:181], v[18:19], v[174:175], v[180:181] op_sel:[0,1,0]
	v_pk_fma_f32 v[192:193], v[20:21], v[174:175], v[192:193] op_sel:[0,1,0]
	v_pk_fma_f32 v[180:181], v[14:15], v[232:233], v[180:181] op_sel_hi:[1,0,1]
	v_pk_fma_f32 v[192:193], v[16:17], v[232:233], v[192:193] op_sel_hi:[1,0,1]
	v_mfma_f32_16x16x4_f32 v[102:105], v143, v52, v[102:105]
	v_pk_fma_f32 v[180:181], v[10:11], v[232:233], v[180:181] op_sel:[0,1,0]
	v_pk_fma_f32 v[192:193], v[12:13], v[232:233], v[192:193] op_sel:[0,1,0]
	v_pk_fma_f32 v[180:181], v[6:7], v[234:235], v[180:181] op_sel_hi:[1,0,1]
	v_pk_fma_f32 v[192:193], v[8:9], v[234:235], v[192:193] op_sel_hi:[1,0,1]
	v_mfma_f32_16x16x4_f32 v[98:101], v143, v53, v[98:101]
	v_pk_fma_f32 v[180:181], v[2:3], v[234:235], v[180:181] op_sel:[0,1,0]
	v_pk_fma_f32 v[192:193], v[4:5], v[234:235], v[192:193] op_sel:[0,1,0]
	v_pk_mul_f32 v[180:181], v[146:147], v[180:181]
	v_pk_mul_f32 v[192:193], v[146:147], v[192:193]
	v_pk_fma_f32 v[236:237], v[144:145], v[50:51], v[180:181]
	v_pk_fma_f32 v[238:239], v[144:145], v[52:53], v[192:193]
	global_store_dwordx4 v[150:151], v[236:239], off nt
	v_lshl_add_u64 v[150:151], v[150:151], 0, s[58:59]
	global_load_dwordx4 v[50:53], v[148:149], off nt
	v_lshl_add_u64 v[148:149], v[148:149], 0, s[58:59]
	ds_read_b32 v143, v160 offset:272
	ds_read_b128 v[172:175], v161 offset:2176
	ds_read_b128 v[232:235], v161 offset:2192
	s_waitcnt vmcnt(22)
; #define RS_LOAD(dst, it0) do { _Pragma("unroll") for (int u = 0; u < 8; ++u) dst[u] = __builtin_nontemporal_load((const f32x4*)(S0 + (size_t)(4 * ((it0) + u)) * DV)); } while (0)
; __device__ __forceinline__ void ret_sample_item(Frame& F, int item) {
;     ...
;     for (int it0 = 0; it0 < 64; it0 += 16) {
;         RS_LOAD(sb, it0 + 8);
;         RS_PROC(sa, it0);
;         { const int itn = it0 + 16 < 64 ? it0 + 16 : it0; RS_LOAD(sa, itn); }
;         RS_PROC(sb, it0 + 8);
;     }
	s_waitcnt lgkmcnt(3)
	v_cndmask_b32_e64 v141, 0, v141, s[6:7]
	v_pk_mul_f32 v[180:181], v[26:27], v[114:115] op_sel:[0,1]
	v_pk_mul_f32 v[192:193], v[28:29], v[114:115] op_sel:[0,1]
	v_mfma_f32_16x16x4_f32 v[110:113], v141, v46, v[110:113]
	v_pk_fma_f32 v[180:181], v[30:31], v[114:115], v[180:181] op_sel_hi:[1,0,1]
	v_pk_fma_f32 v[192:193], v[32:33], v[114:115], v[192:193] op_sel_hi:[1,0,1]
	v_pk_fma_f32 v[180:181], v[22:23], v[116:117], v[180:181] op_sel_hi:[1,0,1]
	v_pk_fma_f32 v[192:193], v[24:25], v[116:117], v[192:193] op_sel_hi:[1,0,1]
	v_mfma_f32_16x16x4_f32 v[106:109], v141, v47, v[106:109]
	v_pk_fma_f32 v[180:181], v[18:19], v[116:117], v[180:181] op_sel:[0,1,0]
	v_pk_fma_f32 v[192:193], v[20:21], v[116:117], v[192:193] op_sel:[0,1,0]
	v_pk_fma_f32 v[180:181], v[14:15], v[176:177], v[180:181] op_sel_hi:[1,0,1]
	v_pk_fma_f32 v[192:193], v[16:17], v[176:177], v[192:193] op_sel_hi:[1,0,1]
	v_mfma_f32_16x16x4_f32 v[102:105], v141, v48, v[102:105]
	v_pk_fma_f32 v[180:181], v[10:11], v[176:177], v[180:181] op_sel:[0,1,0]
	v_pk_fma_f32 v[192:193], v[12:13], v[176:177], v[192:193] op_sel:[0,1,0]
	v_pk_fma_f32 v[180:181], v[6:7], v[178:179], v[180:181] op_sel_hi:[1,0,1]
	v_pk_fma_f32 v[192:193], v[8:9], v[178:179], v[192:193] op_sel_hi:[1,0,1]
	v_mfma_f32_16x16x4_f32 v[98:101], v141, v49, v[98:101]
	v_pk_fma_f32 v[180:181], v[2:3], v[178:179], v[180:181] op_sel:[0,1,0]
	v_pk_fma_f32 v[192:193], v[4:5], v[178:179], v[192:193] op_sel:[0,1,0]
	v_pk_mul_f32 v[180:181], v[146:147], v[180:181]
	v_pk_mul_f32 v[192:193], v[146:147], v[192:193]
	v_pk_fma_f32 v[236:237], v[144:145], v[46:47], v[180:181]
	v_pk_fma_f32 v[238:239], v[144:145], v[48:49], v[192:193]
	global_store_dwordx4 v[150:151], v[236:239], off nt
	v_lshl_add_u64 v[150:151], v[150:151], 0, s[58:59]
	global_load_dwordx4 v[46:49], v[148:149], off nt
	v_lshl_add_u64 v[148:149], v[148:149], 0, s[58:59]
	ds_read_b32 v141, v160 offset:288
	ds_read_b128 v[114:117], v161 offset:2304
	ds_read_b128 v[176:179], v161 offset:2320
	s_waitcnt vmcnt(22)
	s_waitcnt lgkmcnt(3)
	v_cndmask_b32_e64 v143, 0, v143, s[6:7]
	v_pk_mul_f32 v[180:181], v[26:27], v[172:173] op_sel:[0,1]
	v_pk_mul_f32 v[192:193], v[28:29], v[172:173] op_sel:[0,1]
	v_mfma_f32_16x16x4_f32 v[110:113], v143, v42, v[110:113]
	v_pk_fma_f32 v[180:181], v[30:31], v[172:173], v[180:181] op_sel_hi:[1,0,1]
	v_pk_fma_f32 v[192:193], v[32:33], v[172:173], v[192:193] op_sel_hi:[1,0,1]
	v_pk_fma_f32 v[180:181], v[22:23], v[174:175], v[180:181] op_sel_hi:[1,0,1]
	v_pk_fma_f32 v[192:193], v[24:25], v[174:175], v[192:193] op_sel_hi:[1,0,1]
	v_mfma_f32_16x16x4_f32 v[106:109], v143, v43, v[106:109]
	v_pk_fma_f32 v[180:181], v[18:19], v[174:175], v[180:181] op_sel:[0,1,0]
	v_pk_fma_f32 v[192:193], v[20:21], v[174:175], v[192:193] op_sel:[0,1,0]
	v_pk_fma_f32 v[180:181], v[14:15], v[232:233], v[180:181] op_sel_hi:[1,0,1]
	v_pk_fma_f32 v[192:193], v[16:17], v[232:233], v[192:193] op_sel_hi:[1,0,1]
	v_mfma_f32_16x16x4_f32 v[102:105], v143, v44, v[102:105]
	v_pk_fma_f32 v[180:181], v[10:11], v[232:233], v[180:181] op_sel:[0,1,0]
	v_pk_fma_f32 v[192:193], v[12:13], v[232:233], v[192:193] op_sel:[0,1,0]
	v_pk_fma_f32 v[180:181], v[6:7], v[234:235], v[180:181] op_sel_hi:[1,0,1]
	v_pk_fma_f32 v[192:193], v[8:9], v[234:235], v[192:193] op_sel_hi:[1,0,1]
	v_mfma_f32_16x16x4_f32 v[98:101], v143, v45, v[98:101]
	v_pk_fma_f32 v[180:181], v[2:3], v[234:235], v[180:181] op_sel:[0,1,0]
	v_pk_fma_f32 v[192:193], v[4:5], v[234:235], v[192:193] op_sel:[0,1,0]
	v_pk_mul_f32 v[180:181], v[146:147], v[180:181]
	v_pk_mul_f32 v[192:193], v[146:147], v[192:193]
	v_pk_fma_f32 v[236:237], v[144:145], v[42:43], v[180:181]
	v_pk_fma_f32 v[238:239], v[144:145], v[44:45], v[192:193]
	global_store_dwordx4 v[150:151], v[236:239], off nt
	v_lshl_add_u64 v[150:151], v[150:151], 0, s[58:59]
	global_load_dwordx4 v[42:45], v[148:149], off nt
	v_lshl_add_u64 v[148:149], v[148:149], 0, s[58:59]
	ds_read_b32 v143, v160 offset:304
	ds_read_b128 v[172:175], v161 offset:2432
	ds_read_b128 v[232:235], v161 offset:2448
	s_waitcnt vmcnt(22)
	s_waitcnt lgkmcnt(3)
	v_cndmask_b32_e64 v141, 0, v141, s[6:7]
	v_pk_mul_f32 v[180:181], v[26:27], v[114:115] op_sel:[0,1]
	v_pk_mul_f32 v[192:193], v[28:29], v[114:115] op_sel:[0,1]
	v_mfma_f32_16x16x4_f32 v[110:113], v141, v38, v[110:113]
	v_pk_fma_f32 v[180:181], v[30:31], v[114:115], v[180:181] op_sel_hi:[1,0,1]
	v_pk_fma_f32 v[192:193], v[32:33], v[114:115], v[192:193] op_sel_hi:[1,0,1]
	v_pk_fma_f32 v[180:181], v[22:23], v[116:117], v[180:181] op_sel_hi:[1,0,1]
	v_pk_fma_f32 v[192:193], v[24:25], v[116:117], v[192:193] op_sel_hi:[1,0,1]
	v_mfma_f32_16x16x4_f32 v[106:109], v141, v39, v[106:109]
	v_pk_fma_f32 v[180:181], v[18:19], v[116:117], v[180:181] op_sel:[0,1,0]
	v_pk_fma_f32 v[192:193], v[20:21], v[116:117], v[192:193] op_sel:[0,1,0]
	v_pk_fma_f32 v[180:181], v[14:15], v[176:177], v[180:181] op_sel_hi:[1,0,1]
	v_pk_fma_f32 v[192:193], v[16:17], v[176:177], v[192:193] op_sel_hi:[1,0,1]
	v_mfma_f32_16x16x4_f32 v[102:105], v141, v40, v[102:105]
	v_pk_fma_f32 v[180:181], v[10:11], v[176:177], v[180:181] op_sel:[0,1,0]
	v_pk_fma_f32 v[192:193], v[12:13], v[176:177], v[192:193] op_sel:[0,1,0]
	v_pk_fma_f32 v[180:181], v[6:7], v[178:179], v[180:181] op_sel_hi:[1,0,1]
	v_pk_fma_f32 v[192:193], v[8:9], v[178:179], v[192:193] op_sel_hi:[1,0,1]
	v_mfma_f32_16x16x4_f32 v[98:101], v141, v41, v[98:101]
	v_pk_fma_f32 v[180:181], v[2:3], v[178:179], v[180:181] op_sel:[0,1,0]
	v_pk_fma_f32 v[192:193], v[4:5], v[178:179], v[192:193] op_sel:[0,1,0]
	v_pk_mul_f32 v[180:181], v[146:147], v[180:181]
	v_pk_mul_f32 v[192:193], v[146:147], v[192:193]
	v_pk_fma_f32 v[236:237], v[144:145], v[38:39], v[180:181]
	v_pk_fma_f32 v[238:239], v[144:145], v[40:41], v[192:193]
	global_store_dwordx4 v[150:151], v[236:239], off nt
	v_lshl_add_u64 v[150:151], v[150:151], 0, s[58:59]
	global_load_dwordx4 v[38:41], v[148:149], off nt
	v_lshl_add_u64 v[148:149], v[148:149], 0, s[58:59]
	ds_read_b32 v141, v160 offset:320
	ds_read_b128 v[114:117], v161 offset:2560
	ds_read_b128 v[176:179], v161 offset:2576
	s_waitcnt vmcnt(22)
; #define RS_LOAD(dst, it0) do { _Pragma("unroll") for (int u = 0; u < 8; ++u) dst[u] = __builtin_nontemporal_load((const f32x4*)(S0 + (size_t)(4 * ((it0) + u)) * DV)); } while (0)
; __device__ __forceinline__ void ret_sample_item(Frame& F, int item) {
;     ...
;     for (int it0 = 0; it0 < 64; it0 += 16) {
;         RS_LOAD(sb, it0 + 8);
;         RS_PROC(sa, it0);
;         { const int itn = it0 + 16 < 64 ? it0 + 16 : it0; RS_LOAD(sa, itn); }
;         RS_PROC(sb, it0 + 8);
;     }
	s_waitcnt lgkmcnt(3)
	v_cndmask_b32_e64 v143, 0, v143, s[6:7]
	v_pk_mul_f32 v[180:181], v[26:27], v[172:173] op_sel:[0,1]
	v_pk_mul_f32 v[192:193], v[28:29], v[172:173] op_sel:[0,1]
	v_mfma_f32_16x16x4_f32 v[110:113], v143, v34, v[110:113]
	v_pk_fma_f32 v[180:181], v[30:31], v[172:173], v[180:181] op_sel_hi:[1,0,1]
	v_pk_fma_f32 v[192:193], v[32:33], v[172:173], v[192:193] op_sel_hi:[1,0,1]
	v_pk_fma_f32 v[180:181], v[22:23], v[174:175], v[180:181] op_sel_hi:[1,0,1]
	v_pk_fma_f32 v[192:193], v[24:25], v[174:175], v[192:193] op_sel_hi:[1,0,1]
	v_mfma_f32_16x16x4_f32 v[106:109], v143, v35, v[106:109]
	v_pk_fma_f32 v[180:181], v[18:19], v[174:175], v[180:181] op_sel:[0,1,0]
	v_pk_fma_f32 v[192:193], v[20:21], v[174:175], v[192:193] op_sel:[0,1,0]
	v_pk_fma_f32 v[180:181], v[14:15], v[232:233], v[180:181] op_sel_hi:[1,0,1]
	v_pk_fma_f32 v[192:193], v[16:17], v[232:233], v[192:193] op_sel_hi:[1,0,1]
	v_mfma_f32_16x16x4_f32 v[102:105], v143, v36, v[102:105]
	v_pk_fma_f32 v[180:181], v[10:11], v[232:233], v[180:181] op_sel:[0,1,0]
	v_pk_fma_f32 v[192:193], v[12:13], v[232:233], v[192:193] op_sel:[0,1,0]
	v_pk_fma_f32 v[180:181], v[6:7], v[234:235], v[180:181] op_sel_hi:[1,0,1]
	v_pk_fma_f32 v[192:193], v[8:9], v[234:235], v[192:193] op_sel_hi:[1,0,1]
	v_mfma_f32_16x16x4_f32 v[98:101], v143, v37, v[98:101]
	v_pk_fma_f32 v[180:181], v[2:3], v[234:235], v[180:181] op_sel:[0,1,0]
	v_pk_fma_f32 v[192:193], v[4:5], v[234:235], v[192:193] op_sel:[0,1,0]
	v_pk_mul_f32 v[180:181], v[146:147], v[180:181]
	v_pk_mul_f32 v[192:193], v[146:147], v[192:193]
	v_pk_fma_f32 v[236:237], v[144:145], v[34:35], v[180:181]
	v_pk_fma_f32 v[238:239], v[144:145], v[36:37], v[192:193]
	global_store_dwordx4 v[150:151], v[236:239], off nt
	v_lshl_add_u64 v[150:151], v[150:151], 0, s[58:59]
	global_load_dwordx4 v[34:37], v[148:149], off nt
	v_lshl_add_u64 v[148:149], v[148:149], 0, s[58:59]
	ds_read_b32 v143, v160 offset:336
	ds_read_b128 v[172:175], v161 offset:2688
	ds_read_b128 v[232:235], v161 offset:2704
	s_waitcnt vmcnt(22)
	s_waitcnt lgkmcnt(3)
	v_cndmask_b32_e64 v141, 0, v141, s[6:7]
	v_pk_mul_f32 v[180:181], v[26:27], v[114:115] op_sel:[0,1]
	v_pk_mul_f32 v[192:193], v[28:29], v[114:115] op_sel:[0,1]
	v_mfma_f32_16x16x4_f32 v[110:113], v141, v58, v[110:113]
	v_pk_fma_f32 v[180:181], v[30:31], v[114:115], v[180:181] op_sel_hi:[1,0,1]
	v_pk_fma_f32 v[192:193], v[32:33], v[114:115], v[192:193] op_sel_hi:[1,0,1]
	v_pk_fma_f32 v[180:181], v[22:23], v[116:117], v[180:181] op_sel_hi:[1,0,1]
	v_pk_fma_f32 v[192:193], v[24:25], v[116:117], v[192:193] op_sel_hi:[1,0,1]
	v_mfma_f32_16x16x4_f32 v[106:109], v141, v59, v[106:109]
	v_pk_fma_f32 v[180:181], v[18:19], v[116:117], v[180:181] op_sel:[0,1,0]
	v_pk_fma_f32 v[192:193], v[20:21], v[116:117], v[192:193] op_sel:[0,1,0]
	v_pk_fma_f32 v[180:181], v[14:15], v[176:177], v[180:181] op_sel_hi:[1,0,1]
	v_pk_fma_f32 v[192:193], v[16:17], v[176:177], v[192:193] op_sel_hi:[1,0,1]
	v_mfma_f32_16x16x4_f32 v[102:105], v141, v60, v[102:105]
	v_pk_fma_f32 v[180:181], v[10:11], v[176:177], v[180:181] op_sel:[0,1,0]
	v_pk_fma_f32 v[192:193], v[12:13], v[176:177], v[192:193] op_sel:[0,1,0]
	v_pk_fma_f32 v[180:181], v[6:7], v[178:179], v[180:181] op_sel_hi:[1,0,1]
	v_pk_fma_f32 v[192:193], v[8:9], v[178:179], v[192:193] op_sel_hi:[1,0,1]
	v_mfma_f32_16x16x4_f32 v[98:101], v141, v61, v[98:101]
	v_pk_fma_f32 v[180:181], v[2:3], v[178:179], v[180:181] op_sel:[0,1,0]
	v_pk_fma_f32 v[192:193], v[4:5], v[178:179], v[192:193] op_sel:[0,1,0]
	v_pk_mul_f32 v[180:181], v[146:147], v[180:181]
	v_pk_mul_f32 v[192:193], v[146:147], v[192:193]
	v_pk_fma_f32 v[236:237], v[144:145], v[58:59], v[180:181]
	v_pk_fma_f32 v[238:239], v[144:145], v[60:61], v[192:193]
	global_store_dwordx4 v[150:151], v[236:239], off nt
	v_lshl_add_u64 v[150:151], v[150:151], 0, s[58:59]
	global_load_dwordx4 v[58:61], v[148:149], off nt
	v_lshl_add_u64 v[148:149], v[148:149], 0, s[58:59]
	ds_read_b32 v141, v160 offset:352
	ds_read_b128 v[114:117], v161 offset:2816
	ds_read_b128 v[176:179], v161 offset:2832
	s_waitcnt vmcnt(22)
	s_waitcnt lgkmcnt(3)
	v_cndmask_b32_e64 v143, 0, v143, s[6:7]
	v_pk_mul_f32 v[180:181], v[26:27], v[172:173] op_sel:[0,1]
	v_pk_mul_f32 v[192:193], v[28:29], v[172:173] op_sel:[0,1]
	v_mfma_f32_16x16x4_f32 v[110:113], v143, v66, v[110:113]
	v_pk_fma_f32 v[180:181], v[30:31], v[172:173], v[180:181] op_sel_hi:[1,0,1]
	v_pk_fma_f32 v[192:193], v[32:33], v[172:173], v[192:193] op_sel_hi:[1,0,1]
	v_pk_fma_f32 v[180:181], v[22:23], v[174:175], v[180:181] op_sel_hi:[1,0,1]
	v_pk_fma_f32 v[192:193], v[24:25], v[174:175], v[192:193] op_sel_hi:[1,0,1]
	v_mfma_f32_16x16x4_f32 v[106:109], v143, v67, v[106:109]
	v_pk_fma_f32 v[180:181], v[18:19], v[174:175], v[180:181] op_sel:[0,1,0]
	v_pk_fma_f32 v[192:193], v[20:21], v[174:175], v[192:193] op_sel:[0,1,0]
	v_pk_fma_f32 v[180:181], v[14:15], v[232:233], v[180:181] op_sel_hi:[1,0,1]
	v_pk_fma_f32 v[192:193], v[16:17], v[232:233], v[192:193] op_sel_hi:[1,0,1]
	v_mfma_f32_16x16x4_f32 v[102:105], v143, v68, v[102:105]
	v_pk_fma_f32 v[180:181], v[10:11], v[232:233], v[180:181] op_sel:[0,1,0]
	v_pk_fma_f32 v[192:193], v[12:13], v[232:233], v[192:193] op_sel:[0,1,0]
	v_pk_fma_f32 v[180:181], v[6:7], v[234:235], v[180:181] op_sel_hi:[1,0,1]
	v_pk_fma_f32 v[192:193], v[8:9], v[234:235], v[192:193] op_sel_hi:[1,0,1]
	v_mfma_f32_16x16x4_f32 v[98:101], v143, v69, v[98:101]
	v_pk_fma_f32 v[180:181], v[2:3], v[234:235], v[180:181] op_sel:[0,1,0]
	v_pk_fma_f32 v[192:193], v[4:5], v[234:235], v[192:193] op_sel:[0,1,0]
	v_pk_mul_f32 v[180:181], v[146:147], v[180:181]
	v_pk_mul_f32 v[192:193], v[146:147], v[192:193]
	v_pk_fma_f32 v[236:237], v[144:145], v[66:67], v[180:181]
	v_pk_fma_f32 v[238:239], v[144:145], v[68:69], v[192:193]
	global_store_dwordx4 v[150:151], v[236:239], off nt
	v_lshl_add_u64 v[150:151], v[150:151], 0, s[58:59]
	global_load_dwordx4 v[66:69], v[148:149], off nt
	v_lshl_add_u64 v[148:149], v[148:149], 0, s[58:59]
	ds_read_b32 v143, v160 offset:368
	ds_read_b128 v[172:175], v161 offset:2944
	ds_read_b128 v[232:235], v161 offset:2960
	s_waitcnt vmcnt(22)
; #define RS_LOAD(dst, it0) do { _Pragma("unroll") for (int u = 0; u < 8; ++u) dst[u] = __builtin_nontemporal_load((const f32x4*)(S0 + (size_t)(4 * ((it0) + u)) * DV)); } while (0)
; __device__ __forceinline__ void ret_sample_item(Frame& F, int item) {
;     ...
;     for (int it0 = 0; it0 < 64; it0 += 16) {
;         RS_LOAD(sb, it0 + 8);
;         RS_PROC(sa, it0);
;         { const int itn = it0 + 16 < 64 ? it0 + 16 : it0; RS_LOAD(sa, itn); }
;         RS_PROC(sb, it0 + 8);
;     }
	s_waitcnt lgkmcnt(3)
	v_cndmask_b32_e64 v141, 0, v141, s[6:7]
	v_pk_mul_f32 v[180:181], v[26:27], v[114:115] op_sel:[0,1]
	v_pk_mul_f32 v[192:193], v[28:29], v[114:115] op_sel:[0,1]
	v_mfma_f32_16x16x4_f32 v[110:113], v141, v74, v[110:113]
	v_pk_fma_f32 v[180:181], v[30:31], v[114:115], v[180:181] op_sel_hi:[1,0,1]
	v_pk_fma_f32 v[192:193], v[32:33], v[114:115], v[192:193] op_sel_hi:[1,0,1]
	v_pk_fma_f32 v[180:181], v[22:23], v[116:117], v[180:181] op_sel_hi:[1,0,1]
	v_pk_fma_f32 v[192:193], v[24:25], v[116:117], v[192:193] op_sel_hi:[1,0,1]
	v_mfma_f32_16x16x4_f32 v[106:109], v141, v75, v[106:109]
	v_pk_fma_f32 v[180:181], v[18:19], v[116:117], v[180:181] op_sel:[0,1,0]
	v_pk_fma_f32 v[192:193], v[20:21], v[116:117], v[192:193] op_sel:[0,1,0]
	v_pk_fma_f32 v[180:181], v[14:15], v[176:177], v[180:181] op_sel_hi:[1,0,1]
	v_pk_fma_f32 v[192:193], v[16:17], v[176:177], v[192:193] op_sel_hi:[1,0,1]
	v_mfma_f32_16x16x4_f32 v[102:105], v141, v76, v[102:105]
	v_pk_fma_f32 v[180:181], v[10:11], v[176:177], v[180:181] op_sel:[0,1,0]
	v_pk_fma_f32 v[192:193], v[12:13], v[176:177], v[192:193] op_sel:[0,1,0]
	v_pk_fma_f32 v[180:181], v[6:7], v[178:179], v[180:181] op_sel_hi:[1,0,1]
	v_pk_fma_f32 v[192:193], v[8:9], v[178:179], v[192:193] op_sel_hi:[1,0,1]
	v_mfma_f32_16x16x4_f32 v[98:101], v141, v77, v[98:101]
	v_pk_fma_f32 v[180:181], v[2:3], v[178:179], v[180:181] op_sel:[0,1,0]
	v_pk_fma_f32 v[192:193], v[4:5], v[178:179], v[192:193] op_sel:[0,1,0]
	v_pk_mul_f32 v[180:181], v[146:147], v[180:181]
	v_pk_mul_f32 v[192:193], v[146:147], v[192:193]
	v_pk_fma_f32 v[236:237], v[144:145], v[74:75], v[180:181]
	v_pk_fma_f32 v[238:239], v[144:145], v[76:77], v[192:193]
	global_store_dwordx4 v[150:151], v[236:239], off nt
	v_lshl_add_u64 v[150:151], v[150:151], 0, s[58:59]
	global_load_dwordx4 v[74:77], v[148:149], off nt
	v_lshl_add_u64 v[148:149], v[148:149], 0, s[58:59]
	ds_read_b32 v141, v160 offset:384
	ds_read_b128 v[114:117], v161 offset:3072
	ds_read_b128 v[176:179], v161 offset:3088
	s_waitcnt vmcnt(22)
	s_waitcnt lgkmcnt(3)
	v_cndmask_b32_e64 v143, 0, v143, s[6:7]
	v_pk_mul_f32 v[180:181], v[26:27], v[172:173] op_sel:[0,1]
	v_pk_mul_f32 v[192:193], v[28:29], v[172:173] op_sel:[0,1]
	v_mfma_f32_16x16x4_f32 v[110:113], v143, v78, v[110:113]
	v_pk_fma_f32 v[180:181], v[30:31], v[172:173], v[180:181] op_sel_hi:[1,0,1]
	v_pk_fma_f32 v[192:193], v[32:33], v[172:173], v[192:193] op_sel_hi:[1,0,1]
	v_pk_fma_f32 v[180:181], v[22:23], v[174:175], v[180:181] op_sel_hi:[1,0,1]
	v_pk_fma_f32 v[192:193], v[24:25], v[174:175], v[192:193] op_sel_hi:[1,0,1]
	v_mfma_f32_16x16x4_f32 v[106:109], v143, v79, v[106:109]
	v_pk_fma_f32 v[180:181], v[18:19], v[174:175], v[180:181] op_sel:[0,1,0]
	v_pk_fma_f32 v[192:193], v[20:21], v[174:175], v[192:193] op_sel:[0,1,0]
	v_pk_fma_f32 v[180:181], v[14:15], v[232:233], v[180:181] op_sel_hi:[1,0,1]
	v_pk_fma_f32 v[192:193], v[16:17], v[232:233], v[192:193] op_sel_hi:[1,0,1]
	v_mfma_f32_16x16x4_f32 v[102:105], v143, v80, v[102:105]
	v_pk_fma_f32 v[180:181], v[10:11], v[232:233], v[180:181] op_sel:[0,1,0]
	v_pk_fma_f32 v[192:193], v[12:13], v[232:233], v[192:193] op_sel:[0,1,0]
	v_pk_fma_f32 v[180:181], v[6:7], v[234:235], v[180:181] op_sel_hi:[1,0,1]
	v_pk_fma_f32 v[192:193], v[8:9], v[234:235], v[192:193] op_sel_hi:[1,0,1]
	v_mfma_f32_16x16x4_f32 v[98:101], v143, v81, v[98:101]
	v_pk_fma_f32 v[180:181], v[2:3], v[234:235], v[180:181] op_sel:[0,1,0]
	v_pk_fma_f32 v[192:193], v[4:5], v[234:235], v[192:193] op_sel:[0,1,0]
	v_pk_mul_f32 v[180:181], v[146:147], v[180:181]
	v_pk_mul_f32 v[192:193], v[146:147], v[192:193]
	v_pk_fma_f32 v[236:237], v[144:145], v[78:79], v[180:181]
	v_pk_fma_f32 v[238:239], v[144:145], v[80:81], v[192:193]
	global_store_dwordx4 v[150:151], v[236:239], off nt
	v_lshl_add_u64 v[150:151], v[150:151], 0, s[58:59]
	global_load_dwordx4 v[78:81], v[148:149], off nt
	v_lshl_add_u64 v[148:149], v[148:149], 0, s[58:59]
	ds_read_b32 v143, v160 offset:400
	ds_read_b128 v[172:175], v161 offset:3200
	ds_read_b128 v[232:235], v161 offset:3216
	s_waitcnt vmcnt(22)
	s_waitcnt lgkmcnt(3)
	v_cndmask_b32_e64 v141, 0, v141, s[6:7]
	v_pk_mul_f32 v[180:181], v[26:27], v[114:115] op_sel:[0,1]
	v_pk_mul_f32 v[192:193], v[28:29], v[114:115] op_sel:[0,1]
	v_mfma_f32_16x16x4_f32 v[110:113], v141, v70, v[110:113]
	v_pk_fma_f32 v[180:181], v[30:31], v[114:115], v[180:181] op_sel_hi:[1,0,1]
	v_pk_fma_f32 v[192:193], v[32:33], v[114:115], v[192:193] op_sel_hi:[1,0,1]
	v_pk_fma_f32 v[180:181], v[22:23], v[116:117], v[180:181] op_sel_hi:[1,0,1]
	v_pk_fma_f32 v[192:193], v[24:25], v[116:117], v[192:193] op_sel_hi:[1,0,1]
	v_mfma_f32_16x16x4_f32 v[106:109], v141, v71, v[106:109]
	v_pk_fma_f32 v[180:181], v[18:19], v[116:117], v[180:181] op_sel:[0,1,0]
	v_pk_fma_f32 v[192:193], v[20:21], v[116:117], v[192:193] op_sel:[0,1,0]
	v_pk_fma_f32 v[180:181], v[14:15], v[176:177], v[180:181] op_sel_hi:[1,0,1]
	v_pk_fma_f32 v[192:193], v[16:17], v[176:177], v[192:193] op_sel_hi:[1,0,1]
	v_mfma_f32_16x16x4_f32 v[102:105], v141, v72, v[102:105]
	v_pk_fma_f32 v[180:181], v[10:11], v[176:177], v[180:181] op_sel:[0,1,0]
	v_pk_fma_f32 v[192:193], v[12:13], v[176:177], v[192:193] op_sel:[0,1,0]
	v_pk_fma_f32 v[180:181], v[6:7], v[178:179], v[180:181] op_sel_hi:[1,0,1]
	v_pk_fma_f32 v[192:193], v[8:9], v[178:179], v[192:193] op_sel_hi:[1,0,1]
	v_mfma_f32_16x16x4_f32 v[98:101], v141, v73, v[98:101]
	v_pk_fma_f32 v[180:181], v[2:3], v[178:179], v[180:181] op_sel:[0,1,0]
	v_pk_fma_f32 v[192:193], v[4:5], v[178:179], v[192:193] op_sel:[0,1,0]
	v_pk_mul_f32 v[180:181], v[146:147], v[180:181]
	v_pk_mul_f32 v[192:193], v[146:147], v[192:193]
	v_pk_fma_f32 v[236:237], v[144:145], v[70:71], v[180:181]
	v_pk_fma_f32 v[238:239], v[144:145], v[72:73], v[192:193]
	global_store_dwordx4 v[150:151], v[236:239], off nt
	v_lshl_add_u64 v[150:151], v[150:151], 0, s[58:59]
	global_load_dwordx4 v[70:73], v[148:149], off nt
	v_lshl_add_u64 v[148:149], v[148:149], 0, s[58:59]
	ds_read_b32 v141, v160 offset:416
	ds_read_b128 v[114:117], v161 offset:3328
	ds_read_b128 v[176:179], v161 offset:3344
	s_waitcnt vmcnt(22)
; #define RS_LOAD(dst, it0) do { _Pragma("unroll") for (int u = 0; u < 8; ++u) dst[u] = __builtin_nontemporal_load((const f32x4*)(S0 + (size_t)(4 * ((it0) + u)) * DV)); } while (0)
; __device__ __forceinline__ void ret_sample_item(Frame& F, int item) {
;     ...
;     for (int it0 = 0; it0 < 64; it0 += 16) {
;         RS_LOAD(sb, it0 + 8);
;         RS_PROC(sa, it0);
;         { const int itn = it0 + 16 < 64 ? it0 + 16 : it0; RS_LOAD(sa, itn); }
;         RS_PROC(sb, it0 + 8);
;     }
	s_waitcnt lgkmcnt(3)
	v_cndmask_b32_e64 v143, 0, v143, s[6:7]
	v_pk_mul_f32 v[180:181], v[26:27], v[172:173] op_sel:[0,1]
	v_pk_mul_f32 v[192:193], v[28:29], v[172:173] op_sel:[0,1]
	v_mfma_f32_16x16x4_f32 v[110:113], v143, v62, v[110:113]
	v_pk_fma_f32 v[180:181], v[30:31], v[172:173], v[180:181] op_sel_hi:[1,0,1]
	v_pk_fma_f32 v[192:193], v[32:33], v[172:173], v[192:193] op_sel_hi:[1,0,1]
	v_pk_fma_f32 v[180:181], v[22:23], v[174:175], v[180:181] op_sel_hi:[1,0,1]
	v_pk_fma_f32 v[192:193], v[24:25], v[174:175], v[192:193] op_sel_hi:[1,0,1]
	v_mfma_f32_16x16x4_f32 v[106:109], v143, v63, v[106:109]
	v_pk_fma_f32 v[180:181], v[18:19], v[174:175], v[180:181] op_sel:[0,1,0]
	v_pk_fma_f32 v[192:193], v[20:21], v[174:175], v[192:193] op_sel:[0,1,0]
	v_pk_fma_f32 v[180:181], v[14:15], v[232:233], v[180:181] op_sel_hi:[1,0,1]
	v_pk_fma_f32 v[192:193], v[16:17], v[232:233], v[192:193] op_sel_hi:[1,0,1]
	v_mfma_f32_16x16x4_f32 v[102:105], v143, v64, v[102:105]
	v_pk_fma_f32 v[180:181], v[10:11], v[232:233], v[180:181] op_sel:[0,1,0]
	v_pk_fma_f32 v[192:193], v[12:13], v[232:233], v[192:193] op_sel:[0,1,0]
	v_pk_fma_f32 v[180:181], v[6:7], v[234:235], v[180:181] op_sel_hi:[1,0,1]
	v_pk_fma_f32 v[192:193], v[8:9], v[234:235], v[192:193] op_sel_hi:[1,0,1]
	v_mfma_f32_16x16x4_f32 v[98:101], v143, v65, v[98:101]
	v_pk_fma_f32 v[180:181], v[2:3], v[234:235], v[180:181] op_sel:[0,1,0]
	v_pk_fma_f32 v[192:193], v[4:5], v[234:235], v[192:193] op_sel:[0,1,0]
	v_pk_mul_f32 v[180:181], v[146:147], v[180:181]
	v_pk_mul_f32 v[192:193], v[146:147], v[192:193]
	v_pk_fma_f32 v[236:237], v[144:145], v[62:63], v[180:181]
	v_pk_fma_f32 v[238:239], v[144:145], v[64:65], v[192:193]
	global_store_dwordx4 v[150:151], v[236:239], off nt
	v_lshl_add_u64 v[150:151], v[150:151], 0, s[58:59]
	global_load_dwordx4 v[62:65], v[148:149], off nt
	v_lshl_add_u64 v[148:149], v[148:149], 0, s[58:59]
	ds_read_b32 v143, v160 offset:432
	ds_read_b128 v[172:175], v161 offset:3456
	ds_read_b128 v[232:235], v161 offset:3472
	s_waitcnt vmcnt(22)
	s_waitcnt lgkmcnt(3)
	v_cndmask_b32_e64 v141, 0, v141, s[6:7]
	v_pk_mul_f32 v[180:181], v[26:27], v[114:115] op_sel:[0,1]
	v_pk_mul_f32 v[192:193], v[28:29], v[114:115] op_sel:[0,1]
	v_mfma_f32_16x16x4_f32 v[110:113], v141, v54, v[110:113]
	v_pk_fma_f32 v[180:181], v[30:31], v[114:115], v[180:181] op_sel_hi:[1,0,1]
	v_pk_fma_f32 v[192:193], v[32:33], v[114:115], v[192:193] op_sel_hi:[1,0,1]
	v_pk_fma_f32 v[180:181], v[22:23], v[116:117], v[180:181] op_sel_hi:[1,0,1]
	v_pk_fma_f32 v[192:193], v[24:25], v[116:117], v[192:193] op_sel_hi:[1,0,1]
	v_mfma_f32_16x16x4_f32 v[106:109], v141, v55, v[106:109]
	v_pk_fma_f32 v[180:181], v[18:19], v[116:117], v[180:181] op_sel:[0,1,0]
	v_pk_fma_f32 v[192:193], v[20:21], v[116:117], v[192:193] op_sel:[0,1,0]
	v_pk_fma_f32 v[180:181], v[14:15], v[176:177], v[180:181] op_sel_hi:[1,0,1]
	v_pk_fma_f32 v[192:193], v[16:17], v[176:177], v[192:193] op_sel_hi:[1,0,1]
	v_mfma_f32_16x16x4_f32 v[102:105], v141, v56, v[102:105]
	v_pk_fma_f32 v[180:181], v[10:11], v[176:177], v[180:181] op_sel:[0,1,0]
	v_pk_fma_f32 v[192:193], v[12:13], v[176:177], v[192:193] op_sel:[0,1,0]
	v_pk_fma_f32 v[180:181], v[6:7], v[178:179], v[180:181] op_sel_hi:[1,0,1]
	v_pk_fma_f32 v[192:193], v[8:9], v[178:179], v[192:193] op_sel_hi:[1,0,1]
	v_mfma_f32_16x16x4_f32 v[98:101], v141, v57, v[98:101]
	v_pk_fma_f32 v[180:181], v[2:3], v[178:179], v[180:181] op_sel:[0,1,0]
	v_pk_fma_f32 v[192:193], v[4:5], v[178:179], v[192:193] op_sel:[0,1,0]
	v_pk_mul_f32 v[180:181], v[146:147], v[180:181]
	v_pk_mul_f32 v[192:193], v[146:147], v[192:193]
	v_pk_fma_f32 v[236:237], v[144:145], v[54:55], v[180:181]
	v_pk_fma_f32 v[238:239], v[144:145], v[56:57], v[192:193]
	global_store_dwordx4 v[150:151], v[236:239], off nt
	v_lshl_add_u64 v[150:151], v[150:151], 0, s[58:59]
	global_load_dwordx4 v[54:57], v[148:149], off nt
	v_lshl_add_u64 v[148:149], v[148:149], 0, s[58:59]
	ds_read_b32 v141, v160 offset:448
	ds_read_b128 v[114:117], v161 offset:3584
	ds_read_b128 v[176:179], v161 offset:3600
	s_waitcnt vmcnt(22)
	s_waitcnt lgkmcnt(3)
	v_cndmask_b32_e64 v143, 0, v143, s[6:7]
	v_pk_mul_f32 v[180:181], v[26:27], v[172:173] op_sel:[0,1]
	v_pk_mul_f32 v[192:193], v[28:29], v[172:173] op_sel:[0,1]
	v_mfma_f32_16x16x4_f32 v[110:113], v143, v50, v[110:113]
	v_pk_fma_f32 v[180:181], v[30:31], v[172:173], v[180:181] op_sel_hi:[1,0,1]
	v_pk_fma_f32 v[192:193], v[32:33], v[172:173], v[192:193] op_sel_hi:[1,0,1]
	v_pk_fma_f32 v[180:181], v[22:23], v[174:175], v[180:181] op_sel_hi:[1,0,1]
	v_pk_fma_f32 v[192:193], v[24:25], v[174:175], v[192:193] op_sel_hi:[1,0,1]
	v_mfma_f32_16x16x4_f32 v[106:109], v143, v51, v[106:109]
	v_pk_fma_f32 v[180:181], v[18:19], v[174:175], v[180:181] op_sel:[0,1,0]
	v_pk_fma_f32 v[192:193], v[20:21], v[174:175], v[192:193] op_sel:[0,1,0]
	v_pk_fma_f32 v[180:181], v[14:15], v[232:233], v[180:181] op_sel_hi:[1,0,1]
	v_pk_fma_f32 v[192:193], v[16:17], v[232:233], v[192:193] op_sel_hi:[1,0,1]
	v_mfma_f32_16x16x4_f32 v[102:105], v143, v52, v[102:105]
	v_pk_fma_f32 v[180:181], v[10:11], v[232:233], v[180:181] op_sel:[0,1,0]
	v_pk_fma_f32 v[192:193], v[12:13], v[232:233], v[192:193] op_sel:[0,1,0]
	v_pk_fma_f32 v[180:181], v[6:7], v[234:235], v[180:181] op_sel_hi:[1,0,1]
	v_pk_fma_f32 v[192:193], v[8:9], v[234:235], v[192:193] op_sel_hi:[1,0,1]
	v_mfma_f32_16x16x4_f32 v[98:101], v143, v53, v[98:101]
	v_pk_fma_f32 v[180:181], v[2:3], v[234:235], v[180:181] op_sel:[0,1,0]
	v_pk_fma_f32 v[192:193], v[4:5], v[234:235], v[192:193] op_sel:[0,1,0]
	v_pk_mul_f32 v[180:181], v[146:147], v[180:181]
	v_pk_mul_f32 v[192:193], v[146:147], v[192:193]
	v_pk_fma_f32 v[236:237], v[144:145], v[50:51], v[180:181]
	v_pk_fma_f32 v[238:239], v[144:145], v[52:53], v[192:193]
	global_store_dwordx4 v[150:151], v[236:239], off nt
	v_lshl_add_u64 v[150:151], v[150:151], 0, s[58:59]
	global_load_dwordx4 v[50:53], v[148:149], off nt
	v_lshl_add_u64 v[148:149], v[148:149], 0, s[58:59]
	ds_read_b32 v143, v160 offset:464
	ds_read_b128 v[172:175], v161 offset:3712
	ds_read_b128 v[232:235], v161 offset:3728
	s_waitcnt vmcnt(22)
; #define RS_LOAD(dst, it0) do { _Pragma("unroll") for (int u = 0; u < 8; ++u) dst[u] = __builtin_nontemporal_load((const f32x4*)(S0 + (size_t)(4 * ((it0) + u)) * DV)); } while (0)
; __device__ __forceinline__ void ret_sample_item(Frame& F, int item) {
;     ...
;     for (int it0 = 0; it0 < 64; it0 += 16) {
;         RS_LOAD(sb, it0 + 8);
;         RS_PROC(sa, it0);
;         { const int itn = it0 + 16 < 64 ? it0 + 16 : it0; RS_LOAD(sa, itn); }
;         RS_PROC(sb, it0 + 8);
;     }
	s_waitcnt lgkmcnt(3)
	v_cndmask_b32_e64 v141, 0, v141, s[6:7]
	v_pk_mul_f32 v[180:181], v[26:27], v[114:115] op_sel:[0,1]
	v_pk_mul_f32 v[192:193], v[28:29], v[114:115] op_sel:[0,1]
	v_mfma_f32_16x16x4_f32 v[110:113], v141, v46, v[110:113]
	v_pk_fma_f32 v[180:181], v[30:31], v[114:115], v[180:181] op_sel_hi:[1,0,1]
	v_pk_fma_f32 v[192:193], v[32:33], v[114:115], v[192:193] op_sel_hi:[1,0,1]
	v_pk_fma_f32 v[180:181], v[22:23], v[116:117], v[180:181] op_sel_hi:[1,0,1]
	v_pk_fma_f32 v[192:193], v[24:25], v[116:117], v[192:193] op_sel_hi:[1,0,1]
	v_mfma_f32_16x16x4_f32 v[106:109], v141, v47, v[106:109]
	v_pk_fma_f32 v[180:181], v[18:19], v[116:117], v[180:181] op_sel:[0,1,0]
	v_pk_fma_f32 v[192:193], v[20:21], v[116:117], v[192:193] op_sel:[0,1,0]
	v_pk_fma_f32 v[180:181], v[14:15], v[176:177], v[180:181] op_sel_hi:[1,0,1]
	v_pk_fma_f32 v[192:193], v[16:17], v[176:177], v[192:193] op_sel_hi:[1,0,1]
	v_mfma_f32_16x16x4_f32 v[102:105], v141, v48, v[102:105]
	v_pk_fma_f32 v[180:181], v[10:11], v[176:177], v[180:181] op_sel:[0,1,0]
	v_pk_fma_f32 v[192:193], v[12:13], v[176:177], v[192:193] op_sel:[0,1,0]
	v_pk_fma_f32 v[180:181], v[6:7], v[178:179], v[180:181] op_sel_hi:[1,0,1]
	v_pk_fma_f32 v[192:193], v[8:9], v[178:179], v[192:193] op_sel_hi:[1,0,1]
	v_mfma_f32_16x16x4_f32 v[98:101], v141, v49, v[98:101]
	v_pk_fma_f32 v[180:181], v[2:3], v[178:179], v[180:181] op_sel:[0,1,0]
	v_pk_fma_f32 v[192:193], v[4:5], v[178:179], v[192:193] op_sel:[0,1,0]
	v_pk_mul_f32 v[180:181], v[146:147], v[180:181]
	v_pk_mul_f32 v[192:193], v[146:147], v[192:193]
	v_pk_fma_f32 v[236:237], v[144:145], v[46:47], v[180:181]
	v_pk_fma_f32 v[238:239], v[144:145], v[48:49], v[192:193]
	global_store_dwordx4 v[150:151], v[236:239], off nt
	v_lshl_add_u64 v[150:151], v[150:151], 0, s[58:59]
	global_load_dwordx4 v[46:49], v[148:149], off nt
	v_lshl_add_u64 v[148:149], v[148:149], 0, s[58:59]
	ds_read_b32 v141, v160 offset:480
	ds_read_b128 v[114:117], v161 offset:3840
	ds_read_b128 v[176:179], v161 offset:3856
	s_waitcnt vmcnt(22)
	s_waitcnt lgkmcnt(3)
	v_cndmask_b32_e64 v143, 0, v143, s[6:7]
	v_pk_mul_f32 v[180:181], v[26:27], v[172:173] op_sel:[0,1]
	v_pk_mul_f32 v[192:193], v[28:29], v[172:173] op_sel:[0,1]
	v_mfma_f32_16x16x4_f32 v[110:113], v143, v42, v[110:113]
	v_pk_fma_f32 v[180:181], v[30:31], v[172:173], v[180:181] op_sel_hi:[1,0,1]
	v_pk_fma_f32 v[192:193], v[32:33], v[172:173], v[192:193] op_sel_hi:[1,0,1]
	v_pk_fma_f32 v[180:181], v[22:23], v[174:175], v[180:181] op_sel_hi:[1,0,1]
	v_pk_fma_f32 v[192:193], v[24:25], v[174:175], v[192:193] op_sel_hi:[1,0,1]
	v_mfma_f32_16x16x4_f32 v[106:109], v143, v43, v[106:109]
	v_pk_fma_f32 v[180:181], v[18:19], v[174:175], v[180:181] op_sel:[0,1,0]
	v_pk_fma_f32 v[192:193], v[20:21], v[174:175], v[192:193] op_sel:[0,1,0]
	v_pk_fma_f32 v[180:181], v[14:15], v[232:233], v[180:181] op_sel_hi:[1,0,1]
	v_pk_fma_f32 v[192:193], v[16:17], v[232:233], v[192:193] op_sel_hi:[1,0,1]
	v_mfma_f32_16x16x4_f32 v[102:105], v143, v44, v[102:105]
	v_pk_fma_f32 v[180:181], v[10:11], v[232:233], v[180:181] op_sel:[0,1,0]
	v_pk_fma_f32 v[192:193], v[12:13], v[232:233], v[192:193] op_sel:[0,1,0]
	v_pk_fma_f32 v[180:181], v[6:7], v[234:235], v[180:181] op_sel_hi:[1,0,1]
	v_pk_fma_f32 v[192:193], v[8:9], v[234:235], v[192:193] op_sel_hi:[1,0,1]
	v_mfma_f32_16x16x4_f32 v[98:101], v143, v45, v[98:101]
	v_pk_fma_f32 v[180:181], v[2:3], v[234:235], v[180:181] op_sel:[0,1,0]
	v_pk_fma_f32 v[192:193], v[4:5], v[234:235], v[192:193] op_sel:[0,1,0]
	v_pk_mul_f32 v[180:181], v[146:147], v[180:181]
	v_pk_mul_f32 v[192:193], v[146:147], v[192:193]
	v_pk_fma_f32 v[236:237], v[144:145], v[42:43], v[180:181]
	v_pk_fma_f32 v[238:239], v[144:145], v[44:45], v[192:193]
	global_store_dwordx4 v[150:151], v[236:239], off nt
	v_lshl_add_u64 v[150:151], v[150:151], 0, s[58:59]
	global_load_dwordx4 v[42:45], v[148:149], off nt
	v_lshl_add_u64 v[148:149], v[148:149], 0, s[58:59]
	ds_read_b32 v143, v160 offset:496
	ds_read_b128 v[172:175], v161 offset:3968
	ds_read_b128 v[232:235], v161 offset:3984
	s_waitcnt vmcnt(22)
	s_waitcnt lgkmcnt(3)
	v_cndmask_b32_e64 v141, 0, v141, s[6:7]
	v_pk_mul_f32 v[180:181], v[26:27], v[114:115] op_sel:[0,1]
	v_pk_mul_f32 v[192:193], v[28:29], v[114:115] op_sel:[0,1]
	v_mfma_f32_16x16x4_f32 v[110:113], v141, v38, v[110:113]
	v_pk_fma_f32 v[180:181], v[30:31], v[114:115], v[180:181] op_sel_hi:[1,0,1]
	v_pk_fma_f32 v[192:193], v[32:33], v[114:115], v[192:193] op_sel_hi:[1,0,1]
	v_pk_fma_f32 v[180:181], v[22:23], v[116:117], v[180:181] op_sel_hi:[1,0,1]
	v_pk_fma_f32 v[192:193], v[24:25], v[116:117], v[192:193] op_sel_hi:[1,0,1]
	v_mfma_f32_16x16x4_f32 v[106:109], v141, v39, v[106:109]
	v_pk_fma_f32 v[180:181], v[18:19], v[116:117], v[180:181] op_sel:[0,1,0]
	v_pk_fma_f32 v[192:193], v[20:21], v[116:117], v[192:193] op_sel:[0,1,0]
	v_pk_fma_f32 v[180:181], v[14:15], v[176:177], v[180:181] op_sel_hi:[1,0,1]
	v_pk_fma_f32 v[192:193], v[16:17], v[176:177], v[192:193] op_sel_hi:[1,0,1]
	v_mfma_f32_16x16x4_f32 v[102:105], v141, v40, v[102:105]
	v_pk_fma_f32 v[180:181], v[10:11], v[176:177], v[180:181] op_sel:[0,1,0]
	v_pk_fma_f32 v[192:193], v[12:13], v[176:177], v[192:193] op_sel:[0,1,0]
	v_pk_fma_f32 v[180:181], v[6:7], v[178:179], v[180:181] op_sel_hi:[1,0,1]
	v_pk_fma_f32 v[192:193], v[8:9], v[178:179], v[192:193] op_sel_hi:[1,0,1]
	v_mfma_f32_16x16x4_f32 v[98:101], v141, v41, v[98:101]
	v_pk_fma_f32 v[180:181], v[2:3], v[178:179], v[180:181] op_sel:[0,1,0]
	v_pk_fma_f32 v[192:193], v[4:5], v[178:179], v[192:193] op_sel:[0,1,0]
	v_pk_mul_f32 v[180:181], v[146:147], v[180:181]
	v_pk_mul_f32 v[192:193], v[146:147], v[192:193]
	v_pk_fma_f32 v[236:237], v[144:145], v[38:39], v[180:181]
	v_pk_fma_f32 v[238:239], v[144:145], v[40:41], v[192:193]
	global_store_dwordx4 v[150:151], v[236:239], off nt
	v_lshl_add_u64 v[150:151], v[150:151], 0, s[58:59]
	global_load_dwordx4 v[38:41], v[148:149], off nt
	v_lshl_add_u64 v[148:149], v[148:149], 0, s[58:59]
	ds_read_b32 v141, v160 offset:512
	ds_read_b128 v[114:117], v161 offset:4096
	ds_read_b128 v[176:179], v161 offset:4112
	s_waitcnt vmcnt(22)
; #define RS_LOAD(dst, it0) do { _Pragma("unroll") for (int u = 0; u < 8; ++u) dst[u] = __builtin_nontemporal_load((const f32x4*)(S0 + (size_t)(4 * ((it0) + u)) * DV)); } while (0)
; __device__ __forceinline__ void ret_sample_item(Frame& F, int item) {
;     ...
;     for (int it0 = 0; it0 < 64; it0 += 16) {
;         RS_LOAD(sb, it0 + 8);
;         RS_PROC(sa, it0);
;         { const int itn = it0 + 16 < 64 ? it0 + 16 : it0; RS_LOAD(sa, itn); }
;         RS_PROC(sb, it0 + 8);
;     }
	s_waitcnt lgkmcnt(3)
	v_cndmask_b32_e64 v143, 0, v143, s[6:7]
	v_pk_mul_f32 v[180:181], v[26:27], v[172:173] op_sel:[0,1]
	v_pk_mul_f32 v[192:193], v[28:29], v[172:173] op_sel:[0,1]
	v_mfma_f32_16x16x4_f32 v[110:113], v143, v34, v[110:113]
	v_pk_fma_f32 v[180:181], v[30:31], v[172:173], v[180:181] op_sel_hi:[1,0,1]
	v_pk_fma_f32 v[192:193], v[32:33], v[172:173], v[192:193] op_sel_hi:[1,0,1]
	v_pk_fma_f32 v[180:181], v[22:23], v[174:175], v[180:181] op_sel_hi:[1,0,1]
	v_pk_fma_f32 v[192:193], v[24:25], v[174:175], v[192:193] op_sel_hi:[1,0,1]
	v_mfma_f32_16x16x4_f32 v[106:109], v143, v35, v[106:109]
	v_pk_fma_f32 v[180:181], v[18:19], v[174:175], v[180:181] op_sel:[0,1,0]
	v_pk_fma_f32 v[192:193], v[20:21], v[174:175], v[192:193] op_sel:[0,1,0]
	v_pk_fma_f32 v[180:181], v[14:15], v[232:233], v[180:181] op_sel_hi:[1,0,1]
	v_pk_fma_f32 v[192:193], v[16:17], v[232:233], v[192:193] op_sel_hi:[1,0,1]
	v_mfma_f32_16x16x4_f32 v[102:105], v143, v36, v[102:105]
	v_pk_fma_f32 v[180:181], v[10:11], v[232:233], v[180:181] op_sel:[0,1,0]
	v_pk_fma_f32 v[192:193], v[12:13], v[232:233], v[192:193] op_sel:[0,1,0]
	v_pk_fma_f32 v[180:181], v[6:7], v[234:235], v[180:181] op_sel_hi:[1,0,1]
	v_pk_fma_f32 v[192:193], v[8:9], v[234:235], v[192:193] op_sel_hi:[1,0,1]
	v_mfma_f32_16x16x4_f32 v[98:101], v143, v37, v[98:101]
	v_pk_fma_f32 v[180:181], v[2:3], v[234:235], v[180:181] op_sel:[0,1,0]
	v_pk_fma_f32 v[192:193], v[4:5], v[234:235], v[192:193] op_sel:[0,1,0]
	v_pk_mul_f32 v[180:181], v[146:147], v[180:181]
	v_pk_mul_f32 v[192:193], v[146:147], v[192:193]
	v_pk_fma_f32 v[236:237], v[144:145], v[34:35], v[180:181]
	v_pk_fma_f32 v[238:239], v[144:145], v[36:37], v[192:193]
	global_store_dwordx4 v[150:151], v[236:239], off nt
	v_lshl_add_u64 v[150:151], v[150:151], 0, s[58:59]
	global_load_dwordx4 v[34:37], v[148:149], off nt
	v_lshl_add_u64 v[148:149], v[148:149], 0, s[58:59]
	ds_read_b32 v143, v160 offset:528
	ds_read_b128 v[172:175], v161 offset:4224
	ds_read_b128 v[232:235], v161 offset:4240
	s_waitcnt vmcnt(22)
	s_waitcnt lgkmcnt(3)
	v_cndmask_b32_e64 v141, 0, v141, s[6:7]
	v_pk_mul_f32 v[180:181], v[26:27], v[114:115] op_sel:[0,1]
	v_pk_mul_f32 v[192:193], v[28:29], v[114:115] op_sel:[0,1]
	v_mfma_f32_16x16x4_f32 v[110:113], v141, v58, v[110:113]
	v_pk_fma_f32 v[180:181], v[30:31], v[114:115], v[180:181] op_sel_hi:[1,0,1]
	v_pk_fma_f32 v[192:193], v[32:33], v[114:115], v[192:193] op_sel_hi:[1,0,1]
	v_pk_fma_f32 v[180:181], v[22:23], v[116:117], v[180:181] op_sel_hi:[1,0,1]
	v_pk_fma_f32 v[192:193], v[24:25], v[116:117], v[192:193] op_sel_hi:[1,0,1]
	v_mfma_f32_16x16x4_f32 v[106:109], v141, v59, v[106:109]
	v_pk_fma_f32 v[180:181], v[18:19], v[116:117], v[180:181] op_sel:[0,1,0]
	v_pk_fma_f32 v[192:193], v[20:21], v[116:117], v[192:193] op_sel:[0,1,0]
	v_pk_fma_f32 v[180:181], v[14:15], v[176:177], v[180:181] op_sel_hi:[1,0,1]
	v_pk_fma_f32 v[192:193], v[16:17], v[176:177], v[192:193] op_sel_hi:[1,0,1]
	v_mfma_f32_16x16x4_f32 v[102:105], v141, v60, v[102:105]
	v_pk_fma_f32 v[180:181], v[10:11], v[176:177], v[180:181] op_sel:[0,1,0]
	v_pk_fma_f32 v[192:193], v[12:13], v[176:177], v[192:193] op_sel:[0,1,0]
	v_pk_fma_f32 v[180:181], v[6:7], v[178:179], v[180:181] op_sel_hi:[1,0,1]
	v_pk_fma_f32 v[192:193], v[8:9], v[178:179], v[192:193] op_sel_hi:[1,0,1]
	v_mfma_f32_16x16x4_f32 v[98:101], v141, v61, v[98:101]
	v_pk_fma_f32 v[180:181], v[2:3], v[178:179], v[180:181] op_sel:[0,1,0]
	v_pk_fma_f32 v[192:193], v[4:5], v[178:179], v[192:193] op_sel:[0,1,0]
	v_pk_mul_f32 v[180:181], v[146:147], v[180:181]
	v_pk_mul_f32 v[192:193], v[146:147], v[192:193]
	v_pk_fma_f32 v[236:237], v[144:145], v[58:59], v[180:181]
	v_pk_fma_f32 v[238:239], v[144:145], v[60:61], v[192:193]
	global_store_dwordx4 v[150:151], v[236:239], off nt
	v_lshl_add_u64 v[150:151], v[150:151], 0, s[58:59]
	global_load_dwordx4 v[58:61], v[148:149], off nt
	v_lshl_add_u64 v[148:149], v[148:149], 0, s[58:59]
	ds_read_b32 v141, v160 offset:544
	ds_read_b128 v[114:117], v161 offset:4352
	ds_read_b128 v[176:179], v161 offset:4368
	s_waitcnt vmcnt(22)
	s_waitcnt lgkmcnt(3)
	v_cndmask_b32_e64 v143, 0, v143, s[6:7]
	v_pk_mul_f32 v[180:181], v[26:27], v[172:173] op_sel:[0,1]
	v_pk_mul_f32 v[192:193], v[28:29], v[172:173] op_sel:[0,1]
	v_mfma_f32_16x16x4_f32 v[110:113], v143, v66, v[110:113]
	v_pk_fma_f32 v[180:181], v[30:31], v[172:173], v[180:181] op_sel_hi:[1,0,1]
	v_pk_fma_f32 v[192:193], v[32:33], v[172:173], v[192:193] op_sel_hi:[1,0,1]
	v_pk_fma_f32 v[180:181], v[22:23], v[174:175], v[180:181] op_sel_hi:[1,0,1]
	v_pk_fma_f32 v[192:193], v[24:25], v[174:175], v[192:193] op_sel_hi:[1,0,1]
	v_mfma_f32_16x16x4_f32 v[106:109], v143, v67, v[106:109]
	v_pk_fma_f32 v[180:181], v[18:19], v[174:175], v[180:181] op_sel:[0,1,0]
	v_pk_fma_f32 v[192:193], v[20:21], v[174:175], v[192:193] op_sel:[0,1,0]
	v_pk_fma_f32 v[180:181], v[14:15], v[232:233], v[180:181] op_sel_hi:[1,0,1]
	v_pk_fma_f32 v[192:193], v[16:17], v[232:233], v[192:193] op_sel_hi:[1,0,1]
	v_mfma_f32_16x16x4_f32 v[102:105], v143, v68, v[102:105]
	v_pk_fma_f32 v[180:181], v[10:11], v[232:233], v[180:181] op_sel:[0,1,0]
	v_pk_fma_f32 v[192:193], v[12:13], v[232:233], v[192:193] op_sel:[0,1,0]
	v_pk_fma_f32 v[180:181], v[6:7], v[234:235], v[180:181] op_sel_hi:[1,0,1]
	v_pk_fma_f32 v[192:193], v[8:9], v[234:235], v[192:193] op_sel_hi:[1,0,1]
	v_mfma_f32_16x16x4_f32 v[98:101], v143, v69, v[98:101]
	v_pk_fma_f32 v[180:181], v[2:3], v[234:235], v[180:181] op_sel:[0,1,0]
	v_pk_fma_f32 v[192:193], v[4:5], v[234:235], v[192:193] op_sel:[0,1,0]
	v_pk_mul_f32 v[180:181], v[146:147], v[180:181]
	v_pk_mul_f32 v[192:193], v[146:147], v[192:193]
	v_pk_fma_f32 v[236:237], v[144:145], v[66:67], v[180:181]
	v_pk_fma_f32 v[238:239], v[144:145], v[68:69], v[192:193]
	global_store_dwordx4 v[150:151], v[236:239], off nt
	v_lshl_add_u64 v[150:151], v[150:151], 0, s[58:59]
	global_load_dwordx4 v[66:69], v[148:149], off nt
	v_lshl_add_u64 v[148:149], v[148:149], 0, s[58:59]
	ds_read_b32 v143, v160 offset:560
	ds_read_b128 v[172:175], v161 offset:4480
	ds_read_b128 v[232:235], v161 offset:4496
	s_waitcnt vmcnt(22)
; #define RS_LOAD(dst, it0) do { _Pragma("unroll") for (int u = 0; u < 8; ++u) dst[u] = __builtin_nontemporal_load((const f32x4*)(S0 + (size_t)(4 * ((it0) + u)) * DV)); } while (0)
; __device__ __forceinline__ void ret_sample_item(Frame& F, int item) {
;     ...
;     for (int it0 = 0; it0 < 64; it0 += 16) {
;         RS_LOAD(sb, it0 + 8);
;         RS_PROC(sa, it0);
;         { const int itn = it0 + 16 < 64 ? it0 + 16 : it0; RS_LOAD(sa, itn); }
;         RS_PROC(sb, it0 + 8);
;     }
	s_waitcnt lgkmcnt(3)
	v_cndmask_b32_e64 v141, 0, v141, s[6:7]
	v_pk_mul_f32 v[180:181], v[26:27], v[114:115] op_sel:[0,1]
	v_pk_mul_f32 v[192:193], v[28:29], v[114:115] op_sel:[0,1]
	v_mfma_f32_16x16x4_f32 v[110:113], v141, v74, v[110:113]
	v_pk_fma_f32 v[180:181], v[30:31], v[114:115], v[180:181] op_sel_hi:[1,0,1]
	v_pk_fma_f32 v[192:193], v[32:33], v[114:115], v[192:193] op_sel_hi:[1,0,1]
	v_pk_fma_f32 v[180:181], v[22:23], v[116:117], v[180:181] op_sel_hi:[1,0,1]
	v_pk_fma_f32 v[192:193], v[24:25], v[116:117], v[192:193] op_sel_hi:[1,0,1]
	v_mfma_f32_16x16x4_f32 v[106:109], v141, v75, v[106:109]
	v_pk_fma_f32 v[180:181], v[18:19], v[116:117], v[180:181] op_sel:[0,1,0]
	v_pk_fma_f32 v[192:193], v[20:21], v[116:117], v[192:193] op_sel:[0,1,0]
	v_pk_fma_f32 v[180:181], v[14:15], v[176:177], v[180:181] op_sel_hi:[1,0,1]
	v_pk_fma_f32 v[192:193], v[16:17], v[176:177], v[192:193] op_sel_hi:[1,0,1]
	v_mfma_f32_16x16x4_f32 v[102:105], v141, v76, v[102:105]
	v_pk_fma_f32 v[180:181], v[10:11], v[176:177], v[180:181] op_sel:[0,1,0]
	v_pk_fma_f32 v[192:193], v[12:13], v[176:177], v[192:193] op_sel:[0,1,0]
	v_pk_fma_f32 v[180:181], v[6:7], v[178:179], v[180:181] op_sel_hi:[1,0,1]
	v_pk_fma_f32 v[192:193], v[8:9], v[178:179], v[192:193] op_sel_hi:[1,0,1]
	v_mfma_f32_16x16x4_f32 v[98:101], v141, v77, v[98:101]
	v_pk_fma_f32 v[180:181], v[2:3], v[178:179], v[180:181] op_sel:[0,1,0]
	v_pk_fma_f32 v[192:193], v[4:5], v[178:179], v[192:193] op_sel:[0,1,0]
	v_pk_mul_f32 v[180:181], v[146:147], v[180:181]
	v_pk_mul_f32 v[192:193], v[146:147], v[192:193]
	v_pk_fma_f32 v[236:237], v[144:145], v[74:75], v[180:181]
	v_pk_fma_f32 v[238:239], v[144:145], v[76:77], v[192:193]
	global_store_dwordx4 v[150:151], v[236:239], off nt
	v_lshl_add_u64 v[150:151], v[150:151], 0, s[58:59]
	global_load_dwordx4 v[74:77], v[148:149], off nt
	v_lshl_add_u64 v[148:149], v[148:149], 0, s[58:59]
	ds_read_b32 v141, v160 offset:576
	ds_read_b128 v[114:117], v161 offset:4608
	ds_read_b128 v[176:179], v161 offset:4624
	s_waitcnt vmcnt(22)
	s_waitcnt lgkmcnt(3)
	v_cndmask_b32_e64 v143, 0, v143, s[6:7]
	v_pk_mul_f32 v[180:181], v[26:27], v[172:173] op_sel:[0,1]
	v_pk_mul_f32 v[192:193], v[28:29], v[172:173] op_sel:[0,1]
	v_mfma_f32_16x16x4_f32 v[110:113], v143, v78, v[110:113]
	v_pk_fma_f32 v[180:181], v[30:31], v[172:173], v[180:181] op_sel_hi:[1,0,1]
	v_pk_fma_f32 v[192:193], v[32:33], v[172:173], v[192:193] op_sel_hi:[1,0,1]
	v_pk_fma_f32 v[180:181], v[22:23], v[174:175], v[180:181] op_sel_hi:[1,0,1]
	v_pk_fma_f32 v[192:193], v[24:25], v[174:175], v[192:193] op_sel_hi:[1,0,1]
	v_mfma_f32_16x16x4_f32 v[106:109], v143, v79, v[106:109]
	v_pk_fma_f32 v[180:181], v[18:19], v[174:175], v[180:181] op_sel:[0,1,0]
	v_pk_fma_f32 v[192:193], v[20:21], v[174:175], v[192:193] op_sel:[0,1,0]
	v_pk_fma_f32 v[180:181], v[14:15], v[232:233], v[180:181] op_sel_hi:[1,0,1]
	v_pk_fma_f32 v[192:193], v[16:17], v[232:233], v[192:193] op_sel_hi:[1,0,1]
	v_mfma_f32_16x16x4_f32 v[102:105], v143, v80, v[102:105]
	v_pk_fma_f32 v[180:181], v[10:11], v[232:233], v[180:181] op_sel:[0,1,0]
	v_pk_fma_f32 v[192:193], v[12:13], v[232:233], v[192:193] op_sel:[0,1,0]
	v_pk_fma_f32 v[180:181], v[6:7], v[234:235], v[180:181] op_sel_hi:[1,0,1]
	v_pk_fma_f32 v[192:193], v[8:9], v[234:235], v[192:193] op_sel_hi:[1,0,1]
	v_mfma_f32_16x16x4_f32 v[98:101], v143, v81, v[98:101]
	v_pk_fma_f32 v[180:181], v[2:3], v[234:235], v[180:181] op_sel:[0,1,0]
	v_pk_fma_f32 v[192:193], v[4:5], v[234:235], v[192:193] op_sel:[0,1,0]
	v_pk_mul_f32 v[180:181], v[146:147], v[180:181]
	v_pk_mul_f32 v[192:193], v[146:147], v[192:193]
	v_pk_fma_f32 v[236:237], v[144:145], v[78:79], v[180:181]
	v_pk_fma_f32 v[238:239], v[144:145], v[80:81], v[192:193]
	global_store_dwordx4 v[150:151], v[236:239], off nt
	v_lshl_add_u64 v[150:151], v[150:151], 0, s[58:59]
	global_load_dwordx4 v[78:81], v[148:149], off nt
	v_lshl_add_u64 v[148:149], v[148:149], 0, s[58:59]
	ds_read_b32 v143, v160 offset:592
	ds_read_b128 v[172:175], v161 offset:4736
	ds_read_b128 v[232:235], v161 offset:4752
	s_waitcnt vmcnt(22)
	s_waitcnt lgkmcnt(3)
	v_cndmask_b32_e64 v141, 0, v141, s[6:7]
	v_pk_mul_f32 v[180:181], v[26:27], v[114:115] op_sel:[0,1]
	v_pk_mul_f32 v[192:193], v[28:29], v[114:115] op_sel:[0,1]
	v_mfma_f32_16x16x4_f32 v[110:113], v141, v70, v[110:113]
	v_pk_fma_f32 v[180:181], v[30:31], v[114:115], v[180:181] op_sel_hi:[1,0,1]
	v_pk_fma_f32 v[192:193], v[32:33], v[114:115], v[192:193] op_sel_hi:[1,0,1]
	v_pk_fma_f32 v[180:181], v[22:23], v[116:117], v[180:181] op_sel_hi:[1,0,1]
	v_pk_fma_f32 v[192:193], v[24:25], v[116:117], v[192:193] op_sel_hi:[1,0,1]
	v_mfma_f32_16x16x4_f32 v[106:109], v141, v71, v[106:109]
	v_pk_fma_f32 v[180:181], v[18:19], v[116:117], v[180:181] op_sel:[0,1,0]
	v_pk_fma_f32 v[192:193], v[20:21], v[116:117], v[192:193] op_sel:[0,1,0]
	v_pk_fma_f32 v[180:181], v[14:15], v[176:177], v[180:181] op_sel_hi:[1,0,1]
	v_pk_fma_f32 v[192:193], v[16:17], v[176:177], v[192:193] op_sel_hi:[1,0,1]
	v_mfma_f32_16x16x4_f32 v[102:105], v141, v72, v[102:105]
	v_pk_fma_f32 v[180:181], v[10:11], v[176:177], v[180:181] op_sel:[0,1,0]
	v_pk_fma_f32 v[192:193], v[12:13], v[176:177], v[192:193] op_sel:[0,1,0]
	v_pk_fma_f32 v[180:181], v[6:7], v[178:179], v[180:181] op_sel_hi:[1,0,1]
	v_pk_fma_f32 v[192:193], v[8:9], v[178:179], v[192:193] op_sel_hi:[1,0,1]
	v_mfma_f32_16x16x4_f32 v[98:101], v141, v73, v[98:101]
	v_pk_fma_f32 v[180:181], v[2:3], v[178:179], v[180:181] op_sel:[0,1,0]
	v_pk_fma_f32 v[192:193], v[4:5], v[178:179], v[192:193] op_sel:[0,1,0]
	v_pk_mul_f32 v[180:181], v[146:147], v[180:181]
	v_pk_mul_f32 v[192:193], v[146:147], v[192:193]
	v_pk_fma_f32 v[236:237], v[144:145], v[70:71], v[180:181]
	v_pk_fma_f32 v[238:239], v[144:145], v[72:73], v[192:193]
	global_store_dwordx4 v[150:151], v[236:239], off nt
	v_lshl_add_u64 v[150:151], v[150:151], 0, s[58:59]
	global_load_dwordx4 v[70:73], v[148:149], off nt
	v_lshl_add_u64 v[148:149], v[148:149], 0, s[58:59]
	ds_read_b32 v141, v160 offset:608
	ds_read_b128 v[114:117], v161 offset:4864
	ds_read_b128 v[176:179], v161 offset:4880
	s_waitcnt vmcnt(22)
; #define RS_LOAD(dst, it0) do { _Pragma("unroll") for (int u = 0; u < 8; ++u) dst[u] = __builtin_nontemporal_load((const f32x4*)(S0 + (size_t)(4 * ((it0) + u)) * DV)); } while (0)
; __device__ __forceinline__ void ret_sample_item(Frame& F, int item) {
;     ...
;     for (int it0 = 0; it0 < 64; it0 += 16) {
;         RS_LOAD(sb, it0 + 8);
;         RS_PROC(sa, it0);
;         { const int itn = it0 + 16 < 64 ? it0 + 16 : it0; RS_LOAD(sa, itn); }
;         RS_PROC(sb, it0 + 8);
;     }
	s_waitcnt lgkmcnt(3)
	v_cndmask_b32_e64 v143, 0, v143, s[6:7]
	v_pk_mul_f32 v[180:181], v[26:27], v[172:173] op_sel:[0,1]
	v_pk_mul_f32 v[192:193], v[28:29], v[172:173] op_sel:[0,1]
	v_mfma_f32_16x16x4_f32 v[110:113], v143, v62, v[110:113]
	v_pk_fma_f32 v[180:181], v[30:31], v[172:173], v[180:181] op_sel_hi:[1,0,1]
	v_pk_fma_f32 v[192:193], v[32:33], v[172:173], v[192:193] op_sel_hi:[1,0,1]
	v_pk_fma_f32 v[180:181], v[22:23], v[174:175], v[180:181] op_sel_hi:[1,0,1]
	v_pk_fma_f32 v[192:193], v[24:25], v[174:175], v[192:193] op_sel_hi:[1,0,1]
	v_mfma_f32_16x16x4_f32 v[106:109], v143, v63, v[106:109]
	v_pk_fma_f32 v[180:181], v[18:19], v[174:175], v[180:181] op_sel:[0,1,0]
	v_pk_fma_f32 v[192:193], v[20:21], v[174:175], v[192:193] op_sel:[0,1,0]
	v_pk_fma_f32 v[180:181], v[14:15], v[232:233], v[180:181] op_sel_hi:[1,0,1]
	v_pk_fma_f32 v[192:193], v[16:17], v[232:233], v[192:193] op_sel_hi:[1,0,1]
	v_mfma_f32_16x16x4_f32 v[102:105], v143, v64, v[102:105]
	v_pk_fma_f32 v[180:181], v[10:11], v[232:233], v[180:181] op_sel:[0,1,0]
	v_pk_fma_f32 v[192:193], v[12:13], v[232:233], v[192:193] op_sel:[0,1,0]
	v_pk_fma_f32 v[180:181], v[6:7], v[234:235], v[180:181] op_sel_hi:[1,0,1]
	v_pk_fma_f32 v[192:193], v[8:9], v[234:235], v[192:193] op_sel_hi:[1,0,1]
	v_mfma_f32_16x16x4_f32 v[98:101], v143, v65, v[98:101]
	v_pk_fma_f32 v[180:181], v[2:3], v[234:235], v[180:181] op_sel:[0,1,0]
	v_pk_fma_f32 v[192:193], v[4:5], v[234:235], v[192:193] op_sel:[0,1,0]
	v_pk_mul_f32 v[180:181], v[146:147], v[180:181]
	v_pk_mul_f32 v[192:193], v[146:147], v[192:193]
	v_pk_fma_f32 v[236:237], v[144:145], v[62:63], v[180:181]
	v_pk_fma_f32 v[238:239], v[144:145], v[64:65], v[192:193]
	global_store_dwordx4 v[150:151], v[236:239], off nt
	v_lshl_add_u64 v[150:151], v[150:151], 0, s[58:59]
	global_load_dwordx4 v[62:65], v[148:149], off nt
	v_lshl_add_u64 v[148:149], v[148:149], 0, s[58:59]
	ds_read_b32 v143, v160 offset:624
	ds_read_b128 v[172:175], v161 offset:4992
	ds_read_b128 v[232:235], v161 offset:5008
	s_waitcnt vmcnt(22)
	s_waitcnt lgkmcnt(3)
	v_cndmask_b32_e64 v141, 0, v141, s[6:7]
	v_pk_mul_f32 v[180:181], v[26:27], v[114:115] op_sel:[0,1]
	v_pk_mul_f32 v[192:193], v[28:29], v[114:115] op_sel:[0,1]
	v_mfma_f32_16x16x4_f32 v[110:113], v141, v54, v[110:113]
	v_pk_fma_f32 v[180:181], v[30:31], v[114:115], v[180:181] op_sel_hi:[1,0,1]
	v_pk_fma_f32 v[192:193], v[32:33], v[114:115], v[192:193] op_sel_hi:[1,0,1]
	v_pk_fma_f32 v[180:181], v[22:23], v[116:117], v[180:181] op_sel_hi:[1,0,1]
	v_pk_fma_f32 v[192:193], v[24:25], v[116:117], v[192:193] op_sel_hi:[1,0,1]
	v_mfma_f32_16x16x4_f32 v[106:109], v141, v55, v[106:109]
	v_pk_fma_f32 v[180:181], v[18:19], v[116:117], v[180:181] op_sel:[0,1,0]
	v_pk_fma_f32 v[192:193], v[20:21], v[116:117], v[192:193] op_sel:[0,1,0]
	v_pk_fma_f32 v[180:181], v[14:15], v[176:177], v[180:181] op_sel_hi:[1,0,1]
	v_pk_fma_f32 v[192:193], v[16:17], v[176:177], v[192:193] op_sel_hi:[1,0,1]
	v_mfma_f32_16x16x4_f32 v[102:105], v141, v56, v[102:105]
	v_pk_fma_f32 v[180:181], v[10:11], v[176:177], v[180:181] op_sel:[0,1,0]
	v_pk_fma_f32 v[192:193], v[12:13], v[176:177], v[192:193] op_sel:[0,1,0]
	v_pk_fma_f32 v[180:181], v[6:7], v[178:179], v[180:181] op_sel_hi:[1,0,1]
	v_pk_fma_f32 v[192:193], v[8:9], v[178:179], v[192:193] op_sel_hi:[1,0,1]
	v_mfma_f32_16x16x4_f32 v[98:101], v141, v57, v[98:101]
	v_pk_fma_f32 v[180:181], v[2:3], v[178:179], v[180:181] op_sel:[0,1,0]
	v_pk_fma_f32 v[192:193], v[4:5], v[178:179], v[192:193] op_sel:[0,1,0]
	v_pk_mul_f32 v[180:181], v[146:147], v[180:181]
	v_pk_mul_f32 v[192:193], v[146:147], v[192:193]
	v_pk_fma_f32 v[236:237], v[144:145], v[54:55], v[180:181]
	v_pk_fma_f32 v[238:239], v[144:145], v[56:57], v[192:193]
	global_store_dwordx4 v[150:151], v[236:239], off nt
	v_lshl_add_u64 v[150:151], v[150:151], 0, s[58:59]
	global_load_dwordx4 v[54:57], v[148:149], off nt
	v_lshl_add_u64 v[148:149], v[148:149], 0, s[58:59]
	ds_read_b32 v141, v160 offset:640
	ds_read_b128 v[114:117], v161 offset:5120
	ds_read_b128 v[176:179], v161 offset:5136
	s_waitcnt vmcnt(22)
	s_waitcnt lgkmcnt(3)
	v_cndmask_b32_e64 v143, 0, v143, s[6:7]
	v_pk_mul_f32 v[180:181], v[26:27], v[172:173] op_sel:[0,1]
	v_pk_mul_f32 v[192:193], v[28:29], v[172:173] op_sel:[0,1]
	v_mfma_f32_16x16x4_f32 v[110:113], v143, v50, v[110:113]
	v_pk_fma_f32 v[180:181], v[30:31], v[172:173], v[180:181] op_sel_hi:[1,0,1]
	v_pk_fma_f32 v[192:193], v[32:33], v[172:173], v[192:193] op_sel_hi:[1,0,1]
	v_pk_fma_f32 v[180:181], v[22:23], v[174:175], v[180:181] op_sel_hi:[1,0,1]
	v_pk_fma_f32 v[192:193], v[24:25], v[174:175], v[192:193] op_sel_hi:[1,0,1]
	v_mfma_f32_16x16x4_f32 v[106:109], v143, v51, v[106:109]
	v_pk_fma_f32 v[180:181], v[18:19], v[174:175], v[180:181] op_sel:[0,1,0]
	v_pk_fma_f32 v[192:193], v[20:21], v[174:175], v[192:193] op_sel:[0,1,0]
	v_pk_fma_f32 v[180:181], v[14:15], v[232:233], v[180:181] op_sel_hi:[1,0,1]
	v_pk_fma_f32 v[192:193], v[16:17], v[232:233], v[192:193] op_sel_hi:[1,0,1]
	v_mfma_f32_16x16x4_f32 v[102:105], v143, v52, v[102:105]
	v_pk_fma_f32 v[180:181], v[10:11], v[232:233], v[180:181] op_sel:[0,1,0]
	v_pk_fma_f32 v[192:193], v[12:13], v[232:233], v[192:193] op_sel:[0,1,0]
	v_pk_fma_f32 v[180:181], v[6:7], v[234:235], v[180:181] op_sel_hi:[1,0,1]
	v_pk_fma_f32 v[192:193], v[8:9], v[234:235], v[192:193] op_sel_hi:[1,0,1]
	v_mfma_f32_16x16x4_f32 v[98:101], v143, v53, v[98:101]
	v_pk_fma_f32 v[180:181], v[2:3], v[234:235], v[180:181] op_sel:[0,1,0]
	v_pk_fma_f32 v[192:193], v[4:5], v[234:235], v[192:193] op_sel:[0,1,0]
	v_pk_mul_f32 v[180:181], v[146:147], v[180:181]
	v_pk_mul_f32 v[192:193], v[146:147], v[192:193]
	v_pk_fma_f32 v[236:237], v[144:145], v[50:51], v[180:181]
	v_pk_fma_f32 v[238:239], v[144:145], v[52:53], v[192:193]
	global_store_dwordx4 v[150:151], v[236:239], off nt
	v_lshl_add_u64 v[150:151], v[150:151], 0, s[58:59]
	global_load_dwordx4 v[50:53], v[148:149], off nt
	v_lshl_add_u64 v[148:149], v[148:149], 0, s[58:59]
	ds_read_b32 v143, v160 offset:656
	ds_read_b128 v[172:175], v161 offset:5248
	ds_read_b128 v[232:235], v161 offset:5264
	s_waitcnt vmcnt(22)
; #define RS_LOAD(dst, it0) do { _Pragma("unroll") for (int u = 0; u < 8; ++u) dst[u] = __builtin_nontemporal_load((const f32x4*)(S0 + (size_t)(4 * ((it0) + u)) * DV)); } while (0)
; __device__ __forceinline__ void ret_sample_item(Frame& F, int item) {
;     ...
;     for (int it0 = 0; it0 < 64; it0 += 16) {
;         RS_LOAD(sb, it0 + 8);
;         RS_PROC(sa, it0);
;         { const int itn = it0 + 16 < 64 ? it0 + 16 : it0; RS_LOAD(sa, itn); }
;         RS_PROC(sb, it0 + 8);
;     }
	s_waitcnt lgkmcnt(3)
	v_cndmask_b32_e64 v141, 0, v141, s[6:7]
	v_pk_mul_f32 v[180:181], v[26:27], v[114:115] op_sel:[0,1]
	v_pk_mul_f32 v[192:193], v[28:29], v[114:115] op_sel:[0,1]
	v_mfma_f32_16x16x4_f32 v[110:113], v141, v46, v[110:113]
	v_pk_fma_f32 v[180:181], v[30:31], v[114:115], v[180:181] op_sel_hi:[1,0,1]
	v_pk_fma_f32 v[192:193], v[32:33], v[114:115], v[192:193] op_sel_hi:[1,0,1]
	v_pk_fma_f32 v[180:181], v[22:23], v[116:117], v[180:181] op_sel_hi:[1,0,1]
	v_pk_fma_f32 v[192:193], v[24:25], v[116:117], v[192:193] op_sel_hi:[1,0,1]
	v_mfma_f32_16x16x4_f32 v[106:109], v141, v47, v[106:109]
	v_pk_fma_f32 v[180:181], v[18:19], v[116:117], v[180:181] op_sel:[0,1,0]
	v_pk_fma_f32 v[192:193], v[20:21], v[116:117], v[192:193] op_sel:[0,1,0]
	v_pk_fma_f32 v[180:181], v[14:15], v[176:177], v[180:181] op_sel_hi:[1,0,1]
	v_pk_fma_f32 v[192:193], v[16:17], v[176:177], v[192:193] op_sel_hi:[1,0,1]
	v_mfma_f32_16x16x4_f32 v[102:105], v141, v48, v[102:105]
	v_pk_fma_f32 v[180:181], v[10:11], v[176:177], v[180:181] op_sel:[0,1,0]
	v_pk_fma_f32 v[192:193], v[12:13], v[176:177], v[192:193] op_sel:[0,1,0]
	v_pk_fma_f32 v[180:181], v[6:7], v[178:179], v[180:181] op_sel_hi:[1,0,1]
	v_pk_fma_f32 v[192:193], v[8:9], v[178:179], v[192:193] op_sel_hi:[1,0,1]
	v_mfma_f32_16x16x4_f32 v[98:101], v141, v49, v[98:101]
	v_pk_fma_f32 v[180:181], v[2:3], v[178:179], v[180:181] op_sel:[0,1,0]
	v_pk_fma_f32 v[192:193], v[4:5], v[178:179], v[192:193] op_sel:[0,1,0]
	v_pk_mul_f32 v[180:181], v[146:147], v[180:181]
	v_pk_mul_f32 v[192:193], v[146:147], v[192:193]
	v_pk_fma_f32 v[236:237], v[144:145], v[46:47], v[180:181]
	v_pk_fma_f32 v[238:239], v[144:145], v[48:49], v[192:193]
	global_store_dwordx4 v[150:151], v[236:239], off nt
	v_lshl_add_u64 v[150:151], v[150:151], 0, s[58:59]
	global_load_dwordx4 v[46:49], v[148:149], off nt
	v_lshl_add_u64 v[148:149], v[148:149], 0, s[58:59]
	ds_read_b32 v141, v160 offset:672
	ds_read_b128 v[114:117], v161 offset:5376
	ds_read_b128 v[176:179], v161 offset:5392
	s_waitcnt vmcnt(22)
	s_waitcnt lgkmcnt(3)
	v_cndmask_b32_e64 v143, 0, v143, s[6:7]
	v_pk_mul_f32 v[180:181], v[26:27], v[172:173] op_sel:[0,1]
	v_pk_mul_f32 v[192:193], v[28:29], v[172:173] op_sel:[0,1]
	v_mfma_f32_16x16x4_f32 v[110:113], v143, v42, v[110:113]
	v_pk_fma_f32 v[180:181], v[30:31], v[172:173], v[180:181] op_sel_hi:[1,0,1]
	v_pk_fma_f32 v[192:193], v[32:33], v[172:173], v[192:193] op_sel_hi:[1,0,1]
	v_pk_fma_f32 v[180:181], v[22:23], v[174:175], v[180:181] op_sel_hi:[1,0,1]
	v_pk_fma_f32 v[192:193], v[24:25], v[174:175], v[192:193] op_sel_hi:[1,0,1]
	v_mfma_f32_16x16x4_f32 v[106:109], v143, v43, v[106:109]
	v_pk_fma_f32 v[180:181], v[18:19], v[174:175], v[180:181] op_sel:[0,1,0]
	v_pk_fma_f32 v[192:193], v[20:21], v[174:175], v[192:193] op_sel:[0,1,0]
	v_pk_fma_f32 v[180:181], v[14:15], v[232:233], v[180:181] op_sel_hi:[1,0,1]
	v_pk_fma_f32 v[192:193], v[16:17], v[232:233], v[192:193] op_sel_hi:[1,0,1]
	v_mfma_f32_16x16x4_f32 v[102:105], v143, v44, v[102:105]
	v_pk_fma_f32 v[180:181], v[10:11], v[232:233], v[180:181] op_sel:[0,1,0]
	v_pk_fma_f32 v[192:193], v[12:13], v[232:233], v[192:193] op_sel:[0,1,0]
	v_pk_fma_f32 v[180:181], v[6:7], v[234:235], v[180:181] op_sel_hi:[1,0,1]
	v_pk_fma_f32 v[192:193], v[8:9], v[234:235], v[192:193] op_sel_hi:[1,0,1]
	v_mfma_f32_16x16x4_f32 v[98:101], v143, v45, v[98:101]
	v_pk_fma_f32 v[180:181], v[2:3], v[234:235], v[180:181] op_sel:[0,1,0]
	v_pk_fma_f32 v[192:193], v[4:5], v[234:235], v[192:193] op_sel:[0,1,0]
	v_pk_mul_f32 v[180:181], v[146:147], v[180:181]
	v_pk_mul_f32 v[192:193], v[146:147], v[192:193]
	v_pk_fma_f32 v[236:237], v[144:145], v[42:43], v[180:181]
	v_pk_fma_f32 v[238:239], v[144:145], v[44:45], v[192:193]
	global_store_dwordx4 v[150:151], v[236:239], off nt
	v_lshl_add_u64 v[150:151], v[150:151], 0, s[58:59]
	global_load_dwordx4 v[42:45], v[148:149], off nt
	v_lshl_add_u64 v[148:149], v[148:149], 0, s[58:59]
	ds_read_b32 v143, v160 offset:688
	ds_read_b128 v[172:175], v161 offset:5504
	ds_read_b128 v[232:235], v161 offset:5520
	s_waitcnt vmcnt(22)
	s_waitcnt lgkmcnt(3)
	v_cndmask_b32_e64 v141, 0, v141, s[6:7]
	v_pk_mul_f32 v[180:181], v[26:27], v[114:115] op_sel:[0,1]
	v_pk_mul_f32 v[192:193], v[28:29], v[114:115] op_sel:[0,1]
	v_mfma_f32_16x16x4_f32 v[110:113], v141, v38, v[110:113]
	v_pk_fma_f32 v[180:181], v[30:31], v[114:115], v[180:181] op_sel_hi:[1,0,1]
	v_pk_fma_f32 v[192:193], v[32:33], v[114:115], v[192:193] op_sel_hi:[1,0,1]
	v_pk_fma_f32 v[180:181], v[22:23], v[116:117], v[180:181] op_sel_hi:[1,0,1]
	v_pk_fma_f32 v[192:193], v[24:25], v[116:117], v[192:193] op_sel_hi:[1,0,1]
	v_mfma_f32_16x16x4_f32 v[106:109], v141, v39, v[106:109]
	v_pk_fma_f32 v[180:181], v[18:19], v[116:117], v[180:181] op_sel:[0,1,0]
	v_pk_fma_f32 v[192:193], v[20:21], v[116:117], v[192:193] op_sel:[0,1,0]
	v_pk_fma_f32 v[180:181], v[14:15], v[176:177], v[180:181] op_sel_hi:[1,0,1]
	v_pk_fma_f32 v[192:193], v[16:17], v[176:177], v[192:193] op_sel_hi:[1,0,1]
	v_mfma_f32_16x16x4_f32 v[102:105], v141, v40, v[102:105]
	v_pk_fma_f32 v[180:181], v[10:11], v[176:177], v[180:181] op_sel:[0,1,0]
	v_pk_fma_f32 v[192:193], v[12:13], v[176:177], v[192:193] op_sel:[0,1,0]
	v_pk_fma_f32 v[180:181], v[6:7], v[178:179], v[180:181] op_sel_hi:[1,0,1]
	v_pk_fma_f32 v[192:193], v[8:9], v[178:179], v[192:193] op_sel_hi:[1,0,1]
	v_mfma_f32_16x16x4_f32 v[98:101], v141, v41, v[98:101]
	v_pk_fma_f32 v[180:181], v[2:3], v[178:179], v[180:181] op_sel:[0,1,0]
	v_pk_fma_f32 v[192:193], v[4:5], v[178:179], v[192:193] op_sel:[0,1,0]
	v_pk_mul_f32 v[180:181], v[146:147], v[180:181]
	v_pk_mul_f32 v[192:193], v[146:147], v[192:193]
	v_pk_fma_f32 v[236:237], v[144:145], v[38:39], v[180:181]
	v_pk_fma_f32 v[238:239], v[144:145], v[40:41], v[192:193]
	global_store_dwordx4 v[150:151], v[236:239], off nt
	v_lshl_add_u64 v[150:151], v[150:151], 0, s[58:59]
	global_load_dwordx4 v[38:41], v[148:149], off nt
	v_lshl_add_u64 v[148:149], v[148:149], 0, s[58:59]
	ds_read_b32 v141, v160 offset:704
	ds_read_b128 v[114:117], v161 offset:5632
	ds_read_b128 v[176:179], v161 offset:5648
	s_waitcnt vmcnt(22)
; #define RS_LOAD(dst, it0) do { _Pragma("unroll") for (int u = 0; u < 8; ++u) dst[u] = __builtin_nontemporal_load((const f32x4*)(S0 + (size_t)(4 * ((it0) + u)) * DV)); } while (0)
; __device__ __forceinline__ void ret_sample_item(Frame& F, int item) {
;     ...
;     for (int it0 = 0; it0 < 64; it0 += 16) {
;         RS_LOAD(sb, it0 + 8);
;         RS_PROC(sa, it0);
;         { const int itn = it0 + 16 < 64 ? it0 + 16 : it0; RS_LOAD(sa, itn); }
;         RS_PROC(sb, it0 + 8);
;     }
	s_waitcnt lgkmcnt(3)
	v_cndmask_b32_e64 v143, 0, v143, s[6:7]
	v_pk_mul_f32 v[180:181], v[26:27], v[172:173] op_sel:[0,1]
	v_pk_mul_f32 v[192:193], v[28:29], v[172:173] op_sel:[0,1]
	v_mfma_f32_16x16x4_f32 v[110:113], v143, v34, v[110:113]
	v_pk_fma_f32 v[180:181], v[30:31], v[172:173], v[180:181] op_sel_hi:[1,0,1]
	v_pk_fma_f32 v[192:193], v[32:33], v[172:173], v[192:193] op_sel_hi:[1,0,1]
	v_pk_fma_f32 v[180:181], v[22:23], v[174:175], v[180:181] op_sel_hi:[1,0,1]
	v_pk_fma_f32 v[192:193], v[24:25], v[174:175], v[192:193] op_sel_hi:[1,0,1]
	v_mfma_f32_16x16x4_f32 v[106:109], v143, v35, v[106:109]
	v_pk_fma_f32 v[180:181], v[18:19], v[174:175], v[180:181] op_sel:[0,1,0]
	v_pk_fma_f32 v[192:193], v[20:21], v[174:175], v[192:193] op_sel:[0,1,0]
	v_pk_fma_f32 v[180:181], v[14:15], v[232:233], v[180:181] op_sel_hi:[1,0,1]
	v_pk_fma_f32 v[192:193], v[16:17], v[232:233], v[192:193] op_sel_hi:[1,0,1]
	v_mfma_f32_16x16x4_f32 v[102:105], v143, v36, v[102:105]
	v_pk_fma_f32 v[180:181], v[10:11], v[232:233], v[180:181] op_sel:[0,1,0]
	v_pk_fma_f32 v[192:193], v[12:13], v[232:233], v[192:193] op_sel:[0,1,0]
	v_pk_fma_f32 v[180:181], v[6:7], v[234:235], v[180:181] op_sel_hi:[1,0,1]
	v_pk_fma_f32 v[192:193], v[8:9], v[234:235], v[192:193] op_sel_hi:[1,0,1]
	v_mfma_f32_16x16x4_f32 v[98:101], v143, v37, v[98:101]
	v_pk_fma_f32 v[180:181], v[2:3], v[234:235], v[180:181] op_sel:[0,1,0]
	v_pk_fma_f32 v[192:193], v[4:5], v[234:235], v[192:193] op_sel:[0,1,0]
	v_pk_mul_f32 v[180:181], v[146:147], v[180:181]
	v_pk_mul_f32 v[192:193], v[146:147], v[192:193]
	v_pk_fma_f32 v[236:237], v[144:145], v[34:35], v[180:181]
	v_pk_fma_f32 v[238:239], v[144:145], v[36:37], v[192:193]
	global_store_dwordx4 v[150:151], v[236:239], off nt
	v_lshl_add_u64 v[150:151], v[150:151], 0, s[58:59]
	global_load_dwordx4 v[34:37], v[148:149], off nt
	v_lshl_add_u64 v[148:149], v[148:149], 0, s[58:59]
	ds_read_b32 v143, v160 offset:720
	ds_read_b128 v[172:175], v161 offset:5760
	ds_read_b128 v[232:235], v161 offset:5776
	s_waitcnt vmcnt(22)
	s_waitcnt lgkmcnt(3)
	v_cndmask_b32_e64 v141, 0, v141, s[6:7]
	v_pk_mul_f32 v[180:181], v[26:27], v[114:115] op_sel:[0,1]
	v_pk_mul_f32 v[192:193], v[28:29], v[114:115] op_sel:[0,1]
	v_mfma_f32_16x16x4_f32 v[110:113], v141, v58, v[110:113]
	v_pk_fma_f32 v[180:181], v[30:31], v[114:115], v[180:181] op_sel_hi:[1,0,1]
	v_pk_fma_f32 v[192:193], v[32:33], v[114:115], v[192:193] op_sel_hi:[1,0,1]
	v_pk_fma_f32 v[180:181], v[22:23], v[116:117], v[180:181] op_sel_hi:[1,0,1]
	v_pk_fma_f32 v[192:193], v[24:25], v[116:117], v[192:193] op_sel_hi:[1,0,1]
	v_mfma_f32_16x16x4_f32 v[106:109], v141, v59, v[106:109]
	v_pk_fma_f32 v[180:181], v[18:19], v[116:117], v[180:181] op_sel:[0,1,0]
	v_pk_fma_f32 v[192:193], v[20:21], v[116:117], v[192:193] op_sel:[0,1,0]
	v_pk_fma_f32 v[180:181], v[14:15], v[176:177], v[180:181] op_sel_hi:[1,0,1]
	v_pk_fma_f32 v[192:193], v[16:17], v[176:177], v[192:193] op_sel_hi:[1,0,1]
	v_mfma_f32_16x16x4_f32 v[102:105], v141, v60, v[102:105]
	v_pk_fma_f32 v[180:181], v[10:11], v[176:177], v[180:181] op_sel:[0,1,0]
	v_pk_fma_f32 v[192:193], v[12:13], v[176:177], v[192:193] op_sel:[0,1,0]
	v_pk_fma_f32 v[180:181], v[6:7], v[178:179], v[180:181] op_sel_hi:[1,0,1]
	v_pk_fma_f32 v[192:193], v[8:9], v[178:179], v[192:193] op_sel_hi:[1,0,1]
	v_mfma_f32_16x16x4_f32 v[98:101], v141, v61, v[98:101]
	v_pk_fma_f32 v[180:181], v[2:3], v[178:179], v[180:181] op_sel:[0,1,0]
	v_pk_fma_f32 v[192:193], v[4:5], v[178:179], v[192:193] op_sel:[0,1,0]
	v_pk_mul_f32 v[180:181], v[146:147], v[180:181]
	v_pk_mul_f32 v[192:193], v[146:147], v[192:193]
	v_pk_fma_f32 v[236:237], v[144:145], v[58:59], v[180:181]
	v_pk_fma_f32 v[238:239], v[144:145], v[60:61], v[192:193]
	global_store_dwordx4 v[150:151], v[236:239], off nt
	v_lshl_add_u64 v[150:151], v[150:151], 0, s[58:59]
	global_load_dwordx4 v[58:61], v[148:149], off nt
	v_lshl_add_u64 v[148:149], v[148:149], 0, s[58:59]
	ds_read_b32 v141, v160 offset:736
	ds_read_b128 v[114:117], v161 offset:5888
	ds_read_b128 v[176:179], v161 offset:5904
	s_waitcnt vmcnt(22)
	s_waitcnt lgkmcnt(3)
	v_cndmask_b32_e64 v143, 0, v143, s[6:7]
	v_pk_mul_f32 v[180:181], v[26:27], v[172:173] op_sel:[0,1]
	v_pk_mul_f32 v[192:193], v[28:29], v[172:173] op_sel:[0,1]
	v_mfma_f32_16x16x4_f32 v[110:113], v143, v66, v[110:113]
	v_pk_fma_f32 v[180:181], v[30:31], v[172:173], v[180:181] op_sel_hi:[1,0,1]
	v_pk_fma_f32 v[192:193], v[32:33], v[172:173], v[192:193] op_sel_hi:[1,0,1]
	v_pk_fma_f32 v[180:181], v[22:23], v[174:175], v[180:181] op_sel_hi:[1,0,1]
	v_pk_fma_f32 v[192:193], v[24:25], v[174:175], v[192:193] op_sel_hi:[1,0,1]
	v_mfma_f32_16x16x4_f32 v[106:109], v143, v67, v[106:109]
	v_pk_fma_f32 v[180:181], v[18:19], v[174:175], v[180:181] op_sel:[0,1,0]
	v_pk_fma_f32 v[192:193], v[20:21], v[174:175], v[192:193] op_sel:[0,1,0]
	v_pk_fma_f32 v[180:181], v[14:15], v[232:233], v[180:181] op_sel_hi:[1,0,1]
	v_pk_fma_f32 v[192:193], v[16:17], v[232:233], v[192:193] op_sel_hi:[1,0,1]
	v_mfma_f32_16x16x4_f32 v[102:105], v143, v68, v[102:105]
	v_pk_fma_f32 v[180:181], v[10:11], v[232:233], v[180:181] op_sel:[0,1,0]
	v_pk_fma_f32 v[192:193], v[12:13], v[232:233], v[192:193] op_sel:[0,1,0]
	v_pk_fma_f32 v[180:181], v[6:7], v[234:235], v[180:181] op_sel_hi:[1,0,1]
	v_pk_fma_f32 v[192:193], v[8:9], v[234:235], v[192:193] op_sel_hi:[1,0,1]
	v_mfma_f32_16x16x4_f32 v[98:101], v143, v69, v[98:101]
	v_pk_fma_f32 v[180:181], v[2:3], v[234:235], v[180:181] op_sel:[0,1,0]
	v_pk_fma_f32 v[192:193], v[4:5], v[234:235], v[192:193] op_sel:[0,1,0]
	v_pk_mul_f32 v[180:181], v[146:147], v[180:181]
	v_pk_mul_f32 v[192:193], v[146:147], v[192:193]
	v_pk_fma_f32 v[236:237], v[144:145], v[66:67], v[180:181]
	v_pk_fma_f32 v[238:239], v[144:145], v[68:69], v[192:193]
	global_store_dwordx4 v[150:151], v[236:239], off nt
	v_lshl_add_u64 v[150:151], v[150:151], 0, s[58:59]
	global_load_dwordx4 v[66:69], v[148:149], off nt
	v_lshl_add_u64 v[148:149], v[148:149], 0, s[58:59]
	ds_read_b32 v143, v160 offset:752
	ds_read_b128 v[172:175], v161 offset:6016
	ds_read_b128 v[232:235], v161 offset:6032
	s_waitcnt vmcnt(22)
; #define RS_LOAD(dst, it0) do { _Pragma("unroll") for (int u = 0; u < 8; ++u) dst[u] = __builtin_nontemporal_load((const f32x4*)(S0 + (size_t)(4 * ((it0) + u)) * DV)); } while (0)
; __device__ __forceinline__ void ret_sample_item(Frame& F, int item) {
;     ...
;     for (int it0 = 0; it0 < 64; it0 += 16) {
;         RS_LOAD(sb, it0 + 8);
;         RS_PROC(sa, it0);
;         { const int itn = it0 + 16 < 64 ? it0 + 16 : it0; RS_LOAD(sa, itn); }
;         RS_PROC(sb, it0 + 8);
;     }
	s_waitcnt lgkmcnt(3)
	v_cndmask_b32_e64 v141, 0, v141, s[6:7]
	v_pk_mul_f32 v[180:181], v[26:27], v[114:115] op_sel:[0,1]
	v_pk_mul_f32 v[192:193], v[28:29], v[114:115] op_sel:[0,1]
	v_mfma_f32_16x16x4_f32 v[110:113], v141, v74, v[110:113]
	v_pk_fma_f32 v[180:181], v[30:31], v[114:115], v[180:181] op_sel_hi:[1,0,1]
	v_pk_fma_f32 v[192:193], v[32:33], v[114:115], v[192:193] op_sel_hi:[1,0,1]
	v_pk_fma_f32 v[180:181], v[22:23], v[116:117], v[180:181] op_sel_hi:[1,0,1]
	v_pk_fma_f32 v[192:193], v[24:25], v[116:117], v[192:193] op_sel_hi:[1,0,1]
	v_mfma_f32_16x16x4_f32 v[106:109], v141, v75, v[106:109]
	v_pk_fma_f32 v[180:181], v[18:19], v[116:117], v[180:181] op_sel:[0,1,0]
	v_pk_fma_f32 v[192:193], v[20:21], v[116:117], v[192:193] op_sel:[0,1,0]
	v_pk_fma_f32 v[180:181], v[14:15], v[176:177], v[180:181] op_sel_hi:[1,0,1]
	v_pk_fma_f32 v[192:193], v[16:17], v[176:177], v[192:193] op_sel_hi:[1,0,1]
	v_mfma_f32_16x16x4_f32 v[102:105], v141, v76, v[102:105]
	v_pk_fma_f32 v[180:181], v[10:11], v[176:177], v[180:181] op_sel:[0,1,0]
	v_pk_fma_f32 v[192:193], v[12:13], v[176:177], v[192:193] op_sel:[0,1,0]
	v_pk_fma_f32 v[180:181], v[6:7], v[178:179], v[180:181] op_sel_hi:[1,0,1]
	v_pk_fma_f32 v[192:193], v[8:9], v[178:179], v[192:193] op_sel_hi:[1,0,1]
	v_mfma_f32_16x16x4_f32 v[98:101], v141, v77, v[98:101]
	v_pk_fma_f32 v[180:181], v[2:3], v[178:179], v[180:181] op_sel:[0,1,0]
	v_pk_fma_f32 v[192:193], v[4:5], v[178:179], v[192:193] op_sel:[0,1,0]
	v_pk_mul_f32 v[180:181], v[146:147], v[180:181]
	v_pk_mul_f32 v[192:193], v[146:147], v[192:193]
	v_pk_fma_f32 v[236:237], v[144:145], v[74:75], v[180:181]
	v_pk_fma_f32 v[238:239], v[144:145], v[76:77], v[192:193]
	global_store_dwordx4 v[150:151], v[236:239], off nt
	v_lshl_add_u64 v[150:151], v[150:151], 0, s[58:59]
	global_load_dwordx4 v[74:77], v[148:149], off nt
	v_lshl_add_u64 v[148:149], v[148:149], 0, s[58:59]
	ds_read_b32 v141, v160 offset:768
	ds_read_b128 v[114:117], v161 offset:6144
	ds_read_b128 v[176:179], v161 offset:6160
	s_waitcnt vmcnt(22)
	s_waitcnt lgkmcnt(3)
	v_cndmask_b32_e64 v143, 0, v143, s[6:7]
	v_pk_mul_f32 v[180:181], v[26:27], v[172:173] op_sel:[0,1]
	v_pk_mul_f32 v[192:193], v[28:29], v[172:173] op_sel:[0,1]
	v_mfma_f32_16x16x4_f32 v[110:113], v143, v78, v[110:113]
	v_pk_fma_f32 v[180:181], v[30:31], v[172:173], v[180:181] op_sel_hi:[1,0,1]
	v_pk_fma_f32 v[192:193], v[32:33], v[172:173], v[192:193] op_sel_hi:[1,0,1]
	v_pk_fma_f32 v[180:181], v[22:23], v[174:175], v[180:181] op_sel_hi:[1,0,1]
	v_pk_fma_f32 v[192:193], v[24:25], v[174:175], v[192:193] op_sel_hi:[1,0,1]
	v_mfma_f32_16x16x4_f32 v[106:109], v143, v79, v[106:109]
	v_pk_fma_f32 v[180:181], v[18:19], v[174:175], v[180:181] op_sel:[0,1,0]
	v_pk_fma_f32 v[192:193], v[20:21], v[174:175], v[192:193] op_sel:[0,1,0]
	v_pk_fma_f32 v[180:181], v[14:15], v[232:233], v[180:181] op_sel_hi:[1,0,1]
	v_pk_fma_f32 v[192:193], v[16:17], v[232:233], v[192:193] op_sel_hi:[1,0,1]
	v_mfma_f32_16x16x4_f32 v[102:105], v143, v80, v[102:105]
	v_pk_fma_f32 v[180:181], v[10:11], v[232:233], v[180:181] op_sel:[0,1,0]
	v_pk_fma_f32 v[192:193], v[12:13], v[232:233], v[192:193] op_sel:[0,1,0]
	v_pk_fma_f32 v[180:181], v[6:7], v[234:235], v[180:181] op_sel_hi:[1,0,1]
	v_pk_fma_f32 v[192:193], v[8:9], v[234:235], v[192:193] op_sel_hi:[1,0,1]
	v_mfma_f32_16x16x4_f32 v[98:101], v143, v81, v[98:101]
	v_pk_fma_f32 v[180:181], v[2:3], v[234:235], v[180:181] op_sel:[0,1,0]
	v_pk_fma_f32 v[192:193], v[4:5], v[234:235], v[192:193] op_sel:[0,1,0]
	v_pk_mul_f32 v[180:181], v[146:147], v[180:181]
	v_pk_mul_f32 v[192:193], v[146:147], v[192:193]
	v_pk_fma_f32 v[236:237], v[144:145], v[78:79], v[180:181]
	v_pk_fma_f32 v[238:239], v[144:145], v[80:81], v[192:193]
	global_store_dwordx4 v[150:151], v[236:239], off nt
	v_lshl_add_u64 v[150:151], v[150:151], 0, s[58:59]
	global_load_dwordx4 v[78:81], v[148:149], off nt
	v_lshl_add_u64 v[148:149], v[148:149], 0, s[58:59]
	ds_read_b32 v143, v160 offset:784
	ds_read_b128 v[172:175], v161 offset:6272
	ds_read_b128 v[232:235], v161 offset:6288
	s_waitcnt vmcnt(22)
	s_waitcnt lgkmcnt(3)
	v_cndmask_b32_e64 v141, 0, v141, s[6:7]
	v_pk_mul_f32 v[180:181], v[26:27], v[114:115] op_sel:[0,1]
	v_pk_mul_f32 v[192:193], v[28:29], v[114:115] op_sel:[0,1]
	v_mfma_f32_16x16x4_f32 v[110:113], v141, v70, v[110:113]
	v_pk_fma_f32 v[180:181], v[30:31], v[114:115], v[180:181] op_sel_hi:[1,0,1]
	v_pk_fma_f32 v[192:193], v[32:33], v[114:115], v[192:193] op_sel_hi:[1,0,1]
	v_pk_fma_f32 v[180:181], v[22:23], v[116:117], v[180:181] op_sel_hi:[1,0,1]
	v_pk_fma_f32 v[192:193], v[24:25], v[116:117], v[192:193] op_sel_hi:[1,0,1]
	v_mfma_f32_16x16x4_f32 v[106:109], v141, v71, v[106:109]
	v_pk_fma_f32 v[180:181], v[18:19], v[116:117], v[180:181] op_sel:[0,1,0]
	v_pk_fma_f32 v[192:193], v[20:21], v[116:117], v[192:193] op_sel:[0,1,0]
	v_pk_fma_f32 v[180:181], v[14:15], v[176:177], v[180:181] op_sel_hi:[1,0,1]
	v_pk_fma_f32 v[192:193], v[16:17], v[176:177], v[192:193] op_sel_hi:[1,0,1]
	v_mfma_f32_16x16x4_f32 v[102:105], v141, v72, v[102:105]
	v_pk_fma_f32 v[180:181], v[10:11], v[176:177], v[180:181] op_sel:[0,1,0]
	v_pk_fma_f32 v[192:193], v[12:13], v[176:177], v[192:193] op_sel:[0,1,0]
	v_pk_fma_f32 v[180:181], v[6:7], v[178:179], v[180:181] op_sel_hi:[1,0,1]
	v_pk_fma_f32 v[192:193], v[8:9], v[178:179], v[192:193] op_sel_hi:[1,0,1]
	v_mfma_f32_16x16x4_f32 v[98:101], v141, v73, v[98:101]
	v_pk_fma_f32 v[180:181], v[2:3], v[178:179], v[180:181] op_sel:[0,1,0]
	v_pk_fma_f32 v[192:193], v[4:5], v[178:179], v[192:193] op_sel:[0,1,0]
	v_pk_mul_f32 v[180:181], v[146:147], v[180:181]
	v_pk_mul_f32 v[192:193], v[146:147], v[192:193]
	v_pk_fma_f32 v[236:237], v[144:145], v[70:71], v[180:181]
	v_pk_fma_f32 v[238:239], v[144:145], v[72:73], v[192:193]
	global_store_dwordx4 v[150:151], v[236:239], off nt
	v_lshl_add_u64 v[150:151], v[150:151], 0, s[58:59]
	global_load_dwordx4 v[70:73], v[148:149], off nt
	v_lshl_add_u64 v[148:149], v[148:149], 0, s[58:59]
	ds_read_b32 v141, v160 offset:800
	ds_read_b128 v[114:117], v161 offset:6400
	ds_read_b128 v[176:179], v161 offset:6416
	s_waitcnt vmcnt(22)
; #define RS_LOAD(dst, it0) do { _Pragma("unroll") for (int u = 0; u < 8; ++u) dst[u] = __builtin_nontemporal_load((const f32x4*)(S0 + (size_t)(4 * ((it0) + u)) * DV)); } while (0)
; __device__ __forceinline__ void ret_sample_item(Frame& F, int item) {
;     ...
;     for (int it0 = 0; it0 < 64; it0 += 16) {
;         RS_LOAD(sb, it0 + 8);
;         RS_PROC(sa, it0);
;         { const int itn = it0 + 16 < 64 ? it0 + 16 : it0; RS_LOAD(sa, itn); }
;         RS_PROC(sb, it0 + 8);
;     }
	s_waitcnt lgkmcnt(3)
	v_cndmask_b32_e64 v143, 0, v143, s[6:7]
	v_pk_mul_f32 v[180:181], v[26:27], v[172:173] op_sel:[0,1]
	v_pk_mul_f32 v[192:193], v[28:29], v[172:173] op_sel:[0,1]
	v_mfma_f32_16x16x4_f32 v[110:113], v143, v62, v[110:113]
	v_pk_fma_f32 v[180:181], v[30:31], v[172:173], v[180:181] op_sel_hi:[1,0,1]
	v_pk_fma_f32 v[192:193], v[32:33], v[172:173], v[192:193] op_sel_hi:[1,0,1]
	v_pk_fma_f32 v[180:181], v[22:23], v[174:175], v[180:181] op_sel_hi:[1,0,1]
	v_pk_fma_f32 v[192:193], v[24:25], v[174:175], v[192:193] op_sel_hi:[1,0,1]
	v_mfma_f32_16x16x4_f32 v[106:109], v143, v63, v[106:109]
	v_pk_fma_f32 v[180:181], v[18:19], v[174:175], v[180:181] op_sel:[0,1,0]
	v_pk_fma_f32 v[192:193], v[20:21], v[174:175], v[192:193] op_sel:[0,1,0]
	v_pk_fma_f32 v[180:181], v[14:15], v[232:233], v[180:181] op_sel_hi:[1,0,1]
	v_pk_fma_f32 v[192:193], v[16:17], v[232:233], v[192:193] op_sel_hi:[1,0,1]
	v_mfma_f32_16x16x4_f32 v[102:105], v143, v64, v[102:105]
	v_pk_fma_f32 v[180:181], v[10:11], v[232:233], v[180:181] op_sel:[0,1,0]
	v_pk_fma_f32 v[192:193], v[12:13], v[232:233], v[192:193] op_sel:[0,1,0]
	v_pk_fma_f32 v[180:181], v[6:7], v[234:235], v[180:181] op_sel_hi:[1,0,1]
	v_pk_fma_f32 v[192:193], v[8:9], v[234:235], v[192:193] op_sel_hi:[1,0,1]
	v_mfma_f32_16x16x4_f32 v[98:101], v143, v65, v[98:101]
	v_pk_fma_f32 v[180:181], v[2:3], v[234:235], v[180:181] op_sel:[0,1,0]
	v_pk_fma_f32 v[192:193], v[4:5], v[234:235], v[192:193] op_sel:[0,1,0]
	v_pk_mul_f32 v[180:181], v[146:147], v[180:181]
	v_pk_mul_f32 v[192:193], v[146:147], v[192:193]
	v_pk_fma_f32 v[236:237], v[144:145], v[62:63], v[180:181]
	v_pk_fma_f32 v[238:239], v[144:145], v[64:65], v[192:193]
	global_store_dwordx4 v[150:151], v[236:239], off nt
	v_lshl_add_u64 v[150:151], v[150:151], 0, s[58:59]
	global_load_dwordx4 v[62:65], v[148:149], off nt
	v_lshl_add_u64 v[148:149], v[148:149], 0, s[58:59]
	ds_read_b32 v143, v160 offset:816
	ds_read_b128 v[172:175], v161 offset:6528
	ds_read_b128 v[232:235], v161 offset:6544
	s_waitcnt vmcnt(22)
	s_waitcnt lgkmcnt(3)
	v_cndmask_b32_e64 v141, 0, v141, s[6:7]
	v_pk_mul_f32 v[180:181], v[26:27], v[114:115] op_sel:[0,1]
	v_pk_mul_f32 v[192:193], v[28:29], v[114:115] op_sel:[0,1]
	v_mfma_f32_16x16x4_f32 v[110:113], v141, v54, v[110:113]
	v_pk_fma_f32 v[180:181], v[30:31], v[114:115], v[180:181] op_sel_hi:[1,0,1]
	v_pk_fma_f32 v[192:193], v[32:33], v[114:115], v[192:193] op_sel_hi:[1,0,1]
	v_pk_fma_f32 v[180:181], v[22:23], v[116:117], v[180:181] op_sel_hi:[1,0,1]
	v_pk_fma_f32 v[192:193], v[24:25], v[116:117], v[192:193] op_sel_hi:[1,0,1]
	v_mfma_f32_16x16x4_f32 v[106:109], v141, v55, v[106:109]
	v_pk_fma_f32 v[180:181], v[18:19], v[116:117], v[180:181] op_sel:[0,1,0]
	v_pk_fma_f32 v[192:193], v[20:21], v[116:117], v[192:193] op_sel:[0,1,0]
	v_pk_fma_f32 v[180:181], v[14:15], v[176:177], v[180:181] op_sel_hi:[1,0,1]
	v_pk_fma_f32 v[192:193], v[16:17], v[176:177], v[192:193] op_sel_hi:[1,0,1]
	v_mfma_f32_16x16x4_f32 v[102:105], v141, v56, v[102:105]
	v_pk_fma_f32 v[180:181], v[10:11], v[176:177], v[180:181] op_sel:[0,1,0]
	v_pk_fma_f32 v[192:193], v[12:13], v[176:177], v[192:193] op_sel:[0,1,0]
	v_pk_fma_f32 v[180:181], v[6:7], v[178:179], v[180:181] op_sel_hi:[1,0,1]
	v_pk_fma_f32 v[192:193], v[8:9], v[178:179], v[192:193] op_sel_hi:[1,0,1]
	v_mfma_f32_16x16x4_f32 v[98:101], v141, v57, v[98:101]
	v_pk_fma_f32 v[180:181], v[2:3], v[178:179], v[180:181] op_sel:[0,1,0]
	v_pk_fma_f32 v[192:193], v[4:5], v[178:179], v[192:193] op_sel:[0,1,0]
	v_pk_mul_f32 v[180:181], v[146:147], v[180:181]
	v_pk_mul_f32 v[192:193], v[146:147], v[192:193]
	v_pk_fma_f32 v[236:237], v[144:145], v[54:55], v[180:181]
	v_pk_fma_f32 v[238:239], v[144:145], v[56:57], v[192:193]
	global_store_dwordx4 v[150:151], v[236:239], off nt
	v_lshl_add_u64 v[150:151], v[150:151], 0, s[58:59]
	global_load_dwordx4 v[54:57], v[148:149], off nt
	v_lshl_add_u64 v[148:149], v[148:149], 0, s[58:59]
	ds_read_b32 v141, v160 offset:832
	ds_read_b128 v[114:117], v161 offset:6656
	ds_read_b128 v[176:179], v161 offset:6672
	s_waitcnt vmcnt(22)
	s_waitcnt lgkmcnt(3)
	v_cndmask_b32_e64 v143, 0, v143, s[6:7]
	v_pk_mul_f32 v[180:181], v[26:27], v[172:173] op_sel:[0,1]
	v_pk_mul_f32 v[192:193], v[28:29], v[172:173] op_sel:[0,1]
	v_mfma_f32_16x16x4_f32 v[110:113], v143, v50, v[110:113]
	v_pk_fma_f32 v[180:181], v[30:31], v[172:173], v[180:181] op_sel_hi:[1,0,1]
	v_pk_fma_f32 v[192:193], v[32:33], v[172:173], v[192:193] op_sel_hi:[1,0,1]
	v_pk_fma_f32 v[180:181], v[22:23], v[174:175], v[180:181] op_sel_hi:[1,0,1]
	v_pk_fma_f32 v[192:193], v[24:25], v[174:175], v[192:193] op_sel_hi:[1,0,1]
	v_mfma_f32_16x16x4_f32 v[106:109], v143, v51, v[106:109]
	v_pk_fma_f32 v[180:181], v[18:19], v[174:175], v[180:181] op_sel:[0,1,0]
	v_pk_fma_f32 v[192:193], v[20:21], v[174:175], v[192:193] op_sel:[0,1,0]
	v_pk_fma_f32 v[180:181], v[14:15], v[232:233], v[180:181] op_sel_hi:[1,0,1]
	v_pk_fma_f32 v[192:193], v[16:17], v[232:233], v[192:193] op_sel_hi:[1,0,1]
	v_mfma_f32_16x16x4_f32 v[102:105], v143, v52, v[102:105]
	v_pk_fma_f32 v[180:181], v[10:11], v[232:233], v[180:181] op_sel:[0,1,0]
	v_pk_fma_f32 v[192:193], v[12:13], v[232:233], v[192:193] op_sel:[0,1,0]
	v_pk_fma_f32 v[180:181], v[6:7], v[234:235], v[180:181] op_sel_hi:[1,0,1]
	v_pk_fma_f32 v[192:193], v[8:9], v[234:235], v[192:193] op_sel_hi:[1,0,1]
	v_mfma_f32_16x16x4_f32 v[98:101], v143, v53, v[98:101]
	v_pk_fma_f32 v[180:181], v[2:3], v[234:235], v[180:181] op_sel:[0,1,0]
	v_pk_fma_f32 v[192:193], v[4:5], v[234:235], v[192:193] op_sel:[0,1,0]
	v_pk_mul_f32 v[180:181], v[146:147], v[180:181]
	v_pk_mul_f32 v[192:193], v[146:147], v[192:193]
	v_pk_fma_f32 v[236:237], v[144:145], v[50:51], v[180:181]
	v_pk_fma_f32 v[238:239], v[144:145], v[52:53], v[192:193]
	global_store_dwordx4 v[150:151], v[236:239], off nt
	v_lshl_add_u64 v[150:151], v[150:151], 0, s[58:59]
	global_load_dwordx4 v[50:53], v[148:149], off nt
	v_lshl_add_u64 v[148:149], v[148:149], 0, s[58:59]
	ds_read_b32 v143, v160 offset:848
	ds_read_b128 v[172:175], v161 offset:6784
	ds_read_b128 v[232:235], v161 offset:6800
	s_waitcnt vmcnt(22)
; #define RS_LOAD(dst, it0) do { _Pragma("unroll") for (int u = 0; u < 8; ++u) dst[u] = __builtin_nontemporal_load((const f32x4*)(S0 + (size_t)(4 * ((it0) + u)) * DV)); } while (0)
; __device__ __forceinline__ void ret_sample_item(Frame& F, int item) {
;     ...
;     for (int it0 = 0; it0 < 64; it0 += 16) {
;         RS_LOAD(sb, it0 + 8);
;         RS_PROC(sa, it0);
;         { const int itn = it0 + 16 < 64 ? it0 + 16 : it0; RS_LOAD(sa, itn); }
;         RS_PROC(sb, it0 + 8);
;     }
	s_waitcnt lgkmcnt(3)
	v_cndmask_b32_e64 v141, 0, v141, s[6:7]
	v_pk_mul_f32 v[180:181], v[26:27], v[114:115] op_sel:[0,1]
	v_pk_mul_f32 v[192:193], v[28:29], v[114:115] op_sel:[0,1]
	v_mfma_f32_16x16x4_f32 v[110:113], v141, v46, v[110:113]
	v_pk_fma_f32 v[180:181], v[30:31], v[114:115], v[180:181] op_sel_hi:[1,0,1]
	v_pk_fma_f32 v[192:193], v[32:33], v[114:115], v[192:193] op_sel_hi:[1,0,1]
	v_pk_fma_f32 v[180:181], v[22:23], v[116:117], v[180:181] op_sel_hi:[1,0,1]
	v_pk_fma_f32 v[192:193], v[24:25], v[116:117], v[192:193] op_sel_hi:[1,0,1]
	v_mfma_f32_16x16x4_f32 v[106:109], v141, v47, v[106:109]
	v_pk_fma_f32 v[180:181], v[18:19], v[116:117], v[180:181] op_sel:[0,1,0]
	v_pk_fma_f32 v[192:193], v[20:21], v[116:117], v[192:193] op_sel:[0,1,0]
	v_pk_fma_f32 v[180:181], v[14:15], v[176:177], v[180:181] op_sel_hi:[1,0,1]
	v_pk_fma_f32 v[192:193], v[16:17], v[176:177], v[192:193] op_sel_hi:[1,0,1]
	v_mfma_f32_16x16x4_f32 v[102:105], v141, v48, v[102:105]
	v_pk_fma_f32 v[180:181], v[10:11], v[176:177], v[180:181] op_sel:[0,1,0]
	v_pk_fma_f32 v[192:193], v[12:13], v[176:177], v[192:193] op_sel:[0,1,0]
	v_pk_fma_f32 v[180:181], v[6:7], v[178:179], v[180:181] op_sel_hi:[1,0,1]
	v_pk_fma_f32 v[192:193], v[8:9], v[178:179], v[192:193] op_sel_hi:[1,0,1]
	v_mfma_f32_16x16x4_f32 v[98:101], v141, v49, v[98:101]
	v_pk_fma_f32 v[180:181], v[2:3], v[178:179], v[180:181] op_sel:[0,1,0]
	v_pk_fma_f32 v[192:193], v[4:5], v[178:179], v[192:193] op_sel:[0,1,0]
	v_pk_mul_f32 v[180:181], v[146:147], v[180:181]
	v_pk_mul_f32 v[192:193], v[146:147], v[192:193]
	v_pk_fma_f32 v[236:237], v[144:145], v[46:47], v[180:181]
	v_pk_fma_f32 v[238:239], v[144:145], v[48:49], v[192:193]
	global_store_dwordx4 v[150:151], v[236:239], off nt
	v_lshl_add_u64 v[150:151], v[150:151], 0, s[58:59]
	ds_read_b32 v141, v160 offset:864
	ds_read_b128 v[114:117], v161 offset:6912
	ds_read_b128 v[176:179], v161 offset:6928
	s_waitcnt vmcnt(21)
	s_waitcnt lgkmcnt(3)
	v_cndmask_b32_e64 v143, 0, v143, s[6:7]
	v_pk_mul_f32 v[180:181], v[26:27], v[172:173] op_sel:[0,1]
	v_pk_mul_f32 v[192:193], v[28:29], v[172:173] op_sel:[0,1]
	v_mfma_f32_16x16x4_f32 v[110:113], v143, v42, v[110:113]
	v_pk_fma_f32 v[180:181], v[30:31], v[172:173], v[180:181] op_sel_hi:[1,0,1]
	v_pk_fma_f32 v[192:193], v[32:33], v[172:173], v[192:193] op_sel_hi:[1,0,1]
	v_pk_fma_f32 v[180:181], v[22:23], v[174:175], v[180:181] op_sel_hi:[1,0,1]
	v_pk_fma_f32 v[192:193], v[24:25], v[174:175], v[192:193] op_sel_hi:[1,0,1]
	v_mfma_f32_16x16x4_f32 v[106:109], v143, v43, v[106:109]
	v_pk_fma_f32 v[180:181], v[18:19], v[174:175], v[180:181] op_sel:[0,1,0]
	v_pk_fma_f32 v[192:193], v[20:21], v[174:175], v[192:193] op_sel:[0,1,0]
	v_pk_fma_f32 v[180:181], v[14:15], v[232:233], v[180:181] op_sel_hi:[1,0,1]
	v_pk_fma_f32 v[192:193], v[16:17], v[232:233], v[192:193] op_sel_hi:[1,0,1]
	v_mfma_f32_16x16x4_f32 v[102:105], v143, v44, v[102:105]
	v_pk_fma_f32 v[180:181], v[10:11], v[232:233], v[180:181] op_sel:[0,1,0]
	v_pk_fma_f32 v[192:193], v[12:13], v[232:233], v[192:193] op_sel:[0,1,0]
	v_pk_fma_f32 v[180:181], v[6:7], v[234:235], v[180:181] op_sel_hi:[1,0,1]
	v_pk_fma_f32 v[192:193], v[8:9], v[234:235], v[192:193] op_sel_hi:[1,0,1]
	v_mfma_f32_16x16x4_f32 v[98:101], v143, v45, v[98:101]
	v_pk_fma_f32 v[180:181], v[2:3], v[234:235], v[180:181] op_sel:[0,1,0]
	v_pk_fma_f32 v[192:193], v[4:5], v[234:235], v[192:193] op_sel:[0,1,0]
	v_pk_mul_f32 v[180:181], v[146:147], v[180:181]
	v_pk_mul_f32 v[192:193], v[146:147], v[192:193]
	v_pk_fma_f32 v[236:237], v[144:145], v[42:43], v[180:181]
	v_pk_fma_f32 v[238:239], v[144:145], v[44:45], v[192:193]
	global_store_dwordx4 v[150:151], v[236:239], off nt
	v_lshl_add_u64 v[150:151], v[150:151], 0, s[58:59]
	ds_read_b32 v143, v160 offset:880
	ds_read_b128 v[172:175], v161 offset:7040
	ds_read_b128 v[232:235], v161 offset:7056
	s_waitcnt vmcnt(20)
	s_waitcnt lgkmcnt(3)
	v_cndmask_b32_e64 v141, 0, v141, s[6:7]
	v_pk_mul_f32 v[180:181], v[26:27], v[114:115] op_sel:[0,1]
	v_pk_mul_f32 v[192:193], v[28:29], v[114:115] op_sel:[0,1]
	v_mfma_f32_16x16x4_f32 v[110:113], v141, v38, v[110:113]
	v_pk_fma_f32 v[180:181], v[30:31], v[114:115], v[180:181] op_sel_hi:[1,0,1]
	v_pk_fma_f32 v[192:193], v[32:33], v[114:115], v[192:193] op_sel_hi:[1,0,1]
	v_pk_fma_f32 v[180:181], v[22:23], v[116:117], v[180:181] op_sel_hi:[1,0,1]
	v_pk_fma_f32 v[192:193], v[24:25], v[116:117], v[192:193] op_sel_hi:[1,0,1]
	v_mfma_f32_16x16x4_f32 v[106:109], v141, v39, v[106:109]
	v_pk_fma_f32 v[180:181], v[18:19], v[116:117], v[180:181] op_sel:[0,1,0]
	v_pk_fma_f32 v[192:193], v[20:21], v[116:117], v[192:193] op_sel:[0,1,0]
	v_pk_fma_f32 v[180:181], v[14:15], v[176:177], v[180:181] op_sel_hi:[1,0,1]
	v_pk_fma_f32 v[192:193], v[16:17], v[176:177], v[192:193] op_sel_hi:[1,0,1]
	v_mfma_f32_16x16x4_f32 v[102:105], v141, v40, v[102:105]
	v_pk_fma_f32 v[180:181], v[10:11], v[176:177], v[180:181] op_sel:[0,1,0]
	v_pk_fma_f32 v[192:193], v[12:13], v[176:177], v[192:193] op_sel:[0,1,0]
	v_pk_fma_f32 v[180:181], v[6:7], v[178:179], v[180:181] op_sel_hi:[1,0,1]
	v_pk_fma_f32 v[192:193], v[8:9], v[178:179], v[192:193] op_sel_hi:[1,0,1]
	v_mfma_f32_16x16x4_f32 v[98:101], v141, v41, v[98:101]
	v_pk_fma_f32 v[180:181], v[2:3], v[178:179], v[180:181] op_sel:[0,1,0]
	v_pk_fma_f32 v[192:193], v[4:5], v[178:179], v[192:193] op_sel:[0,1,0]
	v_pk_mul_f32 v[180:181], v[146:147], v[180:181]
	v_pk_mul_f32 v[192:193], v[146:147], v[192:193]
	v_pk_fma_f32 v[236:237], v[144:145], v[38:39], v[180:181]
	v_pk_fma_f32 v[238:239], v[144:145], v[40:41], v[192:193]
	global_store_dwordx4 v[150:151], v[236:239], off nt
	v_lshl_add_u64 v[150:151], v[150:151], 0, s[58:59]
	ds_read_b32 v141, v160 offset:896
	ds_read_b128 v[114:117], v161 offset:7168
	ds_read_b128 v[176:179], v161 offset:7184
	s_waitcnt vmcnt(19)
; #define RS_LOAD(dst, it0) do { _Pragma("unroll") for (int u = 0; u < 8; ++u) dst[u] = __builtin_nontemporal_load((const f32x4*)(S0 + (size_t)(4 * ((it0) + u)) * DV)); } while (0)
; __device__ __forceinline__ void ret_sample_item(Frame& F, int item) {
;     ...
;     for (int it0 = 0; it0 < 64; it0 += 16) {
;         RS_LOAD(sb, it0 + 8);
;         RS_PROC(sa, it0);
;         { const int itn = it0 + 16 < 64 ? it0 + 16 : it0; RS_LOAD(sa, itn); }
;         RS_PROC(sb, it0 + 8);
;     }
	s_waitcnt lgkmcnt(3)
	v_cndmask_b32_e64 v143, 0, v143, s[6:7]
	v_pk_mul_f32 v[180:181], v[26:27], v[172:173] op_sel:[0,1]
	v_pk_mul_f32 v[192:193], v[28:29], v[172:173] op_sel:[0,1]
	v_mfma_f32_16x16x4_f32 v[110:113], v143, v34, v[110:113]
	v_pk_fma_f32 v[180:181], v[30:31], v[172:173], v[180:181] op_sel_hi:[1,0,1]
	v_pk_fma_f32 v[192:193], v[32:33], v[172:173], v[192:193] op_sel_hi:[1,0,1]
	v_pk_fma_f32 v[180:181], v[22:23], v[174:175], v[180:181] op_sel_hi:[1,0,1]
	v_pk_fma_f32 v[192:193], v[24:25], v[174:175], v[192:193] op_sel_hi:[1,0,1]
	v_mfma_f32_16x16x4_f32 v[106:109], v143, v35, v[106:109]
	v_pk_fma_f32 v[180:181], v[18:19], v[174:175], v[180:181] op_sel:[0,1,0]
	v_pk_fma_f32 v[192:193], v[20:21], v[174:175], v[192:193] op_sel:[0,1,0]
	v_pk_fma_f32 v[180:181], v[14:15], v[232:233], v[180:181] op_sel_hi:[1,0,1]
	v_pk_fma_f32 v[192:193], v[16:17], v[232:233], v[192:193] op_sel_hi:[1,0,1]
	v_mfma_f32_16x16x4_f32 v[102:105], v143, v36, v[102:105]
	v_pk_fma_f32 v[180:181], v[10:11], v[232:233], v[180:181] op_sel:[0,1,0]
	v_pk_fma_f32 v[192:193], v[12:13], v[232:233], v[192:193] op_sel:[0,1,0]
	v_pk_fma_f32 v[180:181], v[6:7], v[234:235], v[180:181] op_sel_hi:[1,0,1]
	v_pk_fma_f32 v[192:193], v[8:9], v[234:235], v[192:193] op_sel_hi:[1,0,1]
	v_mfma_f32_16x16x4_f32 v[98:101], v143, v37, v[98:101]
	v_pk_fma_f32 v[180:181], v[2:3], v[234:235], v[180:181] op_sel:[0,1,0]
	v_pk_fma_f32 v[192:193], v[4:5], v[234:235], v[192:193] op_sel:[0,1,0]
	v_pk_mul_f32 v[180:181], v[146:147], v[180:181]
	v_pk_mul_f32 v[192:193], v[146:147], v[192:193]
	v_pk_fma_f32 v[236:237], v[144:145], v[34:35], v[180:181]
	v_pk_fma_f32 v[238:239], v[144:145], v[36:37], v[192:193]
	global_store_dwordx4 v[150:151], v[236:239], off nt
	v_lshl_add_u64 v[150:151], v[150:151], 0, s[58:59]
	ds_read_b32 v143, v160 offset:912
	ds_read_b128 v[172:175], v161 offset:7296
	ds_read_b128 v[232:235], v161 offset:7312
	s_waitcnt vmcnt(18)
	s_waitcnt lgkmcnt(3)
	v_cndmask_b32_e64 v141, 0, v141, s[6:7]
	v_pk_mul_f32 v[180:181], v[26:27], v[114:115] op_sel:[0,1]
	v_pk_mul_f32 v[192:193], v[28:29], v[114:115] op_sel:[0,1]
	v_mfma_f32_16x16x4_f32 v[110:113], v141, v58, v[110:113]
	v_pk_fma_f32 v[180:181], v[30:31], v[114:115], v[180:181] op_sel_hi:[1,0,1]
	v_pk_fma_f32 v[192:193], v[32:33], v[114:115], v[192:193] op_sel_hi:[1,0,1]
	v_pk_fma_f32 v[180:181], v[22:23], v[116:117], v[180:181] op_sel_hi:[1,0,1]
	v_pk_fma_f32 v[192:193], v[24:25], v[116:117], v[192:193] op_sel_hi:[1,0,1]
	v_mfma_f32_16x16x4_f32 v[106:109], v141, v59, v[106:109]
	v_pk_fma_f32 v[180:181], v[18:19], v[116:117], v[180:181] op_sel:[0,1,0]
	v_pk_fma_f32 v[192:193], v[20:21], v[116:117], v[192:193] op_sel:[0,1,0]
	v_pk_fma_f32 v[180:181], v[14:15], v[176:177], v[180:181] op_sel_hi:[1,0,1]
	v_pk_fma_f32 v[192:193], v[16:17], v[176:177], v[192:193] op_sel_hi:[1,0,1]
	v_mfma_f32_16x16x4_f32 v[102:105], v141, v60, v[102:105]
	v_pk_fma_f32 v[180:181], v[10:11], v[176:177], v[180:181] op_sel:[0,1,0]
	v_pk_fma_f32 v[192:193], v[12:13], v[176:177], v[192:193] op_sel:[0,1,0]
	v_pk_fma_f32 v[180:181], v[6:7], v[178:179], v[180:181] op_sel_hi:[1,0,1]
	v_pk_fma_f32 v[192:193], v[8:9], v[178:179], v[192:193] op_sel_hi:[1,0,1]
	v_mfma_f32_16x16x4_f32 v[98:101], v141, v61, v[98:101]
	v_pk_fma_f32 v[180:181], v[2:3], v[178:179], v[180:181] op_sel:[0,1,0]
	v_pk_fma_f32 v[192:193], v[4:5], v[178:179], v[192:193] op_sel:[0,1,0]
	v_pk_mul_f32 v[180:181], v[146:147], v[180:181]
	v_pk_mul_f32 v[192:193], v[146:147], v[192:193]
	v_pk_fma_f32 v[236:237], v[144:145], v[58:59], v[180:181]
	v_pk_fma_f32 v[238:239], v[144:145], v[60:61], v[192:193]
	global_store_dwordx4 v[150:151], v[236:239], off nt
	v_lshl_add_u64 v[150:151], v[150:151], 0, s[58:59]
	ds_read_b32 v141, v160 offset:928
	ds_read_b128 v[114:117], v161 offset:7424
	ds_read_b128 v[176:179], v161 offset:7440
	s_waitcnt vmcnt(17)
	s_waitcnt lgkmcnt(3)
	v_cndmask_b32_e64 v143, 0, v143, s[6:7]
	v_pk_mul_f32 v[180:181], v[26:27], v[172:173] op_sel:[0,1]
	v_pk_mul_f32 v[192:193], v[28:29], v[172:173] op_sel:[0,1]
	v_mfma_f32_16x16x4_f32 v[110:113], v143, v66, v[110:113]
	v_pk_fma_f32 v[180:181], v[30:31], v[172:173], v[180:181] op_sel_hi:[1,0,1]
	v_pk_fma_f32 v[192:193], v[32:33], v[172:173], v[192:193] op_sel_hi:[1,0,1]
	v_pk_fma_f32 v[180:181], v[22:23], v[174:175], v[180:181] op_sel_hi:[1,0,1]
	v_pk_fma_f32 v[192:193], v[24:25], v[174:175], v[192:193] op_sel_hi:[1,0,1]
	v_mfma_f32_16x16x4_f32 v[106:109], v143, v67, v[106:109]
	v_pk_fma_f32 v[180:181], v[18:19], v[174:175], v[180:181] op_sel:[0,1,0]
	v_pk_fma_f32 v[192:193], v[20:21], v[174:175], v[192:193] op_sel:[0,1,0]
	v_pk_fma_f32 v[180:181], v[14:15], v[232:233], v[180:181] op_sel_hi:[1,0,1]
	v_pk_fma_f32 v[192:193], v[16:17], v[232:233], v[192:193] op_sel_hi:[1,0,1]
	v_mfma_f32_16x16x4_f32 v[102:105], v143, v68, v[102:105]
	v_pk_fma_f32 v[180:181], v[10:11], v[232:233], v[180:181] op_sel:[0,1,0]
	v_pk_fma_f32 v[192:193], v[12:13], v[232:233], v[192:193] op_sel:[0,1,0]
	v_pk_fma_f32 v[180:181], v[6:7], v[234:235], v[180:181] op_sel_hi:[1,0,1]
	v_pk_fma_f32 v[192:193], v[8:9], v[234:235], v[192:193] op_sel_hi:[1,0,1]
	v_mfma_f32_16x16x4_f32 v[98:101], v143, v69, v[98:101]
	v_pk_fma_f32 v[180:181], v[2:3], v[234:235], v[180:181] op_sel:[0,1,0]
	v_pk_fma_f32 v[192:193], v[4:5], v[234:235], v[192:193] op_sel:[0,1,0]
	v_pk_mul_f32 v[180:181], v[146:147], v[180:181]
	v_pk_mul_f32 v[192:193], v[146:147], v[192:193]
	v_pk_fma_f32 v[236:237], v[144:145], v[66:67], v[180:181]
	v_pk_fma_f32 v[238:239], v[144:145], v[68:69], v[192:193]
	global_store_dwordx4 v[150:151], v[236:239], off nt
	v_lshl_add_u64 v[150:151], v[150:151], 0, s[58:59]
	ds_read_b32 v143, v160 offset:944
	ds_read_b128 v[172:175], v161 offset:7552
	ds_read_b128 v[232:235], v161 offset:7568
	s_waitcnt vmcnt(16)
; #define RS_LOAD(dst, it0) do { _Pragma("unroll") for (int u = 0; u < 8; ++u) dst[u] = __builtin_nontemporal_load((const f32x4*)(S0 + (size_t)(4 * ((it0) + u)) * DV)); } while (0)
; __device__ __forceinline__ void ret_sample_item(Frame& F, int item) {
;     ...
;     for (int it0 = 0; it0 < 64; it0 += 16) {
;         RS_LOAD(sb, it0 + 8);
;         RS_PROC(sa, it0);
;         { const int itn = it0 + 16 < 64 ? it0 + 16 : it0; RS_LOAD(sa, itn); }
;         RS_PROC(sb, it0 + 8);
;     }
	s_waitcnt lgkmcnt(3)
	v_cndmask_b32_e64 v141, 0, v141, s[6:7]
	v_pk_mul_f32 v[180:181], v[26:27], v[114:115] op_sel:[0,1]
	v_pk_mul_f32 v[192:193], v[28:29], v[114:115] op_sel:[0,1]
	v_mfma_f32_16x16x4_f32 v[110:113], v141, v74, v[110:113]
	v_pk_fma_f32 v[180:181], v[30:31], v[114:115], v[180:181] op_sel_hi:[1,0,1]
	v_pk_fma_f32 v[192:193], v[32:33], v[114:115], v[192:193] op_sel_hi:[1,0,1]
	v_pk_fma_f32 v[180:181], v[22:23], v[116:117], v[180:181] op_sel_hi:[1,0,1]
	v_pk_fma_f32 v[192:193], v[24:25], v[116:117], v[192:193] op_sel_hi:[1,0,1]
	v_mfma_f32_16x16x4_f32 v[106:109], v141, v75, v[106:109]
	v_pk_fma_f32 v[180:181], v[18:19], v[116:117], v[180:181] op_sel:[0,1,0]
	v_pk_fma_f32 v[192:193], v[20:21], v[116:117], v[192:193] op_sel:[0,1,0]
	v_pk_fma_f32 v[180:181], v[14:15], v[176:177], v[180:181] op_sel_hi:[1,0,1]
	v_pk_fma_f32 v[192:193], v[16:17], v[176:177], v[192:193] op_sel_hi:[1,0,1]
	v_mfma_f32_16x16x4_f32 v[102:105], v141, v76, v[102:105]
	v_pk_fma_f32 v[180:181], v[10:11], v[176:177], v[180:181] op_sel:[0,1,0]
	v_pk_fma_f32 v[192:193], v[12:13], v[176:177], v[192:193] op_sel:[0,1,0]
	v_pk_fma_f32 v[180:181], v[6:7], v[178:179], v[180:181] op_sel_hi:[1,0,1]
	v_pk_fma_f32 v[192:193], v[8:9], v[178:179], v[192:193] op_sel_hi:[1,0,1]
	v_mfma_f32_16x16x4_f32 v[98:101], v141, v77, v[98:101]
	v_pk_fma_f32 v[180:181], v[2:3], v[178:179], v[180:181] op_sel:[0,1,0]
	v_pk_fma_f32 v[192:193], v[4:5], v[178:179], v[192:193] op_sel:[0,1,0]
	v_pk_mul_f32 v[180:181], v[146:147], v[180:181]
	v_pk_mul_f32 v[192:193], v[146:147], v[192:193]
	v_pk_fma_f32 v[236:237], v[144:145], v[74:75], v[180:181]
	v_pk_fma_f32 v[238:239], v[144:145], v[76:77], v[192:193]
	global_store_dwordx4 v[150:151], v[236:239], off nt
	v_lshl_add_u64 v[150:151], v[150:151], 0, s[58:59]
	ds_read_b32 v141, v160 offset:960
	ds_read_b128 v[114:117], v161 offset:7680
	ds_read_b128 v[176:179], v161 offset:7696
	s_waitcnt vmcnt(15)
	s_waitcnt lgkmcnt(3)
	v_cndmask_b32_e64 v143, 0, v143, s[6:7]
	v_pk_mul_f32 v[180:181], v[26:27], v[172:173] op_sel:[0,1]
	v_pk_mul_f32 v[192:193], v[28:29], v[172:173] op_sel:[0,1]
	v_mfma_f32_16x16x4_f32 v[110:113], v143, v78, v[110:113]
	v_pk_fma_f32 v[180:181], v[30:31], v[172:173], v[180:181] op_sel_hi:[1,0,1]
	v_pk_fma_f32 v[192:193], v[32:33], v[172:173], v[192:193] op_sel_hi:[1,0,1]
	v_pk_fma_f32 v[180:181], v[22:23], v[174:175], v[180:181] op_sel_hi:[1,0,1]
	v_pk_fma_f32 v[192:193], v[24:25], v[174:175], v[192:193] op_sel_hi:[1,0,1]
	v_mfma_f32_16x16x4_f32 v[106:109], v143, v79, v[106:109]
	v_pk_fma_f32 v[180:181], v[18:19], v[174:175], v[180:181] op_sel:[0,1,0]
	v_pk_fma_f32 v[192:193], v[20:21], v[174:175], v[192:193] op_sel:[0,1,0]
	v_pk_fma_f32 v[180:181], v[14:15], v[232:233], v[180:181] op_sel_hi:[1,0,1]
	v_pk_fma_f32 v[192:193], v[16:17], v[232:233], v[192:193] op_sel_hi:[1,0,1]
	v_mfma_f32_16x16x4_f32 v[102:105], v143, v80, v[102:105]
	v_pk_fma_f32 v[180:181], v[10:11], v[232:233], v[180:181] op_sel:[0,1,0]
	v_pk_fma_f32 v[192:193], v[12:13], v[232:233], v[192:193] op_sel:[0,1,0]
	v_pk_fma_f32 v[180:181], v[6:7], v[234:235], v[180:181] op_sel_hi:[1,0,1]
	v_pk_fma_f32 v[192:193], v[8:9], v[234:235], v[192:193] op_sel_hi:[1,0,1]
	v_mfma_f32_16x16x4_f32 v[98:101], v143, v81, v[98:101]
	v_pk_fma_f32 v[180:181], v[2:3], v[234:235], v[180:181] op_sel:[0,1,0]
	v_pk_fma_f32 v[192:193], v[4:5], v[234:235], v[192:193] op_sel:[0,1,0]
	v_pk_mul_f32 v[180:181], v[146:147], v[180:181]
	v_pk_mul_f32 v[192:193], v[146:147], v[192:193]
	v_pk_fma_f32 v[236:237], v[144:145], v[78:79], v[180:181]
	v_pk_fma_f32 v[238:239], v[144:145], v[80:81], v[192:193]
	global_store_dwordx4 v[150:151], v[236:239], off nt
	v_lshl_add_u64 v[150:151], v[150:151], 0, s[58:59]
	ds_read_b32 v143, v160 offset:976
	ds_read_b128 v[172:175], v161 offset:7808
	ds_read_b128 v[232:235], v161 offset:7824
	s_waitcnt vmcnt(14)
	s_waitcnt lgkmcnt(3)
	v_cndmask_b32_e64 v141, 0, v141, s[6:7]
	v_pk_mul_f32 v[180:181], v[26:27], v[114:115] op_sel:[0,1]
	v_pk_mul_f32 v[192:193], v[28:29], v[114:115] op_sel:[0,1]
	v_mfma_f32_16x16x4_f32 v[110:113], v141, v70, v[110:113]
	v_pk_fma_f32 v[180:181], v[30:31], v[114:115], v[180:181] op_sel_hi:[1,0,1]
	v_pk_fma_f32 v[192:193], v[32:33], v[114:115], v[192:193] op_sel_hi:[1,0,1]
	v_pk_fma_f32 v[180:181], v[22:23], v[116:117], v[180:181] op_sel_hi:[1,0,1]
	v_pk_fma_f32 v[192:193], v[24:25], v[116:117], v[192:193] op_sel_hi:[1,0,1]
	v_mfma_f32_16x16x4_f32 v[106:109], v141, v71, v[106:109]
	v_pk_fma_f32 v[180:181], v[18:19], v[116:117], v[180:181] op_sel:[0,1,0]
	v_pk_fma_f32 v[192:193], v[20:21], v[116:117], v[192:193] op_sel:[0,1,0]
	v_pk_fma_f32 v[180:181], v[14:15], v[176:177], v[180:181] op_sel_hi:[1,0,1]
	v_pk_fma_f32 v[192:193], v[16:17], v[176:177], v[192:193] op_sel_hi:[1,0,1]
	v_mfma_f32_16x16x4_f32 v[102:105], v141, v72, v[102:105]
	v_pk_fma_f32 v[180:181], v[10:11], v[176:177], v[180:181] op_sel:[0,1,0]
	v_pk_fma_f32 v[192:193], v[12:13], v[176:177], v[192:193] op_sel:[0,1,0]
	v_pk_fma_f32 v[180:181], v[6:7], v[178:179], v[180:181] op_sel_hi:[1,0,1]
	v_pk_fma_f32 v[192:193], v[8:9], v[178:179], v[192:193] op_sel_hi:[1,0,1]
	v_mfma_f32_16x16x4_f32 v[98:101], v141, v73, v[98:101]
	v_pk_fma_f32 v[180:181], v[2:3], v[178:179], v[180:181] op_sel:[0,1,0]
	v_pk_fma_f32 v[192:193], v[4:5], v[178:179], v[192:193] op_sel:[0,1,0]
	v_pk_mul_f32 v[180:181], v[146:147], v[180:181]
	v_pk_mul_f32 v[192:193], v[146:147], v[192:193]
	v_pk_fma_f32 v[236:237], v[144:145], v[70:71], v[180:181]
	v_pk_fma_f32 v[238:239], v[144:145], v[72:73], v[192:193]
	global_store_dwordx4 v[150:151], v[236:239], off nt
	v_lshl_add_u64 v[150:151], v[150:151], 0, s[58:59]
	ds_read_b32 v141, v160 offset:992
	ds_read_b128 v[114:117], v161 offset:7936
	ds_read_b128 v[176:179], v161 offset:7952
	s_waitcnt vmcnt(13)
; #define RS_LOAD(dst, it0) do { _Pragma("unroll") for (int u = 0; u < 8; ++u) dst[u] = __builtin_nontemporal_load((const f32x4*)(S0 + (size_t)(4 * ((it0) + u)) * DV)); } while (0)
; __device__ __forceinline__ void ret_sample_item(Frame& F, int item) {
;     ...
;     for (int it0 = 0; it0 < 64; it0 += 16) {
;         RS_LOAD(sb, it0 + 8);
;         RS_PROC(sa, it0);
;         { const int itn = it0 + 16 < 64 ? it0 + 16 : it0; RS_LOAD(sa, itn); }
;         RS_PROC(sb, it0 + 8);
;     }
	s_waitcnt lgkmcnt(3)
	v_cndmask_b32_e64 v143, 0, v143, s[6:7]
	v_pk_mul_f32 v[180:181], v[26:27], v[172:173] op_sel:[0,1]
	v_pk_mul_f32 v[192:193], v[28:29], v[172:173] op_sel:[0,1]
	v_mfma_f32_16x16x4_f32 v[110:113], v143, v62, v[110:113]
	v_pk_fma_f32 v[180:181], v[30:31], v[172:173], v[180:181] op_sel_hi:[1,0,1]
	v_pk_fma_f32 v[192:193], v[32:33], v[172:173], v[192:193] op_sel_hi:[1,0,1]
	v_pk_fma_f32 v[180:181], v[22:23], v[174:175], v[180:181] op_sel_hi:[1,0,1]
	v_pk_fma_f32 v[192:193], v[24:25], v[174:175], v[192:193] op_sel_hi:[1,0,1]
	v_mfma_f32_16x16x4_f32 v[106:109], v143, v63, v[106:109]
	v_pk_fma_f32 v[180:181], v[18:19], v[174:175], v[180:181] op_sel:[0,1,0]
	v_pk_fma_f32 v[192:193], v[20:21], v[174:175], v[192:193] op_sel:[0,1,0]
	v_pk_fma_f32 v[180:181], v[14:15], v[232:233], v[180:181] op_sel_hi:[1,0,1]
	v_pk_fma_f32 v[192:193], v[16:17], v[232:233], v[192:193] op_sel_hi:[1,0,1]
	v_mfma_f32_16x16x4_f32 v[102:105], v143, v64, v[102:105]
	v_pk_fma_f32 v[180:181], v[10:11], v[232:233], v[180:181] op_sel:[0,1,0]
	v_pk_fma_f32 v[192:193], v[12:13], v[232:233], v[192:193] op_sel:[0,1,0]
	v_pk_fma_f32 v[180:181], v[6:7], v[234:235], v[180:181] op_sel_hi:[1,0,1]
	v_pk_fma_f32 v[192:193], v[8:9], v[234:235], v[192:193] op_sel_hi:[1,0,1]
	v_mfma_f32_16x16x4_f32 v[98:101], v143, v65, v[98:101]
	v_pk_fma_f32 v[180:181], v[2:3], v[234:235], v[180:181] op_sel:[0,1,0]
	v_pk_fma_f32 v[192:193], v[4:5], v[234:235], v[192:193] op_sel:[0,1,0]
	v_pk_mul_f32 v[180:181], v[146:147], v[180:181]
	v_pk_mul_f32 v[192:193], v[146:147], v[192:193]
	v_pk_fma_f32 v[236:237], v[144:145], v[62:63], v[180:181]
	v_pk_fma_f32 v[238:239], v[144:145], v[64:65], v[192:193]
	global_store_dwordx4 v[150:151], v[236:239], off nt
	v_lshl_add_u64 v[150:151], v[150:151], 0, s[58:59]
	ds_read_b32 v143, v160 offset:1008
	ds_read_b128 v[172:175], v161 offset:8064
	ds_read_b128 v[232:235], v161 offset:8080
	s_waitcnt vmcnt(12)
	s_waitcnt lgkmcnt(3)
	v_cndmask_b32_e64 v141, 0, v141, s[6:7]
	v_pk_mul_f32 v[180:181], v[26:27], v[114:115] op_sel:[0,1]
	v_pk_mul_f32 v[192:193], v[28:29], v[114:115] op_sel:[0,1]
	v_mfma_f32_16x16x4_f32 v[110:113], v141, v54, v[110:113]
	v_pk_fma_f32 v[180:181], v[30:31], v[114:115], v[180:181] op_sel_hi:[1,0,1]
	v_pk_fma_f32 v[192:193], v[32:33], v[114:115], v[192:193] op_sel_hi:[1,0,1]
	v_pk_fma_f32 v[180:181], v[22:23], v[116:117], v[180:181] op_sel_hi:[1,0,1]
	v_pk_fma_f32 v[192:193], v[24:25], v[116:117], v[192:193] op_sel_hi:[1,0,1]
	v_mfma_f32_16x16x4_f32 v[106:109], v141, v55, v[106:109]
	v_pk_fma_f32 v[180:181], v[18:19], v[116:117], v[180:181] op_sel:[0,1,0]
	v_pk_fma_f32 v[192:193], v[20:21], v[116:117], v[192:193] op_sel:[0,1,0]
	v_pk_fma_f32 v[180:181], v[14:15], v[176:177], v[180:181] op_sel_hi:[1,0,1]
	v_pk_fma_f32 v[192:193], v[16:17], v[176:177], v[192:193] op_sel_hi:[1,0,1]
	v_mfma_f32_16x16x4_f32 v[102:105], v141, v56, v[102:105]
	v_pk_fma_f32 v[180:181], v[10:11], v[176:177], v[180:181] op_sel:[0,1,0]
	v_pk_fma_f32 v[192:193], v[12:13], v[176:177], v[192:193] op_sel:[0,1,0]
	v_pk_fma_f32 v[180:181], v[6:7], v[178:179], v[180:181] op_sel_hi:[1,0,1]
	v_pk_fma_f32 v[192:193], v[8:9], v[178:179], v[192:193] op_sel_hi:[1,0,1]
	v_mfma_f32_16x16x4_f32 v[98:101], v141, v57, v[98:101]
	v_pk_fma_f32 v[180:181], v[2:3], v[178:179], v[180:181] op_sel:[0,1,0]
	v_pk_fma_f32 v[192:193], v[4:5], v[178:179], v[192:193] op_sel:[0,1,0]
	v_pk_mul_f32 v[180:181], v[146:147], v[180:181]
	v_pk_mul_f32 v[192:193], v[146:147], v[192:193]
	v_pk_fma_f32 v[236:237], v[144:145], v[54:55], v[180:181]
	v_pk_fma_f32 v[238:239], v[144:145], v[56:57], v[192:193]
	global_store_dwordx4 v[150:151], v[236:239], off nt
	v_lshl_add_u64 v[150:151], v[150:151], 0, s[58:59]
	s_waitcnt vmcnt(11)
	s_waitcnt lgkmcnt(0)
	v_cndmask_b32_e64 v143, 0, v143, s[6:7]
	v_pk_mul_f32 v[180:181], v[26:27], v[172:173] op_sel:[0,1]
	v_pk_mul_f32 v[192:193], v[28:29], v[172:173] op_sel:[0,1]
	v_mfma_f32_16x16x4_f32 v[110:113], v143, v50, v[110:113]
	v_pk_fma_f32 v[180:181], v[30:31], v[172:173], v[180:181] op_sel_hi:[1,0,1]
	v_pk_fma_f32 v[192:193], v[32:33], v[172:173], v[192:193] op_sel_hi:[1,0,1]
	v_pk_fma_f32 v[180:181], v[22:23], v[174:175], v[180:181] op_sel_hi:[1,0,1]
	v_pk_fma_f32 v[192:193], v[24:25], v[174:175], v[192:193] op_sel_hi:[1,0,1]
	v_mfma_f32_16x16x4_f32 v[106:109], v143, v51, v[106:109]
	v_pk_fma_f32 v[180:181], v[18:19], v[174:175], v[180:181] op_sel:[0,1,0]
	v_pk_fma_f32 v[192:193], v[20:21], v[174:175], v[192:193] op_sel:[0,1,0]
	v_pk_fma_f32 v[180:181], v[14:15], v[232:233], v[180:181] op_sel_hi:[1,0,1]
	v_pk_fma_f32 v[192:193], v[16:17], v[232:233], v[192:193] op_sel_hi:[1,0,1]
	v_mfma_f32_16x16x4_f32 v[102:105], v143, v52, v[102:105]
	v_pk_fma_f32 v[180:181], v[10:11], v[232:233], v[180:181] op_sel:[0,1,0]
	v_pk_fma_f32 v[192:193], v[12:13], v[232:233], v[192:193] op_sel:[0,1,0]
	v_pk_fma_f32 v[180:181], v[6:7], v[234:235], v[180:181] op_sel_hi:[1,0,1]
	v_pk_fma_f32 v[192:193], v[8:9], v[234:235], v[192:193] op_sel_hi:[1,0,1]
	v_mfma_f32_16x16x4_f32 v[98:101], v143, v53, v[98:101]
	v_pk_fma_f32 v[180:181], v[2:3], v[234:235], v[180:181] op_sel:[0,1,0]
	v_pk_fma_f32 v[192:193], v[4:5], v[234:235], v[192:193] op_sel:[0,1,0]
	v_pk_mul_f32 v[180:181], v[146:147], v[180:181]
	v_pk_mul_f32 v[192:193], v[146:147], v[192:193]
	v_pk_fma_f32 v[236:237], v[144:145], v[50:51], v[180:181]
	v_pk_fma_f32 v[238:239], v[144:145], v[52:53], v[192:193]
	global_store_dwordx4 v[150:151], v[236:239], off nt
	v_lshl_add_u64 v[150:151], v[150:151], 0, s[58:59]
	s_nop 7
	s_nop 3
	s_branch .LBB0_677
	s_nop 0
	s_nop 0
	s_nop 0
	s_nop 0
	s_nop 0
	s_nop 0
	s_nop 0
	s_nop 0
	s_nop 0
	s_nop 0
	s_nop 0
	s_nop 0
	s_nop 0
	s_nop 0
	s_nop 0
	s_nop 0
	s_nop 0
	s_nop 0
	s_nop 0
	s_nop 0
	s_nop 0
	s_nop 0
	s_nop 0
	s_nop 0
	s_nop 0
	s_nop 0
	s_nop 0
	s_nop 0
	s_nop 0
	s_nop 0
	s_nop 0
	s_nop 0
	s_nop 0
	s_nop 0
	s_nop 0
	s_nop 0
	s_nop 0
	s_nop 0
	s_nop 0
	s_nop 0
	s_nop 0
	s_nop 0
	s_nop 0
	s_nop 0
	s_nop 0
	s_nop 0
	s_nop 0
	s_nop 0
	s_nop 0
	s_nop 0
	s_nop 0
	s_nop 0
	s_nop 0
	s_nop 0
	s_nop 0
	s_nop 0
	s_nop 0
	s_nop 0
	s_nop 0
	s_nop 0
	s_nop 0
